# invprio
# baseline (speedup 1.0000x reference)
; #define STAGE(P, BASE, LD, br, kt) do { const char* _g = (const char*)((BASE) + (size_t)(br) * (LD) + (size_t)(kt) * 64); \
;     for (int _i = 0; _i < 2; ++_i) { int _b = tidx * 16 + _i * 8192; int _r, _c; stage_rc(_b, _r, _c); \
;       __builtin_amdgcn_global_load_lds((const unsigned*)(_g + (unsigned)((_r * (LD) + _c) * 2)), (unsigned*)((char*)(P) + _b), 16, 0, 0); } } while (0)
; #define LDA(dst, b, h) for (int m = 0; m < 4; ++m) for (int k = 0; k < 2; ++k) \
;     dst[m][k] = *reinterpret_cast<const bf16x8*>((char*)SA(b, h) + lds_byte(wr * 64 + m * 16 + fr, k * 32 + fq * 8))
; #define LDB(dst, b, h) for (int n = 0; n < 2; ++n) for (int k = 0; k < 2; ++k) \
;     dst[n][k] = *reinterpret_cast<const bf16x8*>((char*)SB(b, h) + lds_byte(wc * 32 + n * 16 + fr, k * 32 + fq * 8))
; #define MMA(ai, bj, At_, Bt_) do { __builtin_amdgcn_s_setprio(1); \
;     for (int k = 0; k < 2; ++k) for (int m = 0; m < 4; ++m) for (int n = 0; n < 2; ++n) \
;       acc[ai][bj][m][n] = __builtin_amdgcn_mfma_f32_16x16x32_bf16(At_[m][k], Bt_[n][k], acc[ai][bj][m][n], 0, 0, 0); \
;     __builtin_amdgcn_s_setprio(0); } while (0)
; #define WAIT_V(n) asm volatile("s_waitcnt vmcnt(" #n ")" ::: "memory")
; #define WAIT_L(n) asm volatile("s_waitcnt lgkmcnt(" #n ")" ::: "memory")
; #define BAR __builtin_amdgcn_s_barrier()
; #define SCHED __builtin_amdgcn_sched_barrier(0)
; template <int EPI, int lda, int ldb, int N, int K>
; __device__ __forceinline__ void gemm_phase(const u16* __restrict__ A, const u16* __restrict__ Bt, const GemmEpi ep, int wv) {
;     ...
;     for (int t = 0; t < nt - 2; t += 2) {
;       LDB(B0, 0, 0); SCHED; LDA(At, 0, 0); STAGE(SA(1, 1), Ab, lda, brow + HALF, t + 1);
;       WAIT_L(8); BAR; WAIT_L(0); MMA(0, 0, At, B0); BAR; SCHED;
;       LDB(B1, 0, 1); STAGE(SB(0, 0), Bt, ldb, bcol, t + 2);
;       BAR; WAIT_L(0); MMA(0, 1, At, B1); BAR;
;       LDA(At, 0, 1); STAGE(SA(0, 0), Ab, lda, brow, t + 2);
;       BAR; WAIT_L(0); MMA(1, 0, At, B0); BAR; SCHED;
;       STAGE(SB(0, 1), Bt, ldb, bcol + HALF, t + 2);
;       WAIT_V(6); BAR; MMA(1, 1, At, B1); BAR;
;       LDB(B0, 1, 0); SCHED; LDA(At, 1, 0); STAGE(SA(0, 1), Ab, lda, brow + HALF, t + 2);
;       WAIT_L(8); BAR; WAIT_L(0); MMA(0, 0, At, B0); BAR; SCHED;
.LBB0_53:
	ds_read_b128 v[172:175], v161
	ds_read_b128 v[176:179], v161 offset:1024
	ds_read_b128 v[180:183], v161 offset:2048
	ds_read_b128 v[184:187], v161 offset:3072
	v_add_u32_e32 v169, 0xc000, v148
	v_lshl_add_u64 v[236:237], v[136:137], 0, s[42:43]
	v_readfirstlane_b32 s45, v169
	v_add_u32_e32 v170, 0xe000, v148
	v_lshl_add_u64 v[162:163], v[236:237], 0, s[14:15]
	s_mov_b32 m0, s45
	v_lshl_add_u64 v[238:239], v[134:135], 0, s[42:43]
	v_readfirstlane_b32 s45, v170
	ds_read_b128 v[164:167], v152
	ds_read_b128 v[188:191], v152 offset:1024
	ds_read_b128 v[192:195], v151
	ds_read_b128 v[196:199], v151 offset:1024
	ds_read_b128 v[200:203], v150
	ds_read_b128 v[204:207], v150 offset:1024
	ds_read_b128 v[208:211], v149
	ds_read_b128 v[212:215], v149 offset:1024
	global_load_lds_dwordx4 v[162:163], off
	v_lshl_add_u64 v[162:163], v[238:239], 0, s[14:15]
	s_mov_b32 m0, s45
	s_nop 0
	global_load_lds_dwordx4 v[162:163], off
	s_waitcnt lgkmcnt(8)
	s_barrier
	s_waitcnt lgkmcnt(0)
	s_setprio 0
	s_waitcnt lgkmcnt(0)
	v_mfma_f32_16x16x32_bf16 v[124:127], v[172:175], v[164:167], v[124:127]
	v_mfma_f32_16x16x32_bf16 v[120:123], v[180:183], v[164:167], v[120:123]
	v_mfma_f32_16x16x32_bf16 v[116:119], v[172:175], v[192:195], v[116:119]
	v_mfma_f32_16x16x32_bf16 v[112:115], v[180:183], v[192:195], v[112:115]
	v_mfma_f32_16x16x32_bf16 v[108:111], v[172:175], v[200:203], v[108:111]
	v_mfma_f32_16x16x32_bf16 v[104:107], v[180:183], v[200:203], v[104:107]
	v_mfma_f32_16x16x32_bf16 v[100:103], v[172:175], v[208:211], v[100:103]
	v_mfma_f32_16x16x32_bf16 v[96:99], v[180:183], v[208:211], v[96:99]
	v_mfma_f32_16x16x32_bf16 v[124:127], v[176:179], v[188:191], v[124:127]
	v_mfma_f32_16x16x32_bf16 v[120:123], v[184:187], v[188:191], v[120:123]
	v_mfma_f32_16x16x32_bf16 v[116:119], v[176:179], v[196:199], v[116:119]
	v_mfma_f32_16x16x32_bf16 v[112:115], v[184:187], v[196:199], v[112:115]
	v_mfma_f32_16x16x32_bf16 v[108:111], v[176:179], v[204:207], v[108:111]
	v_mfma_f32_16x16x32_bf16 v[104:107], v[184:187], v[204:207], v[104:107]
	v_mfma_f32_16x16x32_bf16 v[100:103], v[176:179], v[212:215], v[100:103]
	v_mfma_f32_16x16x32_bf16 v[96:99], v[184:187], v[212:215], v[96:99]
	s_setprio 1
	s_barrier
	v_add_u32_e32 v162, s54, v153
	v_lshl_add_u64 v[240:241], v[140:141], 0, s[42:43]
	v_readfirstlane_b32 s45, v162
	v_add_u32_e32 v163, 0x2000, v162
	v_lshl_add_u64 v[232:233], v[240:241], 0, s[16:17]
	s_mov_b32 m0, s45
	v_lshl_add_u64 v[242:243], v[138:139], 0, s[42:43]
	v_readfirstlane_b32 s45, v163
	ds_read_b128 v[216:219], v160
	ds_read_b128 v[220:223], v160 offset:1024
	ds_read_b128 v[224:227], v160 offset:2048
	ds_read_b128 v[228:231], v160 offset:3072
	global_load_lds_dwordx4 v[232:233], off
	v_lshl_add_u64 v[232:233], v[242:243], 0, s[16:17]
	s_mov_b32 m0, s45
	s_nop 0
	global_load_lds_dwordx4 v[232:233], off
	s_barrier
	s_waitcnt lgkmcnt(0)
	s_setprio 0
	s_waitcnt lgkmcnt(0)
	v_mfma_f32_16x16x32_bf16 v[92:95], v[216:219], v[164:167], v[92:95]
	v_mfma_f32_16x16x32_bf16 v[88:91], v[224:227], v[164:167], v[88:91]
	v_mfma_f32_16x16x32_bf16 v[84:87], v[216:219], v[192:195], v[84:87]
	v_mfma_f32_16x16x32_bf16 v[80:83], v[224:227], v[192:195], v[80:83]
	v_mfma_f32_16x16x32_bf16 v[76:79], v[216:219], v[200:203], v[76:79]
	v_mfma_f32_16x16x32_bf16 v[72:75], v[224:227], v[200:203], v[72:75]
	v_mfma_f32_16x16x32_bf16 v[68:71], v[216:219], v[208:211], v[68:71]
	v_mfma_f32_16x16x32_bf16 v[64:67], v[224:227], v[208:211], v[64:67]
	v_mfma_f32_16x16x32_bf16 v[92:95], v[220:223], v[188:191], v[92:95]
	v_mfma_f32_16x16x32_bf16 v[88:91], v[228:231], v[188:191], v[88:91]
	v_mfma_f32_16x16x32_bf16 v[84:87], v[220:223], v[196:199], v[84:87]
	v_mfma_f32_16x16x32_bf16 v[80:83], v[228:231], v[196:199], v[80:83]
	v_mfma_f32_16x16x32_bf16 v[76:79], v[220:223], v[204:207], v[76:79]
	v_mfma_f32_16x16x32_bf16 v[72:75], v[228:231], v[204:207], v[72:75]
	v_mfma_f32_16x16x32_bf16 v[68:71], v[220:223], v[212:215], v[68:71]
	v_mfma_f32_16x16x32_bf16 v[64:67], v[228:231], v[212:215], v[64:67]
	s_setprio 1
	v_readfirstlane_b32 s45, v148
	v_lshl_add_u64 v[164:165], v[236:237], 0, s[18:19]
	s_mov_b32 m0, s45
	s_barrier
	ds_read_b128 v[188:191], v152 offset:16384
	ds_read_b128 v[192:195], v152 offset:17408
	ds_read_b128 v[196:199], v151 offset:16384
	ds_read_b128 v[200:203], v151 offset:17408
	ds_read_b128 v[204:207], v150 offset:16384
	ds_read_b128 v[208:211], v150 offset:17408
	ds_read_b128 v[212:215], v149 offset:16384
	ds_read_b128 v[232:235], v149 offset:17408
	global_load_lds_dwordx4 v[164:165], off
	v_add_u32_e32 v164, 0x2000, v148
	v_lshl_add_u64 v[166:167], v[238:239], 0, s[18:19]
	v_readfirstlane_b32 s45, v164
	s_mov_b32 m0, s45
	s_nop 0
	global_load_lds_dwordx4 v[166:167], off
	s_barrier
	s_waitcnt lgkmcnt(0)
	s_setprio 0
	s_waitcnt lgkmcnt(0)
	v_mfma_f32_16x16x32_bf16 v[60:63], v[172:175], v[188:191], v[60:63]
	v_mfma_f32_16x16x32_bf16 v[56:59], v[180:183], v[188:191], v[56:59]
	v_mfma_f32_16x16x32_bf16 v[52:55], v[172:175], v[196:199], v[52:55]
	v_mfma_f32_16x16x32_bf16 v[48:51], v[180:183], v[196:199], v[48:51]
	v_mfma_f32_16x16x32_bf16 v[44:47], v[172:175], v[204:207], v[44:47]
	v_mfma_f32_16x16x32_bf16 v[40:43], v[180:183], v[204:207], v[40:43]
	v_mfma_f32_16x16x32_bf16 v[36:39], v[172:175], v[212:215], v[36:39]
	v_mfma_f32_16x16x32_bf16 v[32:35], v[180:183], v[212:215], v[32:35]
	v_mfma_f32_16x16x32_bf16 v[60:63], v[176:179], v[192:195], v[60:63]
	v_mfma_f32_16x16x32_bf16 v[56:59], v[184:187], v[192:195], v[56:59]
	v_mfma_f32_16x16x32_bf16 v[52:55], v[176:179], v[200:203], v[52:55]
	v_mfma_f32_16x16x32_bf16 v[48:51], v[184:187], v[200:203], v[48:51]
	v_mfma_f32_16x16x32_bf16 v[44:47], v[176:179], v[208:211], v[44:47]
	v_mfma_f32_16x16x32_bf16 v[40:43], v[184:187], v[208:211], v[40:43]
	v_mfma_f32_16x16x32_bf16 v[36:39], v[176:179], v[232:235], v[36:39]
	v_mfma_f32_16x16x32_bf16 v[32:35], v[184:187], v[232:235], v[32:35]
	s_setprio 1
	s_barrier
; #define STAGE(P, BASE, LD, br, kt) do { const char* _g = (const char*)((BASE) + (size_t)(br) * (LD) + (size_t)(kt) * 64); \
;     for (int _i = 0; _i < 2; ++_i) { int _b = tidx * 16 + _i * 8192; int _r, _c; stage_rc(_b, _r, _c); \
;       __builtin_amdgcn_global_load_lds((const unsigned*)(_g + (unsigned)((_r * (LD) + _c) * 2)), (unsigned*)((char*)(P) + _b), 16, 0, 0); } } while (0)
; #define LDA(dst, b, h) for (int m = 0; m < 4; ++m) for (int k = 0; k < 2; ++k) \
;     dst[m][k] = *reinterpret_cast<const bf16x8*>((char*)SA(b, h) + lds_byte(wr * 64 + m * 16 + fr, k * 32 + fq * 8))
; #define LDB(dst, b, h) for (int n = 0; n < 2; ++n) for (int k = 0; k < 2; ++k) \
;     dst[n][k] = *reinterpret_cast<const bf16x8*>((char*)SB(b, h) + lds_byte(wc * 32 + n * 16 + fr, k * 32 + fq * 8))
; #define MMA(ai, bj, At_, Bt_) do { __builtin_amdgcn_s_setprio(1); \
;     for (int k = 0; k < 2; ++k) for (int m = 0; m < 4; ++m) for (int n = 0; n < 2; ++n) \
;       acc[ai][bj][m][n] = __builtin_amdgcn_mfma_f32_16x16x32_bf16(At_[m][k], Bt_[n][k], acc[ai][bj][m][n], 0, 0, 0); \
;     __builtin_amdgcn_s_setprio(0); } while (0)
; #define WAIT_V(n) asm volatile("s_waitcnt vmcnt(" #n ")" ::: "memory")
; #define WAIT_L(n) asm volatile("s_waitcnt lgkmcnt(" #n ")" ::: "memory")
; #define BAR __builtin_amdgcn_s_barrier()
; #define SCHED __builtin_amdgcn_sched_barrier(0)
; template <int EPI, int lda, int ldb, int N, int K>
; __device__ __forceinline__ void gemm_phase(const u16* __restrict__ A, const u16* __restrict__ Bt, const GemmEpi ep, int wv) {
;     ...
;       STAGE(SB(0, 1), Bt, ldb, bcol + HALF, t + 2);
;       WAIT_V(6); BAR; MMA(1, 1, At, B1); BAR;
;       LDB(B0, 1, 0); SCHED; LDA(At, 1, 0); STAGE(SA(0, 1), Ab, lda, brow + HALF, t + 2);
;       WAIT_L(8); BAR; WAIT_L(0); MMA(0, 0, At, B0); BAR; SCHED;
;       LDB(B1, 1, 1); STAGE(SB(1, 0), Bt, ldb, bcol, t + 3);
;       BAR; WAIT_L(0); MMA(0, 1, At, B1); BAR;
;       LDA(At, 1, 1); STAGE(SA(1, 0), Ab, lda, brow, t + 3);
;       BAR; WAIT_L(0); MMA(1, 0, At, B0); BAR; SCHED;
	v_add_u32_e32 v165, s55, v153
	v_lshl_add_u64 v[166:167], v[240:241], 0, s[20:21]
	v_readfirstlane_b32 s45, v165
	s_mov_b32 m0, s45
	v_lshl_add_u64 v[172:173], v[242:243], 0, s[20:21]
	global_load_lds_dwordx4 v[166:167], off
	v_add_u32_e32 v166, 0x2000, v165
	s_nop 0
	v_readfirstlane_b32 s45, v166
	s_mov_b32 m0, s45
	s_nop 0
	global_load_lds_dwordx4 v[172:173], off
	s_waitcnt vmcnt(6)
	s_barrier
	s_setprio 0
	v_mfma_f32_16x16x32_bf16 v[28:31], v[216:219], v[188:191], v[28:31]
	v_mfma_f32_16x16x32_bf16 v[24:27], v[224:227], v[188:191], v[24:27]
	v_mfma_f32_16x16x32_bf16 v[20:23], v[216:219], v[196:199], v[20:23]
	v_mfma_f32_16x16x32_bf16 v[16:19], v[224:227], v[196:199], v[16:19]
	v_mfma_f32_16x16x32_bf16 v[12:15], v[216:219], v[204:207], v[12:15]
	v_mfma_f32_16x16x32_bf16 v[8:11], v[224:227], v[204:207], v[8:11]
	v_mfma_f32_16x16x32_bf16 v[4:7], v[216:219], v[212:215], v[4:7]
	v_mfma_f32_16x16x32_bf16 v[0:3], v[224:227], v[212:215], v[0:3]
	v_mfma_f32_16x16x32_bf16 v[28:31], v[220:223], v[192:195], v[28:31]
	v_mfma_f32_16x16x32_bf16 v[24:27], v[228:231], v[192:195], v[24:27]
	v_mfma_f32_16x16x32_bf16 v[20:23], v[220:223], v[200:203], v[20:23]
	v_mfma_f32_16x16x32_bf16 v[16:19], v[228:231], v[200:203], v[16:19]
	v_mfma_f32_16x16x32_bf16 v[12:15], v[220:223], v[208:211], v[12:15]
	v_mfma_f32_16x16x32_bf16 v[8:11], v[228:231], v[208:211], v[8:11]
	v_mfma_f32_16x16x32_bf16 v[4:7], v[220:223], v[232:235], v[4:7]
	v_mfma_f32_16x16x32_bf16 v[0:3], v[228:231], v[232:235], v[0:3]
	s_setprio 1
	s_barrier
	ds_read_b128 v[172:175], v156
	ds_read_b128 v[176:179], v156 offset:1024
	ds_read_b128 v[180:183], v156 offset:2048
	ds_read_b128 v[184:187], v156 offset:3072
	v_add_u32_e32 v167, 0x4000, v148
	v_add_u32_e32 v168, 0x6000, v148
	v_readfirstlane_b32 s45, v167
	v_lshl_add_u64 v[220:221], v[236:237], 0, s[22:23]
	s_mov_b32 m0, s45
	v_readfirstlane_b32 s45, v168
	ds_read_b128 v[188:191], v152 offset:32768
	ds_read_b128 v[192:195], v152 offset:33792
	ds_read_b128 v[196:199], v151 offset:32768
	ds_read_b128 v[200:203], v151 offset:33792
	ds_read_b128 v[204:207], v150 offset:32768
	ds_read_b128 v[208:211], v150 offset:33792
	ds_read_b128 v[212:215], v149 offset:32768
	ds_read_b128 v[216:219], v149 offset:33792
	global_load_lds_dwordx4 v[220:221], off
	v_lshl_add_u64 v[220:221], v[238:239], 0, s[22:23]
	s_mov_b32 m0, s45
	s_nop 0
	global_load_lds_dwordx4 v[220:221], off
	s_waitcnt lgkmcnt(8)
	s_barrier
	s_waitcnt lgkmcnt(0)
	s_setprio 0
	s_waitcnt lgkmcnt(0)
	v_mfma_f32_16x16x32_bf16 v[124:127], v[172:175], v[188:191], v[124:127]
	v_mfma_f32_16x16x32_bf16 v[120:123], v[180:183], v[188:191], v[120:123]
	v_mfma_f32_16x16x32_bf16 v[116:119], v[172:175], v[196:199], v[116:119]
	v_mfma_f32_16x16x32_bf16 v[112:115], v[180:183], v[196:199], v[112:115]
	v_mfma_f32_16x16x32_bf16 v[108:111], v[172:175], v[204:207], v[108:111]
	v_mfma_f32_16x16x32_bf16 v[104:107], v[180:183], v[204:207], v[104:107]
	v_mfma_f32_16x16x32_bf16 v[100:103], v[172:175], v[212:215], v[100:103]
	v_mfma_f32_16x16x32_bf16 v[96:99], v[180:183], v[212:215], v[96:99]
	v_mfma_f32_16x16x32_bf16 v[124:127], v[176:179], v[192:195], v[124:127]
	v_mfma_f32_16x16x32_bf16 v[120:123], v[184:187], v[192:195], v[120:123]
	v_mfma_f32_16x16x32_bf16 v[116:119], v[176:179], v[200:203], v[116:119]
	v_mfma_f32_16x16x32_bf16 v[112:115], v[184:187], v[200:203], v[112:115]
	v_mfma_f32_16x16x32_bf16 v[108:111], v[176:179], v[208:211], v[108:111]
	v_mfma_f32_16x16x32_bf16 v[104:107], v[184:187], v[208:211], v[104:107]
	v_mfma_f32_16x16x32_bf16 v[100:103], v[176:179], v[216:219], v[100:103]
	v_mfma_f32_16x16x32_bf16 v[96:99], v[184:187], v[216:219], v[96:99]
	s_setprio 1
	s_barrier
	v_readfirstlane_b32 s45, v155
	v_add_u32_e32 v171, 0x2000, v155
	v_lshl_add_u64 v[244:245], v[240:241], 0, s[24:25]
	s_mov_b32 m0, s45
	v_readfirstlane_b32 s45, v171
	ds_read_b128 v[220:223], v154
	ds_read_b128 v[224:227], v154 offset:1024
	ds_read_b128 v[228:231], v154 offset:2048
	ds_read_b128 v[232:235], v154 offset:3072
	global_load_lds_dwordx4 v[244:245], off
	v_lshl_add_u64 v[244:245], v[242:243], 0, s[24:25]
	s_mov_b32 m0, s45
	s_nop 0
	global_load_lds_dwordx4 v[244:245], off
	s_barrier
	s_waitcnt lgkmcnt(0)
	s_setprio 0
	s_waitcnt lgkmcnt(0)
	v_mfma_f32_16x16x32_bf16 v[92:95], v[220:223], v[188:191], v[92:95]
	v_mfma_f32_16x16x32_bf16 v[88:91], v[228:231], v[188:191], v[88:91]
	v_mfma_f32_16x16x32_bf16 v[84:87], v[220:223], v[196:199], v[84:87]
	v_mfma_f32_16x16x32_bf16 v[80:83], v[228:231], v[196:199], v[80:83]
	v_mfma_f32_16x16x32_bf16 v[76:79], v[220:223], v[204:207], v[76:79]
	v_mfma_f32_16x16x32_bf16 v[72:75], v[228:231], v[204:207], v[72:75]
	v_mfma_f32_16x16x32_bf16 v[68:71], v[220:223], v[212:215], v[68:71]
	v_mfma_f32_16x16x32_bf16 v[64:67], v[228:231], v[212:215], v[64:67]
	v_mfma_f32_16x16x32_bf16 v[92:95], v[224:227], v[192:195], v[92:95]
	v_mfma_f32_16x16x32_bf16 v[88:91], v[232:235], v[192:195], v[88:91]
	v_mfma_f32_16x16x32_bf16 v[84:87], v[224:227], v[200:203], v[84:87]
	v_mfma_f32_16x16x32_bf16 v[80:83], v[232:235], v[200:203], v[80:83]
	v_mfma_f32_16x16x32_bf16 v[76:79], v[224:227], v[208:211], v[76:79]
	v_mfma_f32_16x16x32_bf16 v[72:75], v[232:235], v[208:211], v[72:75]
	v_mfma_f32_16x16x32_bf16 v[68:71], v[224:227], v[216:219], v[68:71]
	v_mfma_f32_16x16x32_bf16 v[64:67], v[232:235], v[216:219], v[64:67]
	s_setprio 1
	v_readfirstlane_b32 s45, v157
	v_lshl_add_u64 v[236:237], v[236:237], 0, s[26:27]
	s_mov_b32 m0, s45
	v_readfirstlane_b32 s45, v158
	s_barrier
; #define STAGE(P, BASE, LD, br, kt) do { const char* _g = (const char*)((BASE) + (size_t)(br) * (LD) + (size_t)(kt) * 64); \
;     for (int _i = 0; _i < 2; ++_i) { int _b = tidx * 16 + _i * 8192; int _r, _c; stage_rc(_b, _r, _c); \
;       __builtin_amdgcn_global_load_lds((const unsigned*)(_g + (unsigned)((_r * (LD) + _c) * 2)), (unsigned*)((char*)(P) + _b), 16, 0, 0); } } while (0)
; #define LDA(dst, b, h) for (int m = 0; m < 4; ++m) for (int k = 0; k < 2; ++k) \
;     dst[m][k] = *reinterpret_cast<const bf16x8*>((char*)SA(b, h) + lds_byte(wr * 64 + m * 16 + fr, k * 32 + fq * 8))
; #define LDB(dst, b, h) for (int n = 0; n < 2; ++n) for (int k = 0; k < 2; ++k) \
;     dst[n][k] = *reinterpret_cast<const bf16x8*>((char*)SB(b, h) + lds_byte(wc * 32 + n * 16 + fr, k * 32 + fq * 8))
; #define MMA(ai, bj, At_, Bt_) do { __builtin_amdgcn_s_setprio(1); \
;     for (int k = 0; k < 2; ++k) for (int m = 0; m < 4; ++m) for (int n = 0; n < 2; ++n) \
;       acc[ai][bj][m][n] = __builtin_amdgcn_mfma_f32_16x16x32_bf16(At_[m][k], Bt_[n][k], acc[ai][bj][m][n], 0, 0, 0); \
;     __builtin_amdgcn_s_setprio(0); } while (0)
; #define WAIT_V(n) asm volatile("s_waitcnt vmcnt(" #n ")" ::: "memory")
; #define WAIT_L(n) asm volatile("s_waitcnt lgkmcnt(" #n ")" ::: "memory")
; #define BAR __builtin_amdgcn_s_barrier()
; #define SCHED __builtin_amdgcn_sched_barrier(0)
; template <int EPI, int lda, int ldb, int N, int K>
; __device__ __forceinline__ void gemm_phase(const u16* __restrict__ A, const u16* __restrict__ Bt, const GemmEpi ep, int wv) {
;     ...
;       LDB(B1, 1, 1); STAGE(SB(1, 0), Bt, ldb, bcol, t + 3);
;       BAR; WAIT_L(0); MMA(0, 1, At, B1); BAR;
;       LDA(At, 1, 1); STAGE(SA(1, 0), Ab, lda, brow, t + 3);
;       BAR; WAIT_L(0); MMA(1, 0, At, B0); BAR; SCHED;
;       STAGE(SB(1, 1), Bt, ldb, bcol + HALF, t + 3);
;       WAIT_V(6); BAR; MMA(1, 1, At, B1); BAR;
;     }
;     { LDB(B0, 0, 0); LDA(At, 0, 0); STAGE(SA(1, 1), Ab, lda, brow + HALF, nt - 1);
;       BAR; WAIT_L(0); MMA(0, 0, At, B0); BAR;
;       LDB(B1, 0, 1); BAR; WAIT_L(0); MMA(0, 1, At, B1); BAR;
	ds_read_b128 v[188:191], v152 offset:49152
	ds_read_b128 v[192:195], v152 offset:50176
	ds_read_b128 v[196:199], v151 offset:49152
	ds_read_b128 v[200:203], v151 offset:50176
	ds_read_b128 v[204:207], v150 offset:49152
	ds_read_b128 v[208:211], v150 offset:50176
	ds_read_b128 v[212:215], v149 offset:49152
	ds_read_b128 v[216:219], v149 offset:50176
	global_load_lds_dwordx4 v[236:237], off
	v_lshl_add_u64 v[236:237], v[238:239], 0, s[26:27]
	s_mov_b32 m0, s45
	s_nop 0
	global_load_lds_dwordx4 v[236:237], off
	s_barrier
	s_waitcnt lgkmcnt(0)
	s_setprio 0
	s_waitcnt lgkmcnt(0)
	v_mfma_f32_16x16x32_bf16 v[60:63], v[172:175], v[188:191], v[60:63]
	v_mfma_f32_16x16x32_bf16 v[56:59], v[180:183], v[188:191], v[56:59]
	v_mfma_f32_16x16x32_bf16 v[52:55], v[172:175], v[196:199], v[52:55]
	v_mfma_f32_16x16x32_bf16 v[48:51], v[180:183], v[196:199], v[48:51]
	v_mfma_f32_16x16x32_bf16 v[44:47], v[172:175], v[204:207], v[44:47]
	v_mfma_f32_16x16x32_bf16 v[40:43], v[180:183], v[204:207], v[40:43]
	v_mfma_f32_16x16x32_bf16 v[36:39], v[172:175], v[212:215], v[36:39]
	v_mfma_f32_16x16x32_bf16 v[32:35], v[180:183], v[212:215], v[32:35]
	v_mfma_f32_16x16x32_bf16 v[60:63], v[176:179], v[192:195], v[60:63]
	v_mfma_f32_16x16x32_bf16 v[56:59], v[184:187], v[192:195], v[56:59]
	v_mfma_f32_16x16x32_bf16 v[52:55], v[176:179], v[200:203], v[52:55]
	v_mfma_f32_16x16x32_bf16 v[48:51], v[184:187], v[200:203], v[48:51]
	v_mfma_f32_16x16x32_bf16 v[44:47], v[176:179], v[208:211], v[44:47]
	v_mfma_f32_16x16x32_bf16 v[40:43], v[184:187], v[208:211], v[40:43]
	v_mfma_f32_16x16x32_bf16 v[36:39], v[176:179], v[216:219], v[36:39]
	v_mfma_f32_16x16x32_bf16 v[32:35], v[184:187], v[216:219], v[32:35]
	s_setprio 1
	s_barrier
	v_readfirstlane_b32 s45, v159
	v_add_u32_e32 v171, 0x2000, v159
	v_lshl_add_u64 v[172:173], v[240:241], 0, s[34:35]
	s_mov_b32 m0, s45
	v_readfirstlane_b32 s45, v171
	global_load_lds_dwordx4 v[172:173], off
	v_lshl_add_u64 v[172:173], v[242:243], 0, s[34:35]
	s_mov_b32 m0, s45
	s_nop 0
	global_load_lds_dwordx4 v[172:173], off
	s_waitcnt vmcnt(6)
	s_barrier
	s_setprio 0
	v_mfma_f32_16x16x32_bf16 v[28:31], v[220:223], v[188:191], v[28:31]
	v_mfma_f32_16x16x32_bf16 v[24:27], v[228:231], v[188:191], v[24:27]
	v_mfma_f32_16x16x32_bf16 v[20:23], v[220:223], v[196:199], v[20:23]
	v_mfma_f32_16x16x32_bf16 v[16:19], v[228:231], v[196:199], v[16:19]
	v_mfma_f32_16x16x32_bf16 v[12:15], v[220:223], v[204:207], v[12:15]
	v_mfma_f32_16x16x32_bf16 v[8:11], v[228:231], v[204:207], v[8:11]
	v_mfma_f32_16x16x32_bf16 v[4:7], v[220:223], v[212:215], v[4:7]
	v_mfma_f32_16x16x32_bf16 v[0:3], v[228:231], v[212:215], v[0:3]
	v_mfma_f32_16x16x32_bf16 v[28:31], v[224:227], v[192:195], v[28:31]
	v_mfma_f32_16x16x32_bf16 v[24:27], v[232:235], v[192:195], v[24:27]
	v_mfma_f32_16x16x32_bf16 v[20:23], v[224:227], v[200:203], v[20:23]
	v_mfma_f32_16x16x32_bf16 v[16:19], v[232:235], v[200:203], v[16:19]
	v_mfma_f32_16x16x32_bf16 v[12:15], v[224:227], v[208:211], v[12:15]
	v_mfma_f32_16x16x32_bf16 v[8:11], v[232:235], v[208:211], v[8:11]
	v_mfma_f32_16x16x32_bf16 v[4:7], v[224:227], v[216:219], v[4:7]
	v_mfma_f32_16x16x32_bf16 v[0:3], v[232:235], v[216:219], v[0:3]
	s_setprio 1
	s_add_i32 s44, s44, 2
	s_add_u32 s42, s42, 0x100
	s_addc_u32 s43, s43, 0
	s_cmp_gt_u32 s44, 27
	s_barrier
	s_cbranch_scc0 .LBB0_53
	s_add_i32 s42, s38, 0x80
	s_mul_hi_i32 s43, s42, 0x1080
	s_mulk_i32 s42, 0x1080
	s_add_u32 s42, s51, s42
	s_addc_u32 s43, s52, s43
	v_lshl_add_u64 v[158:159], s[42:43], 0, v[128:129]
	v_readfirstlane_b32 s44, v169
	v_lshl_add_u64 v[158:159], v[158:159], 0, s[36:37]
	s_mov_b32 m0, s44
	ds_read_b128 v[134:137], v161
	ds_read_b128 v[138:141], v161 offset:1024
	ds_read_b128 v[172:175], v161 offset:2048
	ds_read_b128 v[176:179], v161 offset:3072
	ds_read_b128 v[180:183], v152
	ds_read_b128 v[184:187], v152 offset:1024
	ds_read_b128 v[188:191], v151
	ds_read_b128 v[192:195], v151 offset:1024
	ds_read_b128 v[196:199], v150
	ds_read_b128 v[200:203], v150 offset:1024
	ds_read_b128 v[204:207], v149
	ds_read_b128 v[208:211], v149 offset:1024
	global_load_lds_dwordx4 v[158:159], off
	v_lshl_add_u64 v[158:159], s[42:43], 0, v[132:133]
	v_readfirstlane_b32 s42, v170
	v_lshl_add_u64 v[158:159], v[158:159], 0, s[36:37]
	s_mov_b32 m0, s42
	s_nop 0
	global_load_lds_dwordx4 v[158:159], off
	s_barrier
	s_waitcnt lgkmcnt(0)
	s_setprio 0
	s_waitcnt lgkmcnt(0)
	v_mfma_f32_16x16x32_bf16 v[124:127], v[134:137], v[180:183], v[124:127]
	v_mfma_f32_16x16x32_bf16 v[120:123], v[172:175], v[180:183], v[120:123]
	v_mfma_f32_16x16x32_bf16 v[116:119], v[134:137], v[188:191], v[116:119]
	v_mfma_f32_16x16x32_bf16 v[112:115], v[172:175], v[188:191], v[112:115]
	v_mfma_f32_16x16x32_bf16 v[108:111], v[134:137], v[196:199], v[108:111]
	v_mfma_f32_16x16x32_bf16 v[104:107], v[172:175], v[196:199], v[104:107]
	v_mfma_f32_16x16x32_bf16 v[100:103], v[134:137], v[204:207], v[100:103]
	v_mfma_f32_16x16x32_bf16 v[96:99], v[172:175], v[204:207], v[96:99]
	v_mfma_f32_16x16x32_bf16 v[124:127], v[138:141], v[184:187], v[124:127]
	v_mfma_f32_16x16x32_bf16 v[120:123], v[176:179], v[184:187], v[120:123]
	v_mfma_f32_16x16x32_bf16 v[116:119], v[138:141], v[192:195], v[116:119]
	v_mfma_f32_16x16x32_bf16 v[112:115], v[176:179], v[192:195], v[112:115]
	v_mfma_f32_16x16x32_bf16 v[108:111], v[138:141], v[200:203], v[108:111]
	v_mfma_f32_16x16x32_bf16 v[104:107], v[176:179], v[200:203], v[104:107]
	v_mfma_f32_16x16x32_bf16 v[100:103], v[138:141], v[208:211], v[100:103]
	v_mfma_f32_16x16x32_bf16 v[96:99], v[176:179], v[208:211], v[96:99]
	s_setprio 1
	s_barrier
	ds_read_b128 v[212:215], v160
	ds_read_b128 v[216:219], v160 offset:1024
	ds_read_b128 v[220:223], v160 offset:2048
	ds_read_b128 v[158:161], v160 offset:3072
	s_barrier
; #define LDA(dst, b, h) for (int m = 0; m < 4; ++m) for (int k = 0; k < 2; ++k) \
;     dst[m][k] = *reinterpret_cast<const bf16x8*>((char*)SA(b, h) + lds_byte(wr * 64 + m * 16 + fr, k * 32 + fq * 8))
; #define LDB(dst, b, h) for (int n = 0; n < 2; ++n) for (int k = 0; k < 2; ++k) \
;     dst[n][k] = *reinterpret_cast<const bf16x8*>((char*)SB(b, h) + lds_byte(wc * 32 + n * 16 + fr, k * 32 + fq * 8))
; #define MMA(ai, bj, At_, Bt_) do { __builtin_amdgcn_s_setprio(1); \
;     for (int k = 0; k < 2; ++k) for (int m = 0; m < 4; ++m) for (int n = 0; n < 2; ++n) \
;       acc[ai][bj][m][n] = __builtin_amdgcn_mfma_f32_16x16x32_bf16(At_[m][k], Bt_[n][k], acc[ai][bj][m][n], 0, 0, 0); \
;     __builtin_amdgcn_s_setprio(0); } while (0)
; #define WAIT_V(n) asm volatile("s_waitcnt vmcnt(" #n ")" ::: "memory")
; #define WAIT_L(n) asm volatile("s_waitcnt lgkmcnt(" #n ")" ::: "memory")
; #define BAR __builtin_amdgcn_s_barrier()
; template <int EPI, int lda, int ldb, int N, int K>
; __device__ __forceinline__ void gemm_phase(const u16* __restrict__ A, const u16* __restrict__ Bt, const GemmEpi ep, int wv) {
;     ...
;       LDB(B1, 0, 1); BAR; WAIT_L(0); MMA(0, 1, At, B1); BAR;
;       LDA(At, 0, 1); WAIT_V(4); BAR; WAIT_L(0); MMA(1, 0, At, B0); MMA(1, 1, At, B1); BAR; }
;     { LDB(B0, 1, 0); LDA(At, 1, 0); WAIT_V(2); BAR; WAIT_L(0); MMA(0, 0, At, B0); BAR;
	s_waitcnt lgkmcnt(0)
	s_setprio 0
	s_waitcnt lgkmcnt(0)
	v_mfma_f32_16x16x32_bf16 v[92:95], v[212:215], v[180:183], v[92:95]
	v_mfma_f32_16x16x32_bf16 v[88:91], v[220:223], v[180:183], v[88:91]
	v_mfma_f32_16x16x32_bf16 v[76:79], v[212:215], v[196:199], v[76:79]
	v_mfma_f32_16x16x32_bf16 v[72:75], v[220:223], v[196:199], v[72:75]
	v_mfma_f32_16x16x32_bf16 v[84:87], v[212:215], v[188:191], v[84:87]
	v_mfma_f32_16x16x32_bf16 v[80:83], v[220:223], v[188:191], v[80:83]
	v_mfma_f32_16x16x32_bf16 v[68:71], v[212:215], v[204:207], v[68:71]
	v_mfma_f32_16x16x32_bf16 v[64:67], v[220:223], v[204:207], v[64:67]
	v_mfma_f32_16x16x32_bf16 v[92:95], v[216:219], v[184:187], v[92:95]
	v_mfma_f32_16x16x32_bf16 v[88:91], v[158:161], v[184:187], v[88:91]
	v_mfma_f32_16x16x32_bf16 v[76:79], v[216:219], v[200:203], v[76:79]
	v_mfma_f32_16x16x32_bf16 v[72:75], v[158:161], v[200:203], v[72:75]
	v_mfma_f32_16x16x32_bf16 v[180:183], v[216:219], v[192:195], v[84:87]
	v_mfma_f32_16x16x32_bf16 v[184:187], v[158:161], v[192:195], v[80:83]
	v_mfma_f32_16x16x32_bf16 v[188:191], v[216:219], v[208:211], v[68:71]
	v_mfma_f32_16x16x32_bf16 v[192:195], v[158:161], v[208:211], v[64:67]
	s_setprio 1
	s_barrier
	s_nop 0
	ds_read_b128 v[64:67], v152 offset:16384
	ds_read_b128 v[68:71], v152 offset:17408
	ds_read_b128 v[80:83], v151 offset:16384
	ds_read_b128 v[84:87], v151 offset:17408
	ds_read_b128 v[196:199], v150 offset:16384
	ds_read_b128 v[200:203], v150 offset:17408
	ds_read_b128 v[204:207], v149 offset:16384
	ds_read_b128 v[208:211], v149 offset:17408
	s_waitcnt vmcnt(4)
	s_barrier
	s_waitcnt lgkmcnt(0)
	s_setprio 0
	s_waitcnt lgkmcnt(0)
	v_mfma_f32_16x16x32_bf16 v[60:63], v[134:137], v[64:67], v[60:63]
	v_mfma_f32_16x16x32_bf16 v[56:59], v[172:175], v[64:67], v[56:59]
	v_mfma_f32_16x16x32_bf16 v[52:55], v[134:137], v[80:83], v[52:55]
	v_mfma_f32_16x16x32_bf16 v[48:51], v[172:175], v[80:83], v[48:51]
	v_mfma_f32_16x16x32_bf16 v[44:47], v[134:137], v[196:199], v[44:47]
	v_mfma_f32_16x16x32_bf16 v[40:43], v[172:175], v[196:199], v[40:43]
	v_mfma_f32_16x16x32_bf16 v[36:39], v[134:137], v[204:207], v[36:39]
	v_mfma_f32_16x16x32_bf16 v[32:35], v[172:175], v[204:207], v[32:35]
	v_mfma_f32_16x16x32_bf16 v[60:63], v[138:141], v[68:71], v[60:63]
	v_mfma_f32_16x16x32_bf16 v[56:59], v[176:179], v[68:71], v[56:59]
	v_mfma_f32_16x16x32_bf16 v[52:55], v[138:141], v[84:87], v[52:55]
	v_mfma_f32_16x16x32_bf16 v[48:51], v[176:179], v[84:87], v[48:51]
	v_mfma_f32_16x16x32_bf16 v[44:47], v[138:141], v[200:203], v[44:47]
	v_mfma_f32_16x16x32_bf16 v[40:43], v[176:179], v[200:203], v[40:43]
	v_mfma_f32_16x16x32_bf16 v[36:39], v[138:141], v[208:211], v[36:39]
	v_mfma_f32_16x16x32_bf16 v[32:35], v[176:179], v[208:211], v[32:35]
	s_setprio 1
	s_setprio 0
	v_mfma_f32_16x16x32_bf16 v[28:31], v[212:215], v[64:67], v[28:31]
	v_mfma_f32_16x16x32_bf16 v[24:27], v[220:223], v[64:67], v[24:27]
	v_mfma_f32_16x16x32_bf16 v[12:15], v[212:215], v[196:199], v[12:15]
	v_mfma_f32_16x16x32_bf16 v[8:11], v[220:223], v[196:199], v[8:11]
	v_mfma_f32_16x16x32_bf16 v[20:23], v[212:215], v[80:83], v[20:23]
	v_mfma_f32_16x16x32_bf16 v[16:19], v[220:223], v[80:83], v[16:19]
	v_mfma_f32_16x16x32_bf16 v[4:7], v[212:215], v[204:207], v[4:7]
	v_mfma_f32_16x16x32_bf16 v[0:3], v[220:223], v[204:207], v[0:3]
	v_mfma_f32_16x16x32_bf16 v[28:31], v[216:219], v[68:71], v[28:31]
	v_mfma_f32_16x16x32_bf16 v[24:27], v[158:161], v[68:71], v[24:27]
	v_mfma_f32_16x16x32_bf16 v[12:15], v[216:219], v[200:203], v[12:15]
	v_mfma_f32_16x16x32_bf16 v[8:11], v[158:161], v[200:203], v[8:11]
	v_mfma_f32_16x16x32_bf16 v[134:137], v[216:219], v[84:87], v[20:23]
	v_mfma_f32_16x16x32_bf16 v[138:141], v[158:161], v[84:87], v[16:19]
	v_mfma_f32_16x16x32_bf16 v[170:173], v[216:219], v[208:211], v[4:7]
	v_mfma_f32_16x16x32_bf16 v[158:161], v[158:161], v[208:211], v[0:3]
	s_setprio 1
	s_barrier
	s_nop 0
	ds_read_b128 v[0:3], v156
	ds_read_b128 v[4:7], v156 offset:1024
	ds_read_b128 v[16:19], v156 offset:2048
	ds_read_b128 v[174:177], v156 offset:3072
	ds_read_b128 v[20:23], v152 offset:32768
	ds_read_b128 v[196:199], v152 offset:33792
	ds_read_b128 v[200:203], v151 offset:32768
	ds_read_b128 v[204:207], v151 offset:33792
	ds_read_b128 v[208:211], v150 offset:32768
	ds_read_b128 v[212:215], v150 offset:33792
	ds_read_b128 v[216:219], v149 offset:32768
	ds_read_b128 v[220:223], v149 offset:33792
	s_waitcnt vmcnt(2)
	s_barrier
; #define LDA(dst, b, h) for (int m = 0; m < 4; ++m) for (int k = 0; k < 2; ++k) \
;     dst[m][k] = *reinterpret_cast<const bf16x8*>((char*)SA(b, h) + lds_byte(wr * 64 + m * 16 + fr, k * 32 + fq * 8))
; #define LDB(dst, b, h) for (int n = 0; n < 2; ++n) for (int k = 0; k < 2; ++k) \
;     dst[n][k] = *reinterpret_cast<const bf16x8*>((char*)SB(b, h) + lds_byte(wc * 32 + n * 16 + fr, k * 32 + fq * 8))
; #define MMA(ai, bj, At_, Bt_) do { __builtin_amdgcn_s_setprio(1); \
;     for (int k = 0; k < 2; ++k) for (int m = 0; m < 4; ++m) for (int n = 0; n < 2; ++n) \
;       acc[ai][bj][m][n] = __builtin_amdgcn_mfma_f32_16x16x32_bf16(At_[m][k], Bt_[n][k], acc[ai][bj][m][n], 0, 0, 0); \
;     __builtin_amdgcn_s_setprio(0); } while (0)
; #define WAIT_V(n) asm volatile("s_waitcnt vmcnt(" #n ")" ::: "memory")
; #define WAIT_L(n) asm volatile("s_waitcnt lgkmcnt(" #n ")" ::: "memory")
; #define BAR __builtin_amdgcn_s_barrier()
; template <int EPI, int lda, int ldb, int N, int K>
; __device__ __forceinline__ void gemm_phase(const u16* __restrict__ A, const u16* __restrict__ Bt, const GemmEpi ep, int wv) {
;     ...
;     { LDB(B0, 1, 0); LDA(At, 1, 0); WAIT_V(2); BAR; WAIT_L(0); MMA(0, 0, At, B0); BAR;
;       LDB(B1, 1, 1); WAIT_V(0); BAR; WAIT_L(0); MMA(0, 1, At, B1); BAR;
;       LDA(At, 1, 1); BAR; WAIT_L(0); MMA(1, 0, At, B0); MMA(1, 1, At, B1); BAR; }
;     if (wr == 0) BAR;
	s_waitcnt lgkmcnt(0)
	s_setprio 0
	s_waitcnt lgkmcnt(0)
	v_mfma_f32_16x16x32_bf16 v[64:67], v[0:3], v[20:23], v[124:127]
	v_mfma_f32_16x16x32_bf16 v[68:71], v[16:19], v[20:23], v[120:123]
	v_mfma_f32_16x16x32_bf16 v[80:83], v[0:3], v[200:203], v[116:119]
	v_mfma_f32_16x16x32_bf16 v[84:87], v[16:19], v[200:203], v[112:115]
	v_mfma_f32_16x16x32_bf16 v[108:111], v[0:3], v[208:211], v[108:111]
	v_mfma_f32_16x16x32_bf16 v[104:107], v[16:19], v[208:211], v[104:107]
	v_mfma_f32_16x16x32_bf16 v[120:123], v[0:3], v[216:219], v[100:103]
	v_mfma_f32_16x16x32_bf16 v[124:127], v[16:19], v[216:219], v[96:99]
	v_mfma_f32_16x16x32_bf16 v[116:119], v[4:7], v[196:199], v[64:67]
	v_mfma_f32_16x16x32_bf16 v[112:115], v[174:177], v[196:199], v[68:71]
	v_mfma_f32_16x16x32_bf16 v[100:103], v[4:7], v[204:207], v[80:83]
	v_mfma_f32_16x16x32_bf16 v[96:99], v[174:177], v[204:207], v[84:87]
	v_mfma_f32_16x16x32_bf16 v[84:87], v[4:7], v[212:215], v[108:111]
	v_mfma_f32_16x16x32_bf16 v[80:83], v[174:177], v[212:215], v[104:107]
	v_mfma_f32_16x16x32_bf16 v[68:71], v[4:7], v[220:223], v[120:123]
	v_mfma_f32_16x16x32_bf16 v[64:67], v[174:177], v[220:223], v[124:127]
	s_setprio 1
	s_barrier
	ds_read_b128 v[224:227], v154
	ds_read_b128 v[228:231], v154 offset:1024
	ds_read_b128 v[232:235], v154 offset:2048
	ds_read_b128 v[154:157], v154 offset:3072
	s_waitcnt vmcnt(0)
	s_barrier
	s_waitcnt lgkmcnt(0)
	s_setprio 0
	s_waitcnt lgkmcnt(0)
	v_mfma_f32_16x16x32_bf16 v[92:95], v[224:227], v[20:23], v[92:95]
	v_mfma_f32_16x16x32_bf16 v[20:23], v[232:235], v[20:23], v[88:91]
	v_mfma_f32_16x16x32_bf16 v[88:91], v[224:227], v[200:203], v[180:183]
	v_mfma_f32_16x16x32_bf16 v[104:107], v[232:235], v[200:203], v[184:187]
	v_mfma_f32_16x16x32_bf16 v[76:79], v[224:227], v[208:211], v[76:79]
	v_mfma_f32_16x16x32_bf16 v[72:75], v[232:235], v[208:211], v[72:75]
	v_mfma_f32_16x16x32_bf16 v[178:181], v[224:227], v[216:219], v[188:191]
	v_mfma_f32_16x16x32_bf16 v[182:185], v[232:235], v[216:219], v[192:195]
	v_mfma_f32_16x16x32_bf16 v[124:127], v[228:231], v[196:199], v[92:95]
	v_mfma_f32_16x16x32_bf16 v[120:123], v[154:157], v[196:199], v[20:23]
	v_mfma_f32_16x16x32_bf16 v[108:111], v[228:231], v[204:207], v[88:91]
	v_mfma_f32_16x16x32_bf16 v[104:107], v[154:157], v[204:207], v[104:107]
	v_mfma_f32_16x16x32_bf16 v[92:95], v[228:231], v[212:215], v[76:79]
	v_mfma_f32_16x16x32_bf16 v[88:91], v[154:157], v[212:215], v[72:75]
	v_mfma_f32_16x16x32_bf16 v[76:79], v[228:231], v[220:223], v[178:181]
	v_mfma_f32_16x16x32_bf16 v[72:75], v[154:157], v[220:223], v[182:185]
	s_setprio 1
	s_barrier
	ds_read_b128 v[178:181], v152 offset:49152
	ds_read_b128 v[182:185], v152 offset:50176
	ds_read_b128 v[186:189], v151 offset:49152
	ds_read_b128 v[190:193], v151 offset:50176
	ds_read_b128 v[194:197], v150 offset:49152
	ds_read_b128 v[150:153], v150 offset:50176
	ds_read_b128 v[198:201], v149 offset:49152
	ds_read_b128 v[202:205], v149 offset:50176
	s_barrier
	s_waitcnt lgkmcnt(0)
	s_setprio 0
	s_waitcnt lgkmcnt(0)
	v_mfma_f32_16x16x32_bf16 v[20:23], v[0:3], v[178:181], v[60:63]
	v_mfma_f32_16x16x32_bf16 v[56:59], v[16:19], v[178:181], v[56:59]
	v_mfma_f32_16x16x32_bf16 v[60:63], v[0:3], v[186:189], v[52:55]
	v_mfma_f32_16x16x32_bf16 v[206:209], v[16:19], v[186:189], v[48:51]
	v_mfma_f32_16x16x32_bf16 v[44:47], v[0:3], v[194:197], v[44:47]
	v_mfma_f32_16x16x32_bf16 v[40:43], v[16:19], v[194:197], v[40:43]
	v_mfma_f32_16x16x32_bf16 v[0:3], v[0:3], v[198:201], v[36:39]
	v_mfma_f32_16x16x32_bf16 v[210:213], v[16:19], v[198:201], v[32:35]
	v_mfma_f32_16x16x32_bf16 v[52:55], v[4:7], v[182:185], v[20:23]
	v_mfma_f32_16x16x32_bf16 v[48:51], v[174:177], v[182:185], v[56:59]
	v_mfma_f32_16x16x32_bf16 v[36:39], v[4:7], v[190:193], v[60:63]
	v_mfma_f32_16x16x32_bf16 v[32:35], v[174:177], v[190:193], v[206:209]
	v_mfma_f32_16x16x32_bf16 v[20:23], v[4:7], v[150:153], v[44:47]
	v_mfma_f32_16x16x32_bf16 v[16:19], v[174:177], v[150:153], v[40:43]
	v_mfma_f32_16x16x32_bf16 v[4:7], v[4:7], v[202:205], v[0:3]
	v_mfma_f32_16x16x32_bf16 v[0:3], v[174:177], v[202:205], v[210:213]
	s_setprio 1
	s_setprio 0
	v_mfma_f32_16x16x32_bf16 v[28:31], v[224:227], v[178:181], v[28:31]
	v_mfma_f32_16x16x32_bf16 v[24:27], v[232:235], v[178:181], v[24:27]
	v_mfma_f32_16x16x32_bf16 v[40:43], v[224:227], v[186:189], v[134:137]
	v_mfma_f32_16x16x32_bf16 v[134:137], v[232:235], v[186:189], v[138:141]
	v_mfma_f32_16x16x32_bf16 v[12:15], v[224:227], v[194:197], v[12:15]
	v_mfma_f32_16x16x32_bf16 v[8:11], v[232:235], v[194:197], v[8:11]
	v_mfma_f32_16x16x32_bf16 v[138:141], v[224:227], v[198:201], v[170:173]
	v_mfma_f32_16x16x32_bf16 v[158:161], v[232:235], v[198:201], v[158:161]
	v_mfma_f32_16x16x32_bf16 v[60:63], v[228:231], v[182:185], v[28:31]
	v_mfma_f32_16x16x32_bf16 v[56:59], v[154:157], v[182:185], v[24:27]
	v_mfma_f32_16x16x32_bf16 v[44:47], v[228:231], v[190:193], v[40:43]
	v_mfma_f32_16x16x32_bf16 v[40:43], v[154:157], v[190:193], v[134:137]
	v_mfma_f32_16x16x32_bf16 v[28:31], v[228:231], v[150:153], v[12:15]
	v_mfma_f32_16x16x32_bf16 v[24:27], v[154:157], v[150:153], v[8:11]
	v_mfma_f32_16x16x32_bf16 v[12:15], v[228:231], v[202:205], v[138:141]
	v_mfma_f32_16x16x32_bf16 v[8:11], v[154:157], v[202:205], v[158:161]
	s_setprio 1
	v_cmp_gt_u32_e32 vcc, s56, v130
	s_barrier
	s_and_saveexec_b64 s[42:43], vcc
	s_cbranch_execz .LBB0_56
	s_barrier

; #define STAGE(P, BASE, LD, br, kt) do { const char* _g = (const char*)((BASE) + (size_t)(br) * (LD) + (size_t)(kt) * 64); \
;     for (int _i = 0; _i < 2; ++_i) { int _b = tidx * 16 + _i * 8192; int _r, _c; stage_rc(_b, _r, _c); \
;       __builtin_amdgcn_global_load_lds((const unsigned*)(_g + (unsigned)((_r * (LD) + _c) * 2)), (unsigned*)((char*)(P) + _b), 16, 0, 0); } } while (0)
; #define LDA(dst, b, h) for (int m = 0; m < 4; ++m) for (int k = 0; k < 2; ++k) \
;     dst[m][k] = *reinterpret_cast<const bf16x8*>((char*)SA(b, h) + lds_byte(wr * 64 + m * 16 + fr, k * 32 + fq * 8))
; #define LDB(dst, b, h) for (int n = 0; n < 2; ++n) for (int k = 0; k < 2; ++k) \
;     dst[n][k] = *reinterpret_cast<const bf16x8*>((char*)SB(b, h) + lds_byte(wc * 32 + n * 16 + fr, k * 32 + fq * 8))
; #define MMA(ai, bj, At_, Bt_) do { __builtin_amdgcn_s_setprio(1); \
;     for (int k = 0; k < 2; ++k) for (int m = 0; m < 4; ++m) for (int n = 0; n < 2; ++n) \
;       acc[ai][bj][m][n] = __builtin_amdgcn_mfma_f32_16x16x32_bf16(At_[m][k], Bt_[n][k], acc[ai][bj][m][n], 0, 0, 0); \
;     __builtin_amdgcn_s_setprio(0); } while (0)
; #define WAIT_V(n) asm volatile("s_waitcnt vmcnt(" #n ")" ::: "memory")
; #define WAIT_L(n) asm volatile("s_waitcnt lgkmcnt(" #n ")" ::: "memory")
; #define BAR __builtin_amdgcn_s_barrier()
; #define SCHED __builtin_amdgcn_sched_barrier(0)
; template <int EPI, int lda, int ldb, int N, int K>
; __device__ __forceinline__ void gemm_phase(const u16* __restrict__ A, const u16* __restrict__ Bt, const GemmEpi ep, int wv) {
;     ...
;     for (int t = 0; t < nt - 2; t += 2) {
;       LDB(B0, 0, 0); SCHED; LDA(At, 0, 0); STAGE(SA(1, 1), Ab, lda, brow + HALF, t + 1);
;       WAIT_L(8); BAR; WAIT_L(0); MMA(0, 0, At, B0); BAR; SCHED;
;       LDB(B1, 0, 1); STAGE(SB(0, 0), Bt, ldb, bcol, t + 2);
;       BAR; WAIT_L(0); MMA(0, 1, At, B1); BAR;
;       LDA(At, 0, 1); STAGE(SA(0, 0), Ab, lda, brow, t + 2);
;       BAR; WAIT_L(0); MMA(1, 0, At, B0); BAR; SCHED;
;       STAGE(SB(0, 1), Bt, ldb, bcol + HALF, t + 2);
;       WAIT_V(6); BAR; MMA(1, 1, At, B1); BAR;
;       LDB(B0, 1, 0); SCHED; LDA(At, 1, 0); STAGE(SA(0, 1), Ab, lda, brow + HALF, t + 2);
;       WAIT_L(8); BAR; WAIT_L(0); MMA(0, 0, At, B0); BAR; SCHED;
.LBB0_224:
	ds_read_b128 v[168:171], v164
	ds_read_b128 v[174:177], v164 offset:1024
	ds_read_b128 v[178:181], v164 offset:2048
	ds_read_b128 v[182:185], v164 offset:3072
	v_add_u32_e32 v172, 0xc000, v147
	v_lshl_add_u64 v[238:239], v[136:137], 0, s[44:45]
	v_readfirstlane_b32 s66, v172
	v_add_u32_e32 v173, 0xe000, v147
	v_lshl_add_u64 v[166:167], v[238:239], 0, s[18:19]
	s_mov_b32 m0, s66
	v_lshl_add_u64 v[240:241], v[134:135], 0, s[44:45]
	v_readfirstlane_b32 s66, v173
	ds_read_b128 v[186:189], v155
	ds_read_b128 v[190:193], v155 offset:1024
	ds_read_b128 v[194:197], v154
	ds_read_b128 v[198:201], v154 offset:1024
	ds_read_b128 v[202:205], v153
	ds_read_b128 v[206:209], v153 offset:1024
	ds_read_b128 v[210:213], v152
	ds_read_b128 v[214:217], v152 offset:1024
	global_load_lds_dwordx4 v[166:167], off
	v_lshl_add_u64 v[166:167], v[240:241], 0, s[18:19]
	s_mov_b32 m0, s66
	s_nop 0
	global_load_lds_dwordx4 v[166:167], off
	s_waitcnt lgkmcnt(8)
	s_barrier
	s_waitcnt lgkmcnt(0)
	s_setprio 0
	s_waitcnt lgkmcnt(0)
	v_mfma_f32_16x16x32_bf16 v[124:127], v[168:171], v[186:189], v[124:127]
	v_mfma_f32_16x16x32_bf16 v[120:123], v[178:181], v[186:189], v[120:123]
	v_mfma_f32_16x16x32_bf16 v[116:119], v[168:171], v[194:197], v[116:119]
	v_mfma_f32_16x16x32_bf16 v[112:115], v[178:181], v[194:197], v[112:115]
	v_mfma_f32_16x16x32_bf16 v[108:111], v[168:171], v[202:205], v[108:111]
	v_mfma_f32_16x16x32_bf16 v[104:107], v[178:181], v[202:205], v[104:107]
	v_mfma_f32_16x16x32_bf16 v[100:103], v[168:171], v[210:213], v[100:103]
	v_mfma_f32_16x16x32_bf16 v[96:99], v[178:181], v[210:213], v[96:99]
	v_mfma_f32_16x16x32_bf16 v[124:127], v[174:177], v[190:193], v[124:127]
	v_mfma_f32_16x16x32_bf16 v[120:123], v[182:185], v[190:193], v[120:123]
	v_mfma_f32_16x16x32_bf16 v[116:119], v[174:177], v[198:201], v[116:119]
	v_mfma_f32_16x16x32_bf16 v[112:115], v[182:185], v[198:201], v[112:115]
	v_mfma_f32_16x16x32_bf16 v[108:111], v[174:177], v[206:209], v[108:111]
	v_mfma_f32_16x16x32_bf16 v[104:107], v[182:185], v[206:209], v[104:107]
	v_mfma_f32_16x16x32_bf16 v[100:103], v[174:177], v[214:217], v[100:103]
	v_mfma_f32_16x16x32_bf16 v[96:99], v[182:185], v[214:217], v[96:99]
	s_setprio 1
	s_barrier
	v_add_u32_e32 v165, s55, v156
	v_lshl_add_u64 v[242:243], v[144:145], 0, s[44:45]
	v_readfirstlane_b32 s66, v165
	v_lshl_add_u64 v[166:167], v[242:243], 0, s[20:21]
	s_mov_b32 m0, s66
	ds_read_b128 v[218:221], v163
	ds_read_b128 v[222:225], v163 offset:1024
	ds_read_b128 v[226:229], v163 offset:2048
	ds_read_b128 v[230:233], v163 offset:3072
	global_load_lds_dwordx4 v[166:167], off
	v_add_u32_e32 v166, 0x2000, v165
	v_lshl_add_u64 v[244:245], v[142:143], 0, s[44:45]
	v_readfirstlane_b32 s66, v166
	v_lshl_add_u64 v[234:235], v[244:245], 0, s[20:21]
	s_mov_b32 m0, s66
	s_nop 0
	global_load_lds_dwordx4 v[234:235], off
	s_barrier
	s_waitcnt lgkmcnt(0)
	s_setprio 0
	s_waitcnt lgkmcnt(0)
	v_mfma_f32_16x16x32_bf16 v[92:95], v[218:221], v[186:189], v[92:95]
	v_mfma_f32_16x16x32_bf16 v[88:91], v[226:229], v[186:189], v[88:91]
	v_mfma_f32_16x16x32_bf16 v[84:87], v[218:221], v[194:197], v[84:87]
	v_mfma_f32_16x16x32_bf16 v[80:83], v[226:229], v[194:197], v[80:83]
	v_mfma_f32_16x16x32_bf16 v[76:79], v[218:221], v[202:205], v[76:79]
	v_mfma_f32_16x16x32_bf16 v[72:75], v[226:229], v[202:205], v[72:75]
	v_mfma_f32_16x16x32_bf16 v[68:71], v[218:221], v[210:213], v[68:71]
	v_mfma_f32_16x16x32_bf16 v[64:67], v[226:229], v[210:213], v[64:67]
	v_mfma_f32_16x16x32_bf16 v[92:95], v[222:225], v[190:193], v[92:95]
	v_mfma_f32_16x16x32_bf16 v[88:91], v[230:233], v[190:193], v[88:91]
	v_mfma_f32_16x16x32_bf16 v[84:87], v[222:225], v[198:201], v[84:87]
	v_mfma_f32_16x16x32_bf16 v[80:83], v[230:233], v[198:201], v[80:83]
	v_mfma_f32_16x16x32_bf16 v[76:79], v[222:225], v[206:209], v[76:79]
	v_mfma_f32_16x16x32_bf16 v[72:75], v[230:233], v[206:209], v[72:75]
	v_mfma_f32_16x16x32_bf16 v[68:71], v[222:225], v[214:217], v[68:71]
	v_mfma_f32_16x16x32_bf16 v[64:67], v[230:233], v[214:217], v[64:67]
	s_setprio 1
	v_readfirstlane_b32 s66, v147
	v_add_u32_e32 v167, 0x2000, v147
	v_lshl_add_u64 v[234:235], v[238:239], 0, s[22:23]
	s_mov_b32 m0, s66
	v_readfirstlane_b32 s66, v167
	s_barrier
	ds_read_b128 v[186:189], v155 offset:16384
	ds_read_b128 v[190:193], v155 offset:17408
	ds_read_b128 v[194:197], v154 offset:16384
	ds_read_b128 v[198:201], v154 offset:17408
	ds_read_b128 v[202:205], v153 offset:16384
	ds_read_b128 v[206:209], v153 offset:17408
	ds_read_b128 v[210:213], v152 offset:16384
	ds_read_b128 v[214:217], v152 offset:17408
	global_load_lds_dwordx4 v[234:235], off
	v_lshl_add_u64 v[234:235], v[240:241], 0, s[22:23]
	s_mov_b32 m0, s66
	s_nop 0
	global_load_lds_dwordx4 v[234:235], off
	s_barrier
	s_waitcnt lgkmcnt(0)
	s_setprio 0
	s_waitcnt lgkmcnt(0)
	v_mfma_f32_16x16x32_bf16 v[60:63], v[168:171], v[186:189], v[60:63]
	v_mfma_f32_16x16x32_bf16 v[56:59], v[178:181], v[186:189], v[56:59]
	v_mfma_f32_16x16x32_bf16 v[52:55], v[168:171], v[194:197], v[52:55]
	v_mfma_f32_16x16x32_bf16 v[48:51], v[178:181], v[194:197], v[48:51]
	v_mfma_f32_16x16x32_bf16 v[44:47], v[168:171], v[202:205], v[44:47]
	v_mfma_f32_16x16x32_bf16 v[40:43], v[178:181], v[202:205], v[40:43]
	v_mfma_f32_16x16x32_bf16 v[36:39], v[168:171], v[210:213], v[36:39]
	v_mfma_f32_16x16x32_bf16 v[32:35], v[178:181], v[210:213], v[32:35]
	v_mfma_f32_16x16x32_bf16 v[60:63], v[174:177], v[190:193], v[60:63]
	v_mfma_f32_16x16x32_bf16 v[56:59], v[182:185], v[190:193], v[56:59]
	v_mfma_f32_16x16x32_bf16 v[52:55], v[174:177], v[198:201], v[52:55]
	v_mfma_f32_16x16x32_bf16 v[48:51], v[182:185], v[198:201], v[48:51]
	v_mfma_f32_16x16x32_bf16 v[44:47], v[174:177], v[206:209], v[44:47]
	v_mfma_f32_16x16x32_bf16 v[40:43], v[182:185], v[206:209], v[40:43]
	v_mfma_f32_16x16x32_bf16 v[36:39], v[174:177], v[214:217], v[36:39]
	v_mfma_f32_16x16x32_bf16 v[32:35], v[182:185], v[214:217], v[32:35]
	s_setprio 1
	s_barrier
; #define STAGE(P, BASE, LD, br, kt) do { const char* _g = (const char*)((BASE) + (size_t)(br) * (LD) + (size_t)(kt) * 64); \
;     for (int _i = 0; _i < 2; ++_i) { int _b = tidx * 16 + _i * 8192; int _r, _c; stage_rc(_b, _r, _c); \
;       __builtin_amdgcn_global_load_lds((const unsigned*)(_g + (unsigned)((_r * (LD) + _c) * 2)), (unsigned*)((char*)(P) + _b), 16, 0, 0); } } while (0)
; #define LDA(dst, b, h) for (int m = 0; m < 4; ++m) for (int k = 0; k < 2; ++k) \
;     dst[m][k] = *reinterpret_cast<const bf16x8*>((char*)SA(b, h) + lds_byte(wr * 64 + m * 16 + fr, k * 32 + fq * 8))
; #define LDB(dst, b, h) for (int n = 0; n < 2; ++n) for (int k = 0; k < 2; ++k) \
;     dst[n][k] = *reinterpret_cast<const bf16x8*>((char*)SB(b, h) + lds_byte(wc * 32 + n * 16 + fr, k * 32 + fq * 8))
; #define MMA(ai, bj, At_, Bt_) do { __builtin_amdgcn_s_setprio(1); \
;     for (int k = 0; k < 2; ++k) for (int m = 0; m < 4; ++m) for (int n = 0; n < 2; ++n) \
;       acc[ai][bj][m][n] = __builtin_amdgcn_mfma_f32_16x16x32_bf16(At_[m][k], Bt_[n][k], acc[ai][bj][m][n], 0, 0, 0); \
;     __builtin_amdgcn_s_setprio(0); } while (0)
; #define WAIT_V(n) asm volatile("s_waitcnt vmcnt(" #n ")" ::: "memory")
; #define WAIT_L(n) asm volatile("s_waitcnt lgkmcnt(" #n ")" ::: "memory")
; #define BAR __builtin_amdgcn_s_barrier()
; #define SCHED __builtin_amdgcn_sched_barrier(0)
; template <int EPI, int lda, int ldb, int N, int K>
; __device__ __forceinline__ void gemm_phase(const u16* __restrict__ A, const u16* __restrict__ Bt, const GemmEpi ep, int wv) {
;     ...
;       STAGE(SB(0, 1), Bt, ldb, bcol + HALF, t + 2);
;       WAIT_V(6); BAR; MMA(1, 1, At, B1); BAR;
;       LDB(B0, 1, 0); SCHED; LDA(At, 1, 0); STAGE(SA(0, 1), Ab, lda, brow + HALF, t + 2);
;       WAIT_L(8); BAR; WAIT_L(0); MMA(0, 0, At, B0); BAR; SCHED;
;       LDB(B1, 1, 1); STAGE(SB(1, 0), Bt, ldb, bcol, t + 3);
;       BAR; WAIT_L(0); MMA(0, 1, At, B1); BAR;
;       LDA(At, 1, 1); STAGE(SA(1, 0), Ab, lda, brow, t + 3);
;       BAR; WAIT_L(0); MMA(1, 0, At, B0); BAR; SCHED;
	v_add_u32_e32 v168, s56, v156
	v_lshl_add_u64 v[246:247], v[140:141], 0, s[44:45]
	v_readfirstlane_b32 s66, v168
	v_add_u32_e32 v169, 0x2000, v168
	v_lshl_add_u64 v[170:171], v[246:247], 0, s[24:25]
	s_mov_b32 m0, s66
	v_lshl_add_u64 v[248:249], v[138:139], 0, s[44:45]
	v_readfirstlane_b32 s66, v169
	global_load_lds_dwordx4 v[170:171], off
	v_lshl_add_u64 v[170:171], v[248:249], 0, s[24:25]
	s_mov_b32 m0, s66
	s_nop 0
	global_load_lds_dwordx4 v[170:171], off
	s_waitcnt vmcnt(6)
	s_barrier
	s_setprio 0
	v_mfma_f32_16x16x32_bf16 v[28:31], v[218:221], v[186:189], v[28:31]
	v_mfma_f32_16x16x32_bf16 v[24:27], v[226:229], v[186:189], v[24:27]
	v_mfma_f32_16x16x32_bf16 v[20:23], v[218:221], v[194:197], v[20:23]
	v_mfma_f32_16x16x32_bf16 v[16:19], v[226:229], v[194:197], v[16:19]
	v_mfma_f32_16x16x32_bf16 v[12:15], v[218:221], v[202:205], v[12:15]
	v_mfma_f32_16x16x32_bf16 v[8:11], v[226:229], v[202:205], v[8:11]
	v_mfma_f32_16x16x32_bf16 v[4:7], v[218:221], v[210:213], v[4:7]
	v_mfma_f32_16x16x32_bf16 v[0:3], v[226:229], v[210:213], v[0:3]
	v_mfma_f32_16x16x32_bf16 v[28:31], v[222:225], v[190:193], v[28:31]
	v_mfma_f32_16x16x32_bf16 v[24:27], v[230:233], v[190:193], v[24:27]
	v_mfma_f32_16x16x32_bf16 v[20:23], v[222:225], v[198:201], v[20:23]
	v_mfma_f32_16x16x32_bf16 v[16:19], v[230:233], v[198:201], v[16:19]
	v_mfma_f32_16x16x32_bf16 v[12:15], v[222:225], v[206:209], v[12:15]
	v_mfma_f32_16x16x32_bf16 v[8:11], v[230:233], v[206:209], v[8:11]
	v_mfma_f32_16x16x32_bf16 v[4:7], v[222:225], v[214:217], v[4:7]
	v_mfma_f32_16x16x32_bf16 v[0:3], v[230:233], v[214:217], v[0:3]
	s_setprio 1
	s_barrier
	ds_read_b128 v[174:177], v159
	ds_read_b128 v[178:181], v159 offset:1024
	ds_read_b128 v[182:185], v159 offset:2048
	ds_read_b128 v[186:189], v159 offset:3072
	v_add_u32_e32 v170, 0x4000, v147
	v_add_u32_e32 v171, 0x6000, v147
	v_readfirstlane_b32 s66, v170
	v_lshl_add_u64 v[222:223], v[238:239], 0, s[26:27]
	s_mov_b32 m0, s66
	v_readfirstlane_b32 s66, v171
	ds_read_b128 v[190:193], v155 offset:32768
	ds_read_b128 v[194:197], v155 offset:33792
	ds_read_b128 v[198:201], v154 offset:32768
	ds_read_b128 v[202:205], v154 offset:33792
	ds_read_b128 v[206:209], v153 offset:32768
	ds_read_b128 v[210:213], v153 offset:33792
	ds_read_b128 v[214:217], v152 offset:32768
	ds_read_b128 v[218:221], v152 offset:33792
	global_load_lds_dwordx4 v[222:223], off
	v_lshl_add_u64 v[222:223], v[240:241], 0, s[26:27]
	s_mov_b32 m0, s66
	s_nop 0
	global_load_lds_dwordx4 v[222:223], off
	s_waitcnt lgkmcnt(8)
	s_barrier
	s_waitcnt lgkmcnt(0)
	s_setprio 0
	s_waitcnt lgkmcnt(0)
	v_mfma_f32_16x16x32_bf16 v[124:127], v[174:177], v[190:193], v[124:127]
	v_mfma_f32_16x16x32_bf16 v[120:123], v[182:185], v[190:193], v[120:123]
	v_mfma_f32_16x16x32_bf16 v[116:119], v[174:177], v[198:201], v[116:119]
	v_mfma_f32_16x16x32_bf16 v[112:115], v[182:185], v[198:201], v[112:115]
	v_mfma_f32_16x16x32_bf16 v[108:111], v[174:177], v[206:209], v[108:111]
	v_mfma_f32_16x16x32_bf16 v[104:107], v[182:185], v[206:209], v[104:107]
	v_mfma_f32_16x16x32_bf16 v[100:103], v[174:177], v[214:217], v[100:103]
	v_mfma_f32_16x16x32_bf16 v[96:99], v[182:185], v[214:217], v[96:99]
	v_mfma_f32_16x16x32_bf16 v[124:127], v[178:181], v[194:197], v[124:127]
	v_mfma_f32_16x16x32_bf16 v[120:123], v[186:189], v[194:197], v[120:123]
	v_mfma_f32_16x16x32_bf16 v[116:119], v[178:181], v[202:205], v[116:119]
	v_mfma_f32_16x16x32_bf16 v[112:115], v[186:189], v[202:205], v[112:115]
	v_mfma_f32_16x16x32_bf16 v[108:111], v[178:181], v[210:213], v[108:111]
	v_mfma_f32_16x16x32_bf16 v[104:107], v[186:189], v[210:213], v[104:107]
	v_mfma_f32_16x16x32_bf16 v[100:103], v[178:181], v[218:221], v[100:103]
	v_mfma_f32_16x16x32_bf16 v[96:99], v[186:189], v[218:221], v[96:99]
	s_setprio 1
	s_barrier
	v_readfirstlane_b32 s66, v158
	v_lshl_add_u64 v[242:243], v[242:243], 0, s[36:37]
	s_mov_b32 m0, s66
	ds_read_b128 v[222:225], v157
	ds_read_b128 v[226:229], v157 offset:1024
	ds_read_b128 v[230:233], v157 offset:2048
	ds_read_b128 v[234:237], v157 offset:3072
	global_load_lds_dwordx4 v[242:243], off
	v_lshl_add_u64 v[242:243], v[244:245], 0, s[36:37]
	v_add_u32_e32 v244, 0x2000, v158
	s_nop 0
	v_readfirstlane_b32 s66, v244
	s_mov_b32 m0, s66
	s_nop 0
	global_load_lds_dwordx4 v[242:243], off
	s_barrier
	s_waitcnt lgkmcnt(0)
	s_setprio 0
	s_waitcnt lgkmcnt(0)
	v_mfma_f32_16x16x32_bf16 v[92:95], v[222:225], v[190:193], v[92:95]
	v_mfma_f32_16x16x32_bf16 v[88:91], v[230:233], v[190:193], v[88:91]
	v_mfma_f32_16x16x32_bf16 v[84:87], v[222:225], v[198:201], v[84:87]
	v_mfma_f32_16x16x32_bf16 v[80:83], v[230:233], v[198:201], v[80:83]
	v_mfma_f32_16x16x32_bf16 v[76:79], v[222:225], v[206:209], v[76:79]
	v_mfma_f32_16x16x32_bf16 v[72:75], v[230:233], v[206:209], v[72:75]
	v_mfma_f32_16x16x32_bf16 v[68:71], v[222:225], v[214:217], v[68:71]
	v_mfma_f32_16x16x32_bf16 v[64:67], v[230:233], v[214:217], v[64:67]
	v_mfma_f32_16x16x32_bf16 v[92:95], v[226:229], v[194:197], v[92:95]
	v_mfma_f32_16x16x32_bf16 v[88:91], v[234:237], v[194:197], v[88:91]
	v_mfma_f32_16x16x32_bf16 v[84:87], v[226:229], v[202:205], v[84:87]
	v_mfma_f32_16x16x32_bf16 v[80:83], v[234:237], v[202:205], v[80:83]
	v_mfma_f32_16x16x32_bf16 v[76:79], v[226:229], v[210:213], v[76:79]
	v_mfma_f32_16x16x32_bf16 v[72:75], v[234:237], v[210:213], v[72:75]
	v_mfma_f32_16x16x32_bf16 v[68:71], v[226:229], v[218:221], v[68:71]
	v_mfma_f32_16x16x32_bf16 v[64:67], v[234:237], v[218:221], v[64:67]
	s_setprio 1
	v_readfirstlane_b32 s66, v160
	v_lshl_add_u64 v[238:239], v[238:239], 0, s[38:39]
	s_mov_b32 m0, s66
	v_readfirstlane_b32 s66, v161
	s_barrier
; #define STAGE(P, BASE, LD, br, kt) do { const char* _g = (const char*)((BASE) + (size_t)(br) * (LD) + (size_t)(kt) * 64); \
;     for (int _i = 0; _i < 2; ++_i) { int _b = tidx * 16 + _i * 8192; int _r, _c; stage_rc(_b, _r, _c); \
;       __builtin_amdgcn_global_load_lds((const unsigned*)(_g + (unsigned)((_r * (LD) + _c) * 2)), (unsigned*)((char*)(P) + _b), 16, 0, 0); } } while (0)
; #define LDA(dst, b, h) for (int m = 0; m < 4; ++m) for (int k = 0; k < 2; ++k) \
;     dst[m][k] = *reinterpret_cast<const bf16x8*>((char*)SA(b, h) + lds_byte(wr * 64 + m * 16 + fr, k * 32 + fq * 8))
; #define LDB(dst, b, h) for (int n = 0; n < 2; ++n) for (int k = 0; k < 2; ++k) \
;     dst[n][k] = *reinterpret_cast<const bf16x8*>((char*)SB(b, h) + lds_byte(wc * 32 + n * 16 + fr, k * 32 + fq * 8))
; #define MMA(ai, bj, At_, Bt_) do { __builtin_amdgcn_s_setprio(1); \
;     for (int k = 0; k < 2; ++k) for (int m = 0; m < 4; ++m) for (int n = 0; n < 2; ++n) \
;       acc[ai][bj][m][n] = __builtin_amdgcn_mfma_f32_16x16x32_bf16(At_[m][k], Bt_[n][k], acc[ai][bj][m][n], 0, 0, 0); \
;     __builtin_amdgcn_s_setprio(0); } while (0)
; #define WAIT_V(n) asm volatile("s_waitcnt vmcnt(" #n ")" ::: "memory")
; #define WAIT_L(n) asm volatile("s_waitcnt lgkmcnt(" #n ")" ::: "memory")
; #define BAR __builtin_amdgcn_s_barrier()
; #define SCHED __builtin_amdgcn_sched_barrier(0)
; template <int EPI, int lda, int ldb, int N, int K>
; __device__ __forceinline__ void gemm_phase(const u16* __restrict__ A, const u16* __restrict__ Bt, const GemmEpi ep, int wv) {
;     ...
;       LDA(At, 1, 1); STAGE(SA(1, 0), Ab, lda, brow, t + 3);
;       BAR; WAIT_L(0); MMA(1, 0, At, B0); BAR; SCHED;
;       STAGE(SB(1, 1), Bt, ldb, bcol + HALF, t + 3);
;       WAIT_V(6); BAR; MMA(1, 1, At, B1); BAR;
;     }
;     { LDB(B0, 0, 0); LDA(At, 0, 0); STAGE(SA(1, 1), Ab, lda, brow + HALF, nt - 1);
;       BAR; WAIT_L(0); MMA(0, 0, At, B0); BAR;
;       LDB(B1, 0, 1); BAR; WAIT_L(0); MMA(0, 1, At, B1); BAR;
	ds_read_b128 v[190:193], v155 offset:49152
	ds_read_b128 v[194:197], v155 offset:50176
	ds_read_b128 v[198:201], v154 offset:49152
	ds_read_b128 v[202:205], v154 offset:50176
	ds_read_b128 v[206:209], v153 offset:49152
	ds_read_b128 v[210:213], v153 offset:50176
	ds_read_b128 v[214:217], v152 offset:49152
	ds_read_b128 v[218:221], v152 offset:50176
	global_load_lds_dwordx4 v[238:239], off
	v_lshl_add_u64 v[238:239], v[240:241], 0, s[38:39]
	s_mov_b32 m0, s66
	s_nop 0
	global_load_lds_dwordx4 v[238:239], off
	s_barrier
	s_waitcnt lgkmcnt(0)
	s_setprio 0
	s_waitcnt lgkmcnt(0)
	v_mfma_f32_16x16x32_bf16 v[60:63], v[174:177], v[190:193], v[60:63]
	v_mfma_f32_16x16x32_bf16 v[56:59], v[182:185], v[190:193], v[56:59]
	v_mfma_f32_16x16x32_bf16 v[52:55], v[174:177], v[198:201], v[52:55]
	v_mfma_f32_16x16x32_bf16 v[48:51], v[182:185], v[198:201], v[48:51]
	v_mfma_f32_16x16x32_bf16 v[44:47], v[174:177], v[206:209], v[44:47]
	v_mfma_f32_16x16x32_bf16 v[40:43], v[182:185], v[206:209], v[40:43]
	v_mfma_f32_16x16x32_bf16 v[36:39], v[174:177], v[214:217], v[36:39]
	v_mfma_f32_16x16x32_bf16 v[32:35], v[182:185], v[214:217], v[32:35]
	v_mfma_f32_16x16x32_bf16 v[60:63], v[178:181], v[194:197], v[60:63]
	v_mfma_f32_16x16x32_bf16 v[56:59], v[186:189], v[194:197], v[56:59]
	v_mfma_f32_16x16x32_bf16 v[52:55], v[178:181], v[202:205], v[52:55]
	v_mfma_f32_16x16x32_bf16 v[48:51], v[186:189], v[202:205], v[48:51]
	v_mfma_f32_16x16x32_bf16 v[44:47], v[178:181], v[210:213], v[44:47]
	v_mfma_f32_16x16x32_bf16 v[40:43], v[186:189], v[210:213], v[40:43]
	v_mfma_f32_16x16x32_bf16 v[36:39], v[178:181], v[218:221], v[36:39]
	v_mfma_f32_16x16x32_bf16 v[32:35], v[186:189], v[218:221], v[32:35]
	s_setprio 1
	s_barrier
	v_readfirstlane_b32 s66, v162
	v_add_u32_e32 v176, 0x2000, v162
	v_lshl_add_u64 v[174:175], v[246:247], 0, s[42:43]
	s_mov_b32 m0, s66
	v_readfirstlane_b32 s66, v176
	global_load_lds_dwordx4 v[174:175], off
	v_lshl_add_u64 v[174:175], v[248:249], 0, s[42:43]
	s_mov_b32 m0, s66
	s_nop 0
	global_load_lds_dwordx4 v[174:175], off
	s_waitcnt vmcnt(6)
	s_barrier
	s_setprio 0
	v_mfma_f32_16x16x32_bf16 v[28:31], v[222:225], v[190:193], v[28:31]
	v_mfma_f32_16x16x32_bf16 v[24:27], v[230:233], v[190:193], v[24:27]
	v_mfma_f32_16x16x32_bf16 v[20:23], v[222:225], v[198:201], v[20:23]
	v_mfma_f32_16x16x32_bf16 v[16:19], v[230:233], v[198:201], v[16:19]
	v_mfma_f32_16x16x32_bf16 v[12:15], v[222:225], v[206:209], v[12:15]
	v_mfma_f32_16x16x32_bf16 v[8:11], v[230:233], v[206:209], v[8:11]
	v_mfma_f32_16x16x32_bf16 v[4:7], v[222:225], v[214:217], v[4:7]
	v_mfma_f32_16x16x32_bf16 v[0:3], v[230:233], v[214:217], v[0:3]
	v_mfma_f32_16x16x32_bf16 v[28:31], v[226:229], v[194:197], v[28:31]
	v_mfma_f32_16x16x32_bf16 v[24:27], v[234:237], v[194:197], v[24:27]
	v_mfma_f32_16x16x32_bf16 v[20:23], v[226:229], v[202:205], v[20:23]
	v_mfma_f32_16x16x32_bf16 v[16:19], v[234:237], v[202:205], v[16:19]
	v_mfma_f32_16x16x32_bf16 v[12:15], v[226:229], v[210:213], v[12:15]
	v_mfma_f32_16x16x32_bf16 v[8:11], v[234:237], v[210:213], v[8:11]
	v_mfma_f32_16x16x32_bf16 v[4:7], v[226:229], v[218:221], v[4:7]
	v_mfma_f32_16x16x32_bf16 v[0:3], v[234:237], v[218:221], v[0:3]
	s_setprio 1
	s_add_i32 s65, s65, 2
	s_add_u32 s44, s44, 0x100
	s_addc_u32 s45, s45, 0
	s_cmpk_gt_u32 s65, 0x51
	s_barrier
	s_cbranch_scc0 .LBB0_224
	s_add_i32 s44, s14, 0x80
	s_mul_hi_i32 s45, s44, 0x2b00
	s_mulk_i32 s44, 0x2b00
	s_add_u32 s44, s48, s44
	s_addc_u32 s45, s49, s45
	s_add_u32 s44, s44, 0x2a80
	s_addc_u32 s45, s45, 0
	v_readfirstlane_b32 s65, v172
	v_lshl_add_u64 v[160:161], s[44:45], 0, v[128:129]
	s_mov_b32 m0, s65
	ds_read_b128 v[134:137], v164
	ds_read_b128 v[138:141], v164 offset:1024
	ds_read_b128 v[142:145], v164 offset:2048
	ds_read_b128 v[174:177], v164 offset:3072
	ds_read_b128 v[178:181], v155
	ds_read_b128 v[182:185], v155 offset:1024
	ds_read_b128 v[186:189], v154
	ds_read_b128 v[190:193], v154 offset:1024
	ds_read_b128 v[194:197], v153
	ds_read_b128 v[198:201], v153 offset:1024
	ds_read_b128 v[202:205], v152
	ds_read_b128 v[206:209], v152 offset:1024
	global_load_lds_dwordx4 v[160:161], off
	v_lshl_add_u64 v[160:161], s[44:45], 0, v[132:133]
	v_readfirstlane_b32 s44, v173
	s_mov_b32 m0, s44
	s_nop 0
	global_load_lds_dwordx4 v[160:161], off
	s_barrier
	s_waitcnt lgkmcnt(0)
	s_setprio 0
	s_waitcnt lgkmcnt(0)
	v_mfma_f32_16x16x32_bf16 v[124:127], v[134:137], v[178:181], v[124:127]
	v_mfma_f32_16x16x32_bf16 v[120:123], v[142:145], v[178:181], v[120:123]
	v_mfma_f32_16x16x32_bf16 v[116:119], v[134:137], v[186:189], v[116:119]
	v_mfma_f32_16x16x32_bf16 v[112:115], v[142:145], v[186:189], v[112:115]
	v_mfma_f32_16x16x32_bf16 v[108:111], v[134:137], v[194:197], v[108:111]
	v_mfma_f32_16x16x32_bf16 v[104:107], v[142:145], v[194:197], v[104:107]
	v_mfma_f32_16x16x32_bf16 v[100:103], v[134:137], v[202:205], v[100:103]
	v_mfma_f32_16x16x32_bf16 v[96:99], v[142:145], v[202:205], v[96:99]
	v_mfma_f32_16x16x32_bf16 v[124:127], v[138:141], v[182:185], v[124:127]
	v_mfma_f32_16x16x32_bf16 v[120:123], v[174:177], v[182:185], v[120:123]
	v_mfma_f32_16x16x32_bf16 v[116:119], v[138:141], v[190:193], v[116:119]
	v_mfma_f32_16x16x32_bf16 v[112:115], v[174:177], v[190:193], v[112:115]
	v_mfma_f32_16x16x32_bf16 v[108:111], v[138:141], v[198:201], v[108:111]
	v_mfma_f32_16x16x32_bf16 v[104:107], v[174:177], v[198:201], v[104:107]
	v_mfma_f32_16x16x32_bf16 v[100:103], v[138:141], v[206:209], v[100:103]
	v_mfma_f32_16x16x32_bf16 v[96:99], v[174:177], v[206:209], v[96:99]
	s_setprio 1
	s_barrier
	ds_read_b128 v[210:213], v163
	ds_read_b128 v[214:217], v163 offset:1024
	ds_read_b128 v[218:221], v163 offset:2048
	ds_read_b128 v[160:163], v163 offset:3072
	s_barrier
; #define LDA(dst, b, h) for (int m = 0; m < 4; ++m) for (int k = 0; k < 2; ++k) \
;     dst[m][k] = *reinterpret_cast<const bf16x8*>((char*)SA(b, h) + lds_byte(wr * 64 + m * 16 + fr, k * 32 + fq * 8))
; #define LDB(dst, b, h) for (int n = 0; n < 2; ++n) for (int k = 0; k < 2; ++k) \
;     dst[n][k] = *reinterpret_cast<const bf16x8*>((char*)SB(b, h) + lds_byte(wc * 32 + n * 16 + fr, k * 32 + fq * 8))
; #define MMA(ai, bj, At_, Bt_) do { __builtin_amdgcn_s_setprio(1); \
;     for (int k = 0; k < 2; ++k) for (int m = 0; m < 4; ++m) for (int n = 0; n < 2; ++n) \
;       acc[ai][bj][m][n] = __builtin_amdgcn_mfma_f32_16x16x32_bf16(At_[m][k], Bt_[n][k], acc[ai][bj][m][n], 0, 0, 0); \
;     __builtin_amdgcn_s_setprio(0); } while (0)
; #define WAIT_V(n) asm volatile("s_waitcnt vmcnt(" #n ")" ::: "memory")
; #define WAIT_L(n) asm volatile("s_waitcnt lgkmcnt(" #n ")" ::: "memory")
; #define BAR __builtin_amdgcn_s_barrier()
; template <int EPI, int lda, int ldb, int N, int K>
; __device__ __forceinline__ void gemm_phase(const u16* __restrict__ A, const u16* __restrict__ Bt, const GemmEpi ep, int wv) {
;     ...
;       LDB(B1, 0, 1); BAR; WAIT_L(0); MMA(0, 1, At, B1); BAR;
;       LDA(At, 0, 1); WAIT_V(4); BAR; WAIT_L(0); MMA(1, 0, At, B0); MMA(1, 1, At, B1); BAR; }
;     { LDB(B0, 1, 0); LDA(At, 1, 0); WAIT_V(2); BAR; WAIT_L(0); MMA(0, 0, At, B0); BAR;
	s_waitcnt lgkmcnt(0)
	s_setprio 0
	s_waitcnt lgkmcnt(0)
	v_mfma_f32_16x16x32_bf16 v[92:95], v[210:213], v[178:181], v[92:95]
	v_mfma_f32_16x16x32_bf16 v[88:91], v[218:221], v[178:181], v[88:91]
	v_mfma_f32_16x16x32_bf16 v[76:79], v[210:213], v[194:197], v[76:79]
	v_mfma_f32_16x16x32_bf16 v[72:75], v[218:221], v[194:197], v[72:75]
	v_mfma_f32_16x16x32_bf16 v[84:87], v[210:213], v[186:189], v[84:87]
	v_mfma_f32_16x16x32_bf16 v[80:83], v[218:221], v[186:189], v[80:83]
	v_mfma_f32_16x16x32_bf16 v[68:71], v[210:213], v[202:205], v[68:71]
	v_mfma_f32_16x16x32_bf16 v[64:67], v[218:221], v[202:205], v[64:67]
	v_mfma_f32_16x16x32_bf16 v[92:95], v[214:217], v[182:185], v[92:95]
	v_mfma_f32_16x16x32_bf16 v[88:91], v[160:163], v[182:185], v[88:91]
	v_mfma_f32_16x16x32_bf16 v[76:79], v[214:217], v[198:201], v[76:79]
	v_mfma_f32_16x16x32_bf16 v[72:75], v[160:163], v[198:201], v[72:75]
	v_mfma_f32_16x16x32_bf16 v[178:181], v[214:217], v[190:193], v[84:87]
	v_mfma_f32_16x16x32_bf16 v[182:185], v[160:163], v[190:193], v[80:83]
	v_mfma_f32_16x16x32_bf16 v[186:189], v[214:217], v[206:209], v[68:71]
	v_mfma_f32_16x16x32_bf16 v[190:193], v[160:163], v[206:209], v[64:67]
	s_setprio 1
	s_barrier
	s_nop 0
	ds_read_b128 v[64:67], v155 offset:16384
	ds_read_b128 v[68:71], v155 offset:17408
	ds_read_b128 v[80:83], v154 offset:16384
	ds_read_b128 v[84:87], v154 offset:17408
	ds_read_b128 v[194:197], v153 offset:16384
	ds_read_b128 v[198:201], v153 offset:17408
	ds_read_b128 v[202:205], v152 offset:16384
	ds_read_b128 v[206:209], v152 offset:17408
	s_waitcnt vmcnt(4)
	s_barrier
	s_waitcnt lgkmcnt(0)
	s_setprio 0
	s_waitcnt lgkmcnt(0)
	v_mfma_f32_16x16x32_bf16 v[60:63], v[134:137], v[64:67], v[60:63]
	v_mfma_f32_16x16x32_bf16 v[56:59], v[142:145], v[64:67], v[56:59]
	v_mfma_f32_16x16x32_bf16 v[52:55], v[134:137], v[80:83], v[52:55]
	v_mfma_f32_16x16x32_bf16 v[48:51], v[142:145], v[80:83], v[48:51]
	v_mfma_f32_16x16x32_bf16 v[44:47], v[134:137], v[194:197], v[44:47]
	v_mfma_f32_16x16x32_bf16 v[40:43], v[142:145], v[194:197], v[40:43]
	v_mfma_f32_16x16x32_bf16 v[36:39], v[134:137], v[202:205], v[36:39]
	v_mfma_f32_16x16x32_bf16 v[32:35], v[142:145], v[202:205], v[32:35]
	v_mfma_f32_16x16x32_bf16 v[60:63], v[138:141], v[68:71], v[60:63]
	v_mfma_f32_16x16x32_bf16 v[56:59], v[174:177], v[68:71], v[56:59]
	v_mfma_f32_16x16x32_bf16 v[52:55], v[138:141], v[84:87], v[52:55]
	v_mfma_f32_16x16x32_bf16 v[48:51], v[174:177], v[84:87], v[48:51]
	v_mfma_f32_16x16x32_bf16 v[44:47], v[138:141], v[198:201], v[44:47]
	v_mfma_f32_16x16x32_bf16 v[40:43], v[174:177], v[198:201], v[40:43]
	v_mfma_f32_16x16x32_bf16 v[36:39], v[138:141], v[206:209], v[36:39]
	v_mfma_f32_16x16x32_bf16 v[32:35], v[174:177], v[206:209], v[32:35]
	s_setprio 1
	s_setprio 0
	v_mfma_f32_16x16x32_bf16 v[28:31], v[210:213], v[64:67], v[28:31]
	v_mfma_f32_16x16x32_bf16 v[16:19], v[218:221], v[80:83], v[16:19]
	v_mfma_f32_16x16x32_bf16 v[12:15], v[210:213], v[194:197], v[12:15]
	v_mfma_f32_16x16x32_bf16 v[0:3], v[218:221], v[202:205], v[0:3]
	v_mfma_f32_16x16x32_bf16 v[24:27], v[218:221], v[64:67], v[24:27]
	v_mfma_f32_16x16x32_bf16 v[20:23], v[210:213], v[80:83], v[20:23]
	v_mfma_f32_16x16x32_bf16 v[8:11], v[218:221], v[194:197], v[8:11]
	v_mfma_f32_16x16x32_bf16 v[4:7], v[210:213], v[202:205], v[4:7]
	v_mfma_f32_16x16x32_bf16 v[28:31], v[214:217], v[68:71], v[28:31]
	v_mfma_f32_16x16x32_bf16 v[16:19], v[160:163], v[84:87], v[16:19]
	v_mfma_f32_16x16x32_bf16 v[12:15], v[214:217], v[198:201], v[12:15]
	v_mfma_f32_16x16x32_bf16 v[0:3], v[160:163], v[206:209], v[0:3]
	v_mfma_f32_16x16x32_bf16 v[134:137], v[160:163], v[68:71], v[24:27]
	v_mfma_f32_16x16x32_bf16 v[138:141], v[214:217], v[84:87], v[20:23]
	v_mfma_f32_16x16x32_bf16 v[142:145], v[160:163], v[198:201], v[8:11]
	v_mfma_f32_16x16x32_bf16 v[172:175], v[214:217], v[206:209], v[4:7]
	s_setprio 1
	s_barrier
	s_nop 0
	ds_read_b128 v[4:7], v159
	ds_read_b128 v[8:11], v159 offset:1024
	ds_read_b128 v[20:23], v159 offset:2048
	ds_read_b128 v[158:161], v159 offset:3072
	ds_read_b128 v[24:27], v155 offset:32768
	ds_read_b128 v[194:197], v155 offset:33792
	ds_read_b128 v[198:201], v154 offset:32768
	ds_read_b128 v[202:205], v154 offset:33792
	ds_read_b128 v[206:209], v153 offset:32768
	ds_read_b128 v[210:213], v153 offset:33792
	ds_read_b128 v[214:217], v152 offset:32768
	ds_read_b128 v[218:221], v152 offset:33792
	s_waitcnt vmcnt(2)
	s_barrier
; #define UNR _Pragma("unroll")
; #define LDA(dst, b, h) for (int m = 0; m < 4; ++m) for (int k = 0; k < 2; ++k) \
;     dst[m][k] = *reinterpret_cast<const bf16x8*>((char*)SA(b, h) + lds_byte(wr * 64 + m * 16 + fr, k * 32 + fq * 8))
; #define LDB(dst, b, h) for (int n = 0; n < 2; ++n) for (int k = 0; k < 2; ++k) \
;     dst[n][k] = *reinterpret_cast<const bf16x8*>((char*)SB(b, h) + lds_byte(wc * 32 + n * 16 + fr, k * 32 + fq * 8))
; #define MMA(ai, bj, At_, Bt_) do { __builtin_amdgcn_s_setprio(1); \
;     for (int k = 0; k < 2; ++k) for (int m = 0; m < 4; ++m) for (int n = 0; n < 2; ++n) \
;       acc[ai][bj][m][n] = __builtin_amdgcn_mfma_f32_16x16x32_bf16(At_[m][k], Bt_[n][k], acc[ai][bj][m][n], 0, 0, 0); \
;     __builtin_amdgcn_s_setprio(0); } while (0)
; #define WAIT_V(n) asm volatile("s_waitcnt vmcnt(" #n ")" ::: "memory")
; #define WAIT_L(n) asm volatile("s_waitcnt lgkmcnt(" #n ")" ::: "memory")
; #define BAR __builtin_amdgcn_s_barrier()
; #define STAGE4(BROW, BCOL, PN) do { const u16* Ab_ = A + (EPI == EPI_RG ? ((PN) >> 1) * 256 : 0); \
;     STAGE(SB(0, 0), Bt, ldb, (BCOL), 0); STAGE(SA(0, 0), Ab_, lda, (BROW), 0); \
;     STAGE(SB(0, 1), Bt, ldb, (BCOL) + HALF, 0); STAGE(SA(0, 1), Ab_, lda, (BROW) + HALF, 0); } while (0)
; template <int EPI, int lda, int ldb, int N, int K>
; __device__ __forceinline__ void gemm_phase(const u16* __restrict__ A, const u16* __restrict__ Bt, const GemmEpi ep, int wv) {
;     ...
;     { LDB(B0, 1, 0); LDA(At, 1, 0); WAIT_V(2); BAR; WAIT_L(0); MMA(0, 0, At, B0); BAR;
;       LDB(B1, 1, 1); WAIT_V(0); BAR; WAIT_L(0); MMA(0, 1, At, B1); BAR;
;       LDA(At, 1, 1); BAR; WAIT_L(0); MMA(1, 0, At, B0); MMA(1, 1, At, B1); BAR; }
;     if (wr == 0) BAR;
;     int ntile = 0, nbrow = 0, nbcol = 0, npn = 0; bool more = false;
;     if constexpr (PF) { ntile = tile + gridDim.x; more = ntile < nwg; if (more) { TILE_COORDS(ntile, nbrow, nbcol, npn); STAGE4(nbrow, nbcol, npn); } }
;     float nss[8];
;     if constexpr (CONS) { UNR for (int pp = 0; pp < 8; ++pp) nss[pp] = 0.f;
;       if (more && tidx < 256) { UNR for (int pp = 0; pp < 8; ++pp) nss[pp] = ep.ss_in[(size_t)pp * T + nbrow + tidx]; } }
	s_waitcnt lgkmcnt(0)
	s_setprio 0
	s_waitcnt lgkmcnt(0)
	v_mfma_f32_16x16x32_bf16 v[64:67], v[4:7], v[24:27], v[124:127]
	v_mfma_f32_16x16x32_bf16 v[68:71], v[20:23], v[24:27], v[120:123]
	v_mfma_f32_16x16x32_bf16 v[80:83], v[4:7], v[198:201], v[116:119]
	v_mfma_f32_16x16x32_bf16 v[84:87], v[20:23], v[198:201], v[112:115]
	v_mfma_f32_16x16x32_bf16 v[108:111], v[4:7], v[206:209], v[108:111]
	v_mfma_f32_16x16x32_bf16 v[104:107], v[20:23], v[206:209], v[104:107]
	v_mfma_f32_16x16x32_bf16 v[120:123], v[4:7], v[214:217], v[100:103]
	v_mfma_f32_16x16x32_bf16 v[124:127], v[20:23], v[214:217], v[96:99]
	v_mfma_f32_16x16x32_bf16 v[116:119], v[8:11], v[194:197], v[64:67]
	v_mfma_f32_16x16x32_bf16 v[112:115], v[158:161], v[194:197], v[68:71]
	v_mfma_f32_16x16x32_bf16 v[100:103], v[8:11], v[202:205], v[80:83]
	v_mfma_f32_16x16x32_bf16 v[96:99], v[158:161], v[202:205], v[84:87]
	v_mfma_f32_16x16x32_bf16 v[84:87], v[8:11], v[210:213], v[108:111]
	v_mfma_f32_16x16x32_bf16 v[80:83], v[158:161], v[210:213], v[104:107]
	v_mfma_f32_16x16x32_bf16 v[68:71], v[8:11], v[218:221], v[120:123]
	v_mfma_f32_16x16x32_bf16 v[64:67], v[158:161], v[218:221], v[124:127]
	s_setprio 1
	s_barrier
	ds_read_b128 v[222:225], v157
	ds_read_b128 v[226:229], v157 offset:1024
	ds_read_b128 v[230:233], v157 offset:2048
	ds_read_b128 v[234:237], v157 offset:3072
	s_waitcnt vmcnt(0)
	s_barrier
	s_waitcnt lgkmcnt(0)
	s_setprio 0
	s_waitcnt lgkmcnt(0)
	v_mfma_f32_16x16x32_bf16 v[92:95], v[222:225], v[24:27], v[92:95]
	v_mfma_f32_16x16x32_bf16 v[24:27], v[230:233], v[24:27], v[88:91]
	v_mfma_f32_16x16x32_bf16 v[88:91], v[222:225], v[198:201], v[178:181]
	v_mfma_f32_16x16x32_bf16 v[104:107], v[230:233], v[198:201], v[182:185]
	v_mfma_f32_16x16x32_bf16 v[76:79], v[222:225], v[206:209], v[76:79]
	v_mfma_f32_16x16x32_bf16 v[72:75], v[230:233], v[206:209], v[72:75]
	v_mfma_f32_16x16x32_bf16 v[176:179], v[222:225], v[214:217], v[186:189]
	v_mfma_f32_16x16x32_bf16 v[180:183], v[230:233], v[214:217], v[190:193]
	v_mfma_f32_16x16x32_bf16 v[124:127], v[226:229], v[194:197], v[92:95]
	v_mfma_f32_16x16x32_bf16 v[120:123], v[234:237], v[194:197], v[24:27]
	v_mfma_f32_16x16x32_bf16 v[108:111], v[226:229], v[202:205], v[88:91]
	v_mfma_f32_16x16x32_bf16 v[104:107], v[234:237], v[202:205], v[104:107]
	v_mfma_f32_16x16x32_bf16 v[92:95], v[226:229], v[210:213], v[76:79]
	v_mfma_f32_16x16x32_bf16 v[88:91], v[234:237], v[210:213], v[72:75]
	v_mfma_f32_16x16x32_bf16 v[76:79], v[226:229], v[218:221], v[176:179]
	v_mfma_f32_16x16x32_bf16 v[72:75], v[234:237], v[218:221], v[180:183]
	s_setprio 1
	s_barrier
	ds_read_b128 v[176:179], v155 offset:49152
	ds_read_b128 v[180:183], v155 offset:50176
	ds_read_b128 v[184:187], v154 offset:49152
	ds_read_b128 v[154:157], v154 offset:50176
	ds_read_b128 v[188:191], v153 offset:49152
	ds_read_b128 v[192:195], v153 offset:50176
	ds_read_b128 v[196:199], v152 offset:49152
	ds_read_b128 v[200:203], v152 offset:50176
	s_barrier
	s_waitcnt lgkmcnt(0)
	s_setprio 0
	s_waitcnt lgkmcnt(0)
	v_mfma_f32_16x16x32_bf16 v[24:27], v[4:7], v[176:179], v[60:63]
	v_mfma_f32_16x16x32_bf16 v[60:63], v[20:23], v[176:179], v[56:59]
	v_mfma_f32_16x16x32_bf16 v[204:207], v[4:7], v[184:187], v[52:55]
	v_mfma_f32_16x16x32_bf16 v[48:51], v[20:23], v[184:187], v[48:51]
	v_mfma_f32_16x16x32_bf16 v[44:47], v[4:7], v[188:191], v[44:47]
	v_mfma_f32_16x16x32_bf16 v[208:211], v[20:23], v[188:191], v[40:43]
	v_mfma_f32_16x16x32_bf16 v[4:7], v[4:7], v[196:199], v[36:39]
	v_mfma_f32_16x16x32_bf16 v[32:35], v[20:23], v[196:199], v[32:35]
	v_mfma_f32_16x16x32_bf16 v[56:59], v[8:11], v[180:183], v[24:27]
	v_mfma_f32_16x16x32_bf16 v[52:55], v[158:161], v[180:183], v[60:63]
	v_mfma_f32_16x16x32_bf16 v[40:43], v[8:11], v[154:157], v[204:207]
	v_mfma_f32_16x16x32_bf16 v[36:39], v[158:161], v[154:157], v[48:51]
	v_mfma_f32_16x16x32_bf16 v[24:27], v[8:11], v[192:195], v[44:47]
	v_mfma_f32_16x16x32_bf16 v[20:23], v[158:161], v[192:195], v[208:211]
	v_mfma_f32_16x16x32_bf16 v[8:11], v[8:11], v[200:203], v[4:7]
	v_mfma_f32_16x16x32_bf16 v[4:7], v[158:161], v[200:203], v[32:35]
	s_setprio 1
	s_setprio 0
	v_mfma_f32_16x16x32_bf16 v[28:31], v[222:225], v[176:179], v[28:31]
	v_mfma_f32_16x16x32_bf16 v[32:35], v[230:233], v[176:179], v[134:137]
	v_mfma_f32_16x16x32_bf16 v[44:47], v[222:225], v[184:187], v[138:141]
	v_mfma_f32_16x16x32_bf16 v[16:19], v[230:233], v[184:187], v[16:19]
	v_mfma_f32_16x16x32_bf16 v[12:15], v[222:225], v[188:191], v[12:15]
	v_mfma_f32_16x16x32_bf16 v[134:137], v[230:233], v[188:191], v[142:145]
	v_mfma_f32_16x16x32_bf16 v[138:141], v[222:225], v[196:199], v[172:175]
	v_mfma_f32_16x16x32_bf16 v[0:3], v[230:233], v[196:199], v[0:3]
	v_mfma_f32_16x16x32_bf16 v[60:63], v[226:229], v[180:183], v[28:31]
	v_mfma_f32_16x16x32_bf16 v[48:51], v[234:237], v[180:183], v[32:35]
	v_mfma_f32_16x16x32_bf16 v[44:47], v[226:229], v[154:157], v[44:47]
	v_mfma_f32_16x16x32_bf16 v[32:35], v[234:237], v[154:157], v[16:19]
	v_mfma_f32_16x16x32_bf16 v[28:31], v[226:229], v[192:195], v[12:15]
	v_mfma_f32_16x16x32_bf16 v[16:19], v[234:237], v[192:195], v[134:137]
	v_mfma_f32_16x16x32_bf16 v[12:15], v[226:229], v[200:203], v[138:141]
	v_mfma_f32_16x16x32_bf16 v[0:3], v[234:237], v[200:203], v[0:3]
	s_setprio 1
	v_cmp_gt_u32_e32 vcc, s62, v130
	s_barrier
	s_and_saveexec_b64 s[44:45], vcc
	s_cbranch_execz .LBB0_227
	s_barrier

; #define STAGE(P, BASE, LD, br, kt) do { const char* _g = (const char*)((BASE) + (size_t)(br) * (LD) + (size_t)(kt) * 64); \
;     for (int _i = 0; _i < 2; ++_i) { int _b = tidx * 16 + _i * 8192; int _r, _c; stage_rc(_b, _r, _c); \
;       __builtin_amdgcn_global_load_lds((const unsigned*)(_g + (unsigned)((_r * (LD) + _c) * 2)), (unsigned*)((char*)(P) + _b), 16, 0, 0); } } while (0)
; #define LDA(dst, b, h) for (int m = 0; m < 4; ++m) for (int k = 0; k < 2; ++k) \
;     dst[m][k] = *reinterpret_cast<const bf16x8*>((char*)SA(b, h) + lds_byte(wr * 64 + m * 16 + fr, k * 32 + fq * 8))
; #define LDB(dst, b, h) for (int n = 0; n < 2; ++n) for (int k = 0; k < 2; ++k) \
;     dst[n][k] = *reinterpret_cast<const bf16x8*>((char*)SB(b, h) + lds_byte(wc * 32 + n * 16 + fr, k * 32 + fq * 8))
; #define MMA(ai, bj, At_, Bt_) do { __builtin_amdgcn_s_setprio(1); \
;     for (int k = 0; k < 2; ++k) for (int m = 0; m < 4; ++m) for (int n = 0; n < 2; ++n) \
;       acc[ai][bj][m][n] = __builtin_amdgcn_mfma_f32_16x16x32_bf16(At_[m][k], Bt_[n][k], acc[ai][bj][m][n], 0, 0, 0); \
;     __builtin_amdgcn_s_setprio(0); } while (0)
; #define WAIT_L(n) asm volatile("s_waitcnt lgkmcnt(" #n ")" ::: "memory")
; #define BAR __builtin_amdgcn_s_barrier()
; #define SCHED __builtin_amdgcn_sched_barrier(0)
; template <int EPI, int lda, int ldb, int N, int K>
; __device__ __forceinline__ void gemm_phase(const u16* __restrict__ A, const u16* __restrict__ Bt, const GemmEpi ep, int wv) {
;     ...
;     for (int t = 0; t < nt - 2; t += 2) {
;       LDB(B0, 0, 0); SCHED; LDA(At, 0, 0); STAGE(SA(1, 1), Ab, lda, brow + HALF, t + 1);
;       WAIT_L(8); BAR; WAIT_L(0); MMA(0, 0, At, B0); BAR; SCHED;
;       LDB(B1, 0, 1); STAGE(SB(0, 0), Bt, ldb, bcol, t + 2);
;       BAR; WAIT_L(0); MMA(0, 1, At, B1); BAR;
;       LDA(At, 0, 1); STAGE(SA(0, 0), Ab, lda, brow, t + 2);
;       BAR; WAIT_L(0); MMA(1, 0, At, B0); BAR; SCHED;
.LBB0_340:
	ds_read_b128 v[166:169], v162
	ds_read_b128 v[172:175], v162 offset:1024
	ds_read_b128 v[176:179], v162 offset:2048
	ds_read_b128 v[180:183], v162 offset:3072
	v_add_u32_e32 v170, 0xc000, v149
	v_lshl_add_u64 v[236:237], v[138:139], 0, s[48:49]
	v_readfirstlane_b32 s51, v170
	v_add_u32_e32 v171, 0xe000, v149
	v_lshl_add_u64 v[164:165], v[236:237], 0, s[18:19]
	s_mov_b32 m0, s51
	v_lshl_add_u64 v[238:239], v[140:141], 0, s[48:49]
	v_readfirstlane_b32 s51, v171
	ds_read_b128 v[184:187], v153
	ds_read_b128 v[188:191], v153 offset:1024
	ds_read_b128 v[192:195], v152
	ds_read_b128 v[196:199], v152 offset:1024
	ds_read_b128 v[200:203], v151
	ds_read_b128 v[204:207], v151 offset:1024
	ds_read_b128 v[208:211], v150
	ds_read_b128 v[212:215], v150 offset:1024
	global_load_lds_dwordx4 v[164:165], off
	v_lshl_add_u64 v[164:165], v[238:239], 0, s[18:19]
	s_mov_b32 m0, s51
	s_nop 0
	global_load_lds_dwordx4 v[164:165], off
	s_waitcnt lgkmcnt(8)
	s_barrier
	s_waitcnt lgkmcnt(0)
	s_setprio 0
	s_waitcnt lgkmcnt(0)
	v_mfma_f32_16x16x32_bf16 v[124:127], v[184:187], v[166:169], v[124:127]
	v_mfma_f32_16x16x32_bf16 v[120:123], v[184:187], v[176:179], v[120:123]
	v_mfma_f32_16x16x32_bf16 v[116:119], v[192:195], v[166:169], v[116:119]
	v_mfma_f32_16x16x32_bf16 v[112:115], v[192:195], v[176:179], v[112:115]
	v_mfma_f32_16x16x32_bf16 v[108:111], v[200:203], v[166:169], v[108:111]
	v_mfma_f32_16x16x32_bf16 v[104:107], v[200:203], v[176:179], v[104:107]
	v_mfma_f32_16x16x32_bf16 v[100:103], v[208:211], v[166:169], v[100:103]
	v_mfma_f32_16x16x32_bf16 v[96:99], v[208:211], v[176:179], v[96:99]
	v_mfma_f32_16x16x32_bf16 v[124:127], v[188:191], v[172:175], v[124:127]
	v_mfma_f32_16x16x32_bf16 v[120:123], v[188:191], v[180:183], v[120:123]
	v_mfma_f32_16x16x32_bf16 v[116:119], v[196:199], v[172:175], v[116:119]
	v_mfma_f32_16x16x32_bf16 v[112:115], v[196:199], v[180:183], v[112:115]
	v_mfma_f32_16x16x32_bf16 v[108:111], v[204:207], v[172:175], v[108:111]
	v_mfma_f32_16x16x32_bf16 v[104:107], v[204:207], v[180:183], v[104:107]
	v_mfma_f32_16x16x32_bf16 v[100:103], v[212:215], v[172:175], v[100:103]
	v_mfma_f32_16x16x32_bf16 v[96:99], v[212:215], v[180:183], v[96:99]
	s_setprio 1
	s_barrier
	v_add_u32_e32 v163, s62, v155
	v_lshl_add_u64 v[240:241], v[134:135], 0, s[48:49]
	v_readfirstlane_b32 s51, v163
	v_lshl_add_u64 v[164:165], v[240:241], 0, s[20:21]
	s_mov_b32 m0, s51
	ds_read_b128 v[216:219], v161
	ds_read_b128 v[220:223], v161 offset:1024
	ds_read_b128 v[224:227], v161 offset:2048
	ds_read_b128 v[228:231], v161 offset:3072
	global_load_lds_dwordx4 v[164:165], off
	v_add_u32_e32 v164, 0x2000, v163
	v_lshl_add_u64 v[242:243], v[136:137], 0, s[48:49]
	v_readfirstlane_b32 s51, v164
	v_lshl_add_u64 v[232:233], v[242:243], 0, s[20:21]
	s_mov_b32 m0, s51
	s_nop 0
	global_load_lds_dwordx4 v[232:233], off
	s_barrier
	s_waitcnt lgkmcnt(0)
	s_setprio 0
	s_waitcnt lgkmcnt(0)
	v_mfma_f32_16x16x32_bf16 v[92:95], v[184:187], v[216:219], v[92:95]
	v_mfma_f32_16x16x32_bf16 v[88:91], v[184:187], v[224:227], v[88:91]
	v_mfma_f32_16x16x32_bf16 v[84:87], v[192:195], v[216:219], v[84:87]
	v_mfma_f32_16x16x32_bf16 v[80:83], v[192:195], v[224:227], v[80:83]
	v_mfma_f32_16x16x32_bf16 v[76:79], v[200:203], v[216:219], v[76:79]
	v_mfma_f32_16x16x32_bf16 v[72:75], v[200:203], v[224:227], v[72:75]
	v_mfma_f32_16x16x32_bf16 v[68:71], v[208:211], v[216:219], v[68:71]
	v_mfma_f32_16x16x32_bf16 v[64:67], v[208:211], v[224:227], v[64:67]
	v_mfma_f32_16x16x32_bf16 v[92:95], v[188:191], v[220:223], v[92:95]
	v_mfma_f32_16x16x32_bf16 v[88:91], v[188:191], v[228:231], v[88:91]
	v_mfma_f32_16x16x32_bf16 v[84:87], v[196:199], v[220:223], v[84:87]
	v_mfma_f32_16x16x32_bf16 v[80:83], v[196:199], v[228:231], v[80:83]
	v_mfma_f32_16x16x32_bf16 v[76:79], v[204:207], v[220:223], v[76:79]
	v_mfma_f32_16x16x32_bf16 v[72:75], v[204:207], v[228:231], v[72:75]
	v_mfma_f32_16x16x32_bf16 v[68:71], v[212:215], v[220:223], v[68:71]
	v_mfma_f32_16x16x32_bf16 v[64:67], v[212:215], v[228:231], v[64:67]
	s_setprio 1
	v_readfirstlane_b32 s51, v149
	v_add_u32_e32 v165, 0x2000, v149
	v_lshl_add_u64 v[232:233], v[236:237], 0, s[22:23]
	s_mov_b32 m0, s51
	v_readfirstlane_b32 s51, v165
	s_barrier
	ds_read_b128 v[184:187], v153 offset:16384
	ds_read_b128 v[188:191], v153 offset:17408
	ds_read_b128 v[192:195], v152 offset:16384
	ds_read_b128 v[196:199], v152 offset:17408
	ds_read_b128 v[200:203], v151 offset:16384
	ds_read_b128 v[204:207], v151 offset:17408
	ds_read_b128 v[208:211], v150 offset:16384
	ds_read_b128 v[212:215], v150 offset:17408
	global_load_lds_dwordx4 v[232:233], off
	v_lshl_add_u64 v[232:233], v[238:239], 0, s[22:23]
	s_mov_b32 m0, s51
	s_nop 0
	global_load_lds_dwordx4 v[232:233], off
	s_barrier
	s_waitcnt lgkmcnt(0)
	s_setprio 0
	s_waitcnt lgkmcnt(0)
	v_mfma_f32_16x16x32_bf16 v[60:63], v[184:187], v[166:169], v[60:63]
	v_mfma_f32_16x16x32_bf16 v[56:59], v[184:187], v[176:179], v[56:59]
	v_mfma_f32_16x16x32_bf16 v[52:55], v[192:195], v[166:169], v[52:55]
	v_mfma_f32_16x16x32_bf16 v[48:51], v[192:195], v[176:179], v[48:51]
	v_mfma_f32_16x16x32_bf16 v[44:47], v[200:203], v[166:169], v[44:47]
	v_mfma_f32_16x16x32_bf16 v[40:43], v[200:203], v[176:179], v[40:43]
	v_mfma_f32_16x16x32_bf16 v[36:39], v[208:211], v[166:169], v[36:39]
	v_mfma_f32_16x16x32_bf16 v[32:35], v[208:211], v[176:179], v[32:35]
	v_mfma_f32_16x16x32_bf16 v[60:63], v[188:191], v[172:175], v[60:63]
	v_mfma_f32_16x16x32_bf16 v[56:59], v[188:191], v[180:183], v[56:59]
	v_mfma_f32_16x16x32_bf16 v[52:55], v[196:199], v[172:175], v[52:55]
	v_mfma_f32_16x16x32_bf16 v[48:51], v[196:199], v[180:183], v[48:51]
	v_mfma_f32_16x16x32_bf16 v[44:47], v[204:207], v[172:175], v[44:47]
	v_mfma_f32_16x16x32_bf16 v[40:43], v[204:207], v[180:183], v[40:43]
	v_mfma_f32_16x16x32_bf16 v[36:39], v[212:215], v[172:175], v[36:39]
	v_mfma_f32_16x16x32_bf16 v[32:35], v[212:215], v[180:183], v[32:35]
	s_setprio 1
	s_barrier
; #define STAGE(P, BASE, LD, br, kt) do { const char* _g = (const char*)((BASE) + (size_t)(br) * (LD) + (size_t)(kt) * 64); \
;     for (int _i = 0; _i < 2; ++_i) { int _b = tidx * 16 + _i * 8192; int _r, _c; stage_rc(_b, _r, _c); \
;       __builtin_amdgcn_global_load_lds((const unsigned*)(_g + (unsigned)((_r * (LD) + _c) * 2)), (unsigned*)((char*)(P) + _b), 16, 0, 0); } } while (0)
; #define LDA(dst, b, h) for (int m = 0; m < 4; ++m) for (int k = 0; k < 2; ++k) \
;     dst[m][k] = *reinterpret_cast<const bf16x8*>((char*)SA(b, h) + lds_byte(wr * 64 + m * 16 + fr, k * 32 + fq * 8))
; #define LDB(dst, b, h) for (int n = 0; n < 2; ++n) for (int k = 0; k < 2; ++k) \
;     dst[n][k] = *reinterpret_cast<const bf16x8*>((char*)SB(b, h) + lds_byte(wc * 32 + n * 16 + fr, k * 32 + fq * 8))
; #define MMA(ai, bj, At_, Bt_) do { __builtin_amdgcn_s_setprio(1); \
;     for (int k = 0; k < 2; ++k) for (int m = 0; m < 4; ++m) for (int n = 0; n < 2; ++n) \
;       acc[ai][bj][m][n] = __builtin_amdgcn_mfma_f32_16x16x32_bf16(At_[m][k], Bt_[n][k], acc[ai][bj][m][n], 0, 0, 0); \
;     __builtin_amdgcn_s_setprio(0); } while (0)
; #define WAIT_V(n) asm volatile("s_waitcnt vmcnt(" #n ")" ::: "memory")
; #define WAIT_L(n) asm volatile("s_waitcnt lgkmcnt(" #n ")" ::: "memory")
; #define BAR __builtin_amdgcn_s_barrier()
; #define SCHED __builtin_amdgcn_sched_barrier(0)
; template <int EPI, int lda, int ldb, int N, int K>
; __device__ __forceinline__ void gemm_phase(const u16* __restrict__ A, const u16* __restrict__ Bt, const GemmEpi ep, int wv) {
;     ...
;       STAGE(SB(0, 1), Bt, ldb, bcol + HALF, t + 2);
;       WAIT_V(6); BAR; MMA(1, 1, At, B1); BAR;
;       LDB(B0, 1, 0); SCHED; LDA(At, 1, 0); STAGE(SA(0, 1), Ab, lda, brow + HALF, t + 2);
;       WAIT_L(8); BAR; WAIT_L(0); MMA(0, 0, At, B0); BAR; SCHED;
;       LDB(B1, 1, 1); STAGE(SB(1, 0), Bt, ldb, bcol, t + 3);
;       BAR; WAIT_L(0); MMA(0, 1, At, B1); BAR;
	v_add_u32_e32 v166, s63, v155
	v_add_u32_e32 v167, 0x2000, v166
	v_readfirstlane_b32 s51, v166
	v_lshl_add_u64 v[168:169], v[240:241], 0, s[24:25]
	s_mov_b32 m0, s51
	v_readfirstlane_b32 s51, v167
	global_load_lds_dwordx4 v[168:169], off
	v_lshl_add_u64 v[168:169], v[242:243], 0, s[24:25]
	s_mov_b32 m0, s51
	s_nop 0
	global_load_lds_dwordx4 v[168:169], off
	s_waitcnt vmcnt(6)
	s_barrier
	s_setprio 0
	v_mfma_f32_16x16x32_bf16 v[28:31], v[184:187], v[216:219], v[28:31]
	v_mfma_f32_16x16x32_bf16 v[24:27], v[184:187], v[224:227], v[24:27]
	v_mfma_f32_16x16x32_bf16 v[20:23], v[192:195], v[216:219], v[20:23]
	v_mfma_f32_16x16x32_bf16 v[16:19], v[192:195], v[224:227], v[16:19]
	v_mfma_f32_16x16x32_bf16 v[12:15], v[200:203], v[216:219], v[12:15]
	v_mfma_f32_16x16x32_bf16 v[8:11], v[200:203], v[224:227], v[8:11]
	v_mfma_f32_16x16x32_bf16 v[4:7], v[208:211], v[216:219], v[4:7]
	v_mfma_f32_16x16x32_bf16 v[0:3], v[208:211], v[224:227], v[0:3]
	v_mfma_f32_16x16x32_bf16 v[28:31], v[188:191], v[220:223], v[28:31]
	v_mfma_f32_16x16x32_bf16 v[24:27], v[188:191], v[228:231], v[24:27]
	v_mfma_f32_16x16x32_bf16 v[20:23], v[196:199], v[220:223], v[20:23]
	v_mfma_f32_16x16x32_bf16 v[16:19], v[196:199], v[228:231], v[16:19]
	v_mfma_f32_16x16x32_bf16 v[12:15], v[204:207], v[220:223], v[12:15]
	v_mfma_f32_16x16x32_bf16 v[8:11], v[204:207], v[228:231], v[8:11]
	v_mfma_f32_16x16x32_bf16 v[4:7], v[212:215], v[220:223], v[4:7]
	v_mfma_f32_16x16x32_bf16 v[0:3], v[212:215], v[228:231], v[0:3]
	s_setprio 1
	s_barrier
	ds_read_b128 v[172:175], v156
	ds_read_b128 v[176:179], v156 offset:1024
	ds_read_b128 v[180:183], v156 offset:2048
	ds_read_b128 v[184:187], v156 offset:3072
	v_add_u32_e32 v168, 0x4000, v149
	v_add_u32_e32 v169, 0x6000, v149
	v_readfirstlane_b32 s51, v168
	v_lshl_add_u64 v[220:221], v[236:237], 0, s[26:27]
	s_mov_b32 m0, s51
	v_readfirstlane_b32 s51, v169
	ds_read_b128 v[188:191], v153 offset:32768
	ds_read_b128 v[192:195], v153 offset:33792
	ds_read_b128 v[196:199], v152 offset:32768
	ds_read_b128 v[200:203], v152 offset:33792
	ds_read_b128 v[204:207], v151 offset:32768
	ds_read_b128 v[208:211], v151 offset:33792
	ds_read_b128 v[212:215], v150 offset:32768
	ds_read_b128 v[216:219], v150 offset:33792
	global_load_lds_dwordx4 v[220:221], off
	v_lshl_add_u64 v[220:221], v[238:239], 0, s[26:27]
	s_mov_b32 m0, s51
	s_nop 0
	global_load_lds_dwordx4 v[220:221], off
	s_waitcnt lgkmcnt(8)
	s_barrier
	s_waitcnt lgkmcnt(0)
	s_setprio 0
	s_waitcnt lgkmcnt(0)
	v_mfma_f32_16x16x32_bf16 v[124:127], v[188:191], v[172:175], v[124:127]
	v_mfma_f32_16x16x32_bf16 v[120:123], v[188:191], v[180:183], v[120:123]
	v_mfma_f32_16x16x32_bf16 v[116:119], v[196:199], v[172:175], v[116:119]
	v_mfma_f32_16x16x32_bf16 v[112:115], v[196:199], v[180:183], v[112:115]
	v_mfma_f32_16x16x32_bf16 v[108:111], v[204:207], v[172:175], v[108:111]
	v_mfma_f32_16x16x32_bf16 v[104:107], v[204:207], v[180:183], v[104:107]
	v_mfma_f32_16x16x32_bf16 v[100:103], v[212:215], v[172:175], v[100:103]
	v_mfma_f32_16x16x32_bf16 v[96:99], v[212:215], v[180:183], v[96:99]
	v_mfma_f32_16x16x32_bf16 v[124:127], v[192:195], v[176:179], v[124:127]
	v_mfma_f32_16x16x32_bf16 v[120:123], v[192:195], v[184:187], v[120:123]
	v_mfma_f32_16x16x32_bf16 v[116:119], v[200:203], v[176:179], v[116:119]
	v_mfma_f32_16x16x32_bf16 v[112:115], v[200:203], v[184:187], v[112:115]
	v_mfma_f32_16x16x32_bf16 v[108:111], v[208:211], v[176:179], v[108:111]
	v_mfma_f32_16x16x32_bf16 v[104:107], v[208:211], v[184:187], v[104:107]
	v_mfma_f32_16x16x32_bf16 v[100:103], v[216:219], v[176:179], v[100:103]
	v_mfma_f32_16x16x32_bf16 v[96:99], v[216:219], v[184:187], v[96:99]
	s_setprio 1
	s_barrier
	v_readfirstlane_b32 s51, v157
	v_add_u32_e32 v246, 0x2000, v157
	v_lshl_add_u64 v[244:245], v[240:241], 0, s[36:37]
	s_mov_b32 m0, s51
	v_readfirstlane_b32 s51, v246
	ds_read_b128 v[220:223], v154
	ds_read_b128 v[224:227], v154 offset:1024
	ds_read_b128 v[228:231], v154 offset:2048
	ds_read_b128 v[232:235], v154 offset:3072
	global_load_lds_dwordx4 v[244:245], off
	v_lshl_add_u64 v[244:245], v[242:243], 0, s[36:37]
	s_mov_b32 m0, s51
	s_nop 0
	global_load_lds_dwordx4 v[244:245], off
	s_barrier
	s_waitcnt lgkmcnt(0)
	s_setprio 0
	s_waitcnt lgkmcnt(0)
	v_mfma_f32_16x16x32_bf16 v[92:95], v[188:191], v[220:223], v[92:95]
	v_mfma_f32_16x16x32_bf16 v[88:91], v[188:191], v[228:231], v[88:91]
	v_mfma_f32_16x16x32_bf16 v[84:87], v[196:199], v[220:223], v[84:87]
	v_mfma_f32_16x16x32_bf16 v[80:83], v[196:199], v[228:231], v[80:83]
	v_mfma_f32_16x16x32_bf16 v[76:79], v[204:207], v[220:223], v[76:79]
	v_mfma_f32_16x16x32_bf16 v[72:75], v[204:207], v[228:231], v[72:75]
	v_mfma_f32_16x16x32_bf16 v[68:71], v[212:215], v[220:223], v[68:71]
	v_mfma_f32_16x16x32_bf16 v[64:67], v[212:215], v[228:231], v[64:67]
	v_mfma_f32_16x16x32_bf16 v[92:95], v[192:195], v[224:227], v[92:95]
	v_mfma_f32_16x16x32_bf16 v[88:91], v[192:195], v[232:235], v[88:91]
	v_mfma_f32_16x16x32_bf16 v[84:87], v[200:203], v[224:227], v[84:87]
	v_mfma_f32_16x16x32_bf16 v[80:83], v[200:203], v[232:235], v[80:83]
	v_mfma_f32_16x16x32_bf16 v[76:79], v[208:211], v[224:227], v[76:79]
	v_mfma_f32_16x16x32_bf16 v[72:75], v[208:211], v[232:235], v[72:75]
	v_mfma_f32_16x16x32_bf16 v[68:71], v[216:219], v[224:227], v[68:71]
	v_mfma_f32_16x16x32_bf16 v[64:67], v[216:219], v[232:235], v[64:67]
	s_setprio 1
	v_readfirstlane_b32 s51, v158
	v_lshl_add_u64 v[236:237], v[236:237], 0, s[38:39]
	s_mov_b32 m0, s51
	v_readfirstlane_b32 s51, v159
	s_barrier
; #define STAGE(P, BASE, LD, br, kt) do { const char* _g = (const char*)((BASE) + (size_t)(br) * (LD) + (size_t)(kt) * 64); \
;     for (int _i = 0; _i < 2; ++_i) { int _b = tidx * 16 + _i * 8192; int _r, _c; stage_rc(_b, _r, _c); \
;       __builtin_amdgcn_global_load_lds((const unsigned*)(_g + (unsigned)((_r * (LD) + _c) * 2)), (unsigned*)((char*)(P) + _b), 16, 0, 0); } } while (0)
; #define LDA(dst, b, h) for (int m = 0; m < 4; ++m) for (int k = 0; k < 2; ++k) \
;     dst[m][k] = *reinterpret_cast<const bf16x8*>((char*)SA(b, h) + lds_byte(wr * 64 + m * 16 + fr, k * 32 + fq * 8))
; #define LDB(dst, b, h) for (int n = 0; n < 2; ++n) for (int k = 0; k < 2; ++k) \
;     dst[n][k] = *reinterpret_cast<const bf16x8*>((char*)SB(b, h) + lds_byte(wc * 32 + n * 16 + fr, k * 32 + fq * 8))
; #define MMA(ai, bj, At_, Bt_) do { __builtin_amdgcn_s_setprio(1); \
;     for (int k = 0; k < 2; ++k) for (int m = 0; m < 4; ++m) for (int n = 0; n < 2; ++n) \
;       acc[ai][bj][m][n] = __builtin_amdgcn_mfma_f32_16x16x32_bf16(At_[m][k], Bt_[n][k], acc[ai][bj][m][n], 0, 0, 0); \
;     __builtin_amdgcn_s_setprio(0); } while (0)
; #define WAIT_V(n) asm volatile("s_waitcnt vmcnt(" #n ")" ::: "memory")
; #define WAIT_L(n) asm volatile("s_waitcnt lgkmcnt(" #n ")" ::: "memory")
; #define BAR __builtin_amdgcn_s_barrier()
; #define SCHED __builtin_amdgcn_sched_barrier(0)
; template <int EPI, int lda, int ldb, int N, int K>
; __device__ __forceinline__ void gemm_phase(const u16* __restrict__ A, const u16* __restrict__ Bt, const GemmEpi ep, int wv) {
;     ...
;       LDA(At, 1, 1); STAGE(SA(1, 0), Ab, lda, brow, t + 3);
;       BAR; WAIT_L(0); MMA(1, 0, At, B0); BAR; SCHED;
;       STAGE(SB(1, 1), Bt, ldb, bcol + HALF, t + 3);
;       WAIT_V(6); BAR; MMA(1, 1, At, B1); BAR;
;     }
;     { LDB(B0, 0, 0); LDA(At, 0, 0); STAGE(SA(1, 1), Ab, lda, brow + HALF, nt - 1);
;       BAR; WAIT_L(0); MMA(0, 0, At, B0); BAR;
;       LDB(B1, 0, 1); BAR; WAIT_L(0); MMA(0, 1, At, B1); BAR;
	ds_read_b128 v[188:191], v153 offset:49152
	ds_read_b128 v[192:195], v153 offset:50176
	ds_read_b128 v[196:199], v152 offset:49152
	ds_read_b128 v[200:203], v152 offset:50176
	ds_read_b128 v[204:207], v151 offset:49152
	ds_read_b128 v[208:211], v151 offset:50176
	ds_read_b128 v[212:215], v150 offset:49152
	ds_read_b128 v[216:219], v150 offset:50176
	global_load_lds_dwordx4 v[236:237], off
	v_lshl_add_u64 v[236:237], v[238:239], 0, s[38:39]
	s_mov_b32 m0, s51
	s_nop 0
	global_load_lds_dwordx4 v[236:237], off
	s_barrier
	s_waitcnt lgkmcnt(0)
	s_setprio 0
	s_waitcnt lgkmcnt(0)
	v_mfma_f32_16x16x32_bf16 v[60:63], v[188:191], v[172:175], v[60:63]
	v_mfma_f32_16x16x32_bf16 v[56:59], v[188:191], v[180:183], v[56:59]
	v_mfma_f32_16x16x32_bf16 v[52:55], v[196:199], v[172:175], v[52:55]
	v_mfma_f32_16x16x32_bf16 v[48:51], v[196:199], v[180:183], v[48:51]
	v_mfma_f32_16x16x32_bf16 v[44:47], v[204:207], v[172:175], v[44:47]
	v_mfma_f32_16x16x32_bf16 v[40:43], v[204:207], v[180:183], v[40:43]
	v_mfma_f32_16x16x32_bf16 v[36:39], v[212:215], v[172:175], v[36:39]
	v_mfma_f32_16x16x32_bf16 v[32:35], v[212:215], v[180:183], v[32:35]
	v_mfma_f32_16x16x32_bf16 v[60:63], v[192:195], v[176:179], v[60:63]
	v_mfma_f32_16x16x32_bf16 v[56:59], v[192:195], v[184:187], v[56:59]
	v_mfma_f32_16x16x32_bf16 v[52:55], v[200:203], v[176:179], v[52:55]
	v_mfma_f32_16x16x32_bf16 v[48:51], v[200:203], v[184:187], v[48:51]
	v_mfma_f32_16x16x32_bf16 v[44:47], v[208:211], v[176:179], v[44:47]
	v_mfma_f32_16x16x32_bf16 v[40:43], v[208:211], v[184:187], v[40:43]
	v_mfma_f32_16x16x32_bf16 v[36:39], v[216:219], v[176:179], v[36:39]
	v_mfma_f32_16x16x32_bf16 v[32:35], v[216:219], v[184:187], v[32:35]
	s_setprio 1
	s_barrier
	v_readfirstlane_b32 s51, v160
	v_add_u32_e32 v174, 0x2000, v160
	v_lshl_add_u64 v[172:173], v[240:241], 0, s[42:43]
	s_mov_b32 m0, s51
	v_readfirstlane_b32 s51, v174
	global_load_lds_dwordx4 v[172:173], off
	v_lshl_add_u64 v[172:173], v[242:243], 0, s[42:43]
	s_mov_b32 m0, s51
	s_nop 0
	global_load_lds_dwordx4 v[172:173], off
	s_waitcnt vmcnt(6)
	s_barrier
	s_setprio 0
	v_mfma_f32_16x16x32_bf16 v[28:31], v[188:191], v[220:223], v[28:31]
	v_mfma_f32_16x16x32_bf16 v[24:27], v[188:191], v[228:231], v[24:27]
	v_mfma_f32_16x16x32_bf16 v[20:23], v[196:199], v[220:223], v[20:23]
	v_mfma_f32_16x16x32_bf16 v[16:19], v[196:199], v[228:231], v[16:19]
	v_mfma_f32_16x16x32_bf16 v[12:15], v[204:207], v[220:223], v[12:15]
	v_mfma_f32_16x16x32_bf16 v[8:11], v[204:207], v[228:231], v[8:11]
	v_mfma_f32_16x16x32_bf16 v[4:7], v[212:215], v[220:223], v[4:7]
	v_mfma_f32_16x16x32_bf16 v[0:3], v[212:215], v[228:231], v[0:3]
	v_mfma_f32_16x16x32_bf16 v[28:31], v[192:195], v[224:227], v[28:31]
	v_mfma_f32_16x16x32_bf16 v[24:27], v[192:195], v[232:235], v[24:27]
	v_mfma_f32_16x16x32_bf16 v[20:23], v[200:203], v[224:227], v[20:23]
	v_mfma_f32_16x16x32_bf16 v[16:19], v[200:203], v[232:235], v[16:19]
	v_mfma_f32_16x16x32_bf16 v[12:15], v[208:211], v[224:227], v[12:15]
	v_mfma_f32_16x16x32_bf16 v[8:11], v[208:211], v[232:235], v[8:11]
	v_mfma_f32_16x16x32_bf16 v[4:7], v[216:219], v[224:227], v[4:7]
	v_mfma_f32_16x16x32_bf16 v[0:3], v[216:219], v[232:235], v[0:3]
	s_setprio 1
	s_add_i32 s50, s50, 2
	s_add_u32 s48, s48, 0x100
	s_addc_u32 s49, s49, 0
	s_cmp_gt_u32 s50, 27
	s_barrier
	s_cbranch_scc0 .LBB0_340
	s_add_i32 s48, s46, 0x80
	s_mul_hi_i32 s49, s48, 0x1080
	s_mulk_i32 s48, 0x1080
	s_add_u32 s48, s31, s48
	s_addc_u32 s49, s56, s49
	v_lshl_add_u64 v[158:159], s[48:49], 0, v[128:129]
	v_readfirstlane_b32 s50, v170
	v_lshl_add_u64 v[158:159], v[158:159], 0, s[44:45]
	s_mov_b32 m0, s50
	ds_read_b128 v[134:137], v162
	ds_read_b128 v[138:141], v162 offset:1024
	ds_read_b128 v[172:175], v162 offset:2048
	ds_read_b128 v[176:179], v162 offset:3072
	ds_read_b128 v[180:183], v153
	ds_read_b128 v[184:187], v153 offset:1024
	ds_read_b128 v[188:191], v152
	ds_read_b128 v[192:195], v152 offset:1024
	ds_read_b128 v[196:199], v151
	ds_read_b128 v[200:203], v151 offset:1024
	ds_read_b128 v[204:207], v150
	ds_read_b128 v[208:211], v150 offset:1024
	global_load_lds_dwordx4 v[158:159], off
	v_lshl_add_u64 v[158:159], s[48:49], 0, v[132:133]
	v_readfirstlane_b32 s48, v171
	v_lshl_add_u64 v[158:159], v[158:159], 0, s[44:45]
	s_mov_b32 m0, s48
	s_nop 0
	global_load_lds_dwordx4 v[158:159], off
	s_barrier
	s_waitcnt lgkmcnt(0)
	s_setprio 0
	s_waitcnt lgkmcnt(0)
	v_mfma_f32_16x16x32_bf16 v[124:127], v[180:183], v[134:137], v[124:127]
	v_mfma_f32_16x16x32_bf16 v[120:123], v[180:183], v[172:175], v[120:123]
	v_mfma_f32_16x16x32_bf16 v[116:119], v[188:191], v[134:137], v[116:119]
	v_mfma_f32_16x16x32_bf16 v[112:115], v[188:191], v[172:175], v[112:115]
	v_mfma_f32_16x16x32_bf16 v[108:111], v[196:199], v[134:137], v[108:111]
	v_mfma_f32_16x16x32_bf16 v[104:107], v[196:199], v[172:175], v[104:107]
	v_mfma_f32_16x16x32_bf16 v[100:103], v[204:207], v[134:137], v[100:103]
	v_mfma_f32_16x16x32_bf16 v[96:99], v[204:207], v[172:175], v[96:99]
	v_mfma_f32_16x16x32_bf16 v[124:127], v[184:187], v[138:141], v[124:127]
	v_mfma_f32_16x16x32_bf16 v[120:123], v[184:187], v[176:179], v[120:123]
	v_mfma_f32_16x16x32_bf16 v[116:119], v[192:195], v[138:141], v[116:119]
	v_mfma_f32_16x16x32_bf16 v[112:115], v[192:195], v[176:179], v[112:115]
	v_mfma_f32_16x16x32_bf16 v[108:111], v[200:203], v[138:141], v[108:111]
	v_mfma_f32_16x16x32_bf16 v[104:107], v[200:203], v[176:179], v[104:107]
	v_mfma_f32_16x16x32_bf16 v[100:103], v[208:211], v[138:141], v[100:103]
	v_mfma_f32_16x16x32_bf16 v[96:99], v[208:211], v[176:179], v[96:99]
	s_setprio 1
	s_barrier
	ds_read_b128 v[212:215], v161
	ds_read_b128 v[216:219], v161 offset:1024
	ds_read_b128 v[220:223], v161 offset:2048
	ds_read_b128 v[158:161], v161 offset:3072
	s_barrier
; #define LDA(dst, b, h) for (int m = 0; m < 4; ++m) for (int k = 0; k < 2; ++k) \
;     dst[m][k] = *reinterpret_cast<const bf16x8*>((char*)SA(b, h) + lds_byte(wr * 64 + m * 16 + fr, k * 32 + fq * 8))
; #define LDB(dst, b, h) for (int n = 0; n < 2; ++n) for (int k = 0; k < 2; ++k) \
;     dst[n][k] = *reinterpret_cast<const bf16x8*>((char*)SB(b, h) + lds_byte(wc * 32 + n * 16 + fr, k * 32 + fq * 8))
; #define MMA(ai, bj, At_, Bt_) do { __builtin_amdgcn_s_setprio(1); \
;     for (int k = 0; k < 2; ++k) for (int m = 0; m < 4; ++m) for (int n = 0; n < 2; ++n) \
;       acc[ai][bj][m][n] = __builtin_amdgcn_mfma_f32_16x16x32_bf16(At_[m][k], Bt_[n][k], acc[ai][bj][m][n], 0, 0, 0); \
;     __builtin_amdgcn_s_setprio(0); } while (0)
; #define WAIT_V(n) asm volatile("s_waitcnt vmcnt(" #n ")" ::: "memory")
; #define WAIT_L(n) asm volatile("s_waitcnt lgkmcnt(" #n ")" ::: "memory")
; #define BAR __builtin_amdgcn_s_barrier()
; template <int EPI, int lda, int ldb, int N, int K>
; __device__ __forceinline__ void gemm_phase(const u16* __restrict__ A, const u16* __restrict__ Bt, const GemmEpi ep, int wv) {
;     ...
;       LDB(B1, 0, 1); BAR; WAIT_L(0); MMA(0, 1, At, B1); BAR;
;       LDA(At, 0, 1); WAIT_V(4); BAR; WAIT_L(0); MMA(1, 0, At, B0); MMA(1, 1, At, B1); BAR; }
;     { LDB(B0, 1, 0); LDA(At, 1, 0); WAIT_V(2); BAR; WAIT_L(0); MMA(0, 0, At, B0); BAR;
	s_waitcnt lgkmcnt(0)
	s_setprio 0
	s_waitcnt lgkmcnt(0)
	v_mfma_f32_16x16x32_bf16 v[92:95], v[180:183], v[212:215], v[92:95]
	v_mfma_f32_16x16x32_bf16 v[88:91], v[180:183], v[220:223], v[88:91]
	v_mfma_f32_16x16x32_bf16 v[76:79], v[196:199], v[212:215], v[76:79]
	v_mfma_f32_16x16x32_bf16 v[72:75], v[196:199], v[220:223], v[72:75]
	v_mfma_f32_16x16x32_bf16 v[68:71], v[204:207], v[212:215], v[68:71]
	v_mfma_f32_16x16x32_bf16 v[64:67], v[204:207], v[220:223], v[64:67]
	v_mfma_f32_16x16x32_bf16 v[84:87], v[188:191], v[212:215], v[84:87]
	v_mfma_f32_16x16x32_bf16 v[80:83], v[188:191], v[220:223], v[80:83]
	v_mfma_f32_16x16x32_bf16 v[92:95], v[184:187], v[216:219], v[92:95]
	v_mfma_f32_16x16x32_bf16 v[88:91], v[184:187], v[158:161], v[88:91]
	v_mfma_f32_16x16x32_bf16 v[76:79], v[200:203], v[216:219], v[76:79]
	v_mfma_f32_16x16x32_bf16 v[72:75], v[200:203], v[158:161], v[72:75]
	v_mfma_f32_16x16x32_bf16 v[68:71], v[208:211], v[216:219], v[68:71]
	v_mfma_f32_16x16x32_bf16 v[64:67], v[208:211], v[158:161], v[64:67]
	v_mfma_f32_16x16x32_bf16 v[180:183], v[192:195], v[216:219], v[84:87]
	v_mfma_f32_16x16x32_bf16 v[184:187], v[192:195], v[158:161], v[80:83]
	s_setprio 1
	s_barrier
	s_nop 0
	ds_read_b128 v[80:83], v153 offset:16384
	ds_read_b128 v[84:87], v153 offset:17408
	ds_read_b128 v[188:191], v152 offset:16384
	ds_read_b128 v[192:195], v152 offset:17408
	ds_read_b128 v[196:199], v151 offset:16384
	ds_read_b128 v[200:203], v151 offset:17408
	ds_read_b128 v[204:207], v150 offset:16384
	ds_read_b128 v[208:211], v150 offset:17408
	s_waitcnt vmcnt(4)
	s_barrier
	s_waitcnt lgkmcnt(0)
	s_setprio 0
	s_waitcnt lgkmcnt(0)
	v_mfma_f32_16x16x32_bf16 v[60:63], v[80:83], v[134:137], v[60:63]
	v_mfma_f32_16x16x32_bf16 v[44:47], v[196:199], v[134:137], v[44:47]
	v_mfma_f32_16x16x32_bf16 v[40:43], v[196:199], v[172:175], v[40:43]
	v_mfma_f32_16x16x32_bf16 v[36:39], v[204:207], v[134:137], v[36:39]
	v_mfma_f32_16x16x32_bf16 v[32:35], v[204:207], v[172:175], v[32:35]
	v_mfma_f32_16x16x32_bf16 v[56:59], v[80:83], v[172:175], v[56:59]
	v_mfma_f32_16x16x32_bf16 v[52:55], v[188:191], v[134:137], v[52:55]
	v_mfma_f32_16x16x32_bf16 v[48:51], v[188:191], v[172:175], v[48:51]
	v_mfma_f32_16x16x32_bf16 v[60:63], v[84:87], v[138:141], v[60:63]
	v_mfma_f32_16x16x32_bf16 v[44:47], v[200:203], v[138:141], v[44:47]
	v_mfma_f32_16x16x32_bf16 v[40:43], v[200:203], v[176:179], v[40:43]
	v_mfma_f32_16x16x32_bf16 v[36:39], v[208:211], v[138:141], v[36:39]
	v_mfma_f32_16x16x32_bf16 v[32:35], v[208:211], v[176:179], v[32:35]
	v_mfma_f32_16x16x32_bf16 v[134:137], v[84:87], v[176:179], v[56:59]
	v_mfma_f32_16x16x32_bf16 v[170:173], v[192:195], v[138:141], v[52:55]
	v_mfma_f32_16x16x32_bf16 v[224:227], v[192:195], v[176:179], v[48:51]
	s_setprio 1
	s_setprio 0
	v_mfma_f32_16x16x32_bf16 v[28:31], v[80:83], v[212:215], v[28:31]
	v_mfma_f32_16x16x32_bf16 v[20:23], v[188:191], v[212:215], v[20:23]
	v_mfma_f32_16x16x32_bf16 v[12:15], v[196:199], v[212:215], v[12:15]
	v_mfma_f32_16x16x32_bf16 v[4:7], v[204:207], v[212:215], v[4:7]
	v_mfma_f32_16x16x32_bf16 v[24:27], v[80:83], v[220:223], v[24:27]
	v_mfma_f32_16x16x32_bf16 v[16:19], v[188:191], v[220:223], v[16:19]
	v_mfma_f32_16x16x32_bf16 v[8:11], v[196:199], v[220:223], v[8:11]
	v_mfma_f32_16x16x32_bf16 v[0:3], v[204:207], v[220:223], v[0:3]
	v_mfma_f32_16x16x32_bf16 v[28:31], v[84:87], v[216:219], v[28:31]
	v_mfma_f32_16x16x32_bf16 v[20:23], v[192:195], v[216:219], v[20:23]
	v_mfma_f32_16x16x32_bf16 v[12:15], v[200:203], v[216:219], v[12:15]
	v_mfma_f32_16x16x32_bf16 v[4:7], v[208:211], v[216:219], v[4:7]
	v_mfma_f32_16x16x32_bf16 v[138:141], v[84:87], v[158:161], v[24:27]
	v_mfma_f32_16x16x32_bf16 v[174:177], v[192:195], v[158:161], v[16:19]
	v_mfma_f32_16x16x32_bf16 v[188:191], v[200:203], v[158:161], v[8:11]
	v_mfma_f32_16x16x32_bf16 v[158:161], v[208:211], v[158:161], v[0:3]
	s_setprio 1
	s_barrier
	s_nop 0
	ds_read_b128 v[0:3], v156
	ds_read_b128 v[8:11], v156 offset:1024
	ds_read_b128 v[16:19], v156 offset:2048
	ds_read_b128 v[192:195], v156 offset:3072
	ds_read_b128 v[24:27], v153 offset:32768
	ds_read_b128 v[56:59], v153 offset:33792
	ds_read_b128 v[196:199], v152 offset:32768
	ds_read_b128 v[200:203], v152 offset:33792
	ds_read_b128 v[204:207], v151 offset:32768
	ds_read_b128 v[208:211], v151 offset:33792
	ds_read_b128 v[212:215], v150 offset:32768
	ds_read_b128 v[216:219], v150 offset:33792
	s_waitcnt vmcnt(2)
	s_barrier
; #define UNR _Pragma("unroll")
; #define LDA(dst, b, h) for (int m = 0; m < 4; ++m) for (int k = 0; k < 2; ++k) \
;     dst[m][k] = *reinterpret_cast<const bf16x8*>((char*)SA(b, h) + lds_byte(wr * 64 + m * 16 + fr, k * 32 + fq * 8))
; #define LDB(dst, b, h) for (int n = 0; n < 2; ++n) for (int k = 0; k < 2; ++k) \
;     dst[n][k] = *reinterpret_cast<const bf16x8*>((char*)SB(b, h) + lds_byte(wc * 32 + n * 16 + fr, k * 32 + fq * 8))
; #define MMA(ai, bj, At_, Bt_) do { __builtin_amdgcn_s_setprio(1); \
;     for (int k = 0; k < 2; ++k) for (int m = 0; m < 4; ++m) for (int n = 0; n < 2; ++n) \
;       acc[ai][bj][m][n] = __builtin_amdgcn_mfma_f32_16x16x32_bf16(At_[m][k], Bt_[n][k], acc[ai][bj][m][n], 0, 0, 0); \
;     __builtin_amdgcn_s_setprio(0); } while (0)
; #define WAIT_V(n) asm volatile("s_waitcnt vmcnt(" #n ")" ::: "memory")
; #define WAIT_L(n) asm volatile("s_waitcnt lgkmcnt(" #n ")" ::: "memory")
; #define BAR __builtin_amdgcn_s_barrier()
; #define STAGE4(BROW, BCOL, PN) do { const u16* Ab_ = A + (EPI == EPI_RG ? ((PN) >> 1) * 256 : 0); \
;     STAGE(SB(0, 0), Bt, ldb, (BCOL), 0); STAGE(SA(0, 0), Ab_, lda, (BROW), 0); \
;     STAGE(SB(0, 1), Bt, ldb, (BCOL) + HALF, 0); STAGE(SA(0, 1), Ab_, lda, (BROW) + HALF, 0); } while (0)
; template <int EPI, int lda, int ldb, int N, int K>
; __device__ __forceinline__ void gemm_phase(const u16* __restrict__ A, const u16* __restrict__ Bt, const GemmEpi ep, int wv) {
;     ...
;     { LDB(B0, 1, 0); LDA(At, 1, 0); WAIT_V(2); BAR; WAIT_L(0); MMA(0, 0, At, B0); BAR;
;       LDB(B1, 1, 1); WAIT_V(0); BAR; WAIT_L(0); MMA(0, 1, At, B1); BAR;
;       LDA(At, 1, 1); BAR; WAIT_L(0); MMA(1, 0, At, B0); MMA(1, 1, At, B1); BAR; }
;     if (wr == 0) BAR;
;     int ntile = 0, nbrow = 0, nbcol = 0, npn = 0; bool more = false;
;     if constexpr (PF) { ntile = tile + gridDim.x; more = ntile < nwg; if (more) { TILE_COORDS(ntile, nbrow, nbcol, npn); STAGE4(nbrow, nbcol, npn); } }
;     float nss[8];
;     if constexpr (CONS) { UNR for (int pp = 0; pp < 8; ++pp) nss[pp] = 0.f;
;       if (more && tidx < 256) { UNR for (int pp = 0; pp < 8; ++pp) nss[pp] = ep.ss_in[(size_t)pp * T + nbrow + tidx]; } }
	s_waitcnt lgkmcnt(0)
	s_setprio 0
	s_waitcnt lgkmcnt(0)
	v_mfma_f32_16x16x32_bf16 v[48:51], v[24:27], v[0:3], v[124:127]
	v_mfma_f32_16x16x32_bf16 v[52:55], v[24:27], v[16:19], v[120:123]
	v_mfma_f32_16x16x32_bf16 v[80:83], v[196:199], v[0:3], v[116:119]
	v_mfma_f32_16x16x32_bf16 v[84:87], v[196:199], v[16:19], v[112:115]
	v_mfma_f32_16x16x32_bf16 v[108:111], v[204:207], v[0:3], v[108:111]
	v_mfma_f32_16x16x32_bf16 v[104:107], v[204:207], v[16:19], v[104:107]
	v_mfma_f32_16x16x32_bf16 v[112:115], v[212:215], v[0:3], v[100:103]
	v_mfma_f32_16x16x32_bf16 v[120:123], v[212:215], v[16:19], v[96:99]
	v_mfma_f32_16x16x32_bf16 v[124:127], v[56:59], v[8:11], v[48:51]
	v_mfma_f32_16x16x32_bf16 v[116:119], v[56:59], v[192:195], v[52:55]
	v_mfma_f32_16x16x32_bf16 v[100:103], v[200:203], v[8:11], v[80:83]
	v_mfma_f32_16x16x32_bf16 v[96:99], v[200:203], v[192:195], v[84:87]
	v_mfma_f32_16x16x32_bf16 v[84:87], v[208:211], v[8:11], v[108:111]
	v_mfma_f32_16x16x32_bf16 v[80:83], v[208:211], v[192:195], v[104:107]
	v_mfma_f32_16x16x32_bf16 v[52:55], v[216:219], v[8:11], v[112:115]
	v_mfma_f32_16x16x32_bf16 v[48:51], v[216:219], v[192:195], v[120:123]
	s_setprio 1
	s_barrier
	ds_read_b128 v[220:223], v154
	ds_read_b128 v[228:231], v154 offset:1024
	ds_read_b128 v[232:235], v154 offset:2048
	ds_read_b128 v[154:157], v154 offset:3072
	s_waitcnt vmcnt(0)
	s_barrier
	s_waitcnt lgkmcnt(0)
	s_setprio 0
	s_waitcnt lgkmcnt(0)
	v_mfma_f32_16x16x32_bf16 v[92:95], v[24:27], v[220:223], v[92:95]
	v_mfma_f32_16x16x32_bf16 v[24:27], v[24:27], v[232:235], v[88:91]
	v_mfma_f32_16x16x32_bf16 v[88:91], v[196:199], v[220:223], v[180:183]
	v_mfma_f32_16x16x32_bf16 v[104:107], v[196:199], v[232:235], v[184:187]
	v_mfma_f32_16x16x32_bf16 v[76:79], v[204:207], v[220:223], v[76:79]
	v_mfma_f32_16x16x32_bf16 v[72:75], v[204:207], v[232:235], v[72:75]
	v_mfma_f32_16x16x32_bf16 v[68:71], v[212:215], v[220:223], v[68:71]
	v_mfma_f32_16x16x32_bf16 v[64:67], v[212:215], v[232:235], v[64:67]
	v_mfma_f32_16x16x32_bf16 v[120:123], v[56:59], v[228:231], v[92:95]
	v_mfma_f32_16x16x32_bf16 v[112:115], v[56:59], v[154:157], v[24:27]
	v_mfma_f32_16x16x32_bf16 v[108:111], v[200:203], v[228:231], v[88:91]
	v_mfma_f32_16x16x32_bf16 v[104:107], v[200:203], v[154:157], v[104:107]
	v_mfma_f32_16x16x32_bf16 v[92:95], v[208:211], v[228:231], v[76:79]
	v_mfma_f32_16x16x32_bf16 v[88:91], v[208:211], v[154:157], v[72:75]
	v_mfma_f32_16x16x32_bf16 v[68:71], v[216:219], v[228:231], v[68:71]
	v_mfma_f32_16x16x32_bf16 v[56:59], v[216:219], v[154:157], v[64:67]
	s_setprio 1
	s_barrier
	s_nop 0
	ds_read_b128 v[64:67], v153 offset:49152
	ds_read_b128 v[178:181], v153 offset:50176
	ds_read_b128 v[76:79], v152 offset:49152
	ds_read_b128 v[182:185], v152 offset:50176
	ds_read_b128 v[196:199], v151 offset:49152
	ds_read_b128 v[200:203], v151 offset:50176
	ds_read_b128 v[204:207], v150 offset:49152
	ds_read_b128 v[150:153], v150 offset:50176
	s_barrier
	s_waitcnt lgkmcnt(0)
	s_setprio 0
	s_waitcnt lgkmcnt(0)
	v_mfma_f32_16x16x32_bf16 v[24:27], v[64:67], v[0:3], v[60:63]
	v_mfma_f32_16x16x32_bf16 v[60:63], v[64:67], v[16:19], v[134:137]
	v_mfma_f32_16x16x32_bf16 v[134:137], v[76:79], v[0:3], v[170:173]
	v_mfma_f32_16x16x32_bf16 v[170:173], v[76:79], v[16:19], v[224:227]
	v_mfma_f32_16x16x32_bf16 v[44:47], v[196:199], v[0:3], v[44:47]
	v_mfma_f32_16x16x32_bf16 v[208:211], v[196:199], v[16:19], v[40:43]
	v_mfma_f32_16x16x32_bf16 v[0:3], v[204:207], v[0:3], v[36:39]
	v_mfma_f32_16x16x32_bf16 v[36:39], v[204:207], v[16:19], v[32:35]
	v_mfma_f32_16x16x32_bf16 v[72:75], v[178:181], v[8:11], v[24:27]
	v_mfma_f32_16x16x32_bf16 v[60:63], v[178:181], v[192:195], v[60:63]
	v_mfma_f32_16x16x32_bf16 v[40:43], v[182:185], v[8:11], v[134:137]
	v_mfma_f32_16x16x32_bf16 v[32:35], v[182:185], v[192:195], v[170:173]
	v_mfma_f32_16x16x32_bf16 v[24:27], v[200:203], v[8:11], v[44:47]
	v_mfma_f32_16x16x32_bf16 v[16:19], v[200:203], v[192:195], v[208:211]
	v_mfma_f32_16x16x32_bf16 v[8:11], v[150:153], v[8:11], v[0:3]
	v_mfma_f32_16x16x32_bf16 v[0:3], v[150:153], v[192:195], v[36:39]
	s_setprio 1
	s_setprio 0
	v_mfma_f32_16x16x32_bf16 v[28:31], v[64:67], v[220:223], v[28:31]
	v_mfma_f32_16x16x32_bf16 v[36:39], v[64:67], v[232:235], v[138:141]
	v_mfma_f32_16x16x32_bf16 v[20:23], v[76:79], v[220:223], v[20:23]
	v_mfma_f32_16x16x32_bf16 v[134:137], v[76:79], v[232:235], v[174:177]
	v_mfma_f32_16x16x32_bf16 v[12:15], v[196:199], v[220:223], v[12:15]
	v_mfma_f32_16x16x32_bf16 v[138:141], v[196:199], v[232:235], v[188:191]
	v_mfma_f32_16x16x32_bf16 v[4:7], v[204:207], v[220:223], v[4:7]
	v_mfma_f32_16x16x32_bf16 v[158:161], v[204:207], v[232:235], v[158:161]
	v_mfma_f32_16x16x32_bf16 v[76:79], v[178:181], v[228:231], v[28:31]
	v_mfma_f32_16x16x32_bf16 v[64:67], v[178:181], v[154:157], v[36:39]
	v_mfma_f32_16x16x32_bf16 v[44:47], v[182:185], v[228:231], v[20:23]
	v_mfma_f32_16x16x32_bf16 v[36:39], v[182:185], v[154:157], v[134:137]
	v_mfma_f32_16x16x32_bf16 v[28:31], v[200:203], v[228:231], v[12:15]
	v_mfma_f32_16x16x32_bf16 v[20:23], v[200:203], v[154:157], v[138:141]
	v_mfma_f32_16x16x32_bf16 v[12:15], v[150:153], v[228:231], v[4:7]
	v_mfma_f32_16x16x32_bf16 v[4:7], v[150:153], v[154:157], v[158:161]
	s_setprio 1
	v_cmp_gt_u32_e32 vcc, s64, v130
	s_barrier
	s_and_saveexec_b64 s[48:49], vcc
	s_cbranch_execz .LBB0_343
	s_barrier

; #define STAGE(P, BASE, LD, br, kt) do { const char* _g = (const char*)((BASE) + (size_t)(br) * (LD) + (size_t)(kt) * 64); \
;     for (int _i = 0; _i < 2; ++_i) { int _b = tidx * 16 + _i * 8192; int _r, _c; stage_rc(_b, _r, _c); \
;       __builtin_amdgcn_global_load_lds((const unsigned*)(_g + (unsigned)((_r * (LD) + _c) * 2)), (unsigned*)((char*)(P) + _b), 16, 0, 0); } } while (0)
; #define LDA(dst, b, h) for (int m = 0; m < 4; ++m) for (int k = 0; k < 2; ++k) \
;     dst[m][k] = *reinterpret_cast<const bf16x8*>((char*)SA(b, h) + lds_byte(wr * 64 + m * 16 + fr, k * 32 + fq * 8))
; #define LDB(dst, b, h) for (int n = 0; n < 2; ++n) for (int k = 0; k < 2; ++k) \
;     dst[n][k] = *reinterpret_cast<const bf16x8*>((char*)SB(b, h) + lds_byte(wc * 32 + n * 16 + fr, k * 32 + fq * 8))
; #define MMA(ai, bj, At_, Bt_) do { __builtin_amdgcn_s_setprio(1); \
;     for (int k = 0; k < 2; ++k) for (int m = 0; m < 4; ++m) for (int n = 0; n < 2; ++n) \
;       acc[ai][bj][m][n] = __builtin_amdgcn_mfma_f32_16x16x32_bf16(At_[m][k], Bt_[n][k], acc[ai][bj][m][n], 0, 0, 0); \
;     __builtin_amdgcn_s_setprio(0); } while (0)
; #define WAIT_L(n) asm volatile("s_waitcnt lgkmcnt(" #n ")" ::: "memory")
; #define BAR __builtin_amdgcn_s_barrier()
; #define SCHED __builtin_amdgcn_sched_barrier(0)
; template <int EPI, int lda, int ldb, int N, int K>
; __device__ __forceinline__ void gemm_phase(const u16* __restrict__ A, const u16* __restrict__ Bt, const GemmEpi ep, int wv) {
;     ...
;     for (int t = 0; t < nt - 2; t += 2) {
;       LDB(B0, 0, 0); SCHED; LDA(At, 0, 0); STAGE(SA(1, 1), Ab, lda, brow + HALF, t + 1);
;       WAIT_L(8); BAR; WAIT_L(0); MMA(0, 0, At, B0); BAR; SCHED;
;       LDB(B1, 0, 1); STAGE(SB(0, 0), Bt, ldb, bcol, t + 2);
;       BAR; WAIT_L(0); MMA(0, 1, At, B1); BAR;
;       LDA(At, 0, 1); STAGE(SA(0, 0), Ab, lda, brow, t + 2);
;       BAR; WAIT_L(0); MMA(1, 0, At, B0); BAR; SCHED;
.LBB0_654:
	ds_read_b128 v[164:167], v160
	ds_read_b128 v[170:173], v160 offset:1024
	ds_read_b128 v[174:177], v160 offset:2048
	ds_read_b128 v[178:181], v160 offset:3072
	v_add_u32_e32 v168, 0xc000, v143
	v_lshl_add_u64 v[234:235], v[138:139], 0, s[52:53]
	v_readfirstlane_b32 s55, v168
	v_add_u32_e32 v169, 0xe000, v143
	v_lshl_add_u64 v[162:163], v[234:235], 0, s[20:21]
	s_mov_b32 m0, s55
	v_lshl_add_u64 v[236:237], v[140:141], 0, s[52:53]
	v_readfirstlane_b32 s55, v169
	ds_read_b128 v[182:185], v151
	ds_read_b128 v[186:189], v151 offset:1024
	ds_read_b128 v[190:193], v150
	ds_read_b128 v[194:197], v150 offset:1024
	ds_read_b128 v[198:201], v149
	ds_read_b128 v[202:205], v149 offset:1024
	ds_read_b128 v[206:209], v148
	ds_read_b128 v[210:213], v148 offset:1024
	global_load_lds_dwordx4 v[162:163], off
	v_lshl_add_u64 v[162:163], v[236:237], 0, s[20:21]
	s_mov_b32 m0, s55
	s_nop 0
	global_load_lds_dwordx4 v[162:163], off
	s_waitcnt lgkmcnt(8)
	s_barrier
	s_waitcnt lgkmcnt(0)
	s_setprio 0
	s_waitcnt lgkmcnt(0)
	v_mfma_f32_16x16x32_bf16 v[124:127], v[164:167], v[182:185], v[124:127]
	v_mfma_f32_16x16x32_bf16 v[120:123], v[174:177], v[182:185], v[120:123]
	v_mfma_f32_16x16x32_bf16 v[116:119], v[164:167], v[190:193], v[116:119]
	v_mfma_f32_16x16x32_bf16 v[112:115], v[174:177], v[190:193], v[112:115]
	v_mfma_f32_16x16x32_bf16 v[108:111], v[164:167], v[198:201], v[108:111]
	v_mfma_f32_16x16x32_bf16 v[104:107], v[174:177], v[198:201], v[104:107]
	v_mfma_f32_16x16x32_bf16 v[100:103], v[164:167], v[206:209], v[100:103]
	v_mfma_f32_16x16x32_bf16 v[96:99], v[174:177], v[206:209], v[96:99]
	v_mfma_f32_16x16x32_bf16 v[124:127], v[170:173], v[186:189], v[124:127]
	v_mfma_f32_16x16x32_bf16 v[120:123], v[178:181], v[186:189], v[120:123]
	v_mfma_f32_16x16x32_bf16 v[116:119], v[170:173], v[194:197], v[116:119]
	v_mfma_f32_16x16x32_bf16 v[112:115], v[178:181], v[194:197], v[112:115]
	v_mfma_f32_16x16x32_bf16 v[108:111], v[170:173], v[202:205], v[108:111]
	v_mfma_f32_16x16x32_bf16 v[104:107], v[178:181], v[202:205], v[104:107]
	v_mfma_f32_16x16x32_bf16 v[100:103], v[170:173], v[210:213], v[100:103]
	v_mfma_f32_16x16x32_bf16 v[96:99], v[178:181], v[210:213], v[96:99]
	s_setprio 1
	s_barrier
	v_add_u32_e32 v161, s65, v153
	v_lshl_add_u64 v[238:239], v[134:135], 0, s[52:53]
	v_readfirstlane_b32 s55, v161
	v_lshl_add_u64 v[162:163], v[238:239], 0, s[22:23]
	s_mov_b32 m0, s55
	ds_read_b128 v[214:217], v159
	ds_read_b128 v[218:221], v159 offset:1024
	ds_read_b128 v[222:225], v159 offset:2048
	ds_read_b128 v[226:229], v159 offset:3072
	global_load_lds_dwordx4 v[162:163], off
	v_add_u32_e32 v162, 0x2000, v161
	v_lshl_add_u64 v[240:241], v[136:137], 0, s[52:53]
	v_readfirstlane_b32 s55, v162
	v_lshl_add_u64 v[230:231], v[240:241], 0, s[22:23]
	s_mov_b32 m0, s55
	s_nop 0
	global_load_lds_dwordx4 v[230:231], off
	s_barrier
	s_waitcnt lgkmcnt(0)
	s_setprio 0
	s_waitcnt lgkmcnt(0)
	v_mfma_f32_16x16x32_bf16 v[92:95], v[214:217], v[182:185], v[92:95]
	v_mfma_f32_16x16x32_bf16 v[88:91], v[222:225], v[182:185], v[88:91]
	v_mfma_f32_16x16x32_bf16 v[84:87], v[214:217], v[190:193], v[84:87]
	v_mfma_f32_16x16x32_bf16 v[80:83], v[222:225], v[190:193], v[80:83]
	v_mfma_f32_16x16x32_bf16 v[76:79], v[214:217], v[198:201], v[76:79]
	v_mfma_f32_16x16x32_bf16 v[72:75], v[222:225], v[198:201], v[72:75]
	v_mfma_f32_16x16x32_bf16 v[68:71], v[214:217], v[206:209], v[68:71]
	v_mfma_f32_16x16x32_bf16 v[64:67], v[222:225], v[206:209], v[64:67]
	v_mfma_f32_16x16x32_bf16 v[92:95], v[218:221], v[186:189], v[92:95]
	v_mfma_f32_16x16x32_bf16 v[88:91], v[226:229], v[186:189], v[88:91]
	v_mfma_f32_16x16x32_bf16 v[84:87], v[218:221], v[194:197], v[84:87]
	v_mfma_f32_16x16x32_bf16 v[80:83], v[226:229], v[194:197], v[80:83]
	v_mfma_f32_16x16x32_bf16 v[76:79], v[218:221], v[202:205], v[76:79]
	v_mfma_f32_16x16x32_bf16 v[72:75], v[226:229], v[202:205], v[72:75]
	v_mfma_f32_16x16x32_bf16 v[68:71], v[218:221], v[210:213], v[68:71]
	v_mfma_f32_16x16x32_bf16 v[64:67], v[226:229], v[210:213], v[64:67]
	s_setprio 1
	v_readfirstlane_b32 s55, v143
	v_add_u32_e32 v163, 0x2000, v143
	v_lshl_add_u64 v[230:231], v[234:235], 0, s[24:25]
	s_mov_b32 m0, s55
	v_readfirstlane_b32 s55, v163
	s_barrier
	ds_read_b128 v[182:185], v151 offset:16384
	ds_read_b128 v[186:189], v151 offset:17408
	ds_read_b128 v[190:193], v150 offset:16384
	ds_read_b128 v[194:197], v150 offset:17408
	ds_read_b128 v[198:201], v149 offset:16384
	ds_read_b128 v[202:205], v149 offset:17408
	ds_read_b128 v[206:209], v148 offset:16384
	ds_read_b128 v[210:213], v148 offset:17408
	global_load_lds_dwordx4 v[230:231], off
	v_lshl_add_u64 v[230:231], v[236:237], 0, s[24:25]
	s_mov_b32 m0, s55
	s_nop 0
	global_load_lds_dwordx4 v[230:231], off
	s_barrier
	s_waitcnt lgkmcnt(0)
	s_setprio 0
	s_waitcnt lgkmcnt(0)
	v_mfma_f32_16x16x32_bf16 v[60:63], v[164:167], v[182:185], v[60:63]
	v_mfma_f32_16x16x32_bf16 v[56:59], v[174:177], v[182:185], v[56:59]
	v_mfma_f32_16x16x32_bf16 v[52:55], v[164:167], v[190:193], v[52:55]
	v_mfma_f32_16x16x32_bf16 v[48:51], v[174:177], v[190:193], v[48:51]
	v_mfma_f32_16x16x32_bf16 v[44:47], v[164:167], v[198:201], v[44:47]
	v_mfma_f32_16x16x32_bf16 v[40:43], v[174:177], v[198:201], v[40:43]
	v_mfma_f32_16x16x32_bf16 v[36:39], v[164:167], v[206:209], v[36:39]
	v_mfma_f32_16x16x32_bf16 v[32:35], v[174:177], v[206:209], v[32:35]
	v_mfma_f32_16x16x32_bf16 v[60:63], v[170:173], v[186:189], v[60:63]
	v_mfma_f32_16x16x32_bf16 v[56:59], v[178:181], v[186:189], v[56:59]
	v_mfma_f32_16x16x32_bf16 v[52:55], v[170:173], v[194:197], v[52:55]
	v_mfma_f32_16x16x32_bf16 v[48:51], v[178:181], v[194:197], v[48:51]
	v_mfma_f32_16x16x32_bf16 v[44:47], v[170:173], v[202:205], v[44:47]
	v_mfma_f32_16x16x32_bf16 v[40:43], v[178:181], v[202:205], v[40:43]
	v_mfma_f32_16x16x32_bf16 v[36:39], v[170:173], v[210:213], v[36:39]
	v_mfma_f32_16x16x32_bf16 v[32:35], v[178:181], v[210:213], v[32:35]
	s_setprio 1
	s_barrier
; #define STAGE(P, BASE, LD, br, kt) do { const char* _g = (const char*)((BASE) + (size_t)(br) * (LD) + (size_t)(kt) * 64); \
;     for (int _i = 0; _i < 2; ++_i) { int _b = tidx * 16 + _i * 8192; int _r, _c; stage_rc(_b, _r, _c); \
;       __builtin_amdgcn_global_load_lds((const unsigned*)(_g + (unsigned)((_r * (LD) + _c) * 2)), (unsigned*)((char*)(P) + _b), 16, 0, 0); } } while (0)
; #define LDA(dst, b, h) for (int m = 0; m < 4; ++m) for (int k = 0; k < 2; ++k) \
;     dst[m][k] = *reinterpret_cast<const bf16x8*>((char*)SA(b, h) + lds_byte(wr * 64 + m * 16 + fr, k * 32 + fq * 8))
; #define LDB(dst, b, h) for (int n = 0; n < 2; ++n) for (int k = 0; k < 2; ++k) \
;     dst[n][k] = *reinterpret_cast<const bf16x8*>((char*)SB(b, h) + lds_byte(wc * 32 + n * 16 + fr, k * 32 + fq * 8))
; #define MMA(ai, bj, At_, Bt_) do { __builtin_amdgcn_s_setprio(1); \
;     for (int k = 0; k < 2; ++k) for (int m = 0; m < 4; ++m) for (int n = 0; n < 2; ++n) \
;       acc[ai][bj][m][n] = __builtin_amdgcn_mfma_f32_16x16x32_bf16(At_[m][k], Bt_[n][k], acc[ai][bj][m][n], 0, 0, 0); \
;     __builtin_amdgcn_s_setprio(0); } while (0)
; #define WAIT_V(n) asm volatile("s_waitcnt vmcnt(" #n ")" ::: "memory")
; #define WAIT_L(n) asm volatile("s_waitcnt lgkmcnt(" #n ")" ::: "memory")
; #define BAR __builtin_amdgcn_s_barrier()
; #define SCHED __builtin_amdgcn_sched_barrier(0)
; template <int EPI, int lda, int ldb, int N, int K>
; __device__ __forceinline__ void gemm_phase(const u16* __restrict__ A, const u16* __restrict__ Bt, const GemmEpi ep, int wv) {
;     ...
;       STAGE(SB(0, 1), Bt, ldb, bcol + HALF, t + 2);
;       WAIT_V(6); BAR; MMA(1, 1, At, B1); BAR;
;       LDB(B0, 1, 0); SCHED; LDA(At, 1, 0); STAGE(SA(0, 1), Ab, lda, brow + HALF, t + 2);
;       WAIT_L(8); BAR; WAIT_L(0); MMA(0, 0, At, B0); BAR; SCHED;
;       LDB(B1, 1, 1); STAGE(SB(1, 0), Bt, ldb, bcol, t + 3);
;       BAR; WAIT_L(0); MMA(0, 1, At, B1); BAR;
	v_add_u32_e32 v164, s66, v153
	v_add_u32_e32 v165, 0x2000, v164
	v_readfirstlane_b32 s55, v164
	v_lshl_add_u64 v[166:167], v[238:239], 0, s[26:27]
	s_mov_b32 m0, s55
	v_readfirstlane_b32 s55, v165
	global_load_lds_dwordx4 v[166:167], off
	v_lshl_add_u64 v[166:167], v[240:241], 0, s[26:27]
	s_mov_b32 m0, s55
	s_nop 0
	global_load_lds_dwordx4 v[166:167], off
	s_waitcnt vmcnt(6)
	s_barrier
	s_setprio 0
	v_mfma_f32_16x16x32_bf16 v[28:31], v[214:217], v[182:185], v[28:31]
	v_mfma_f32_16x16x32_bf16 v[24:27], v[222:225], v[182:185], v[24:27]
	v_mfma_f32_16x16x32_bf16 v[20:23], v[214:217], v[190:193], v[20:23]
	v_mfma_f32_16x16x32_bf16 v[16:19], v[222:225], v[190:193], v[16:19]
	v_mfma_f32_16x16x32_bf16 v[12:15], v[214:217], v[198:201], v[12:15]
	v_mfma_f32_16x16x32_bf16 v[8:11], v[222:225], v[198:201], v[8:11]
	v_mfma_f32_16x16x32_bf16 v[4:7], v[214:217], v[206:209], v[4:7]
	v_mfma_f32_16x16x32_bf16 v[0:3], v[222:225], v[206:209], v[0:3]
	v_mfma_f32_16x16x32_bf16 v[28:31], v[218:221], v[186:189], v[28:31]
	v_mfma_f32_16x16x32_bf16 v[24:27], v[226:229], v[186:189], v[24:27]
	v_mfma_f32_16x16x32_bf16 v[20:23], v[218:221], v[194:197], v[20:23]
	v_mfma_f32_16x16x32_bf16 v[16:19], v[226:229], v[194:197], v[16:19]
	v_mfma_f32_16x16x32_bf16 v[12:15], v[218:221], v[202:205], v[12:15]
	v_mfma_f32_16x16x32_bf16 v[8:11], v[226:229], v[202:205], v[8:11]
	v_mfma_f32_16x16x32_bf16 v[4:7], v[218:221], v[210:213], v[4:7]
	v_mfma_f32_16x16x32_bf16 v[0:3], v[226:229], v[210:213], v[0:3]
	s_setprio 1
	s_barrier
	ds_read_b128 v[170:173], v154
	ds_read_b128 v[174:177], v154 offset:1024
	ds_read_b128 v[178:181], v154 offset:2048
	ds_read_b128 v[182:185], v154 offset:3072
	v_add_u32_e32 v166, 0x4000, v143
	v_add_u32_e32 v167, 0x6000, v143
	v_readfirstlane_b32 s55, v166
	v_lshl_add_u64 v[218:219], v[234:235], 0, s[42:43]
	s_mov_b32 m0, s55
	v_readfirstlane_b32 s55, v167
	ds_read_b128 v[186:189], v151 offset:32768
	ds_read_b128 v[190:193], v151 offset:33792
	ds_read_b128 v[194:197], v150 offset:32768
	ds_read_b128 v[198:201], v150 offset:33792
	ds_read_b128 v[202:205], v149 offset:32768
	ds_read_b128 v[206:209], v149 offset:33792
	ds_read_b128 v[210:213], v148 offset:32768
	ds_read_b128 v[214:217], v148 offset:33792
	global_load_lds_dwordx4 v[218:219], off
	v_lshl_add_u64 v[218:219], v[236:237], 0, s[42:43]
	s_mov_b32 m0, s55
	s_nop 0
	global_load_lds_dwordx4 v[218:219], off
	s_waitcnt lgkmcnt(8)
	s_barrier
	s_waitcnt lgkmcnt(0)
	s_setprio 0
	s_waitcnt lgkmcnt(0)
	v_mfma_f32_16x16x32_bf16 v[124:127], v[170:173], v[186:189], v[124:127]
	v_mfma_f32_16x16x32_bf16 v[120:123], v[178:181], v[186:189], v[120:123]
	v_mfma_f32_16x16x32_bf16 v[116:119], v[170:173], v[194:197], v[116:119]
	v_mfma_f32_16x16x32_bf16 v[112:115], v[178:181], v[194:197], v[112:115]
	v_mfma_f32_16x16x32_bf16 v[108:111], v[170:173], v[202:205], v[108:111]
	v_mfma_f32_16x16x32_bf16 v[104:107], v[178:181], v[202:205], v[104:107]
	v_mfma_f32_16x16x32_bf16 v[100:103], v[170:173], v[210:213], v[100:103]
	v_mfma_f32_16x16x32_bf16 v[96:99], v[178:181], v[210:213], v[96:99]
	v_mfma_f32_16x16x32_bf16 v[124:127], v[174:177], v[190:193], v[124:127]
	v_mfma_f32_16x16x32_bf16 v[120:123], v[182:185], v[190:193], v[120:123]
	v_mfma_f32_16x16x32_bf16 v[116:119], v[174:177], v[198:201], v[116:119]
	v_mfma_f32_16x16x32_bf16 v[112:115], v[182:185], v[198:201], v[112:115]
	v_mfma_f32_16x16x32_bf16 v[108:111], v[174:177], v[206:209], v[108:111]
	v_mfma_f32_16x16x32_bf16 v[104:107], v[182:185], v[206:209], v[104:107]
	v_mfma_f32_16x16x32_bf16 v[100:103], v[174:177], v[214:217], v[100:103]
	v_mfma_f32_16x16x32_bf16 v[96:99], v[182:185], v[214:217], v[96:99]
	s_setprio 1
	s_barrier
	v_readfirstlane_b32 s55, v155
	v_add_u32_e32 v244, 0x2000, v155
	v_lshl_add_u64 v[242:243], v[238:239], 0, s[44:45]
	s_mov_b32 m0, s55
	v_readfirstlane_b32 s55, v244
	ds_read_b128 v[218:221], v152
	ds_read_b128 v[222:225], v152 offset:1024
	ds_read_b128 v[226:229], v152 offset:2048
	ds_read_b128 v[230:233], v152 offset:3072
	global_load_lds_dwordx4 v[242:243], off
	v_lshl_add_u64 v[242:243], v[240:241], 0, s[44:45]
	s_mov_b32 m0, s55
	s_nop 0
	global_load_lds_dwordx4 v[242:243], off
	s_barrier
	s_waitcnt lgkmcnt(0)
	s_setprio 0
	s_waitcnt lgkmcnt(0)
	v_mfma_f32_16x16x32_bf16 v[92:95], v[218:221], v[186:189], v[92:95]
	v_mfma_f32_16x16x32_bf16 v[88:91], v[226:229], v[186:189], v[88:91]
	v_mfma_f32_16x16x32_bf16 v[84:87], v[218:221], v[194:197], v[84:87]
	v_mfma_f32_16x16x32_bf16 v[80:83], v[226:229], v[194:197], v[80:83]
	v_mfma_f32_16x16x32_bf16 v[76:79], v[218:221], v[202:205], v[76:79]
	v_mfma_f32_16x16x32_bf16 v[72:75], v[226:229], v[202:205], v[72:75]
	v_mfma_f32_16x16x32_bf16 v[68:71], v[218:221], v[210:213], v[68:71]
	v_mfma_f32_16x16x32_bf16 v[64:67], v[226:229], v[210:213], v[64:67]
	v_mfma_f32_16x16x32_bf16 v[92:95], v[222:225], v[190:193], v[92:95]
	v_mfma_f32_16x16x32_bf16 v[88:91], v[230:233], v[190:193], v[88:91]
	v_mfma_f32_16x16x32_bf16 v[84:87], v[222:225], v[198:201], v[84:87]
	v_mfma_f32_16x16x32_bf16 v[80:83], v[230:233], v[198:201], v[80:83]
	v_mfma_f32_16x16x32_bf16 v[76:79], v[222:225], v[206:209], v[76:79]
	v_mfma_f32_16x16x32_bf16 v[72:75], v[230:233], v[206:209], v[72:75]
	v_mfma_f32_16x16x32_bf16 v[68:71], v[222:225], v[214:217], v[68:71]
	v_mfma_f32_16x16x32_bf16 v[64:67], v[230:233], v[214:217], v[64:67]
	s_setprio 1
	v_readfirstlane_b32 s55, v156
	v_lshl_add_u64 v[234:235], v[234:235], 0, s[46:47]
	s_mov_b32 m0, s55
	v_readfirstlane_b32 s55, v157
	s_barrier
; #define STAGE(P, BASE, LD, br, kt) do { const char* _g = (const char*)((BASE) + (size_t)(br) * (LD) + (size_t)(kt) * 64); \
;     for (int _i = 0; _i < 2; ++_i) { int _b = tidx * 16 + _i * 8192; int _r, _c; stage_rc(_b, _r, _c); \
;       __builtin_amdgcn_global_load_lds((const unsigned*)(_g + (unsigned)((_r * (LD) + _c) * 2)), (unsigned*)((char*)(P) + _b), 16, 0, 0); } } while (0)
; #define LDA(dst, b, h) for (int m = 0; m < 4; ++m) for (int k = 0; k < 2; ++k) \
;     dst[m][k] = *reinterpret_cast<const bf16x8*>((char*)SA(b, h) + lds_byte(wr * 64 + m * 16 + fr, k * 32 + fq * 8))
; #define LDB(dst, b, h) for (int n = 0; n < 2; ++n) for (int k = 0; k < 2; ++k) \
;     dst[n][k] = *reinterpret_cast<const bf16x8*>((char*)SB(b, h) + lds_byte(wc * 32 + n * 16 + fr, k * 32 + fq * 8))
; #define MMA(ai, bj, At_, Bt_) do { __builtin_amdgcn_s_setprio(1); \
;     for (int k = 0; k < 2; ++k) for (int m = 0; m < 4; ++m) for (int n = 0; n < 2; ++n) \
;       acc[ai][bj][m][n] = __builtin_amdgcn_mfma_f32_16x16x32_bf16(At_[m][k], Bt_[n][k], acc[ai][bj][m][n], 0, 0, 0); \
;     __builtin_amdgcn_s_setprio(0); } while (0)
; #define WAIT_V(n) asm volatile("s_waitcnt vmcnt(" #n ")" ::: "memory")
; #define WAIT_L(n) asm volatile("s_waitcnt lgkmcnt(" #n ")" ::: "memory")
; #define BAR __builtin_amdgcn_s_barrier()
; #define SCHED __builtin_amdgcn_sched_barrier(0)
; template <int EPI, int lda, int ldb, int N, int K>
; __device__ __forceinline__ void gemm_phase(const u16* __restrict__ A, const u16* __restrict__ Bt, const GemmEpi ep, int wv) {
;     ...
;       LDA(At, 1, 1); STAGE(SA(1, 0), Ab, lda, brow, t + 3);
;       BAR; WAIT_L(0); MMA(1, 0, At, B0); BAR; SCHED;
;       STAGE(SB(1, 1), Bt, ldb, bcol + HALF, t + 3);
;       WAIT_V(6); BAR; MMA(1, 1, At, B1); BAR;
;     }
;     { LDB(B0, 0, 0); LDA(At, 0, 0); STAGE(SA(1, 1), Ab, lda, brow + HALF, nt - 1);
;       BAR; WAIT_L(0); MMA(0, 0, At, B0); BAR;
;       LDB(B1, 0, 1); BAR; WAIT_L(0); MMA(0, 1, At, B1); BAR;
	ds_read_b128 v[186:189], v151 offset:49152
	ds_read_b128 v[190:193], v151 offset:50176
	ds_read_b128 v[194:197], v150 offset:49152
	ds_read_b128 v[198:201], v150 offset:50176
	ds_read_b128 v[202:205], v149 offset:49152
	ds_read_b128 v[206:209], v149 offset:50176
	ds_read_b128 v[210:213], v148 offset:49152
	ds_read_b128 v[214:217], v148 offset:50176
	global_load_lds_dwordx4 v[234:235], off
	v_lshl_add_u64 v[234:235], v[236:237], 0, s[46:47]
	s_mov_b32 m0, s55
	s_nop 0
	global_load_lds_dwordx4 v[234:235], off
	s_barrier
	s_waitcnt lgkmcnt(0)
	s_setprio 0
	s_waitcnt lgkmcnt(0)
	v_mfma_f32_16x16x32_bf16 v[60:63], v[170:173], v[186:189], v[60:63]
	v_mfma_f32_16x16x32_bf16 v[56:59], v[178:181], v[186:189], v[56:59]
	v_mfma_f32_16x16x32_bf16 v[52:55], v[170:173], v[194:197], v[52:55]
	v_mfma_f32_16x16x32_bf16 v[48:51], v[178:181], v[194:197], v[48:51]
	v_mfma_f32_16x16x32_bf16 v[44:47], v[170:173], v[202:205], v[44:47]
	v_mfma_f32_16x16x32_bf16 v[40:43], v[178:181], v[202:205], v[40:43]
	v_mfma_f32_16x16x32_bf16 v[36:39], v[170:173], v[210:213], v[36:39]
	v_mfma_f32_16x16x32_bf16 v[32:35], v[178:181], v[210:213], v[32:35]
	v_mfma_f32_16x16x32_bf16 v[60:63], v[174:177], v[190:193], v[60:63]
	v_mfma_f32_16x16x32_bf16 v[56:59], v[182:185], v[190:193], v[56:59]
	v_mfma_f32_16x16x32_bf16 v[52:55], v[174:177], v[198:201], v[52:55]
	v_mfma_f32_16x16x32_bf16 v[48:51], v[182:185], v[198:201], v[48:51]
	v_mfma_f32_16x16x32_bf16 v[44:47], v[174:177], v[206:209], v[44:47]
	v_mfma_f32_16x16x32_bf16 v[40:43], v[182:185], v[206:209], v[40:43]
	v_mfma_f32_16x16x32_bf16 v[36:39], v[174:177], v[214:217], v[36:39]
	v_mfma_f32_16x16x32_bf16 v[32:35], v[182:185], v[214:217], v[32:35]
	s_setprio 1
	s_barrier
	v_readfirstlane_b32 s55, v158
	v_add_u32_e32 v172, 0x2000, v158
	v_lshl_add_u64 v[170:171], v[238:239], 0, s[48:49]
	s_mov_b32 m0, s55
	v_readfirstlane_b32 s55, v172
	global_load_lds_dwordx4 v[170:171], off
	v_lshl_add_u64 v[170:171], v[240:241], 0, s[48:49]
	s_mov_b32 m0, s55
	s_nop 0
	global_load_lds_dwordx4 v[170:171], off
	s_waitcnt vmcnt(6)
	s_barrier
	s_setprio 0
	v_mfma_f32_16x16x32_bf16 v[28:31], v[218:221], v[186:189], v[28:31]
	v_mfma_f32_16x16x32_bf16 v[24:27], v[226:229], v[186:189], v[24:27]
	v_mfma_f32_16x16x32_bf16 v[20:23], v[218:221], v[194:197], v[20:23]
	v_mfma_f32_16x16x32_bf16 v[16:19], v[226:229], v[194:197], v[16:19]
	v_mfma_f32_16x16x32_bf16 v[12:15], v[218:221], v[202:205], v[12:15]
	v_mfma_f32_16x16x32_bf16 v[8:11], v[226:229], v[202:205], v[8:11]
	v_mfma_f32_16x16x32_bf16 v[4:7], v[218:221], v[210:213], v[4:7]
	v_mfma_f32_16x16x32_bf16 v[0:3], v[226:229], v[210:213], v[0:3]
	v_mfma_f32_16x16x32_bf16 v[28:31], v[222:225], v[190:193], v[28:31]
	v_mfma_f32_16x16x32_bf16 v[24:27], v[230:233], v[190:193], v[24:27]
	v_mfma_f32_16x16x32_bf16 v[20:23], v[222:225], v[198:201], v[20:23]
	v_mfma_f32_16x16x32_bf16 v[16:19], v[230:233], v[198:201], v[16:19]
	v_mfma_f32_16x16x32_bf16 v[12:15], v[222:225], v[206:209], v[12:15]
	v_mfma_f32_16x16x32_bf16 v[8:11], v[230:233], v[206:209], v[8:11]
	v_mfma_f32_16x16x32_bf16 v[4:7], v[222:225], v[214:217], v[4:7]
	v_mfma_f32_16x16x32_bf16 v[0:3], v[230:233], v[214:217], v[0:3]
	s_setprio 1
	s_add_i32 s54, s54, 2
	s_add_u32 s52, s52, 0x100
	s_addc_u32 s53, s53, 0
	s_cmp_gt_u32 s54, 27
	s_barrier
	s_cbranch_scc0 .LBB0_654
	s_lshl_b64 s[52:53], s[16:17], 12
	s_add_u32 s52, s14, s52
	s_addc_u32 s53, s15, s53
	s_add_u32 s52, s52, 0x80000
	s_addc_u32 s53, s53, 0
	v_lshl_add_u64 v[156:157], s[52:53], 0, v[128:129]
	v_readfirstlane_b32 s54, v168
	v_lshl_add_u64 v[156:157], v[156:157], 0, s[50:51]
	s_mov_b32 m0, s54
	ds_read_b128 v[134:137], v160
	ds_read_b128 v[138:141], v160 offset:1024
	ds_read_b128 v[170:173], v160 offset:2048
	ds_read_b128 v[174:177], v160 offset:3072
	ds_read_b128 v[178:181], v151
	ds_read_b128 v[182:185], v151 offset:1024
	ds_read_b128 v[186:189], v150
	ds_read_b128 v[190:193], v150 offset:1024
	ds_read_b128 v[194:197], v149
	ds_read_b128 v[198:201], v149 offset:1024
	ds_read_b128 v[202:205], v148
	ds_read_b128 v[206:209], v148 offset:1024
	global_load_lds_dwordx4 v[156:157], off
	v_lshl_add_u64 v[156:157], s[52:53], 0, v[132:133]
	v_readfirstlane_b32 s52, v169
	v_lshl_add_u64 v[156:157], v[156:157], 0, s[50:51]
	s_mov_b32 m0, s52
	s_nop 0
	global_load_lds_dwordx4 v[156:157], off
	s_barrier
	s_waitcnt lgkmcnt(0)
	s_setprio 0
	s_waitcnt lgkmcnt(0)
	v_mfma_f32_16x16x32_bf16 v[124:127], v[134:137], v[178:181], v[124:127]
	v_mfma_f32_16x16x32_bf16 v[120:123], v[170:173], v[178:181], v[120:123]
	v_mfma_f32_16x16x32_bf16 v[116:119], v[134:137], v[186:189], v[116:119]
	v_mfma_f32_16x16x32_bf16 v[112:115], v[170:173], v[186:189], v[112:115]
	v_mfma_f32_16x16x32_bf16 v[108:111], v[134:137], v[194:197], v[108:111]
	v_mfma_f32_16x16x32_bf16 v[104:107], v[170:173], v[194:197], v[104:107]
	v_mfma_f32_16x16x32_bf16 v[100:103], v[134:137], v[202:205], v[100:103]
	v_mfma_f32_16x16x32_bf16 v[96:99], v[170:173], v[202:205], v[96:99]
	v_mfma_f32_16x16x32_bf16 v[124:127], v[138:141], v[182:185], v[124:127]
	v_mfma_f32_16x16x32_bf16 v[120:123], v[174:177], v[182:185], v[120:123]
	v_mfma_f32_16x16x32_bf16 v[116:119], v[138:141], v[190:193], v[116:119]
	v_mfma_f32_16x16x32_bf16 v[112:115], v[174:177], v[190:193], v[112:115]
	v_mfma_f32_16x16x32_bf16 v[108:111], v[138:141], v[198:201], v[108:111]
	v_mfma_f32_16x16x32_bf16 v[104:107], v[174:177], v[198:201], v[104:107]
	v_mfma_f32_16x16x32_bf16 v[100:103], v[138:141], v[206:209], v[100:103]
	v_mfma_f32_16x16x32_bf16 v[96:99], v[174:177], v[206:209], v[96:99]
	s_setprio 1
	s_barrier
; #define LDA(dst, b, h) for (int m = 0; m < 4; ++m) for (int k = 0; k < 2; ++k) \
;     dst[m][k] = *reinterpret_cast<const bf16x8*>((char*)SA(b, h) + lds_byte(wr * 64 + m * 16 + fr, k * 32 + fq * 8))
; #define LDB(dst, b, h) for (int n = 0; n < 2; ++n) for (int k = 0; k < 2; ++k) \
;     dst[n][k] = *reinterpret_cast<const bf16x8*>((char*)SB(b, h) + lds_byte(wc * 32 + n * 16 + fr, k * 32 + fq * 8))
; #define MMA(ai, bj, At_, Bt_) do { __builtin_amdgcn_s_setprio(1); \
;     for (int k = 0; k < 2; ++k) for (int m = 0; m < 4; ++m) for (int n = 0; n < 2; ++n) \
;       acc[ai][bj][m][n] = __builtin_amdgcn_mfma_f32_16x16x32_bf16(At_[m][k], Bt_[n][k], acc[ai][bj][m][n], 0, 0, 0); \
;     __builtin_amdgcn_s_setprio(0); } while (0)
; #define WAIT_V(n) asm volatile("s_waitcnt vmcnt(" #n ")" ::: "memory")
; #define WAIT_L(n) asm volatile("s_waitcnt lgkmcnt(" #n ")" ::: "memory")
; #define BAR __builtin_amdgcn_s_barrier()
; template <int EPI, int lda, int ldb, int N, int K>
; __device__ __forceinline__ void gemm_phase(const u16* __restrict__ A, const u16* __restrict__ Bt, const GemmEpi ep, int wv) {
;     ...
;       LDB(B1, 0, 1); BAR; WAIT_L(0); MMA(0, 1, At, B1); BAR;
;       LDA(At, 0, 1); WAIT_V(4); BAR; WAIT_L(0); MMA(1, 0, At, B0); MMA(1, 1, At, B1); BAR; }
;     { LDB(B0, 1, 0); LDA(At, 1, 0); WAIT_V(2); BAR; WAIT_L(0); MMA(0, 0, At, B0); BAR;
	ds_read_b128 v[210:213], v159
	ds_read_b128 v[214:217], v159 offset:1024
	ds_read_b128 v[218:221], v159 offset:2048
	ds_read_b128 v[156:159], v159 offset:3072
	s_barrier
	s_waitcnt lgkmcnt(0)
	s_setprio 0
	s_waitcnt lgkmcnt(0)
	v_mfma_f32_16x16x32_bf16 v[92:95], v[210:213], v[178:181], v[92:95]
	v_mfma_f32_16x16x32_bf16 v[88:91], v[218:221], v[178:181], v[88:91]
	v_mfma_f32_16x16x32_bf16 v[76:79], v[210:213], v[194:197], v[76:79]
	v_mfma_f32_16x16x32_bf16 v[72:75], v[218:221], v[194:197], v[72:75]
	v_mfma_f32_16x16x32_bf16 v[84:87], v[210:213], v[186:189], v[84:87]
	v_mfma_f32_16x16x32_bf16 v[80:83], v[218:221], v[186:189], v[80:83]
	v_mfma_f32_16x16x32_bf16 v[68:71], v[210:213], v[202:205], v[68:71]
	v_mfma_f32_16x16x32_bf16 v[64:67], v[218:221], v[202:205], v[64:67]
	v_mfma_f32_16x16x32_bf16 v[92:95], v[214:217], v[182:185], v[92:95]
	v_mfma_f32_16x16x32_bf16 v[88:91], v[156:159], v[182:185], v[88:91]
	v_mfma_f32_16x16x32_bf16 v[76:79], v[214:217], v[198:201], v[76:79]
	v_mfma_f32_16x16x32_bf16 v[72:75], v[156:159], v[198:201], v[72:75]
	v_mfma_f32_16x16x32_bf16 v[178:181], v[214:217], v[190:193], v[84:87]
	v_mfma_f32_16x16x32_bf16 v[182:185], v[156:159], v[190:193], v[80:83]
	v_mfma_f32_16x16x32_bf16 v[186:189], v[214:217], v[206:209], v[68:71]
	v_mfma_f32_16x16x32_bf16 v[190:193], v[156:159], v[206:209], v[64:67]
	s_setprio 1
	s_barrier
	s_nop 0
	ds_read_b128 v[64:67], v151 offset:16384
	ds_read_b128 v[68:71], v151 offset:17408
	ds_read_b128 v[80:83], v150 offset:16384
	ds_read_b128 v[84:87], v150 offset:17408
	ds_read_b128 v[194:197], v149 offset:16384
	ds_read_b128 v[198:201], v149 offset:17408
	ds_read_b128 v[202:205], v148 offset:16384
	ds_read_b128 v[206:209], v148 offset:17408
	s_waitcnt vmcnt(4)
	s_barrier
	s_waitcnt lgkmcnt(0)
	s_setprio 0
	s_waitcnt lgkmcnt(0)
	v_mfma_f32_16x16x32_bf16 v[60:63], v[134:137], v[64:67], v[60:63]
	v_mfma_f32_16x16x32_bf16 v[56:59], v[170:173], v[64:67], v[56:59]
	v_mfma_f32_16x16x32_bf16 v[52:55], v[134:137], v[80:83], v[52:55]
	v_mfma_f32_16x16x32_bf16 v[48:51], v[170:173], v[80:83], v[48:51]
	v_mfma_f32_16x16x32_bf16 v[44:47], v[134:137], v[194:197], v[44:47]
	v_mfma_f32_16x16x32_bf16 v[40:43], v[170:173], v[194:197], v[40:43]
	v_mfma_f32_16x16x32_bf16 v[36:39], v[134:137], v[202:205], v[36:39]
	v_mfma_f32_16x16x32_bf16 v[32:35], v[170:173], v[202:205], v[32:35]
	v_mfma_f32_16x16x32_bf16 v[60:63], v[138:141], v[68:71], v[60:63]
	v_mfma_f32_16x16x32_bf16 v[56:59], v[174:177], v[68:71], v[56:59]
	v_mfma_f32_16x16x32_bf16 v[52:55], v[138:141], v[84:87], v[52:55]
	v_mfma_f32_16x16x32_bf16 v[48:51], v[174:177], v[84:87], v[48:51]
	v_mfma_f32_16x16x32_bf16 v[44:47], v[138:141], v[198:201], v[44:47]
	v_mfma_f32_16x16x32_bf16 v[40:43], v[174:177], v[198:201], v[40:43]
	v_mfma_f32_16x16x32_bf16 v[36:39], v[138:141], v[206:209], v[36:39]
	v_mfma_f32_16x16x32_bf16 v[32:35], v[174:177], v[206:209], v[32:35]
	s_setprio 1
	s_setprio 0
	v_mfma_f32_16x16x32_bf16 v[28:31], v[210:213], v[64:67], v[28:31]
	v_mfma_f32_16x16x32_bf16 v[20:23], v[210:213], v[80:83], v[20:23]
	v_mfma_f32_16x16x32_bf16 v[12:15], v[210:213], v[194:197], v[12:15]
	v_mfma_f32_16x16x32_bf16 v[4:7], v[210:213], v[202:205], v[4:7]
	v_mfma_f32_16x16x32_bf16 v[24:27], v[218:221], v[64:67], v[24:27]
	v_mfma_f32_16x16x32_bf16 v[16:19], v[218:221], v[80:83], v[16:19]
	v_mfma_f32_16x16x32_bf16 v[8:11], v[218:221], v[194:197], v[8:11]
	v_mfma_f32_16x16x32_bf16 v[0:3], v[218:221], v[202:205], v[0:3]
	v_mfma_f32_16x16x32_bf16 v[28:31], v[214:217], v[68:71], v[28:31]
	v_mfma_f32_16x16x32_bf16 v[20:23], v[214:217], v[84:87], v[20:23]
	v_mfma_f32_16x16x32_bf16 v[12:15], v[214:217], v[198:201], v[12:15]
	v_mfma_f32_16x16x32_bf16 v[4:7], v[214:217], v[206:209], v[4:7]
	v_mfma_f32_16x16x32_bf16 v[134:137], v[156:159], v[68:71], v[24:27]
	v_mfma_f32_16x16x32_bf16 v[138:141], v[156:159], v[84:87], v[16:19]
	v_mfma_f32_16x16x32_bf16 v[168:171], v[156:159], v[198:201], v[8:11]
	v_mfma_f32_16x16x32_bf16 v[156:159], v[156:159], v[206:209], v[0:3]
	s_setprio 1
	s_barrier
	s_nop 0
	ds_read_b128 v[0:3], v154
	ds_read_b128 v[8:11], v154 offset:1024
	ds_read_b128 v[16:19], v154 offset:2048
	ds_read_b128 v[172:175], v154 offset:3072
	ds_read_b128 v[24:27], v151 offset:32768
	ds_read_b128 v[194:197], v151 offset:33792
	ds_read_b128 v[198:201], v150 offset:32768
	ds_read_b128 v[202:205], v150 offset:33792
	ds_read_b128 v[206:209], v149 offset:32768
	ds_read_b128 v[210:213], v149 offset:33792
	ds_read_b128 v[214:217], v148 offset:32768
	ds_read_b128 v[218:221], v148 offset:33792
	s_waitcnt vmcnt(2)
	s_barrier
; #define UNR _Pragma("unroll")
; #define LDA(dst, b, h) for (int m = 0; m < 4; ++m) for (int k = 0; k < 2; ++k) \
;     dst[m][k] = *reinterpret_cast<const bf16x8*>((char*)SA(b, h) + lds_byte(wr * 64 + m * 16 + fr, k * 32 + fq * 8))
; #define LDB(dst, b, h) for (int n = 0; n < 2; ++n) for (int k = 0; k < 2; ++k) \
;     dst[n][k] = *reinterpret_cast<const bf16x8*>((char*)SB(b, h) + lds_byte(wc * 32 + n * 16 + fr, k * 32 + fq * 8))
; #define MMA(ai, bj, At_, Bt_) do { __builtin_amdgcn_s_setprio(1); \
;     for (int k = 0; k < 2; ++k) for (int m = 0; m < 4; ++m) for (int n = 0; n < 2; ++n) \
;       acc[ai][bj][m][n] = __builtin_amdgcn_mfma_f32_16x16x32_bf16(At_[m][k], Bt_[n][k], acc[ai][bj][m][n], 0, 0, 0); \
;     __builtin_amdgcn_s_setprio(0); } while (0)
; #define WAIT_V(n) asm volatile("s_waitcnt vmcnt(" #n ")" ::: "memory")
; #define WAIT_L(n) asm volatile("s_waitcnt lgkmcnt(" #n ")" ::: "memory")
; #define BAR __builtin_amdgcn_s_barrier()
; #define STAGE4(BROW, BCOL, PN) do { const u16* Ab_ = A + (EPI == EPI_RG ? ((PN) >> 1) * 256 : 0); \
;     STAGE(SB(0, 0), Bt, ldb, (BCOL), 0); STAGE(SA(0, 0), Ab_, lda, (BROW), 0); \
;     STAGE(SB(0, 1), Bt, ldb, (BCOL) + HALF, 0); STAGE(SA(0, 1), Ab_, lda, (BROW) + HALF, 0); } while (0)
; template <int EPI, int lda, int ldb, int N, int K>
; __device__ __forceinline__ void gemm_phase(const u16* __restrict__ A, const u16* __restrict__ Bt, const GemmEpi ep, int wv) {
;     ...
;     { LDB(B0, 1, 0); LDA(At, 1, 0); WAIT_V(2); BAR; WAIT_L(0); MMA(0, 0, At, B0); BAR;
;       LDB(B1, 1, 1); WAIT_V(0); BAR; WAIT_L(0); MMA(0, 1, At, B1); BAR;
;       LDA(At, 1, 1); BAR; WAIT_L(0); MMA(1, 0, At, B0); MMA(1, 1, At, B1); BAR; }
;     if (wr == 0) BAR;
;     int ntile = 0, nbrow = 0, nbcol = 0, npn = 0; bool more = false;
;     if constexpr (PF) { ntile = tile + gridDim.x; more = ntile < nwg; if (more) { TILE_COORDS(ntile, nbrow, nbcol, npn); STAGE4(nbrow, nbcol, npn); } }
;     float nss[8];
;     if constexpr (CONS) { UNR for (int pp = 0; pp < 8; ++pp) nss[pp] = 0.f;
;       if (more && tidx < 256) { UNR for (int pp = 0; pp < 8; ++pp) nss[pp] = ep.ss_in[(size_t)pp * T + nbrow + tidx]; } }
	s_waitcnt lgkmcnt(0)
	s_setprio 0
	s_waitcnt lgkmcnt(0)
	v_mfma_f32_16x16x32_bf16 v[64:67], v[0:3], v[24:27], v[124:127]
	v_mfma_f32_16x16x32_bf16 v[68:71], v[16:19], v[24:27], v[120:123]
	v_mfma_f32_16x16x32_bf16 v[80:83], v[0:3], v[198:201], v[116:119]
	v_mfma_f32_16x16x32_bf16 v[84:87], v[16:19], v[198:201], v[112:115]
	v_mfma_f32_16x16x32_bf16 v[108:111], v[0:3], v[206:209], v[108:111]
	v_mfma_f32_16x16x32_bf16 v[104:107], v[16:19], v[206:209], v[104:107]
	v_mfma_f32_16x16x32_bf16 v[120:123], v[0:3], v[214:217], v[100:103]
	v_mfma_f32_16x16x32_bf16 v[124:127], v[16:19], v[214:217], v[96:99]
	v_mfma_f32_16x16x32_bf16 v[116:119], v[8:11], v[194:197], v[64:67]
	v_mfma_f32_16x16x32_bf16 v[112:115], v[172:175], v[194:197], v[68:71]
	v_mfma_f32_16x16x32_bf16 v[100:103], v[8:11], v[202:205], v[80:83]
	v_mfma_f32_16x16x32_bf16 v[96:99], v[172:175], v[202:205], v[84:87]
	v_mfma_f32_16x16x32_bf16 v[84:87], v[8:11], v[210:213], v[108:111]
	v_mfma_f32_16x16x32_bf16 v[80:83], v[172:175], v[210:213], v[104:107]
	v_mfma_f32_16x16x32_bf16 v[68:71], v[8:11], v[218:221], v[120:123]
	v_mfma_f32_16x16x32_bf16 v[64:67], v[172:175], v[218:221], v[124:127]
	s_setprio 1
	s_barrier
	ds_read_b128 v[222:225], v152
	ds_read_b128 v[226:229], v152 offset:1024
	ds_read_b128 v[230:233], v152 offset:2048
	ds_read_b128 v[152:155], v152 offset:3072
	s_waitcnt vmcnt(0)
	s_barrier
	s_waitcnt lgkmcnt(0)
	s_setprio 0
	s_waitcnt lgkmcnt(0)
	v_mfma_f32_16x16x32_bf16 v[92:95], v[222:225], v[24:27], v[92:95]
	v_mfma_f32_16x16x32_bf16 v[24:27], v[230:233], v[24:27], v[88:91]
	v_mfma_f32_16x16x32_bf16 v[88:91], v[222:225], v[198:201], v[178:181]
	v_mfma_f32_16x16x32_bf16 v[104:107], v[230:233], v[198:201], v[182:185]
	v_mfma_f32_16x16x32_bf16 v[76:79], v[222:225], v[206:209], v[76:79]
	v_mfma_f32_16x16x32_bf16 v[72:75], v[230:233], v[206:209], v[72:75]
	v_mfma_f32_16x16x32_bf16 v[176:179], v[222:225], v[214:217], v[186:189]
	v_mfma_f32_16x16x32_bf16 v[180:183], v[230:233], v[214:217], v[190:193]
	v_mfma_f32_16x16x32_bf16 v[124:127], v[226:229], v[194:197], v[92:95]
	v_mfma_f32_16x16x32_bf16 v[120:123], v[152:155], v[194:197], v[24:27]
	v_mfma_f32_16x16x32_bf16 v[108:111], v[226:229], v[202:205], v[88:91]
	v_mfma_f32_16x16x32_bf16 v[104:107], v[152:155], v[202:205], v[104:107]
	v_mfma_f32_16x16x32_bf16 v[92:95], v[226:229], v[210:213], v[76:79]
	v_mfma_f32_16x16x32_bf16 v[88:91], v[152:155], v[210:213], v[72:75]
	v_mfma_f32_16x16x32_bf16 v[76:79], v[226:229], v[218:221], v[176:179]
	v_mfma_f32_16x16x32_bf16 v[72:75], v[152:155], v[218:221], v[180:183]
	s_setprio 1
	s_barrier
	ds_read_b128 v[176:179], v151 offset:49152
	ds_read_b128 v[180:183], v151 offset:50176
	ds_read_b128 v[184:187], v150 offset:49152
	ds_read_b128 v[188:191], v150 offset:50176
	ds_read_b128 v[192:195], v149 offset:49152
	ds_read_b128 v[196:199], v149 offset:50176
	ds_read_b128 v[200:203], v148 offset:49152
	ds_read_b128 v[148:151], v148 offset:50176
	s_barrier
	s_waitcnt lgkmcnt(0)
	s_setprio 0
	s_waitcnt lgkmcnt(0)
	v_mfma_f32_16x16x32_bf16 v[24:27], v[0:3], v[176:179], v[60:63]
	v_mfma_f32_16x16x32_bf16 v[60:63], v[16:19], v[176:179], v[56:59]
	v_mfma_f32_16x16x32_bf16 v[52:55], v[0:3], v[184:187], v[52:55]
	v_mfma_f32_16x16x32_bf16 v[204:207], v[16:19], v[184:187], v[48:51]
	v_mfma_f32_16x16x32_bf16 v[44:47], v[0:3], v[192:195], v[44:47]
	v_mfma_f32_16x16x32_bf16 v[208:211], v[16:19], v[192:195], v[40:43]
	v_mfma_f32_16x16x32_bf16 v[0:3], v[0:3], v[200:203], v[36:39]
	v_mfma_f32_16x16x32_bf16 v[36:39], v[16:19], v[200:203], v[32:35]
	v_mfma_f32_16x16x32_bf16 v[56:59], v[8:11], v[180:183], v[24:27]
	v_mfma_f32_16x16x32_bf16 v[48:51], v[172:175], v[180:183], v[60:63]
	v_mfma_f32_16x16x32_bf16 v[40:43], v[8:11], v[188:191], v[52:55]
	v_mfma_f32_16x16x32_bf16 v[32:35], v[172:175], v[188:191], v[204:207]
	v_mfma_f32_16x16x32_bf16 v[24:27], v[8:11], v[196:199], v[44:47]
	v_mfma_f32_16x16x32_bf16 v[16:19], v[172:175], v[196:199], v[208:211]
	v_mfma_f32_16x16x32_bf16 v[8:11], v[8:11], v[148:151], v[0:3]
	v_mfma_f32_16x16x32_bf16 v[0:3], v[172:175], v[148:151], v[36:39]
	s_setprio 1
	s_setprio 0
	v_mfma_f32_16x16x32_bf16 v[28:31], v[222:225], v[176:179], v[28:31]
	v_mfma_f32_16x16x32_bf16 v[36:39], v[230:233], v[176:179], v[134:137]
	v_mfma_f32_16x16x32_bf16 v[20:23], v[222:225], v[184:187], v[20:23]
	v_mfma_f32_16x16x32_bf16 v[134:137], v[230:233], v[184:187], v[138:141]
	v_mfma_f32_16x16x32_bf16 v[12:15], v[222:225], v[192:195], v[12:15]
	v_mfma_f32_16x16x32_bf16 v[138:141], v[230:233], v[192:195], v[168:171]
	v_mfma_f32_16x16x32_bf16 v[4:7], v[222:225], v[200:203], v[4:7]
	v_mfma_f32_16x16x32_bf16 v[156:159], v[230:233], v[200:203], v[156:159]
	v_mfma_f32_16x16x32_bf16 v[60:63], v[226:229], v[180:183], v[28:31]
	v_mfma_f32_16x16x32_bf16 v[52:55], v[152:155], v[180:183], v[36:39]
	v_mfma_f32_16x16x32_bf16 v[44:47], v[226:229], v[188:191], v[20:23]
	v_mfma_f32_16x16x32_bf16 v[36:39], v[152:155], v[188:191], v[134:137]
	v_mfma_f32_16x16x32_bf16 v[28:31], v[226:229], v[196:199], v[12:15]
	v_mfma_f32_16x16x32_bf16 v[20:23], v[152:155], v[196:199], v[138:141]
	v_mfma_f32_16x16x32_bf16 v[12:15], v[226:229], v[148:151], v[4:7]
	v_mfma_f32_16x16x32_bf16 v[4:7], v[152:155], v[148:151], v[156:159]
	s_setprio 1
	v_cmp_gt_u32_e32 vcc, s70, v130
	s_barrier
	s_and_saveexec_b64 s[52:53], vcc
	s_cbranch_execz .LBB0_657
	s_barrier

; #define STAGE(P, BASE, LD, br, kt) do { const char* _g = (const char*)((BASE) + (size_t)(br) * (LD) + (size_t)(kt) * 64); \
;     for (int _i = 0; _i < 2; ++_i) { int _b = tidx * 16 + _i * 8192; int _r, _c; stage_rc(_b, _r, _c); \
;       __builtin_amdgcn_global_load_lds((const unsigned*)(_g + (unsigned)((_r * (LD) + _c) * 2)), (unsigned*)((char*)(P) + _b), 16, 0, 0); } } while (0)
; #define LDA(dst, b, h) for (int m = 0; m < 4; ++m) for (int k = 0; k < 2; ++k) \
;     dst[m][k] = *reinterpret_cast<const bf16x8*>((char*)SA(b, h) + lds_byte(wr * 64 + m * 16 + fr, k * 32 + fq * 8))
; #define LDB(dst, b, h) for (int n = 0; n < 2; ++n) for (int k = 0; k < 2; ++k) \
;     dst[n][k] = *reinterpret_cast<const bf16x8*>((char*)SB(b, h) + lds_byte(wc * 32 + n * 16 + fr, k * 32 + fq * 8))
; #define MMA(ai, bj, At_, Bt_) do { __builtin_amdgcn_s_setprio(1); \
;     for (int k = 0; k < 2; ++k) for (int m = 0; m < 4; ++m) for (int n = 0; n < 2; ++n) \
;       acc[ai][bj][m][n] = __builtin_amdgcn_mfma_f32_16x16x32_bf16(At_[m][k], Bt_[n][k], acc[ai][bj][m][n], 0, 0, 0); \
;     __builtin_amdgcn_s_setprio(0); } while (0)
; #define WAIT_L(n) asm volatile("s_waitcnt lgkmcnt(" #n ")" ::: "memory")
; #define BAR __builtin_amdgcn_s_barrier()
; #define SCHED __builtin_amdgcn_sched_barrier(0)
; template <int EPI, int lda, int ldb, int N, int K>
; __device__ __forceinline__ void gemm_phase(const u16* __restrict__ A, const u16* __restrict__ Bt, const GemmEpi ep, int wv) {
;     ...
;     for (int t = 0; t < nt - 2; t += 2) {
;       LDB(B0, 0, 0); SCHED; LDA(At, 0, 0); STAGE(SA(1, 1), Ab, lda, brow + HALF, t + 1);
;       WAIT_L(8); BAR; WAIT_L(0); MMA(0, 0, At, B0); BAR; SCHED;
;       LDB(B1, 0, 1); STAGE(SB(0, 0), Bt, ldb, bcol, t + 2);
;       BAR; WAIT_L(0); MMA(0, 1, At, B1); BAR;
;       LDA(At, 0, 1); STAGE(SA(0, 0), Ab, lda, brow, t + 2);
;       BAR; WAIT_L(0); MMA(1, 0, At, B0); BAR; SCHED;
.LBB0_770:
	ds_read_b128 v[172:175], v161
	ds_read_b128 v[176:179], v161 offset:1024
	ds_read_b128 v[180:183], v161 offset:2048
	ds_read_b128 v[184:187], v161 offset:3072
	v_add_u32_e32 v169, 0xc000, v148
	v_lshl_add_u64 v[236:237], v[136:137], 0, s[50:51]
	v_readfirstlane_b32 s53, v169
	v_add_u32_e32 v170, 0xe000, v148
	v_lshl_add_u64 v[162:163], v[236:237], 0, s[18:19]
	s_mov_b32 m0, s53
	v_lshl_add_u64 v[238:239], v[134:135], 0, s[50:51]
	v_readfirstlane_b32 s53, v170
	ds_read_b128 v[164:167], v152
	ds_read_b128 v[188:191], v152 offset:1024
	ds_read_b128 v[192:195], v151
	ds_read_b128 v[196:199], v151 offset:1024
	ds_read_b128 v[200:203], v150
	ds_read_b128 v[204:207], v150 offset:1024
	ds_read_b128 v[208:211], v149
	ds_read_b128 v[212:215], v149 offset:1024
	global_load_lds_dwordx4 v[162:163], off
	v_lshl_add_u64 v[162:163], v[238:239], 0, s[18:19]
	s_mov_b32 m0, s53
	s_nop 0
	global_load_lds_dwordx4 v[162:163], off
	s_waitcnt lgkmcnt(8)
	s_barrier
	s_waitcnt lgkmcnt(0)
	s_setprio 0
	s_waitcnt lgkmcnt(0)
	v_mfma_f32_16x16x32_bf16 v[124:127], v[172:175], v[164:167], v[124:127]
	v_mfma_f32_16x16x32_bf16 v[120:123], v[180:183], v[164:167], v[120:123]
	v_mfma_f32_16x16x32_bf16 v[116:119], v[172:175], v[192:195], v[116:119]
	v_mfma_f32_16x16x32_bf16 v[112:115], v[180:183], v[192:195], v[112:115]
	v_mfma_f32_16x16x32_bf16 v[108:111], v[172:175], v[200:203], v[108:111]
	v_mfma_f32_16x16x32_bf16 v[104:107], v[180:183], v[200:203], v[104:107]
	v_mfma_f32_16x16x32_bf16 v[100:103], v[172:175], v[208:211], v[100:103]
	v_mfma_f32_16x16x32_bf16 v[96:99], v[180:183], v[208:211], v[96:99]
	v_mfma_f32_16x16x32_bf16 v[124:127], v[176:179], v[188:191], v[124:127]
	v_mfma_f32_16x16x32_bf16 v[120:123], v[184:187], v[188:191], v[120:123]
	v_mfma_f32_16x16x32_bf16 v[116:119], v[176:179], v[196:199], v[116:119]
	v_mfma_f32_16x16x32_bf16 v[112:115], v[184:187], v[196:199], v[112:115]
	v_mfma_f32_16x16x32_bf16 v[108:111], v[176:179], v[204:207], v[108:111]
	v_mfma_f32_16x16x32_bf16 v[104:107], v[184:187], v[204:207], v[104:107]
	v_mfma_f32_16x16x32_bf16 v[100:103], v[176:179], v[212:215], v[100:103]
	v_mfma_f32_16x16x32_bf16 v[96:99], v[184:187], v[212:215], v[96:99]
	s_setprio 1
	s_barrier
	v_add_u32_e32 v162, s64, v153
	v_lshl_add_u64 v[240:241], v[140:141], 0, s[50:51]
	v_readfirstlane_b32 s53, v162
	v_add_u32_e32 v163, 0x2000, v162
	v_lshl_add_u64 v[232:233], v[240:241], 0, s[20:21]
	s_mov_b32 m0, s53
	v_lshl_add_u64 v[242:243], v[138:139], 0, s[50:51]
	v_readfirstlane_b32 s53, v163
	ds_read_b128 v[216:219], v160
	ds_read_b128 v[220:223], v160 offset:1024
	ds_read_b128 v[224:227], v160 offset:2048
	ds_read_b128 v[228:231], v160 offset:3072
	global_load_lds_dwordx4 v[232:233], off
	v_lshl_add_u64 v[232:233], v[242:243], 0, s[20:21]
	s_mov_b32 m0, s53
	s_nop 0
	global_load_lds_dwordx4 v[232:233], off
	s_barrier
	s_waitcnt lgkmcnt(0)
	s_setprio 0
	s_waitcnt lgkmcnt(0)
	v_mfma_f32_16x16x32_bf16 v[92:95], v[216:219], v[164:167], v[92:95]
	v_mfma_f32_16x16x32_bf16 v[88:91], v[224:227], v[164:167], v[88:91]
	v_mfma_f32_16x16x32_bf16 v[84:87], v[216:219], v[192:195], v[84:87]
	v_mfma_f32_16x16x32_bf16 v[80:83], v[224:227], v[192:195], v[80:83]
	v_mfma_f32_16x16x32_bf16 v[76:79], v[216:219], v[200:203], v[76:79]
	v_mfma_f32_16x16x32_bf16 v[72:75], v[224:227], v[200:203], v[72:75]
	v_mfma_f32_16x16x32_bf16 v[68:71], v[216:219], v[208:211], v[68:71]
	v_mfma_f32_16x16x32_bf16 v[64:67], v[224:227], v[208:211], v[64:67]
	v_mfma_f32_16x16x32_bf16 v[92:95], v[220:223], v[188:191], v[92:95]
	v_mfma_f32_16x16x32_bf16 v[88:91], v[228:231], v[188:191], v[88:91]
	v_mfma_f32_16x16x32_bf16 v[84:87], v[220:223], v[196:199], v[84:87]
	v_mfma_f32_16x16x32_bf16 v[80:83], v[228:231], v[196:199], v[80:83]
	v_mfma_f32_16x16x32_bf16 v[76:79], v[220:223], v[204:207], v[76:79]
	v_mfma_f32_16x16x32_bf16 v[72:75], v[228:231], v[204:207], v[72:75]
	v_mfma_f32_16x16x32_bf16 v[68:71], v[220:223], v[212:215], v[68:71]
	v_mfma_f32_16x16x32_bf16 v[64:67], v[228:231], v[212:215], v[64:67]
	s_setprio 1
	v_readfirstlane_b32 s53, v148
	v_lshl_add_u64 v[164:165], v[236:237], 0, s[22:23]
	s_mov_b32 m0, s53
	s_barrier
	ds_read_b128 v[188:191], v152 offset:16384
	ds_read_b128 v[192:195], v152 offset:17408
	ds_read_b128 v[196:199], v151 offset:16384
	ds_read_b128 v[200:203], v151 offset:17408
	ds_read_b128 v[204:207], v150 offset:16384
	ds_read_b128 v[208:211], v150 offset:17408
	ds_read_b128 v[212:215], v149 offset:16384
	ds_read_b128 v[232:235], v149 offset:17408
	global_load_lds_dwordx4 v[164:165], off
	v_add_u32_e32 v164, 0x2000, v148
	v_lshl_add_u64 v[166:167], v[238:239], 0, s[22:23]
	v_readfirstlane_b32 s53, v164
	s_mov_b32 m0, s53
	s_nop 0
	global_load_lds_dwordx4 v[166:167], off
	s_barrier
	s_waitcnt lgkmcnt(0)
	s_setprio 0
	s_waitcnt lgkmcnt(0)
	v_mfma_f32_16x16x32_bf16 v[60:63], v[172:175], v[188:191], v[60:63]
	v_mfma_f32_16x16x32_bf16 v[56:59], v[180:183], v[188:191], v[56:59]
	v_mfma_f32_16x16x32_bf16 v[52:55], v[172:175], v[196:199], v[52:55]
	v_mfma_f32_16x16x32_bf16 v[48:51], v[180:183], v[196:199], v[48:51]
	v_mfma_f32_16x16x32_bf16 v[44:47], v[172:175], v[204:207], v[44:47]
	v_mfma_f32_16x16x32_bf16 v[40:43], v[180:183], v[204:207], v[40:43]
	v_mfma_f32_16x16x32_bf16 v[36:39], v[172:175], v[212:215], v[36:39]
	v_mfma_f32_16x16x32_bf16 v[32:35], v[180:183], v[212:215], v[32:35]
	v_mfma_f32_16x16x32_bf16 v[60:63], v[176:179], v[192:195], v[60:63]
	v_mfma_f32_16x16x32_bf16 v[56:59], v[184:187], v[192:195], v[56:59]
	v_mfma_f32_16x16x32_bf16 v[52:55], v[176:179], v[200:203], v[52:55]
	v_mfma_f32_16x16x32_bf16 v[48:51], v[184:187], v[200:203], v[48:51]
	v_mfma_f32_16x16x32_bf16 v[44:47], v[176:179], v[208:211], v[44:47]
	v_mfma_f32_16x16x32_bf16 v[40:43], v[184:187], v[208:211], v[40:43]
	v_mfma_f32_16x16x32_bf16 v[36:39], v[176:179], v[232:235], v[36:39]
	v_mfma_f32_16x16x32_bf16 v[32:35], v[184:187], v[232:235], v[32:35]
	s_setprio 1
	s_barrier
; #define STAGE(P, BASE, LD, br, kt) do { const char* _g = (const char*)((BASE) + (size_t)(br) * (LD) + (size_t)(kt) * 64); \
;     for (int _i = 0; _i < 2; ++_i) { int _b = tidx * 16 + _i * 8192; int _r, _c; stage_rc(_b, _r, _c); \
;       __builtin_amdgcn_global_load_lds((const unsigned*)(_g + (unsigned)((_r * (LD) + _c) * 2)), (unsigned*)((char*)(P) + _b), 16, 0, 0); } } while (0)
; #define LDA(dst, b, h) for (int m = 0; m < 4; ++m) for (int k = 0; k < 2; ++k) \
;     dst[m][k] = *reinterpret_cast<const bf16x8*>((char*)SA(b, h) + lds_byte(wr * 64 + m * 16 + fr, k * 32 + fq * 8))
; #define LDB(dst, b, h) for (int n = 0; n < 2; ++n) for (int k = 0; k < 2; ++k) \
;     dst[n][k] = *reinterpret_cast<const bf16x8*>((char*)SB(b, h) + lds_byte(wc * 32 + n * 16 + fr, k * 32 + fq * 8))
; #define MMA(ai, bj, At_, Bt_) do { __builtin_amdgcn_s_setprio(1); \
;     for (int k = 0; k < 2; ++k) for (int m = 0; m < 4; ++m) for (int n = 0; n < 2; ++n) \
;       acc[ai][bj][m][n] = __builtin_amdgcn_mfma_f32_16x16x32_bf16(At_[m][k], Bt_[n][k], acc[ai][bj][m][n], 0, 0, 0); \
;     __builtin_amdgcn_s_setprio(0); } while (0)
; #define WAIT_V(n) asm volatile("s_waitcnt vmcnt(" #n ")" ::: "memory")
; #define WAIT_L(n) asm volatile("s_waitcnt lgkmcnt(" #n ")" ::: "memory")
; #define BAR __builtin_amdgcn_s_barrier()
; #define SCHED __builtin_amdgcn_sched_barrier(0)
; template <int EPI, int lda, int ldb, int N, int K>
; __device__ __forceinline__ void gemm_phase(const u16* __restrict__ A, const u16* __restrict__ Bt, const GemmEpi ep, int wv) {
;     ...
;       STAGE(SB(0, 1), Bt, ldb, bcol + HALF, t + 2);
;       WAIT_V(6); BAR; MMA(1, 1, At, B1); BAR;
;       LDB(B0, 1, 0); SCHED; LDA(At, 1, 0); STAGE(SA(0, 1), Ab, lda, brow + HALF, t + 2);
;       WAIT_L(8); BAR; WAIT_L(0); MMA(0, 0, At, B0); BAR; SCHED;
;       LDB(B1, 1, 1); STAGE(SB(1, 0), Bt, ldb, bcol, t + 3);
;       BAR; WAIT_L(0); MMA(0, 1, At, B1); BAR;
	v_add_u32_e32 v165, s65, v153
	v_lshl_add_u64 v[166:167], v[240:241], 0, s[24:25]
	v_readfirstlane_b32 s53, v165
	s_mov_b32 m0, s53
	v_lshl_add_u64 v[172:173], v[242:243], 0, s[24:25]
	global_load_lds_dwordx4 v[166:167], off
	v_add_u32_e32 v166, 0x2000, v165
	s_nop 0
	v_readfirstlane_b32 s53, v166
	s_mov_b32 m0, s53
	s_nop 0
	global_load_lds_dwordx4 v[172:173], off
	s_waitcnt vmcnt(6)
	s_barrier
	s_setprio 0
	v_mfma_f32_16x16x32_bf16 v[28:31], v[216:219], v[188:191], v[28:31]
	v_mfma_f32_16x16x32_bf16 v[24:27], v[224:227], v[188:191], v[24:27]
	v_mfma_f32_16x16x32_bf16 v[20:23], v[216:219], v[196:199], v[20:23]
	v_mfma_f32_16x16x32_bf16 v[16:19], v[224:227], v[196:199], v[16:19]
	v_mfma_f32_16x16x32_bf16 v[12:15], v[216:219], v[204:207], v[12:15]
	v_mfma_f32_16x16x32_bf16 v[8:11], v[224:227], v[204:207], v[8:11]
	v_mfma_f32_16x16x32_bf16 v[4:7], v[216:219], v[212:215], v[4:7]
	v_mfma_f32_16x16x32_bf16 v[0:3], v[224:227], v[212:215], v[0:3]
	v_mfma_f32_16x16x32_bf16 v[28:31], v[220:223], v[192:195], v[28:31]
	v_mfma_f32_16x16x32_bf16 v[24:27], v[228:231], v[192:195], v[24:27]
	v_mfma_f32_16x16x32_bf16 v[20:23], v[220:223], v[200:203], v[20:23]
	v_mfma_f32_16x16x32_bf16 v[16:19], v[228:231], v[200:203], v[16:19]
	v_mfma_f32_16x16x32_bf16 v[12:15], v[220:223], v[208:211], v[12:15]
	v_mfma_f32_16x16x32_bf16 v[8:11], v[228:231], v[208:211], v[8:11]
	v_mfma_f32_16x16x32_bf16 v[4:7], v[220:223], v[232:235], v[4:7]
	v_mfma_f32_16x16x32_bf16 v[0:3], v[228:231], v[232:235], v[0:3]
	s_setprio 1
	s_barrier
	ds_read_b128 v[172:175], v156
	ds_read_b128 v[176:179], v156 offset:1024
	ds_read_b128 v[180:183], v156 offset:2048
	ds_read_b128 v[184:187], v156 offset:3072
	v_add_u32_e32 v167, 0x4000, v148
	v_add_u32_e32 v168, 0x6000, v148
	v_readfirstlane_b32 s53, v167
	v_lshl_add_u64 v[220:221], v[236:237], 0, s[26:27]
	s_mov_b32 m0, s53
	v_readfirstlane_b32 s53, v168
	ds_read_b128 v[188:191], v152 offset:32768
	ds_read_b128 v[192:195], v152 offset:33792
	ds_read_b128 v[196:199], v151 offset:32768
	ds_read_b128 v[200:203], v151 offset:33792
	ds_read_b128 v[204:207], v150 offset:32768
	ds_read_b128 v[208:211], v150 offset:33792
	ds_read_b128 v[212:215], v149 offset:32768
	ds_read_b128 v[216:219], v149 offset:33792
	global_load_lds_dwordx4 v[220:221], off
	v_lshl_add_u64 v[220:221], v[238:239], 0, s[26:27]
	s_mov_b32 m0, s53
	s_nop 0
	global_load_lds_dwordx4 v[220:221], off
	s_waitcnt lgkmcnt(8)
	s_barrier
	s_waitcnt lgkmcnt(0)
	s_setprio 0
	s_waitcnt lgkmcnt(0)
	v_mfma_f32_16x16x32_bf16 v[124:127], v[172:175], v[188:191], v[124:127]
	v_mfma_f32_16x16x32_bf16 v[120:123], v[180:183], v[188:191], v[120:123]
	v_mfma_f32_16x16x32_bf16 v[116:119], v[172:175], v[196:199], v[116:119]
	v_mfma_f32_16x16x32_bf16 v[112:115], v[180:183], v[196:199], v[112:115]
	v_mfma_f32_16x16x32_bf16 v[108:111], v[172:175], v[204:207], v[108:111]
	v_mfma_f32_16x16x32_bf16 v[104:107], v[180:183], v[204:207], v[104:107]
	v_mfma_f32_16x16x32_bf16 v[100:103], v[172:175], v[212:215], v[100:103]
	v_mfma_f32_16x16x32_bf16 v[96:99], v[180:183], v[212:215], v[96:99]
	v_mfma_f32_16x16x32_bf16 v[124:127], v[176:179], v[192:195], v[124:127]
	v_mfma_f32_16x16x32_bf16 v[120:123], v[184:187], v[192:195], v[120:123]
	v_mfma_f32_16x16x32_bf16 v[116:119], v[176:179], v[200:203], v[116:119]
	v_mfma_f32_16x16x32_bf16 v[112:115], v[184:187], v[200:203], v[112:115]
	v_mfma_f32_16x16x32_bf16 v[108:111], v[176:179], v[208:211], v[108:111]
	v_mfma_f32_16x16x32_bf16 v[104:107], v[184:187], v[208:211], v[104:107]
	v_mfma_f32_16x16x32_bf16 v[100:103], v[176:179], v[216:219], v[100:103]
	v_mfma_f32_16x16x32_bf16 v[96:99], v[184:187], v[216:219], v[96:99]
	s_setprio 1
	s_barrier
	v_readfirstlane_b32 s53, v155
	v_add_u32_e32 v171, 0x2000, v155
	v_lshl_add_u64 v[244:245], v[240:241], 0, s[40:41]
	s_mov_b32 m0, s53
	v_readfirstlane_b32 s53, v171
	ds_read_b128 v[220:223], v154
	ds_read_b128 v[224:227], v154 offset:1024
	ds_read_b128 v[228:231], v154 offset:2048
	ds_read_b128 v[232:235], v154 offset:3072
	global_load_lds_dwordx4 v[244:245], off
	v_lshl_add_u64 v[244:245], v[242:243], 0, s[40:41]
	s_mov_b32 m0, s53
	s_nop 0
	global_load_lds_dwordx4 v[244:245], off
	s_barrier
	s_waitcnt lgkmcnt(0)
	s_setprio 0
	s_waitcnt lgkmcnt(0)
	v_mfma_f32_16x16x32_bf16 v[92:95], v[220:223], v[188:191], v[92:95]
	v_mfma_f32_16x16x32_bf16 v[88:91], v[228:231], v[188:191], v[88:91]
	v_mfma_f32_16x16x32_bf16 v[84:87], v[220:223], v[196:199], v[84:87]
	v_mfma_f32_16x16x32_bf16 v[80:83], v[228:231], v[196:199], v[80:83]
	v_mfma_f32_16x16x32_bf16 v[76:79], v[220:223], v[204:207], v[76:79]
	v_mfma_f32_16x16x32_bf16 v[72:75], v[228:231], v[204:207], v[72:75]
	v_mfma_f32_16x16x32_bf16 v[68:71], v[220:223], v[212:215], v[68:71]
	v_mfma_f32_16x16x32_bf16 v[64:67], v[228:231], v[212:215], v[64:67]
	v_mfma_f32_16x16x32_bf16 v[92:95], v[224:227], v[192:195], v[92:95]
	v_mfma_f32_16x16x32_bf16 v[88:91], v[232:235], v[192:195], v[88:91]
	v_mfma_f32_16x16x32_bf16 v[84:87], v[224:227], v[200:203], v[84:87]
	v_mfma_f32_16x16x32_bf16 v[80:83], v[232:235], v[200:203], v[80:83]
	v_mfma_f32_16x16x32_bf16 v[76:79], v[224:227], v[208:211], v[76:79]
	v_mfma_f32_16x16x32_bf16 v[72:75], v[232:235], v[208:211], v[72:75]
	v_mfma_f32_16x16x32_bf16 v[68:71], v[224:227], v[216:219], v[68:71]
	v_mfma_f32_16x16x32_bf16 v[64:67], v[232:235], v[216:219], v[64:67]
	s_setprio 1
	v_readfirstlane_b32 s53, v157
	v_lshl_add_u64 v[236:237], v[236:237], 0, s[42:43]
	s_mov_b32 m0, s53
	v_readfirstlane_b32 s53, v158
	s_barrier
; #define STAGE(P, BASE, LD, br, kt) do { const char* _g = (const char*)((BASE) + (size_t)(br) * (LD) + (size_t)(kt) * 64); \
;     for (int _i = 0; _i < 2; ++_i) { int _b = tidx * 16 + _i * 8192; int _r, _c; stage_rc(_b, _r, _c); \
;       __builtin_amdgcn_global_load_lds((const unsigned*)(_g + (unsigned)((_r * (LD) + _c) * 2)), (unsigned*)((char*)(P) + _b), 16, 0, 0); } } while (0)
; #define LDA(dst, b, h) for (int m = 0; m < 4; ++m) for (int k = 0; k < 2; ++k) \
;     dst[m][k] = *reinterpret_cast<const bf16x8*>((char*)SA(b, h) + lds_byte(wr * 64 + m * 16 + fr, k * 32 + fq * 8))
; #define LDB(dst, b, h) for (int n = 0; n < 2; ++n) for (int k = 0; k < 2; ++k) \
;     dst[n][k] = *reinterpret_cast<const bf16x8*>((char*)SB(b, h) + lds_byte(wc * 32 + n * 16 + fr, k * 32 + fq * 8))
; #define MMA(ai, bj, At_, Bt_) do { __builtin_amdgcn_s_setprio(1); \
;     for (int k = 0; k < 2; ++k) for (int m = 0; m < 4; ++m) for (int n = 0; n < 2; ++n) \
;       acc[ai][bj][m][n] = __builtin_amdgcn_mfma_f32_16x16x32_bf16(At_[m][k], Bt_[n][k], acc[ai][bj][m][n], 0, 0, 0); \
;     __builtin_amdgcn_s_setprio(0); } while (0)
; #define WAIT_V(n) asm volatile("s_waitcnt vmcnt(" #n ")" ::: "memory")
; #define WAIT_L(n) asm volatile("s_waitcnt lgkmcnt(" #n ")" ::: "memory")
; #define BAR __builtin_amdgcn_s_barrier()
; #define SCHED __builtin_amdgcn_sched_barrier(0)
; template <int EPI, int lda, int ldb, int N, int K>
; __device__ __forceinline__ void gemm_phase(const u16* __restrict__ A, const u16* __restrict__ Bt, const GemmEpi ep, int wv) {
;     ...
;       LDA(At, 1, 1); STAGE(SA(1, 0), Ab, lda, brow, t + 3);
;       BAR; WAIT_L(0); MMA(1, 0, At, B0); BAR; SCHED;
;       STAGE(SB(1, 1), Bt, ldb, bcol + HALF, t + 3);
;       WAIT_V(6); BAR; MMA(1, 1, At, B1); BAR;
;     }
;     { LDB(B0, 0, 0); LDA(At, 0, 0); STAGE(SA(1, 1), Ab, lda, brow + HALF, nt - 1);
;       BAR; WAIT_L(0); MMA(0, 0, At, B0); BAR;
;       LDB(B1, 0, 1); BAR; WAIT_L(0); MMA(0, 1, At, B1); BAR;
	ds_read_b128 v[188:191], v152 offset:49152
	ds_read_b128 v[192:195], v152 offset:50176
	ds_read_b128 v[196:199], v151 offset:49152
	ds_read_b128 v[200:203], v151 offset:50176
	ds_read_b128 v[204:207], v150 offset:49152
	ds_read_b128 v[208:211], v150 offset:50176
	ds_read_b128 v[212:215], v149 offset:49152
	ds_read_b128 v[216:219], v149 offset:50176
	global_load_lds_dwordx4 v[236:237], off
	v_lshl_add_u64 v[236:237], v[238:239], 0, s[42:43]
	s_mov_b32 m0, s53
	s_nop 0
	global_load_lds_dwordx4 v[236:237], off
	s_barrier
	s_waitcnt lgkmcnt(0)
	s_setprio 0
	s_waitcnt lgkmcnt(0)
	v_mfma_f32_16x16x32_bf16 v[60:63], v[172:175], v[188:191], v[60:63]
	v_mfma_f32_16x16x32_bf16 v[56:59], v[180:183], v[188:191], v[56:59]
	v_mfma_f32_16x16x32_bf16 v[52:55], v[172:175], v[196:199], v[52:55]
	v_mfma_f32_16x16x32_bf16 v[48:51], v[180:183], v[196:199], v[48:51]
	v_mfma_f32_16x16x32_bf16 v[44:47], v[172:175], v[204:207], v[44:47]
	v_mfma_f32_16x16x32_bf16 v[40:43], v[180:183], v[204:207], v[40:43]
	v_mfma_f32_16x16x32_bf16 v[36:39], v[172:175], v[212:215], v[36:39]
	v_mfma_f32_16x16x32_bf16 v[32:35], v[180:183], v[212:215], v[32:35]
	v_mfma_f32_16x16x32_bf16 v[60:63], v[176:179], v[192:195], v[60:63]
	v_mfma_f32_16x16x32_bf16 v[56:59], v[184:187], v[192:195], v[56:59]
	v_mfma_f32_16x16x32_bf16 v[52:55], v[176:179], v[200:203], v[52:55]
	v_mfma_f32_16x16x32_bf16 v[48:51], v[184:187], v[200:203], v[48:51]
	v_mfma_f32_16x16x32_bf16 v[44:47], v[176:179], v[208:211], v[44:47]
	v_mfma_f32_16x16x32_bf16 v[40:43], v[184:187], v[208:211], v[40:43]
	v_mfma_f32_16x16x32_bf16 v[36:39], v[176:179], v[216:219], v[36:39]
	v_mfma_f32_16x16x32_bf16 v[32:35], v[184:187], v[216:219], v[32:35]
	s_setprio 1
	s_barrier
	v_readfirstlane_b32 s53, v159
	v_add_u32_e32 v171, 0x2000, v159
	v_lshl_add_u64 v[172:173], v[240:241], 0, s[44:45]
	s_mov_b32 m0, s53
	v_readfirstlane_b32 s53, v171
	global_load_lds_dwordx4 v[172:173], off
	v_lshl_add_u64 v[172:173], v[242:243], 0, s[44:45]
	s_mov_b32 m0, s53
	s_nop 0
	global_load_lds_dwordx4 v[172:173], off
	s_waitcnt vmcnt(6)
	s_barrier
	s_setprio 0
	v_mfma_f32_16x16x32_bf16 v[28:31], v[220:223], v[188:191], v[28:31]
	v_mfma_f32_16x16x32_bf16 v[24:27], v[228:231], v[188:191], v[24:27]
	v_mfma_f32_16x16x32_bf16 v[20:23], v[220:223], v[196:199], v[20:23]
	v_mfma_f32_16x16x32_bf16 v[16:19], v[228:231], v[196:199], v[16:19]
	v_mfma_f32_16x16x32_bf16 v[12:15], v[220:223], v[204:207], v[12:15]
	v_mfma_f32_16x16x32_bf16 v[8:11], v[228:231], v[204:207], v[8:11]
	v_mfma_f32_16x16x32_bf16 v[4:7], v[220:223], v[212:215], v[4:7]
	v_mfma_f32_16x16x32_bf16 v[0:3], v[228:231], v[212:215], v[0:3]
	v_mfma_f32_16x16x32_bf16 v[28:31], v[224:227], v[192:195], v[28:31]
	v_mfma_f32_16x16x32_bf16 v[24:27], v[232:235], v[192:195], v[24:27]
	v_mfma_f32_16x16x32_bf16 v[20:23], v[224:227], v[200:203], v[20:23]
	v_mfma_f32_16x16x32_bf16 v[16:19], v[232:235], v[200:203], v[16:19]
	v_mfma_f32_16x16x32_bf16 v[12:15], v[224:227], v[208:211], v[12:15]
	v_mfma_f32_16x16x32_bf16 v[8:11], v[232:235], v[208:211], v[8:11]
	v_mfma_f32_16x16x32_bf16 v[4:7], v[224:227], v[216:219], v[4:7]
	v_mfma_f32_16x16x32_bf16 v[0:3], v[232:235], v[216:219], v[0:3]
	s_setprio 1
	s_add_i32 s52, s52, 2
	s_add_u32 s50, s50, 0x100
	s_addc_u32 s51, s51, 0
	s_cmp_gt_u32 s52, 27
	s_barrier
	s_cbranch_scc0 .LBB0_770
	s_add_i32 s50, s48, 0x80
	s_mul_hi_i32 s51, s50, 0x1080
	s_mulk_i32 s50, 0x1080
	s_add_u32 s50, s61, s50
	s_addc_u32 s51, s62, s51
	v_lshl_add_u64 v[158:159], s[50:51], 0, v[128:129]
	v_readfirstlane_b32 s52, v169
	v_lshl_add_u64 v[158:159], v[158:159], 0, s[46:47]
	s_mov_b32 m0, s52
	ds_read_b128 v[134:137], v161
	ds_read_b128 v[138:141], v161 offset:1024
	ds_read_b128 v[172:175], v161 offset:2048
	ds_read_b128 v[176:179], v161 offset:3072
	ds_read_b128 v[180:183], v152
	ds_read_b128 v[184:187], v152 offset:1024
	ds_read_b128 v[188:191], v151
	ds_read_b128 v[192:195], v151 offset:1024
	ds_read_b128 v[196:199], v150
	ds_read_b128 v[200:203], v150 offset:1024
	ds_read_b128 v[204:207], v149
	ds_read_b128 v[208:211], v149 offset:1024
	global_load_lds_dwordx4 v[158:159], off
	v_lshl_add_u64 v[158:159], s[50:51], 0, v[132:133]
	v_readfirstlane_b32 s50, v170
	v_lshl_add_u64 v[158:159], v[158:159], 0, s[46:47]
	s_mov_b32 m0, s50
	s_nop 0
	global_load_lds_dwordx4 v[158:159], off
	s_barrier
	s_waitcnt lgkmcnt(0)
	s_setprio 0
	s_waitcnt lgkmcnt(0)
	v_mfma_f32_16x16x32_bf16 v[124:127], v[134:137], v[180:183], v[124:127]
	v_mfma_f32_16x16x32_bf16 v[120:123], v[172:175], v[180:183], v[120:123]
	v_mfma_f32_16x16x32_bf16 v[116:119], v[134:137], v[188:191], v[116:119]
	v_mfma_f32_16x16x32_bf16 v[112:115], v[172:175], v[188:191], v[112:115]
	v_mfma_f32_16x16x32_bf16 v[108:111], v[134:137], v[196:199], v[108:111]
	v_mfma_f32_16x16x32_bf16 v[104:107], v[172:175], v[196:199], v[104:107]
	v_mfma_f32_16x16x32_bf16 v[100:103], v[134:137], v[204:207], v[100:103]
	v_mfma_f32_16x16x32_bf16 v[96:99], v[172:175], v[204:207], v[96:99]
	v_mfma_f32_16x16x32_bf16 v[124:127], v[138:141], v[184:187], v[124:127]
	v_mfma_f32_16x16x32_bf16 v[120:123], v[176:179], v[184:187], v[120:123]
	v_mfma_f32_16x16x32_bf16 v[116:119], v[138:141], v[192:195], v[116:119]
	v_mfma_f32_16x16x32_bf16 v[112:115], v[176:179], v[192:195], v[112:115]
	v_mfma_f32_16x16x32_bf16 v[108:111], v[138:141], v[200:203], v[108:111]
	v_mfma_f32_16x16x32_bf16 v[104:107], v[176:179], v[200:203], v[104:107]
	v_mfma_f32_16x16x32_bf16 v[100:103], v[138:141], v[208:211], v[100:103]
	v_mfma_f32_16x16x32_bf16 v[96:99], v[176:179], v[208:211], v[96:99]
	s_setprio 1
	s_barrier
	ds_read_b128 v[212:215], v160
	ds_read_b128 v[216:219], v160 offset:1024
	ds_read_b128 v[220:223], v160 offset:2048
	ds_read_b128 v[158:161], v160 offset:3072
	s_barrier
; #define LDA(dst, b, h) for (int m = 0; m < 4; ++m) for (int k = 0; k < 2; ++k) \
;     dst[m][k] = *reinterpret_cast<const bf16x8*>((char*)SA(b, h) + lds_byte(wr * 64 + m * 16 + fr, k * 32 + fq * 8))
; #define LDB(dst, b, h) for (int n = 0; n < 2; ++n) for (int k = 0; k < 2; ++k) \
;     dst[n][k] = *reinterpret_cast<const bf16x8*>((char*)SB(b, h) + lds_byte(wc * 32 + n * 16 + fr, k * 32 + fq * 8))
; #define MMA(ai, bj, At_, Bt_) do { __builtin_amdgcn_s_setprio(1); \
;     for (int k = 0; k < 2; ++k) for (int m = 0; m < 4; ++m) for (int n = 0; n < 2; ++n) \
;       acc[ai][bj][m][n] = __builtin_amdgcn_mfma_f32_16x16x32_bf16(At_[m][k], Bt_[n][k], acc[ai][bj][m][n], 0, 0, 0); \
;     __builtin_amdgcn_s_setprio(0); } while (0)
; #define WAIT_V(n) asm volatile("s_waitcnt vmcnt(" #n ")" ::: "memory")
; #define WAIT_L(n) asm volatile("s_waitcnt lgkmcnt(" #n ")" ::: "memory")
; #define BAR __builtin_amdgcn_s_barrier()
; template <int EPI, int lda, int ldb, int N, int K>
; __device__ __forceinline__ void gemm_phase(const u16* __restrict__ A, const u16* __restrict__ Bt, const GemmEpi ep, int wv) {
;     ...
;       LDB(B1, 0, 1); BAR; WAIT_L(0); MMA(0, 1, At, B1); BAR;
;       LDA(At, 0, 1); WAIT_V(4); BAR; WAIT_L(0); MMA(1, 0, At, B0); MMA(1, 1, At, B1); BAR; }
;     { LDB(B0, 1, 0); LDA(At, 1, 0); WAIT_V(2); BAR; WAIT_L(0); MMA(0, 0, At, B0); BAR;
	s_waitcnt lgkmcnt(0)
	s_setprio 0
	s_waitcnt lgkmcnt(0)
	v_mfma_f32_16x16x32_bf16 v[92:95], v[212:215], v[180:183], v[92:95]
	v_mfma_f32_16x16x32_bf16 v[88:91], v[220:223], v[180:183], v[88:91]
	v_mfma_f32_16x16x32_bf16 v[76:79], v[212:215], v[196:199], v[76:79]
	v_mfma_f32_16x16x32_bf16 v[72:75], v[220:223], v[196:199], v[72:75]
	v_mfma_f32_16x16x32_bf16 v[84:87], v[212:215], v[188:191], v[84:87]
	v_mfma_f32_16x16x32_bf16 v[80:83], v[220:223], v[188:191], v[80:83]
	v_mfma_f32_16x16x32_bf16 v[68:71], v[212:215], v[204:207], v[68:71]
	v_mfma_f32_16x16x32_bf16 v[64:67], v[220:223], v[204:207], v[64:67]
	v_mfma_f32_16x16x32_bf16 v[92:95], v[216:219], v[184:187], v[92:95]
	v_mfma_f32_16x16x32_bf16 v[88:91], v[158:161], v[184:187], v[88:91]
	v_mfma_f32_16x16x32_bf16 v[76:79], v[216:219], v[200:203], v[76:79]
	v_mfma_f32_16x16x32_bf16 v[72:75], v[158:161], v[200:203], v[72:75]
	v_mfma_f32_16x16x32_bf16 v[180:183], v[216:219], v[192:195], v[84:87]
	v_mfma_f32_16x16x32_bf16 v[184:187], v[158:161], v[192:195], v[80:83]
	v_mfma_f32_16x16x32_bf16 v[188:191], v[216:219], v[208:211], v[68:71]
	v_mfma_f32_16x16x32_bf16 v[192:195], v[158:161], v[208:211], v[64:67]
	s_setprio 1
	s_barrier
	s_nop 0
	ds_read_b128 v[64:67], v152 offset:16384
	ds_read_b128 v[68:71], v152 offset:17408
	ds_read_b128 v[80:83], v151 offset:16384
	ds_read_b128 v[84:87], v151 offset:17408
	ds_read_b128 v[196:199], v150 offset:16384
	ds_read_b128 v[200:203], v150 offset:17408
	ds_read_b128 v[204:207], v149 offset:16384
	ds_read_b128 v[208:211], v149 offset:17408
	s_waitcnt vmcnt(4)
	s_barrier
	s_waitcnt lgkmcnt(0)
	s_setprio 0
	s_waitcnt lgkmcnt(0)
	v_mfma_f32_16x16x32_bf16 v[60:63], v[134:137], v[64:67], v[60:63]
	v_mfma_f32_16x16x32_bf16 v[56:59], v[172:175], v[64:67], v[56:59]
	v_mfma_f32_16x16x32_bf16 v[52:55], v[134:137], v[80:83], v[52:55]
	v_mfma_f32_16x16x32_bf16 v[48:51], v[172:175], v[80:83], v[48:51]
	v_mfma_f32_16x16x32_bf16 v[44:47], v[134:137], v[196:199], v[44:47]
	v_mfma_f32_16x16x32_bf16 v[40:43], v[172:175], v[196:199], v[40:43]
	v_mfma_f32_16x16x32_bf16 v[36:39], v[134:137], v[204:207], v[36:39]
	v_mfma_f32_16x16x32_bf16 v[32:35], v[172:175], v[204:207], v[32:35]
	v_mfma_f32_16x16x32_bf16 v[60:63], v[138:141], v[68:71], v[60:63]
	v_mfma_f32_16x16x32_bf16 v[56:59], v[176:179], v[68:71], v[56:59]
	v_mfma_f32_16x16x32_bf16 v[52:55], v[138:141], v[84:87], v[52:55]
	v_mfma_f32_16x16x32_bf16 v[48:51], v[176:179], v[84:87], v[48:51]
	v_mfma_f32_16x16x32_bf16 v[44:47], v[138:141], v[200:203], v[44:47]
	v_mfma_f32_16x16x32_bf16 v[40:43], v[176:179], v[200:203], v[40:43]
	v_mfma_f32_16x16x32_bf16 v[36:39], v[138:141], v[208:211], v[36:39]
	v_mfma_f32_16x16x32_bf16 v[32:35], v[176:179], v[208:211], v[32:35]
	s_setprio 1
	s_setprio 0
	v_mfma_f32_16x16x32_bf16 v[28:31], v[212:215], v[64:67], v[28:31]
	v_mfma_f32_16x16x32_bf16 v[24:27], v[220:223], v[64:67], v[24:27]
	v_mfma_f32_16x16x32_bf16 v[12:15], v[212:215], v[196:199], v[12:15]
	v_mfma_f32_16x16x32_bf16 v[8:11], v[220:223], v[196:199], v[8:11]
	v_mfma_f32_16x16x32_bf16 v[20:23], v[212:215], v[80:83], v[20:23]
	v_mfma_f32_16x16x32_bf16 v[16:19], v[220:223], v[80:83], v[16:19]
	v_mfma_f32_16x16x32_bf16 v[4:7], v[212:215], v[204:207], v[4:7]
	v_mfma_f32_16x16x32_bf16 v[0:3], v[220:223], v[204:207], v[0:3]
	v_mfma_f32_16x16x32_bf16 v[28:31], v[216:219], v[68:71], v[28:31]
	v_mfma_f32_16x16x32_bf16 v[24:27], v[158:161], v[68:71], v[24:27]
	v_mfma_f32_16x16x32_bf16 v[12:15], v[216:219], v[200:203], v[12:15]
	v_mfma_f32_16x16x32_bf16 v[8:11], v[158:161], v[200:203], v[8:11]
	v_mfma_f32_16x16x32_bf16 v[134:137], v[216:219], v[84:87], v[20:23]
	v_mfma_f32_16x16x32_bf16 v[138:141], v[158:161], v[84:87], v[16:19]
	v_mfma_f32_16x16x32_bf16 v[170:173], v[216:219], v[208:211], v[4:7]
	v_mfma_f32_16x16x32_bf16 v[158:161], v[158:161], v[208:211], v[0:3]
	s_setprio 1
	s_barrier
	s_nop 0
	ds_read_b128 v[0:3], v156
	ds_read_b128 v[4:7], v156 offset:1024
	ds_read_b128 v[16:19], v156 offset:2048
	ds_read_b128 v[174:177], v156 offset:3072
	ds_read_b128 v[20:23], v152 offset:32768
	ds_read_b128 v[196:199], v152 offset:33792
	ds_read_b128 v[200:203], v151 offset:32768
	ds_read_b128 v[204:207], v151 offset:33792
	ds_read_b128 v[208:211], v150 offset:32768
	ds_read_b128 v[212:215], v150 offset:33792
	ds_read_b128 v[216:219], v149 offset:32768
	ds_read_b128 v[220:223], v149 offset:33792
	s_waitcnt vmcnt(2)
	s_barrier
; #define UNR _Pragma("unroll")
; #define LDA(dst, b, h) for (int m = 0; m < 4; ++m) for (int k = 0; k < 2; ++k) \
;     dst[m][k] = *reinterpret_cast<const bf16x8*>((char*)SA(b, h) + lds_byte(wr * 64 + m * 16 + fr, k * 32 + fq * 8))
; #define LDB(dst, b, h) for (int n = 0; n < 2; ++n) for (int k = 0; k < 2; ++k) \
;     dst[n][k] = *reinterpret_cast<const bf16x8*>((char*)SB(b, h) + lds_byte(wc * 32 + n * 16 + fr, k * 32 + fq * 8))
; #define MMA(ai, bj, At_, Bt_) do { __builtin_amdgcn_s_setprio(1); \
;     for (int k = 0; k < 2; ++k) for (int m = 0; m < 4; ++m) for (int n = 0; n < 2; ++n) \
;       acc[ai][bj][m][n] = __builtin_amdgcn_mfma_f32_16x16x32_bf16(At_[m][k], Bt_[n][k], acc[ai][bj][m][n], 0, 0, 0); \
;     __builtin_amdgcn_s_setprio(0); } while (0)
; #define WAIT_V(n) asm volatile("s_waitcnt vmcnt(" #n ")" ::: "memory")
; #define WAIT_L(n) asm volatile("s_waitcnt lgkmcnt(" #n ")" ::: "memory")
; #define BAR __builtin_amdgcn_s_barrier()
; #define STAGE4(BROW, BCOL, PN) do { const u16* Ab_ = A + (EPI == EPI_RG ? ((PN) >> 1) * 256 : 0); \
;     STAGE(SB(0, 0), Bt, ldb, (BCOL), 0); STAGE(SA(0, 0), Ab_, lda, (BROW), 0); \
;     STAGE(SB(0, 1), Bt, ldb, (BCOL) + HALF, 0); STAGE(SA(0, 1), Ab_, lda, (BROW) + HALF, 0); } while (0)
; template <int EPI, int lda, int ldb, int N, int K>
; __device__ __forceinline__ void gemm_phase(const u16* __restrict__ A, const u16* __restrict__ Bt, const GemmEpi ep, int wv) {
;     ...
;     { LDB(B0, 1, 0); LDA(At, 1, 0); WAIT_V(2); BAR; WAIT_L(0); MMA(0, 0, At, B0); BAR;
;       LDB(B1, 1, 1); WAIT_V(0); BAR; WAIT_L(0); MMA(0, 1, At, B1); BAR;
;       LDA(At, 1, 1); BAR; WAIT_L(0); MMA(1, 0, At, B0); MMA(1, 1, At, B1); BAR; }
;     if (wr == 0) BAR;
;     int ntile = 0, nbrow = 0, nbcol = 0, npn = 0; bool more = false;
;     if constexpr (PF) { ntile = tile + gridDim.x; more = ntile < nwg; if (more) { TILE_COORDS(ntile, nbrow, nbcol, npn); STAGE4(nbrow, nbcol, npn); } }
;     float nss[8];
;     if constexpr (CONS) { UNR for (int pp = 0; pp < 8; ++pp) nss[pp] = 0.f;
;       if (more && tidx < 256) { UNR for (int pp = 0; pp < 8; ++pp) nss[pp] = ep.ss_in[(size_t)pp * T + nbrow + tidx]; } }
	s_waitcnt lgkmcnt(0)
	s_setprio 0
	s_waitcnt lgkmcnt(0)
	v_mfma_f32_16x16x32_bf16 v[64:67], v[0:3], v[20:23], v[124:127]
	v_mfma_f32_16x16x32_bf16 v[68:71], v[16:19], v[20:23], v[120:123]
	v_mfma_f32_16x16x32_bf16 v[80:83], v[0:3], v[200:203], v[116:119]
	v_mfma_f32_16x16x32_bf16 v[84:87], v[16:19], v[200:203], v[112:115]
	v_mfma_f32_16x16x32_bf16 v[108:111], v[0:3], v[208:211], v[108:111]
	v_mfma_f32_16x16x32_bf16 v[104:107], v[16:19], v[208:211], v[104:107]
	v_mfma_f32_16x16x32_bf16 v[120:123], v[0:3], v[216:219], v[100:103]
	v_mfma_f32_16x16x32_bf16 v[124:127], v[16:19], v[216:219], v[96:99]
	v_mfma_f32_16x16x32_bf16 v[116:119], v[4:7], v[196:199], v[64:67]
	v_mfma_f32_16x16x32_bf16 v[112:115], v[174:177], v[196:199], v[68:71]
	v_mfma_f32_16x16x32_bf16 v[100:103], v[4:7], v[204:207], v[80:83]
	v_mfma_f32_16x16x32_bf16 v[96:99], v[174:177], v[204:207], v[84:87]
	v_mfma_f32_16x16x32_bf16 v[84:87], v[4:7], v[212:215], v[108:111]
	v_mfma_f32_16x16x32_bf16 v[80:83], v[174:177], v[212:215], v[104:107]
	v_mfma_f32_16x16x32_bf16 v[68:71], v[4:7], v[220:223], v[120:123]
	v_mfma_f32_16x16x32_bf16 v[64:67], v[174:177], v[220:223], v[124:127]
	s_setprio 1
	s_barrier
	ds_read_b128 v[224:227], v154
	ds_read_b128 v[228:231], v154 offset:1024
	ds_read_b128 v[232:235], v154 offset:2048
	ds_read_b128 v[154:157], v154 offset:3072
	s_waitcnt vmcnt(0)
	s_barrier
	s_waitcnt lgkmcnt(0)
	s_setprio 0
	s_waitcnt lgkmcnt(0)
	v_mfma_f32_16x16x32_bf16 v[92:95], v[224:227], v[20:23], v[92:95]
	v_mfma_f32_16x16x32_bf16 v[20:23], v[232:235], v[20:23], v[88:91]
	v_mfma_f32_16x16x32_bf16 v[88:91], v[224:227], v[200:203], v[180:183]
	v_mfma_f32_16x16x32_bf16 v[104:107], v[232:235], v[200:203], v[184:187]
	v_mfma_f32_16x16x32_bf16 v[76:79], v[224:227], v[208:211], v[76:79]
	v_mfma_f32_16x16x32_bf16 v[72:75], v[232:235], v[208:211], v[72:75]
	v_mfma_f32_16x16x32_bf16 v[178:181], v[224:227], v[216:219], v[188:191]
	v_mfma_f32_16x16x32_bf16 v[182:185], v[232:235], v[216:219], v[192:195]
	v_mfma_f32_16x16x32_bf16 v[124:127], v[228:231], v[196:199], v[92:95]
	v_mfma_f32_16x16x32_bf16 v[120:123], v[154:157], v[196:199], v[20:23]
	v_mfma_f32_16x16x32_bf16 v[108:111], v[228:231], v[204:207], v[88:91]
	v_mfma_f32_16x16x32_bf16 v[104:107], v[154:157], v[204:207], v[104:107]
	v_mfma_f32_16x16x32_bf16 v[92:95], v[228:231], v[212:215], v[76:79]
	v_mfma_f32_16x16x32_bf16 v[88:91], v[154:157], v[212:215], v[72:75]
	v_mfma_f32_16x16x32_bf16 v[76:79], v[228:231], v[220:223], v[178:181]
	v_mfma_f32_16x16x32_bf16 v[72:75], v[154:157], v[220:223], v[182:185]
	s_setprio 1
	s_barrier
	ds_read_b128 v[178:181], v152 offset:49152
	ds_read_b128 v[182:185], v152 offset:50176
	ds_read_b128 v[186:189], v151 offset:49152
	ds_read_b128 v[190:193], v151 offset:50176
	ds_read_b128 v[194:197], v150 offset:49152
	ds_read_b128 v[150:153], v150 offset:50176
	ds_read_b128 v[198:201], v149 offset:49152
	ds_read_b128 v[202:205], v149 offset:50176
	s_barrier
	s_waitcnt lgkmcnt(0)
	s_setprio 0
	s_waitcnt lgkmcnt(0)
	v_mfma_f32_16x16x32_bf16 v[20:23], v[0:3], v[178:181], v[60:63]
	v_mfma_f32_16x16x32_bf16 v[56:59], v[16:19], v[178:181], v[56:59]
	v_mfma_f32_16x16x32_bf16 v[60:63], v[0:3], v[186:189], v[52:55]
	v_mfma_f32_16x16x32_bf16 v[206:209], v[16:19], v[186:189], v[48:51]
	v_mfma_f32_16x16x32_bf16 v[44:47], v[0:3], v[194:197], v[44:47]
	v_mfma_f32_16x16x32_bf16 v[40:43], v[16:19], v[194:197], v[40:43]
	v_mfma_f32_16x16x32_bf16 v[0:3], v[0:3], v[198:201], v[36:39]
	v_mfma_f32_16x16x32_bf16 v[210:213], v[16:19], v[198:201], v[32:35]
	v_mfma_f32_16x16x32_bf16 v[52:55], v[4:7], v[182:185], v[20:23]
	v_mfma_f32_16x16x32_bf16 v[48:51], v[174:177], v[182:185], v[56:59]
	v_mfma_f32_16x16x32_bf16 v[36:39], v[4:7], v[190:193], v[60:63]
	v_mfma_f32_16x16x32_bf16 v[32:35], v[174:177], v[190:193], v[206:209]
	v_mfma_f32_16x16x32_bf16 v[20:23], v[4:7], v[150:153], v[44:47]
	v_mfma_f32_16x16x32_bf16 v[16:19], v[174:177], v[150:153], v[40:43]
	v_mfma_f32_16x16x32_bf16 v[4:7], v[4:7], v[202:205], v[0:3]
	v_mfma_f32_16x16x32_bf16 v[0:3], v[174:177], v[202:205], v[210:213]
	s_setprio 1
	s_setprio 0
	v_mfma_f32_16x16x32_bf16 v[28:31], v[224:227], v[178:181], v[28:31]
	v_mfma_f32_16x16x32_bf16 v[24:27], v[232:235], v[178:181], v[24:27]
	v_mfma_f32_16x16x32_bf16 v[40:43], v[224:227], v[186:189], v[134:137]
	v_mfma_f32_16x16x32_bf16 v[134:137], v[232:235], v[186:189], v[138:141]
	v_mfma_f32_16x16x32_bf16 v[12:15], v[224:227], v[194:197], v[12:15]
	v_mfma_f32_16x16x32_bf16 v[8:11], v[232:235], v[194:197], v[8:11]
	v_mfma_f32_16x16x32_bf16 v[138:141], v[224:227], v[198:201], v[170:173]
	v_mfma_f32_16x16x32_bf16 v[158:161], v[232:235], v[198:201], v[158:161]
	v_mfma_f32_16x16x32_bf16 v[60:63], v[228:231], v[182:185], v[28:31]
	v_mfma_f32_16x16x32_bf16 v[56:59], v[154:157], v[182:185], v[24:27]
	v_mfma_f32_16x16x32_bf16 v[44:47], v[228:231], v[190:193], v[40:43]
	v_mfma_f32_16x16x32_bf16 v[40:43], v[154:157], v[190:193], v[134:137]
	v_mfma_f32_16x16x32_bf16 v[28:31], v[228:231], v[150:153], v[12:15]
	v_mfma_f32_16x16x32_bf16 v[24:27], v[154:157], v[150:153], v[8:11]
	v_mfma_f32_16x16x32_bf16 v[12:15], v[228:231], v[202:205], v[138:141]
	v_mfma_f32_16x16x32_bf16 v[8:11], v[154:157], v[202:205], v[158:161]
	s_setprio 1
	v_cmp_gt_u32_e32 vcc, s66, v130
	s_barrier
	s_and_saveexec_b64 s[50:51], vcc
	s_cbranch_execz .LBB0_773
	s_barrier

; #define STAGE(P, BASE, LD, br, kt) do { const char* _g = (const char*)((BASE) + (size_t)(br) * (LD) + (size_t)(kt) * 64); \
;     for (int _i = 0; _i < 2; ++_i) { int _b = tidx * 16 + _i * 8192; int _r, _c; stage_rc(_b, _r, _c); \
;       __builtin_amdgcn_global_load_lds((const unsigned*)(_g + (unsigned)((_r * (LD) + _c) * 2)), (unsigned*)((char*)(P) + _b), 16, 0, 0); } } while (0)
; #define LDA(dst, b, h) for (int m = 0; m < 4; ++m) for (int k = 0; k < 2; ++k) \
;     dst[m][k] = *reinterpret_cast<const bf16x8*>((char*)SA(b, h) + lds_byte(wr * 64 + m * 16 + fr, k * 32 + fq * 8))
; #define LDB(dst, b, h) for (int n = 0; n < 2; ++n) for (int k = 0; k < 2; ++k) \
;     dst[n][k] = *reinterpret_cast<const bf16x8*>((char*)SB(b, h) + lds_byte(wc * 32 + n * 16 + fr, k * 32 + fq * 8))
; #define MMA(ai, bj, At_, Bt_) do { __builtin_amdgcn_s_setprio(1); \
;     for (int k = 0; k < 2; ++k) for (int m = 0; m < 4; ++m) for (int n = 0; n < 2; ++n) \
;       acc[ai][bj][m][n] = __builtin_amdgcn_mfma_f32_16x16x32_bf16(At_[m][k], Bt_[n][k], acc[ai][bj][m][n], 0, 0, 0); \
;     __builtin_amdgcn_s_setprio(0); } while (0)
; #define WAIT_L(n) asm volatile("s_waitcnt lgkmcnt(" #n ")" ::: "memory")
; #define BAR __builtin_amdgcn_s_barrier()
; #define SCHED __builtin_amdgcn_sched_barrier(0)
; template <int EPI, int lda, int ldb, int N, int K>
; __device__ __forceinline__ void gemm_phase(const u16* __restrict__ A, const u16* __restrict__ Bt, const GemmEpi ep, int wv) {
;     ...
;     for (int t = 0; t < nt - 2; t += 2) {
;       LDB(B0, 0, 0); SCHED; LDA(At, 0, 0); STAGE(SA(1, 1), Ab, lda, brow + HALF, t + 1);
;       WAIT_L(8); BAR; WAIT_L(0); MMA(0, 0, At, B0); BAR; SCHED;
;       LDB(B1, 0, 1); STAGE(SB(0, 0), Bt, ldb, bcol, t + 2);
;       BAR; WAIT_L(0); MMA(0, 1, At, B1); BAR;
;       LDA(At, 0, 1); STAGE(SA(0, 0), Ab, lda, brow, t + 2);
;       BAR; WAIT_L(0); MMA(1, 0, At, B0); BAR; SCHED;
.LBB0_838:
	ds_read_b128 v[168:171], v164
	ds_read_b128 v[174:177], v164 offset:1024
	ds_read_b128 v[178:181], v164 offset:2048
	ds_read_b128 v[182:185], v164 offset:3072
	v_add_u32_e32 v172, 0xc000, v147
	v_lshl_add_u64 v[238:239], v[136:137], 0, s[50:51]
	v_readfirstlane_b32 s73, v172
	v_add_u32_e32 v173, 0xe000, v147
	v_lshl_add_u64 v[166:167], v[238:239], 0, s[22:23]
	s_mov_b32 m0, s73
	v_lshl_add_u64 v[240:241], v[134:135], 0, s[50:51]
	v_readfirstlane_b32 s73, v173
	ds_read_b128 v[186:189], v155
	ds_read_b128 v[190:193], v155 offset:1024
	ds_read_b128 v[194:197], v154
	ds_read_b128 v[198:201], v154 offset:1024
	ds_read_b128 v[202:205], v153
	ds_read_b128 v[206:209], v153 offset:1024
	ds_read_b128 v[210:213], v152
	ds_read_b128 v[214:217], v152 offset:1024
	global_load_lds_dwordx4 v[166:167], off
	v_lshl_add_u64 v[166:167], v[240:241], 0, s[22:23]
	s_mov_b32 m0, s73
	s_nop 0
	global_load_lds_dwordx4 v[166:167], off
	s_waitcnt lgkmcnt(8)
	s_barrier
	s_waitcnt lgkmcnt(0)
	s_setprio 0
	s_waitcnt lgkmcnt(0)
	v_mfma_f32_16x16x32_bf16 v[124:127], v[168:171], v[186:189], v[124:127]
	v_mfma_f32_16x16x32_bf16 v[120:123], v[178:181], v[186:189], v[120:123]
	v_mfma_f32_16x16x32_bf16 v[116:119], v[168:171], v[194:197], v[116:119]
	v_mfma_f32_16x16x32_bf16 v[112:115], v[178:181], v[194:197], v[112:115]
	v_mfma_f32_16x16x32_bf16 v[108:111], v[168:171], v[202:205], v[108:111]
	v_mfma_f32_16x16x32_bf16 v[104:107], v[178:181], v[202:205], v[104:107]
	v_mfma_f32_16x16x32_bf16 v[100:103], v[168:171], v[210:213], v[100:103]
	v_mfma_f32_16x16x32_bf16 v[96:99], v[178:181], v[210:213], v[96:99]
	v_mfma_f32_16x16x32_bf16 v[124:127], v[174:177], v[190:193], v[124:127]
	v_mfma_f32_16x16x32_bf16 v[120:123], v[182:185], v[190:193], v[120:123]
	v_mfma_f32_16x16x32_bf16 v[116:119], v[174:177], v[198:201], v[116:119]
	v_mfma_f32_16x16x32_bf16 v[112:115], v[182:185], v[198:201], v[112:115]
	v_mfma_f32_16x16x32_bf16 v[108:111], v[174:177], v[206:209], v[108:111]
	v_mfma_f32_16x16x32_bf16 v[104:107], v[182:185], v[206:209], v[104:107]
	v_mfma_f32_16x16x32_bf16 v[100:103], v[174:177], v[214:217], v[100:103]
	v_mfma_f32_16x16x32_bf16 v[96:99], v[182:185], v[214:217], v[96:99]
	s_setprio 1
	s_barrier
	v_add_u32_e32 v165, s63, v156
	v_lshl_add_u64 v[242:243], v[144:145], 0, s[50:51]
	v_readfirstlane_b32 s73, v165
	v_lshl_add_u64 v[166:167], v[242:243], 0, s[24:25]
	s_mov_b32 m0, s73
	ds_read_b128 v[218:221], v163
	ds_read_b128 v[222:225], v163 offset:1024
	ds_read_b128 v[226:229], v163 offset:2048
	ds_read_b128 v[230:233], v163 offset:3072
	global_load_lds_dwordx4 v[166:167], off
	v_add_u32_e32 v166, 0x2000, v165
	v_lshl_add_u64 v[244:245], v[142:143], 0, s[50:51]
	v_readfirstlane_b32 s73, v166
	v_lshl_add_u64 v[234:235], v[244:245], 0, s[24:25]
	s_mov_b32 m0, s73
	s_nop 0
	global_load_lds_dwordx4 v[234:235], off
	s_barrier
	s_waitcnt lgkmcnt(0)
	s_setprio 0
	s_waitcnt lgkmcnt(0)
	v_mfma_f32_16x16x32_bf16 v[92:95], v[218:221], v[186:189], v[92:95]
	v_mfma_f32_16x16x32_bf16 v[88:91], v[226:229], v[186:189], v[88:91]
	v_mfma_f32_16x16x32_bf16 v[84:87], v[218:221], v[194:197], v[84:87]
	v_mfma_f32_16x16x32_bf16 v[80:83], v[226:229], v[194:197], v[80:83]
	v_mfma_f32_16x16x32_bf16 v[76:79], v[218:221], v[202:205], v[76:79]
	v_mfma_f32_16x16x32_bf16 v[72:75], v[226:229], v[202:205], v[72:75]
	v_mfma_f32_16x16x32_bf16 v[68:71], v[218:221], v[210:213], v[68:71]
	v_mfma_f32_16x16x32_bf16 v[64:67], v[226:229], v[210:213], v[64:67]
	v_mfma_f32_16x16x32_bf16 v[92:95], v[222:225], v[190:193], v[92:95]
	v_mfma_f32_16x16x32_bf16 v[88:91], v[230:233], v[190:193], v[88:91]
	v_mfma_f32_16x16x32_bf16 v[84:87], v[222:225], v[198:201], v[84:87]
	v_mfma_f32_16x16x32_bf16 v[80:83], v[230:233], v[198:201], v[80:83]
	v_mfma_f32_16x16x32_bf16 v[76:79], v[222:225], v[206:209], v[76:79]
	v_mfma_f32_16x16x32_bf16 v[72:75], v[230:233], v[206:209], v[72:75]
	v_mfma_f32_16x16x32_bf16 v[68:71], v[222:225], v[214:217], v[68:71]
	v_mfma_f32_16x16x32_bf16 v[64:67], v[230:233], v[214:217], v[64:67]
	s_setprio 1
	v_readfirstlane_b32 s73, v147
	v_add_u32_e32 v167, 0x2000, v147
	v_lshl_add_u64 v[234:235], v[238:239], 0, s[26:27]
	s_mov_b32 m0, s73
	v_readfirstlane_b32 s73, v167
	s_barrier
	ds_read_b128 v[186:189], v155 offset:16384
	ds_read_b128 v[190:193], v155 offset:17408
	ds_read_b128 v[194:197], v154 offset:16384
	ds_read_b128 v[198:201], v154 offset:17408
	ds_read_b128 v[202:205], v153 offset:16384
	ds_read_b128 v[206:209], v153 offset:17408
	ds_read_b128 v[210:213], v152 offset:16384
	ds_read_b128 v[214:217], v152 offset:17408
	global_load_lds_dwordx4 v[234:235], off
	v_lshl_add_u64 v[234:235], v[240:241], 0, s[26:27]
	s_mov_b32 m0, s73
	s_nop 0
	global_load_lds_dwordx4 v[234:235], off
	s_barrier
	s_waitcnt lgkmcnt(0)
	s_setprio 0
	s_waitcnt lgkmcnt(0)
	v_mfma_f32_16x16x32_bf16 v[60:63], v[168:171], v[186:189], v[60:63]
	v_mfma_f32_16x16x32_bf16 v[56:59], v[178:181], v[186:189], v[56:59]
	v_mfma_f32_16x16x32_bf16 v[52:55], v[168:171], v[194:197], v[52:55]
	v_mfma_f32_16x16x32_bf16 v[48:51], v[178:181], v[194:197], v[48:51]
	v_mfma_f32_16x16x32_bf16 v[44:47], v[168:171], v[202:205], v[44:47]
	v_mfma_f32_16x16x32_bf16 v[40:43], v[178:181], v[202:205], v[40:43]
	v_mfma_f32_16x16x32_bf16 v[36:39], v[168:171], v[210:213], v[36:39]
	v_mfma_f32_16x16x32_bf16 v[32:35], v[178:181], v[210:213], v[32:35]
	v_mfma_f32_16x16x32_bf16 v[60:63], v[174:177], v[190:193], v[60:63]
	v_mfma_f32_16x16x32_bf16 v[56:59], v[182:185], v[190:193], v[56:59]
	v_mfma_f32_16x16x32_bf16 v[52:55], v[174:177], v[198:201], v[52:55]
	v_mfma_f32_16x16x32_bf16 v[48:51], v[182:185], v[198:201], v[48:51]
	v_mfma_f32_16x16x32_bf16 v[44:47], v[174:177], v[206:209], v[44:47]
	v_mfma_f32_16x16x32_bf16 v[40:43], v[182:185], v[206:209], v[40:43]
	v_mfma_f32_16x16x32_bf16 v[36:39], v[174:177], v[214:217], v[36:39]
	v_mfma_f32_16x16x32_bf16 v[32:35], v[182:185], v[214:217], v[32:35]
	s_setprio 1
	s_barrier
; #define STAGE(P, BASE, LD, br, kt) do { const char* _g = (const char*)((BASE) + (size_t)(br) * (LD) + (size_t)(kt) * 64); \
;     for (int _i = 0; _i < 2; ++_i) { int _b = tidx * 16 + _i * 8192; int _r, _c; stage_rc(_b, _r, _c); \
;       __builtin_amdgcn_global_load_lds((const unsigned*)(_g + (unsigned)((_r * (LD) + _c) * 2)), (unsigned*)((char*)(P) + _b), 16, 0, 0); } } while (0)
; #define LDA(dst, b, h) for (int m = 0; m < 4; ++m) for (int k = 0; k < 2; ++k) \
;     dst[m][k] = *reinterpret_cast<const bf16x8*>((char*)SA(b, h) + lds_byte(wr * 64 + m * 16 + fr, k * 32 + fq * 8))
; #define LDB(dst, b, h) for (int n = 0; n < 2; ++n) for (int k = 0; k < 2; ++k) \
;     dst[n][k] = *reinterpret_cast<const bf16x8*>((char*)SB(b, h) + lds_byte(wc * 32 + n * 16 + fr, k * 32 + fq * 8))
; #define MMA(ai, bj, At_, Bt_) do { __builtin_amdgcn_s_setprio(1); \
;     for (int k = 0; k < 2; ++k) for (int m = 0; m < 4; ++m) for (int n = 0; n < 2; ++n) \
;       acc[ai][bj][m][n] = __builtin_amdgcn_mfma_f32_16x16x32_bf16(At_[m][k], Bt_[n][k], acc[ai][bj][m][n], 0, 0, 0); \
;     __builtin_amdgcn_s_setprio(0); } while (0)
; #define WAIT_V(n) asm volatile("s_waitcnt vmcnt(" #n ")" ::: "memory")
; #define WAIT_L(n) asm volatile("s_waitcnt lgkmcnt(" #n ")" ::: "memory")
; #define BAR __builtin_amdgcn_s_barrier()
; #define SCHED __builtin_amdgcn_sched_barrier(0)
; template <int EPI, int lda, int ldb, int N, int K>
; __device__ __forceinline__ void gemm_phase(const u16* __restrict__ A, const u16* __restrict__ Bt, const GemmEpi ep, int wv) {
;     ...
;       STAGE(SB(0, 1), Bt, ldb, bcol + HALF, t + 2);
;       WAIT_V(6); BAR; MMA(1, 1, At, B1); BAR;
;       LDB(B0, 1, 0); SCHED; LDA(At, 1, 0); STAGE(SA(0, 1), Ab, lda, brow + HALF, t + 2);
;       WAIT_L(8); BAR; WAIT_L(0); MMA(0, 0, At, B0); BAR; SCHED;
;       LDB(B1, 1, 1); STAGE(SB(1, 0), Bt, ldb, bcol, t + 3);
;       BAR; WAIT_L(0); MMA(0, 1, At, B1); BAR;
	v_add_u32_e32 v168, s64, v156
	v_lshl_add_u64 v[246:247], v[140:141], 0, s[50:51]
	v_readfirstlane_b32 s73, v168
	v_add_u32_e32 v169, 0x2000, v168
	v_lshl_add_u64 v[170:171], v[246:247], 0, s[40:41]
	s_mov_b32 m0, s73
	v_lshl_add_u64 v[248:249], v[138:139], 0, s[50:51]
	v_readfirstlane_b32 s73, v169
	global_load_lds_dwordx4 v[170:171], off
	v_lshl_add_u64 v[170:171], v[248:249], 0, s[40:41]
	s_mov_b32 m0, s73
	s_nop 0
	global_load_lds_dwordx4 v[170:171], off
	s_waitcnt vmcnt(6)
	s_barrier
	s_setprio 0
	v_mfma_f32_16x16x32_bf16 v[28:31], v[218:221], v[186:189], v[28:31]
	v_mfma_f32_16x16x32_bf16 v[24:27], v[226:229], v[186:189], v[24:27]
	v_mfma_f32_16x16x32_bf16 v[20:23], v[218:221], v[194:197], v[20:23]
	v_mfma_f32_16x16x32_bf16 v[16:19], v[226:229], v[194:197], v[16:19]
	v_mfma_f32_16x16x32_bf16 v[12:15], v[218:221], v[202:205], v[12:15]
	v_mfma_f32_16x16x32_bf16 v[8:11], v[226:229], v[202:205], v[8:11]
	v_mfma_f32_16x16x32_bf16 v[4:7], v[218:221], v[210:213], v[4:7]
	v_mfma_f32_16x16x32_bf16 v[0:3], v[226:229], v[210:213], v[0:3]
	v_mfma_f32_16x16x32_bf16 v[28:31], v[222:225], v[190:193], v[28:31]
	v_mfma_f32_16x16x32_bf16 v[24:27], v[230:233], v[190:193], v[24:27]
	v_mfma_f32_16x16x32_bf16 v[20:23], v[222:225], v[198:201], v[20:23]
	v_mfma_f32_16x16x32_bf16 v[16:19], v[230:233], v[198:201], v[16:19]
	v_mfma_f32_16x16x32_bf16 v[12:15], v[222:225], v[206:209], v[12:15]
	v_mfma_f32_16x16x32_bf16 v[8:11], v[230:233], v[206:209], v[8:11]
	v_mfma_f32_16x16x32_bf16 v[4:7], v[222:225], v[214:217], v[4:7]
	v_mfma_f32_16x16x32_bf16 v[0:3], v[230:233], v[214:217], v[0:3]
	s_setprio 1
	s_barrier
	ds_read_b128 v[174:177], v159
	ds_read_b128 v[178:181], v159 offset:1024
	ds_read_b128 v[182:185], v159 offset:2048
	ds_read_b128 v[186:189], v159 offset:3072
	v_add_u32_e32 v170, 0x4000, v147
	v_add_u32_e32 v171, 0x6000, v147
	v_readfirstlane_b32 s73, v170
	v_lshl_add_u64 v[222:223], v[238:239], 0, s[42:43]
	s_mov_b32 m0, s73
	v_readfirstlane_b32 s73, v171
	ds_read_b128 v[190:193], v155 offset:32768
	ds_read_b128 v[194:197], v155 offset:33792
	ds_read_b128 v[198:201], v154 offset:32768
	ds_read_b128 v[202:205], v154 offset:33792
	ds_read_b128 v[206:209], v153 offset:32768
	ds_read_b128 v[210:213], v153 offset:33792
	ds_read_b128 v[214:217], v152 offset:32768
	ds_read_b128 v[218:221], v152 offset:33792
	global_load_lds_dwordx4 v[222:223], off
	v_lshl_add_u64 v[222:223], v[240:241], 0, s[42:43]
	s_mov_b32 m0, s73
	s_nop 0
	global_load_lds_dwordx4 v[222:223], off
	s_waitcnt lgkmcnt(8)
	s_barrier
	s_waitcnt lgkmcnt(0)
	s_setprio 0
	s_waitcnt lgkmcnt(0)
	v_mfma_f32_16x16x32_bf16 v[124:127], v[174:177], v[190:193], v[124:127]
	v_mfma_f32_16x16x32_bf16 v[120:123], v[182:185], v[190:193], v[120:123]
	v_mfma_f32_16x16x32_bf16 v[116:119], v[174:177], v[198:201], v[116:119]
	v_mfma_f32_16x16x32_bf16 v[112:115], v[182:185], v[198:201], v[112:115]
	v_mfma_f32_16x16x32_bf16 v[108:111], v[174:177], v[206:209], v[108:111]
	v_mfma_f32_16x16x32_bf16 v[104:107], v[182:185], v[206:209], v[104:107]
	v_mfma_f32_16x16x32_bf16 v[100:103], v[174:177], v[214:217], v[100:103]
	v_mfma_f32_16x16x32_bf16 v[96:99], v[182:185], v[214:217], v[96:99]
	v_mfma_f32_16x16x32_bf16 v[124:127], v[178:181], v[194:197], v[124:127]
	v_mfma_f32_16x16x32_bf16 v[120:123], v[186:189], v[194:197], v[120:123]
	v_mfma_f32_16x16x32_bf16 v[116:119], v[178:181], v[202:205], v[116:119]
	v_mfma_f32_16x16x32_bf16 v[112:115], v[186:189], v[202:205], v[112:115]
	v_mfma_f32_16x16x32_bf16 v[108:111], v[178:181], v[210:213], v[108:111]
	v_mfma_f32_16x16x32_bf16 v[104:107], v[186:189], v[210:213], v[104:107]
	v_mfma_f32_16x16x32_bf16 v[100:103], v[178:181], v[218:221], v[100:103]
	v_mfma_f32_16x16x32_bf16 v[96:99], v[186:189], v[218:221], v[96:99]
	s_setprio 1
	s_barrier
	v_readfirstlane_b32 s73, v158
	v_lshl_add_u64 v[242:243], v[242:243], 0, s[44:45]
	s_mov_b32 m0, s73
	ds_read_b128 v[222:225], v157
	ds_read_b128 v[226:229], v157 offset:1024
	ds_read_b128 v[230:233], v157 offset:2048
	ds_read_b128 v[234:237], v157 offset:3072
	global_load_lds_dwordx4 v[242:243], off
	v_lshl_add_u64 v[242:243], v[244:245], 0, s[44:45]
	v_add_u32_e32 v244, 0x2000, v158
	s_nop 0
	v_readfirstlane_b32 s73, v244
	s_mov_b32 m0, s73
	s_nop 0
	global_load_lds_dwordx4 v[242:243], off
	s_barrier
	s_waitcnt lgkmcnt(0)
	s_setprio 0
	s_waitcnt lgkmcnt(0)
	v_mfma_f32_16x16x32_bf16 v[92:95], v[222:225], v[190:193], v[92:95]
	v_mfma_f32_16x16x32_bf16 v[88:91], v[230:233], v[190:193], v[88:91]
	v_mfma_f32_16x16x32_bf16 v[84:87], v[222:225], v[198:201], v[84:87]
	v_mfma_f32_16x16x32_bf16 v[80:83], v[230:233], v[198:201], v[80:83]
	v_mfma_f32_16x16x32_bf16 v[76:79], v[222:225], v[206:209], v[76:79]
	v_mfma_f32_16x16x32_bf16 v[72:75], v[230:233], v[206:209], v[72:75]
	v_mfma_f32_16x16x32_bf16 v[68:71], v[222:225], v[214:217], v[68:71]
	v_mfma_f32_16x16x32_bf16 v[64:67], v[230:233], v[214:217], v[64:67]
	v_mfma_f32_16x16x32_bf16 v[92:95], v[226:229], v[194:197], v[92:95]
	v_mfma_f32_16x16x32_bf16 v[88:91], v[234:237], v[194:197], v[88:91]
	v_mfma_f32_16x16x32_bf16 v[84:87], v[226:229], v[202:205], v[84:87]
	v_mfma_f32_16x16x32_bf16 v[80:83], v[234:237], v[202:205], v[80:83]
	v_mfma_f32_16x16x32_bf16 v[76:79], v[226:229], v[210:213], v[76:79]
	v_mfma_f32_16x16x32_bf16 v[72:75], v[234:237], v[210:213], v[72:75]
	v_mfma_f32_16x16x32_bf16 v[68:71], v[226:229], v[218:221], v[68:71]
	v_mfma_f32_16x16x32_bf16 v[64:67], v[234:237], v[218:221], v[64:67]
	s_setprio 1
	v_readfirstlane_b32 s73, v160
	v_lshl_add_u64 v[238:239], v[238:239], 0, s[46:47]
	s_mov_b32 m0, s73
	v_readfirstlane_b32 s73, v161
	s_barrier
; #define STAGE(P, BASE, LD, br, kt) do { const char* _g = (const char*)((BASE) + (size_t)(br) * (LD) + (size_t)(kt) * 64); \
;     for (int _i = 0; _i < 2; ++_i) { int _b = tidx * 16 + _i * 8192; int _r, _c; stage_rc(_b, _r, _c); \
;       __builtin_amdgcn_global_load_lds((const unsigned*)(_g + (unsigned)((_r * (LD) + _c) * 2)), (unsigned*)((char*)(P) + _b), 16, 0, 0); } } while (0)
; #define LDA(dst, b, h) for (int m = 0; m < 4; ++m) for (int k = 0; k < 2; ++k) \
;     dst[m][k] = *reinterpret_cast<const bf16x8*>((char*)SA(b, h) + lds_byte(wr * 64 + m * 16 + fr, k * 32 + fq * 8))
; #define LDB(dst, b, h) for (int n = 0; n < 2; ++n) for (int k = 0; k < 2; ++k) \
;     dst[n][k] = *reinterpret_cast<const bf16x8*>((char*)SB(b, h) + lds_byte(wc * 32 + n * 16 + fr, k * 32 + fq * 8))
; #define MMA(ai, bj, At_, Bt_) do { __builtin_amdgcn_s_setprio(1); \
;     for (int k = 0; k < 2; ++k) for (int m = 0; m < 4; ++m) for (int n = 0; n < 2; ++n) \
;       acc[ai][bj][m][n] = __builtin_amdgcn_mfma_f32_16x16x32_bf16(At_[m][k], Bt_[n][k], acc[ai][bj][m][n], 0, 0, 0); \
;     __builtin_amdgcn_s_setprio(0); } while (0)
; #define WAIT_V(n) asm volatile("s_waitcnt vmcnt(" #n ")" ::: "memory")
; #define WAIT_L(n) asm volatile("s_waitcnt lgkmcnt(" #n ")" ::: "memory")
; #define BAR __builtin_amdgcn_s_barrier()
; #define SCHED __builtin_amdgcn_sched_barrier(0)
; template <int EPI, int lda, int ldb, int N, int K>
; __device__ __forceinline__ void gemm_phase(const u16* __restrict__ A, const u16* __restrict__ Bt, const GemmEpi ep, int wv) {
;     ...
;       LDA(At, 1, 1); STAGE(SA(1, 0), Ab, lda, brow, t + 3);
;       BAR; WAIT_L(0); MMA(1, 0, At, B0); BAR; SCHED;
;       STAGE(SB(1, 1), Bt, ldb, bcol + HALF, t + 3);
;       WAIT_V(6); BAR; MMA(1, 1, At, B1); BAR;
;     }
;     { LDB(B0, 0, 0); LDA(At, 0, 0); STAGE(SA(1, 1), Ab, lda, brow + HALF, nt - 1);
;       BAR; WAIT_L(0); MMA(0, 0, At, B0); BAR;
;       LDB(B1, 0, 1); BAR; WAIT_L(0); MMA(0, 1, At, B1); BAR;
	ds_read_b128 v[190:193], v155 offset:49152
	ds_read_b128 v[194:197], v155 offset:50176
	ds_read_b128 v[198:201], v154 offset:49152
	ds_read_b128 v[202:205], v154 offset:50176
	ds_read_b128 v[206:209], v153 offset:49152
	ds_read_b128 v[210:213], v153 offset:50176
	ds_read_b128 v[214:217], v152 offset:49152
	ds_read_b128 v[218:221], v152 offset:50176
	global_load_lds_dwordx4 v[238:239], off
	v_lshl_add_u64 v[238:239], v[240:241], 0, s[46:47]
	s_mov_b32 m0, s73
	s_nop 0
	global_load_lds_dwordx4 v[238:239], off
	s_barrier
	s_waitcnt lgkmcnt(0)
	s_setprio 0
	s_waitcnt lgkmcnt(0)
	v_mfma_f32_16x16x32_bf16 v[60:63], v[174:177], v[190:193], v[60:63]
	v_mfma_f32_16x16x32_bf16 v[56:59], v[182:185], v[190:193], v[56:59]
	v_mfma_f32_16x16x32_bf16 v[52:55], v[174:177], v[198:201], v[52:55]
	v_mfma_f32_16x16x32_bf16 v[48:51], v[182:185], v[198:201], v[48:51]
	v_mfma_f32_16x16x32_bf16 v[44:47], v[174:177], v[206:209], v[44:47]
	v_mfma_f32_16x16x32_bf16 v[40:43], v[182:185], v[206:209], v[40:43]
	v_mfma_f32_16x16x32_bf16 v[36:39], v[174:177], v[214:217], v[36:39]
	v_mfma_f32_16x16x32_bf16 v[32:35], v[182:185], v[214:217], v[32:35]
	v_mfma_f32_16x16x32_bf16 v[60:63], v[178:181], v[194:197], v[60:63]
	v_mfma_f32_16x16x32_bf16 v[56:59], v[186:189], v[194:197], v[56:59]
	v_mfma_f32_16x16x32_bf16 v[52:55], v[178:181], v[202:205], v[52:55]
	v_mfma_f32_16x16x32_bf16 v[48:51], v[186:189], v[202:205], v[48:51]
	v_mfma_f32_16x16x32_bf16 v[44:47], v[178:181], v[210:213], v[44:47]
	v_mfma_f32_16x16x32_bf16 v[40:43], v[186:189], v[210:213], v[40:43]
	v_mfma_f32_16x16x32_bf16 v[36:39], v[178:181], v[218:221], v[36:39]
	v_mfma_f32_16x16x32_bf16 v[32:35], v[186:189], v[218:221], v[32:35]
	s_setprio 1
	s_barrier
	v_readfirstlane_b32 s73, v162
	v_add_u32_e32 v176, 0x2000, v162
	v_lshl_add_u64 v[174:175], v[246:247], 0, s[48:49]
	s_mov_b32 m0, s73
	v_readfirstlane_b32 s73, v176
	global_load_lds_dwordx4 v[174:175], off
	v_lshl_add_u64 v[174:175], v[248:249], 0, s[48:49]
	s_mov_b32 m0, s73
	s_nop 0
	global_load_lds_dwordx4 v[174:175], off
	s_waitcnt vmcnt(6)
	s_barrier
	s_setprio 0
	v_mfma_f32_16x16x32_bf16 v[28:31], v[222:225], v[190:193], v[28:31]
	v_mfma_f32_16x16x32_bf16 v[24:27], v[230:233], v[190:193], v[24:27]
	v_mfma_f32_16x16x32_bf16 v[20:23], v[222:225], v[198:201], v[20:23]
	v_mfma_f32_16x16x32_bf16 v[16:19], v[230:233], v[198:201], v[16:19]
	v_mfma_f32_16x16x32_bf16 v[12:15], v[222:225], v[206:209], v[12:15]
	v_mfma_f32_16x16x32_bf16 v[8:11], v[230:233], v[206:209], v[8:11]
	v_mfma_f32_16x16x32_bf16 v[4:7], v[222:225], v[214:217], v[4:7]
	v_mfma_f32_16x16x32_bf16 v[0:3], v[230:233], v[214:217], v[0:3]
	v_mfma_f32_16x16x32_bf16 v[28:31], v[226:229], v[194:197], v[28:31]
	v_mfma_f32_16x16x32_bf16 v[24:27], v[234:237], v[194:197], v[24:27]
	v_mfma_f32_16x16x32_bf16 v[20:23], v[226:229], v[202:205], v[20:23]
	v_mfma_f32_16x16x32_bf16 v[16:19], v[234:237], v[202:205], v[16:19]
	v_mfma_f32_16x16x32_bf16 v[12:15], v[226:229], v[210:213], v[12:15]
	v_mfma_f32_16x16x32_bf16 v[8:11], v[234:237], v[210:213], v[8:11]
	v_mfma_f32_16x16x32_bf16 v[4:7], v[226:229], v[218:221], v[4:7]
	v_mfma_f32_16x16x32_bf16 v[0:3], v[234:237], v[218:221], v[0:3]
	s_setprio 1
	s_add_i32 s72, s72, 2
	s_add_u32 s50, s50, 0x100
	s_addc_u32 s51, s51, 0
	s_cmpk_gt_u32 s72, 0x51
	s_barrier
	s_cbranch_scc0 .LBB0_838
	s_add_i32 s50, s18, 0x80
	s_mul_hi_i32 s51, s50, 0x2b00
	s_mulk_i32 s50, 0x2b00
	s_add_u32 s50, s56, s50
	s_addc_u32 s51, s57, s51
	s_add_u32 s50, s50, 0x2a80
	s_addc_u32 s51, s51, 0
	v_readfirstlane_b32 s72, v172
	v_lshl_add_u64 v[160:161], s[50:51], 0, v[128:129]
	s_mov_b32 m0, s72
	ds_read_b128 v[134:137], v164
	ds_read_b128 v[138:141], v164 offset:1024
	ds_read_b128 v[142:145], v164 offset:2048
	ds_read_b128 v[174:177], v164 offset:3072
	ds_read_b128 v[178:181], v155
	ds_read_b128 v[182:185], v155 offset:1024
	ds_read_b128 v[186:189], v154
	ds_read_b128 v[190:193], v154 offset:1024
	ds_read_b128 v[194:197], v153
	ds_read_b128 v[198:201], v153 offset:1024
	ds_read_b128 v[202:205], v152
	ds_read_b128 v[206:209], v152 offset:1024
	global_load_lds_dwordx4 v[160:161], off
	v_lshl_add_u64 v[160:161], s[50:51], 0, v[132:133]
	v_readfirstlane_b32 s50, v173
	s_mov_b32 m0, s50
	s_nop 0
	global_load_lds_dwordx4 v[160:161], off
	s_barrier
	s_waitcnt lgkmcnt(0)
	s_setprio 0
	s_waitcnt lgkmcnt(0)
	v_mfma_f32_16x16x32_bf16 v[124:127], v[134:137], v[178:181], v[124:127]
	v_mfma_f32_16x16x32_bf16 v[120:123], v[142:145], v[178:181], v[120:123]
	v_mfma_f32_16x16x32_bf16 v[116:119], v[134:137], v[186:189], v[116:119]
	v_mfma_f32_16x16x32_bf16 v[112:115], v[142:145], v[186:189], v[112:115]
	v_mfma_f32_16x16x32_bf16 v[108:111], v[134:137], v[194:197], v[108:111]
	v_mfma_f32_16x16x32_bf16 v[104:107], v[142:145], v[194:197], v[104:107]
	v_mfma_f32_16x16x32_bf16 v[100:103], v[134:137], v[202:205], v[100:103]
	v_mfma_f32_16x16x32_bf16 v[96:99], v[142:145], v[202:205], v[96:99]
	v_mfma_f32_16x16x32_bf16 v[124:127], v[138:141], v[182:185], v[124:127]
	v_mfma_f32_16x16x32_bf16 v[120:123], v[174:177], v[182:185], v[120:123]
	v_mfma_f32_16x16x32_bf16 v[116:119], v[138:141], v[190:193], v[116:119]
	v_mfma_f32_16x16x32_bf16 v[112:115], v[174:177], v[190:193], v[112:115]
	v_mfma_f32_16x16x32_bf16 v[108:111], v[138:141], v[198:201], v[108:111]
	v_mfma_f32_16x16x32_bf16 v[104:107], v[174:177], v[198:201], v[104:107]
	v_mfma_f32_16x16x32_bf16 v[100:103], v[138:141], v[206:209], v[100:103]
	v_mfma_f32_16x16x32_bf16 v[96:99], v[174:177], v[206:209], v[96:99]
	s_setprio 1
	s_barrier
	ds_read_b128 v[210:213], v163
	ds_read_b128 v[214:217], v163 offset:1024
	ds_read_b128 v[218:221], v163 offset:2048
	ds_read_b128 v[160:163], v163 offset:3072
	s_barrier
; #define LDA(dst, b, h) for (int m = 0; m < 4; ++m) for (int k = 0; k < 2; ++k) \
;     dst[m][k] = *reinterpret_cast<const bf16x8*>((char*)SA(b, h) + lds_byte(wr * 64 + m * 16 + fr, k * 32 + fq * 8))
; #define LDB(dst, b, h) for (int n = 0; n < 2; ++n) for (int k = 0; k < 2; ++k) \
;     dst[n][k] = *reinterpret_cast<const bf16x8*>((char*)SB(b, h) + lds_byte(wc * 32 + n * 16 + fr, k * 32 + fq * 8))
; #define MMA(ai, bj, At_, Bt_) do { __builtin_amdgcn_s_setprio(1); \
;     for (int k = 0; k < 2; ++k) for (int m = 0; m < 4; ++m) for (int n = 0; n < 2; ++n) \
;       acc[ai][bj][m][n] = __builtin_amdgcn_mfma_f32_16x16x32_bf16(At_[m][k], Bt_[n][k], acc[ai][bj][m][n], 0, 0, 0); \
;     __builtin_amdgcn_s_setprio(0); } while (0)
; #define WAIT_V(n) asm volatile("s_waitcnt vmcnt(" #n ")" ::: "memory")
; #define WAIT_L(n) asm volatile("s_waitcnt lgkmcnt(" #n ")" ::: "memory")
; #define BAR __builtin_amdgcn_s_barrier()
; template <int EPI, int lda, int ldb, int N, int K>
; __device__ __forceinline__ void gemm_phase(const u16* __restrict__ A, const u16* __restrict__ Bt, const GemmEpi ep, int wv) {
;     ...
;       LDB(B1, 0, 1); BAR; WAIT_L(0); MMA(0, 1, At, B1); BAR;
;       LDA(At, 0, 1); WAIT_V(4); BAR; WAIT_L(0); MMA(1, 0, At, B0); MMA(1, 1, At, B1); BAR; }
;     { LDB(B0, 1, 0); LDA(At, 1, 0); WAIT_V(2); BAR; WAIT_L(0); MMA(0, 0, At, B0); BAR;
	s_waitcnt lgkmcnt(0)
	s_setprio 0
	s_waitcnt lgkmcnt(0)
	v_mfma_f32_16x16x32_bf16 v[92:95], v[210:213], v[178:181], v[92:95]
	v_mfma_f32_16x16x32_bf16 v[88:91], v[218:221], v[178:181], v[88:91]
	v_mfma_f32_16x16x32_bf16 v[76:79], v[210:213], v[194:197], v[76:79]
	v_mfma_f32_16x16x32_bf16 v[72:75], v[218:221], v[194:197], v[72:75]
	v_mfma_f32_16x16x32_bf16 v[84:87], v[210:213], v[186:189], v[84:87]
	v_mfma_f32_16x16x32_bf16 v[80:83], v[218:221], v[186:189], v[80:83]
	v_mfma_f32_16x16x32_bf16 v[68:71], v[210:213], v[202:205], v[68:71]
	v_mfma_f32_16x16x32_bf16 v[64:67], v[218:221], v[202:205], v[64:67]
	v_mfma_f32_16x16x32_bf16 v[92:95], v[214:217], v[182:185], v[92:95]
	v_mfma_f32_16x16x32_bf16 v[88:91], v[160:163], v[182:185], v[88:91]
	v_mfma_f32_16x16x32_bf16 v[76:79], v[214:217], v[198:201], v[76:79]
	v_mfma_f32_16x16x32_bf16 v[72:75], v[160:163], v[198:201], v[72:75]
	v_mfma_f32_16x16x32_bf16 v[178:181], v[214:217], v[190:193], v[84:87]
	v_mfma_f32_16x16x32_bf16 v[182:185], v[160:163], v[190:193], v[80:83]
	v_mfma_f32_16x16x32_bf16 v[186:189], v[214:217], v[206:209], v[68:71]
	v_mfma_f32_16x16x32_bf16 v[190:193], v[160:163], v[206:209], v[64:67]
	s_setprio 1
	s_barrier
	s_nop 0
	ds_read_b128 v[64:67], v155 offset:16384
	ds_read_b128 v[68:71], v155 offset:17408
	ds_read_b128 v[80:83], v154 offset:16384
	ds_read_b128 v[84:87], v154 offset:17408
	ds_read_b128 v[194:197], v153 offset:16384
	ds_read_b128 v[198:201], v153 offset:17408
	ds_read_b128 v[202:205], v152 offset:16384
	ds_read_b128 v[206:209], v152 offset:17408
	s_waitcnt vmcnt(4)
	s_barrier
	s_waitcnt lgkmcnt(0)
	s_setprio 0
	s_waitcnt lgkmcnt(0)
	v_mfma_f32_16x16x32_bf16 v[60:63], v[134:137], v[64:67], v[60:63]
	v_mfma_f32_16x16x32_bf16 v[56:59], v[142:145], v[64:67], v[56:59]
	v_mfma_f32_16x16x32_bf16 v[52:55], v[134:137], v[80:83], v[52:55]
	v_mfma_f32_16x16x32_bf16 v[48:51], v[142:145], v[80:83], v[48:51]
	v_mfma_f32_16x16x32_bf16 v[44:47], v[134:137], v[194:197], v[44:47]
	v_mfma_f32_16x16x32_bf16 v[40:43], v[142:145], v[194:197], v[40:43]
	v_mfma_f32_16x16x32_bf16 v[36:39], v[134:137], v[202:205], v[36:39]
	v_mfma_f32_16x16x32_bf16 v[32:35], v[142:145], v[202:205], v[32:35]
	v_mfma_f32_16x16x32_bf16 v[60:63], v[138:141], v[68:71], v[60:63]
	v_mfma_f32_16x16x32_bf16 v[56:59], v[174:177], v[68:71], v[56:59]
	v_mfma_f32_16x16x32_bf16 v[52:55], v[138:141], v[84:87], v[52:55]
	v_mfma_f32_16x16x32_bf16 v[48:51], v[174:177], v[84:87], v[48:51]
	v_mfma_f32_16x16x32_bf16 v[44:47], v[138:141], v[198:201], v[44:47]
	v_mfma_f32_16x16x32_bf16 v[40:43], v[174:177], v[198:201], v[40:43]
	v_mfma_f32_16x16x32_bf16 v[36:39], v[138:141], v[206:209], v[36:39]
	v_mfma_f32_16x16x32_bf16 v[32:35], v[174:177], v[206:209], v[32:35]
	s_setprio 1
	s_setprio 0
	v_mfma_f32_16x16x32_bf16 v[28:31], v[210:213], v[64:67], v[28:31]
	v_mfma_f32_16x16x32_bf16 v[16:19], v[218:221], v[80:83], v[16:19]
	v_mfma_f32_16x16x32_bf16 v[12:15], v[210:213], v[194:197], v[12:15]
	v_mfma_f32_16x16x32_bf16 v[0:3], v[218:221], v[202:205], v[0:3]
	v_mfma_f32_16x16x32_bf16 v[24:27], v[218:221], v[64:67], v[24:27]
	v_mfma_f32_16x16x32_bf16 v[20:23], v[210:213], v[80:83], v[20:23]
	v_mfma_f32_16x16x32_bf16 v[8:11], v[218:221], v[194:197], v[8:11]
	v_mfma_f32_16x16x32_bf16 v[4:7], v[210:213], v[202:205], v[4:7]
	v_mfma_f32_16x16x32_bf16 v[28:31], v[214:217], v[68:71], v[28:31]
	v_mfma_f32_16x16x32_bf16 v[16:19], v[160:163], v[84:87], v[16:19]
	v_mfma_f32_16x16x32_bf16 v[12:15], v[214:217], v[198:201], v[12:15]
	v_mfma_f32_16x16x32_bf16 v[0:3], v[160:163], v[206:209], v[0:3]
	v_mfma_f32_16x16x32_bf16 v[134:137], v[160:163], v[68:71], v[24:27]
	v_mfma_f32_16x16x32_bf16 v[138:141], v[214:217], v[84:87], v[20:23]
	v_mfma_f32_16x16x32_bf16 v[142:145], v[160:163], v[198:201], v[8:11]
	v_mfma_f32_16x16x32_bf16 v[172:175], v[214:217], v[206:209], v[4:7]
	s_setprio 1
	s_barrier
	s_nop 0
	ds_read_b128 v[4:7], v159
	ds_read_b128 v[8:11], v159 offset:1024
	ds_read_b128 v[20:23], v159 offset:2048
	ds_read_b128 v[158:161], v159 offset:3072
	ds_read_b128 v[24:27], v155 offset:32768
	ds_read_b128 v[194:197], v155 offset:33792
	ds_read_b128 v[198:201], v154 offset:32768
	ds_read_b128 v[202:205], v154 offset:33792
	ds_read_b128 v[206:209], v153 offset:32768
	ds_read_b128 v[210:213], v153 offset:33792
	ds_read_b128 v[214:217], v152 offset:32768
	ds_read_b128 v[218:221], v152 offset:33792
	s_waitcnt vmcnt(2)
	s_barrier
; #define UNR _Pragma("unroll")
; #define LDA(dst, b, h) for (int m = 0; m < 4; ++m) for (int k = 0; k < 2; ++k) \
;     dst[m][k] = *reinterpret_cast<const bf16x8*>((char*)SA(b, h) + lds_byte(wr * 64 + m * 16 + fr, k * 32 + fq * 8))
; #define LDB(dst, b, h) for (int n = 0; n < 2; ++n) for (int k = 0; k < 2; ++k) \
;     dst[n][k] = *reinterpret_cast<const bf16x8*>((char*)SB(b, h) + lds_byte(wc * 32 + n * 16 + fr, k * 32 + fq * 8))
; #define MMA(ai, bj, At_, Bt_) do { __builtin_amdgcn_s_setprio(1); \
;     for (int k = 0; k < 2; ++k) for (int m = 0; m < 4; ++m) for (int n = 0; n < 2; ++n) \
;       acc[ai][bj][m][n] = __builtin_amdgcn_mfma_f32_16x16x32_bf16(At_[m][k], Bt_[n][k], acc[ai][bj][m][n], 0, 0, 0); \
;     __builtin_amdgcn_s_setprio(0); } while (0)
; #define WAIT_V(n) asm volatile("s_waitcnt vmcnt(" #n ")" ::: "memory")
; #define WAIT_L(n) asm volatile("s_waitcnt lgkmcnt(" #n ")" ::: "memory")
; #define BAR __builtin_amdgcn_s_barrier()
; #define STAGE4(BROW, BCOL, PN) do { const u16* Ab_ = A + (EPI == EPI_RG ? ((PN) >> 1) * 256 : 0); \
;     STAGE(SB(0, 0), Bt, ldb, (BCOL), 0); STAGE(SA(0, 0), Ab_, lda, (BROW), 0); \
;     STAGE(SB(0, 1), Bt, ldb, (BCOL) + HALF, 0); STAGE(SA(0, 1), Ab_, lda, (BROW) + HALF, 0); } while (0)
; template <int EPI, int lda, int ldb, int N, int K>
; __device__ __forceinline__ void gemm_phase(const u16* __restrict__ A, const u16* __restrict__ Bt, const GemmEpi ep, int wv) {
;     ...
;     { LDB(B0, 1, 0); LDA(At, 1, 0); WAIT_V(2); BAR; WAIT_L(0); MMA(0, 0, At, B0); BAR;
;       LDB(B1, 1, 1); WAIT_V(0); BAR; WAIT_L(0); MMA(0, 1, At, B1); BAR;
;       LDA(At, 1, 1); BAR; WAIT_L(0); MMA(1, 0, At, B0); MMA(1, 1, At, B1); BAR; }
;     if (wr == 0) BAR;
;     int ntile = 0, nbrow = 0, nbcol = 0, npn = 0; bool more = false;
;     if constexpr (PF) { ntile = tile + gridDim.x; more = ntile < nwg; if (more) { TILE_COORDS(ntile, nbrow, nbcol, npn); STAGE4(nbrow, nbcol, npn); } }
;     float nss[8];
;     if constexpr (CONS) { UNR for (int pp = 0; pp < 8; ++pp) nss[pp] = 0.f;
;       if (more && tidx < 256) { UNR for (int pp = 0; pp < 8; ++pp) nss[pp] = ep.ss_in[(size_t)pp * T + nbrow + tidx]; } }
	s_waitcnt lgkmcnt(0)
	s_setprio 0
	s_waitcnt lgkmcnt(0)
	v_mfma_f32_16x16x32_bf16 v[64:67], v[4:7], v[24:27], v[124:127]
	v_mfma_f32_16x16x32_bf16 v[68:71], v[20:23], v[24:27], v[120:123]
	v_mfma_f32_16x16x32_bf16 v[80:83], v[4:7], v[198:201], v[116:119]
	v_mfma_f32_16x16x32_bf16 v[84:87], v[20:23], v[198:201], v[112:115]
	v_mfma_f32_16x16x32_bf16 v[108:111], v[4:7], v[206:209], v[108:111]
	v_mfma_f32_16x16x32_bf16 v[104:107], v[20:23], v[206:209], v[104:107]
	v_mfma_f32_16x16x32_bf16 v[120:123], v[4:7], v[214:217], v[100:103]
	v_mfma_f32_16x16x32_bf16 v[124:127], v[20:23], v[214:217], v[96:99]
	v_mfma_f32_16x16x32_bf16 v[116:119], v[8:11], v[194:197], v[64:67]
	v_mfma_f32_16x16x32_bf16 v[112:115], v[158:161], v[194:197], v[68:71]
	v_mfma_f32_16x16x32_bf16 v[100:103], v[8:11], v[202:205], v[80:83]
	v_mfma_f32_16x16x32_bf16 v[96:99], v[158:161], v[202:205], v[84:87]
	v_mfma_f32_16x16x32_bf16 v[84:87], v[8:11], v[210:213], v[108:111]
	v_mfma_f32_16x16x32_bf16 v[80:83], v[158:161], v[210:213], v[104:107]
	v_mfma_f32_16x16x32_bf16 v[68:71], v[8:11], v[218:221], v[120:123]
	v_mfma_f32_16x16x32_bf16 v[64:67], v[158:161], v[218:221], v[124:127]
	s_setprio 1
	s_barrier
	ds_read_b128 v[222:225], v157
	ds_read_b128 v[226:229], v157 offset:1024
	ds_read_b128 v[230:233], v157 offset:2048
	ds_read_b128 v[234:237], v157 offset:3072
	s_waitcnt vmcnt(0)
	s_barrier
	s_waitcnt lgkmcnt(0)
	s_setprio 0
	s_waitcnt lgkmcnt(0)
	v_mfma_f32_16x16x32_bf16 v[92:95], v[222:225], v[24:27], v[92:95]
	v_mfma_f32_16x16x32_bf16 v[24:27], v[230:233], v[24:27], v[88:91]
	v_mfma_f32_16x16x32_bf16 v[88:91], v[222:225], v[198:201], v[178:181]
	v_mfma_f32_16x16x32_bf16 v[104:107], v[230:233], v[198:201], v[182:185]
	v_mfma_f32_16x16x32_bf16 v[76:79], v[222:225], v[206:209], v[76:79]
	v_mfma_f32_16x16x32_bf16 v[72:75], v[230:233], v[206:209], v[72:75]
	v_mfma_f32_16x16x32_bf16 v[176:179], v[222:225], v[214:217], v[186:189]
	v_mfma_f32_16x16x32_bf16 v[180:183], v[230:233], v[214:217], v[190:193]
	v_mfma_f32_16x16x32_bf16 v[124:127], v[226:229], v[194:197], v[92:95]
	v_mfma_f32_16x16x32_bf16 v[120:123], v[234:237], v[194:197], v[24:27]
	v_mfma_f32_16x16x32_bf16 v[108:111], v[226:229], v[202:205], v[88:91]
	v_mfma_f32_16x16x32_bf16 v[104:107], v[234:237], v[202:205], v[104:107]
	v_mfma_f32_16x16x32_bf16 v[92:95], v[226:229], v[210:213], v[76:79]
	v_mfma_f32_16x16x32_bf16 v[88:91], v[234:237], v[210:213], v[72:75]
	v_mfma_f32_16x16x32_bf16 v[76:79], v[226:229], v[218:221], v[176:179]
	v_mfma_f32_16x16x32_bf16 v[72:75], v[234:237], v[218:221], v[180:183]
	s_setprio 1
	s_barrier
	ds_read_b128 v[176:179], v155 offset:49152
	ds_read_b128 v[180:183], v155 offset:50176
	ds_read_b128 v[184:187], v154 offset:49152
	ds_read_b128 v[154:157], v154 offset:50176
	ds_read_b128 v[188:191], v153 offset:49152
	ds_read_b128 v[192:195], v153 offset:50176
	ds_read_b128 v[196:199], v152 offset:49152
	ds_read_b128 v[200:203], v152 offset:50176
	s_barrier
	s_waitcnt lgkmcnt(0)
	s_setprio 0
	s_waitcnt lgkmcnt(0)
	v_mfma_f32_16x16x32_bf16 v[24:27], v[4:7], v[176:179], v[60:63]
	v_mfma_f32_16x16x32_bf16 v[60:63], v[20:23], v[176:179], v[56:59]
	v_mfma_f32_16x16x32_bf16 v[204:207], v[4:7], v[184:187], v[52:55]
	v_mfma_f32_16x16x32_bf16 v[48:51], v[20:23], v[184:187], v[48:51]
	v_mfma_f32_16x16x32_bf16 v[44:47], v[4:7], v[188:191], v[44:47]
	v_mfma_f32_16x16x32_bf16 v[208:211], v[20:23], v[188:191], v[40:43]
	v_mfma_f32_16x16x32_bf16 v[4:7], v[4:7], v[196:199], v[36:39]
	v_mfma_f32_16x16x32_bf16 v[32:35], v[20:23], v[196:199], v[32:35]
	v_mfma_f32_16x16x32_bf16 v[56:59], v[8:11], v[180:183], v[24:27]
	v_mfma_f32_16x16x32_bf16 v[52:55], v[158:161], v[180:183], v[60:63]
	v_mfma_f32_16x16x32_bf16 v[40:43], v[8:11], v[154:157], v[204:207]
	v_mfma_f32_16x16x32_bf16 v[36:39], v[158:161], v[154:157], v[48:51]
	v_mfma_f32_16x16x32_bf16 v[24:27], v[8:11], v[192:195], v[44:47]
	v_mfma_f32_16x16x32_bf16 v[20:23], v[158:161], v[192:195], v[208:211]
	v_mfma_f32_16x16x32_bf16 v[8:11], v[8:11], v[200:203], v[4:7]
	v_mfma_f32_16x16x32_bf16 v[4:7], v[158:161], v[200:203], v[32:35]
	s_setprio 1
	s_setprio 0
	v_mfma_f32_16x16x32_bf16 v[28:31], v[222:225], v[176:179], v[28:31]
	v_mfma_f32_16x16x32_bf16 v[32:35], v[230:233], v[176:179], v[134:137]
	v_mfma_f32_16x16x32_bf16 v[44:47], v[222:225], v[184:187], v[138:141]
	v_mfma_f32_16x16x32_bf16 v[16:19], v[230:233], v[184:187], v[16:19]
	v_mfma_f32_16x16x32_bf16 v[12:15], v[222:225], v[188:191], v[12:15]
	v_mfma_f32_16x16x32_bf16 v[134:137], v[230:233], v[188:191], v[142:145]
	v_mfma_f32_16x16x32_bf16 v[138:141], v[222:225], v[196:199], v[172:175]
	v_mfma_f32_16x16x32_bf16 v[0:3], v[230:233], v[196:199], v[0:3]
	v_mfma_f32_16x16x32_bf16 v[60:63], v[226:229], v[180:183], v[28:31]
	v_mfma_f32_16x16x32_bf16 v[48:51], v[234:237], v[180:183], v[32:35]
	v_mfma_f32_16x16x32_bf16 v[44:47], v[226:229], v[154:157], v[44:47]
	v_mfma_f32_16x16x32_bf16 v[32:35], v[234:237], v[154:157], v[16:19]
	v_mfma_f32_16x16x32_bf16 v[28:31], v[226:229], v[192:195], v[12:15]
	v_mfma_f32_16x16x32_bf16 v[16:19], v[234:237], v[192:195], v[134:137]
	v_mfma_f32_16x16x32_bf16 v[12:15], v[226:229], v[200:203], v[138:141]
	v_mfma_f32_16x16x32_bf16 v[0:3], v[234:237], v[200:203], v[0:3]
	s_setprio 1
	v_cmp_gt_u32_e32 vcc, s69, v130
	s_barrier
	s_and_saveexec_b64 s[50:51], vcc
	s_cbranch_execz .LBB0_841
	s_barrier

; #define STAGE(P, BASE, LD, br, kt) do { const char* _g = (const char*)((BASE) + (size_t)(br) * (LD) + (size_t)(kt) * 64); \
;     for (int _i = 0; _i < 2; ++_i) { int _b = tidx * 16 + _i * 8192; int _r, _c; stage_rc(_b, _r, _c); \
;       __builtin_amdgcn_global_load_lds((const unsigned*)(_g + (unsigned)((_r * (LD) + _c) * 2)), (unsigned*)((char*)(P) + _b), 16, 0, 0); } } while (0)
; #define LDA(dst, b, h) for (int m = 0; m < 4; ++m) for (int k = 0; k < 2; ++k) \
;     dst[m][k] = *reinterpret_cast<const bf16x8*>((char*)SA(b, h) + lds_byte(wr * 64 + m * 16 + fr, k * 32 + fq * 8))
; #define LDB(dst, b, h) for (int n = 0; n < 2; ++n) for (int k = 0; k < 2; ++k) \
;     dst[n][k] = *reinterpret_cast<const bf16x8*>((char*)SB(b, h) + lds_byte(wc * 32 + n * 16 + fr, k * 32 + fq * 8))
; #define MMA(ai, bj, At_, Bt_) do { __builtin_amdgcn_s_setprio(1); \
;     for (int k = 0; k < 2; ++k) for (int m = 0; m < 4; ++m) for (int n = 0; n < 2; ++n) \
;       acc[ai][bj][m][n] = __builtin_amdgcn_mfma_f32_16x16x32_bf16(At_[m][k], Bt_[n][k], acc[ai][bj][m][n], 0, 0, 0); \
;     __builtin_amdgcn_s_setprio(0); } while (0)
; #define WAIT_L(n) asm volatile("s_waitcnt lgkmcnt(" #n ")" ::: "memory")
; #define BAR __builtin_amdgcn_s_barrier()
; #define SCHED __builtin_amdgcn_sched_barrier(0)
; template <int EPI, int lda, int ldb, int N, int K>
; __device__ __forceinline__ void gemm_phase(const u16* __restrict__ A, const u16* __restrict__ Bt, const GemmEpi ep, int wv) {
;     ...
;       LDB(B0, 0, 0); SCHED; LDA(At, 0, 0); STAGE(SA(1, 1), Ab, lda, brow + HALF, t + 1);
;       WAIT_L(8); BAR; WAIT_L(0); MMA(0, 0, At, B0); BAR; SCHED;
;       LDB(B1, 0, 1); STAGE(SB(0, 0), Bt, ldb, bcol, t + 2);
;       BAR; WAIT_L(0); MMA(0, 1, At, B1); BAR;
;       LDA(At, 0, 1); STAGE(SA(0, 0), Ab, lda, brow, t + 2);
;       BAR; WAIT_L(0); MMA(1, 0, At, B0); BAR; SCHED;
.LBB0_1147:
	ds_read_b128 v[172:175], v161
	ds_read_b128 v[176:179], v161 offset:1024
	ds_read_b128 v[180:183], v161 offset:2048
	ds_read_b128 v[184:187], v161 offset:3072
	v_add_u32_e32 v169, 0xc000, v148
	v_lshl_add_u64 v[236:237], v[138:139], 0, s[60:61]
	v_readfirstlane_b32 s63, v169
	v_add_u32_e32 v170, 0xe000, v148
	v_lshl_add_u64 v[162:163], v[236:237], 0, s[22:23]
	s_mov_b32 m0, s63
	v_lshl_add_u64 v[238:239], v[140:141], 0, s[60:61]
	v_readfirstlane_b32 s63, v170
	ds_read_b128 v[164:167], v152
	ds_read_b128 v[188:191], v152 offset:1024
	ds_read_b128 v[192:195], v151
	ds_read_b128 v[196:199], v151 offset:1024
	ds_read_b128 v[200:203], v150
	ds_read_b128 v[204:207], v150 offset:1024
	ds_read_b128 v[208:211], v149
	ds_read_b128 v[212:215], v149 offset:1024
	global_load_lds_dwordx4 v[162:163], off
	v_lshl_add_u64 v[162:163], v[238:239], 0, s[22:23]
	s_mov_b32 m0, s63
	s_nop 0
	global_load_lds_dwordx4 v[162:163], off
	s_waitcnt lgkmcnt(8)
	s_barrier
	s_waitcnt lgkmcnt(0)
	s_setprio 0
	s_waitcnt lgkmcnt(0)
	v_mfma_f32_16x16x32_bf16 v[124:127], v[164:167], v[172:175], v[124:127]
	v_mfma_f32_16x16x32_bf16 v[120:123], v[164:167], v[180:183], v[120:123]
	v_mfma_f32_16x16x32_bf16 v[116:119], v[192:195], v[172:175], v[116:119]
	v_mfma_f32_16x16x32_bf16 v[112:115], v[192:195], v[180:183], v[112:115]
	v_mfma_f32_16x16x32_bf16 v[108:111], v[200:203], v[172:175], v[108:111]
	v_mfma_f32_16x16x32_bf16 v[104:107], v[200:203], v[180:183], v[104:107]
	v_mfma_f32_16x16x32_bf16 v[100:103], v[208:211], v[172:175], v[100:103]
	v_mfma_f32_16x16x32_bf16 v[96:99], v[208:211], v[180:183], v[96:99]
	v_mfma_f32_16x16x32_bf16 v[124:127], v[188:191], v[176:179], v[124:127]
	v_mfma_f32_16x16x32_bf16 v[120:123], v[188:191], v[184:187], v[120:123]
	v_mfma_f32_16x16x32_bf16 v[116:119], v[196:199], v[176:179], v[116:119]
	v_mfma_f32_16x16x32_bf16 v[112:115], v[196:199], v[184:187], v[112:115]
	v_mfma_f32_16x16x32_bf16 v[108:111], v[204:207], v[176:179], v[108:111]
	v_mfma_f32_16x16x32_bf16 v[104:107], v[204:207], v[184:187], v[104:107]
	v_mfma_f32_16x16x32_bf16 v[100:103], v[212:215], v[176:179], v[100:103]
	v_mfma_f32_16x16x32_bf16 v[96:99], v[212:215], v[184:187], v[96:99]
	s_setprio 1
	s_barrier
	v_add_u32_e32 v162, s75, v154
	v_lshl_add_u64 v[240:241], v[134:135], 0, s[60:61]
	v_readfirstlane_b32 s63, v162
	v_add_u32_e32 v163, 0x2000, v162
	v_lshl_add_u64 v[232:233], v[240:241], 0, s[24:25]
	s_mov_b32 m0, s63
	v_lshl_add_u64 v[242:243], v[136:137], 0, s[60:61]
	v_readfirstlane_b32 s63, v163
	ds_read_b128 v[216:219], v160
	ds_read_b128 v[220:223], v160 offset:1024
	ds_read_b128 v[224:227], v160 offset:2048
	ds_read_b128 v[228:231], v160 offset:3072
	global_load_lds_dwordx4 v[232:233], off
	v_lshl_add_u64 v[232:233], v[242:243], 0, s[24:25]
	s_mov_b32 m0, s63
	s_nop 0
	global_load_lds_dwordx4 v[232:233], off
	s_barrier
	s_waitcnt lgkmcnt(0)
	s_setprio 0
	s_waitcnt lgkmcnt(0)
	v_mfma_f32_16x16x32_bf16 v[92:95], v[164:167], v[216:219], v[92:95]
	v_mfma_f32_16x16x32_bf16 v[88:91], v[164:167], v[224:227], v[88:91]
	v_mfma_f32_16x16x32_bf16 v[84:87], v[192:195], v[216:219], v[84:87]
	v_mfma_f32_16x16x32_bf16 v[80:83], v[192:195], v[224:227], v[80:83]
	v_mfma_f32_16x16x32_bf16 v[76:79], v[200:203], v[216:219], v[76:79]
	v_mfma_f32_16x16x32_bf16 v[72:75], v[200:203], v[224:227], v[72:75]
	v_mfma_f32_16x16x32_bf16 v[68:71], v[208:211], v[216:219], v[68:71]
	v_mfma_f32_16x16x32_bf16 v[64:67], v[208:211], v[224:227], v[64:67]
	v_mfma_f32_16x16x32_bf16 v[92:95], v[188:191], v[220:223], v[92:95]
	v_mfma_f32_16x16x32_bf16 v[88:91], v[188:191], v[228:231], v[88:91]
	v_mfma_f32_16x16x32_bf16 v[84:87], v[196:199], v[220:223], v[84:87]
	v_mfma_f32_16x16x32_bf16 v[80:83], v[196:199], v[228:231], v[80:83]
	v_mfma_f32_16x16x32_bf16 v[76:79], v[204:207], v[220:223], v[76:79]
	v_mfma_f32_16x16x32_bf16 v[72:75], v[204:207], v[228:231], v[72:75]
	v_mfma_f32_16x16x32_bf16 v[68:71], v[212:215], v[220:223], v[68:71]
	v_mfma_f32_16x16x32_bf16 v[64:67], v[212:215], v[228:231], v[64:67]
	s_setprio 1
	v_readfirstlane_b32 s63, v148
	v_lshl_add_u64 v[164:165], v[236:237], 0, s[26:27]
	s_mov_b32 m0, s63
	s_barrier
	ds_read_b128 v[188:191], v152 offset:16384
	ds_read_b128 v[192:195], v152 offset:17408
	ds_read_b128 v[196:199], v151 offset:16384
	ds_read_b128 v[200:203], v151 offset:17408
	ds_read_b128 v[204:207], v150 offset:16384
	ds_read_b128 v[208:211], v150 offset:17408
	ds_read_b128 v[212:215], v149 offset:16384
	ds_read_b128 v[232:235], v149 offset:17408
	global_load_lds_dwordx4 v[164:165], off
	v_add_u32_e32 v164, 0x2000, v148
	v_lshl_add_u64 v[166:167], v[238:239], 0, s[26:27]
	v_readfirstlane_b32 s63, v164
	s_mov_b32 m0, s63
	s_nop 0
	global_load_lds_dwordx4 v[166:167], off
	s_barrier
	s_waitcnt lgkmcnt(0)
	s_setprio 0
	s_waitcnt lgkmcnt(0)
	v_mfma_f32_16x16x32_bf16 v[60:63], v[188:191], v[172:175], v[60:63]
	v_mfma_f32_16x16x32_bf16 v[56:59], v[188:191], v[180:183], v[56:59]
	v_mfma_f32_16x16x32_bf16 v[52:55], v[196:199], v[172:175], v[52:55]
	v_mfma_f32_16x16x32_bf16 v[48:51], v[196:199], v[180:183], v[48:51]
	v_mfma_f32_16x16x32_bf16 v[44:47], v[204:207], v[172:175], v[44:47]
	v_mfma_f32_16x16x32_bf16 v[40:43], v[204:207], v[180:183], v[40:43]
	v_mfma_f32_16x16x32_bf16 v[36:39], v[212:215], v[172:175], v[36:39]
	v_mfma_f32_16x16x32_bf16 v[32:35], v[212:215], v[180:183], v[32:35]
	v_mfma_f32_16x16x32_bf16 v[60:63], v[192:195], v[176:179], v[60:63]
	v_mfma_f32_16x16x32_bf16 v[56:59], v[192:195], v[184:187], v[56:59]
	v_mfma_f32_16x16x32_bf16 v[52:55], v[200:203], v[176:179], v[52:55]
	v_mfma_f32_16x16x32_bf16 v[48:51], v[200:203], v[184:187], v[48:51]
	v_mfma_f32_16x16x32_bf16 v[44:47], v[208:211], v[176:179], v[44:47]
	v_mfma_f32_16x16x32_bf16 v[40:43], v[208:211], v[184:187], v[40:43]
	v_mfma_f32_16x16x32_bf16 v[36:39], v[232:235], v[176:179], v[36:39]
	v_mfma_f32_16x16x32_bf16 v[32:35], v[232:235], v[184:187], v[32:35]
	s_setprio 1
	s_barrier
; #define STAGE(P, BASE, LD, br, kt) do { const char* _g = (const char*)((BASE) + (size_t)(br) * (LD) + (size_t)(kt) * 64); \
;     for (int _i = 0; _i < 2; ++_i) { int _b = tidx * 16 + _i * 8192; int _r, _c; stage_rc(_b, _r, _c); \
;       __builtin_amdgcn_global_load_lds((const unsigned*)(_g + (unsigned)((_r * (LD) + _c) * 2)), (unsigned*)((char*)(P) + _b), 16, 0, 0); } } while (0)
; #define LDA(dst, b, h) for (int m = 0; m < 4; ++m) for (int k = 0; k < 2; ++k) \
;     dst[m][k] = *reinterpret_cast<const bf16x8*>((char*)SA(b, h) + lds_byte(wr * 64 + m * 16 + fr, k * 32 + fq * 8))
; #define LDB(dst, b, h) for (int n = 0; n < 2; ++n) for (int k = 0; k < 2; ++k) \
;     dst[n][k] = *reinterpret_cast<const bf16x8*>((char*)SB(b, h) + lds_byte(wc * 32 + n * 16 + fr, k * 32 + fq * 8))
; #define MMA(ai, bj, At_, Bt_) do { __builtin_amdgcn_s_setprio(1); \
;     for (int k = 0; k < 2; ++k) for (int m = 0; m < 4; ++m) for (int n = 0; n < 2; ++n) \
;       acc[ai][bj][m][n] = __builtin_amdgcn_mfma_f32_16x16x32_bf16(At_[m][k], Bt_[n][k], acc[ai][bj][m][n], 0, 0, 0); \
;     __builtin_amdgcn_s_setprio(0); } while (0)
; #define WAIT_V(n) asm volatile("s_waitcnt vmcnt(" #n ")" ::: "memory")
; #define WAIT_L(n) asm volatile("s_waitcnt lgkmcnt(" #n ")" ::: "memory")
; #define BAR __builtin_amdgcn_s_barrier()
; #define SCHED __builtin_amdgcn_sched_barrier(0)
; template <int EPI, int lda, int ldb, int N, int K>
; __device__ __forceinline__ void gemm_phase(const u16* __restrict__ A, const u16* __restrict__ Bt, const GemmEpi ep, int wv) {
;     ...
;       STAGE(SB(0, 1), Bt, ldb, bcol + HALF, t + 2);
;       WAIT_V(6); BAR; MMA(1, 1, At, B1); BAR;
;       LDB(B0, 1, 0); SCHED; LDA(At, 1, 0); STAGE(SA(0, 1), Ab, lda, brow + HALF, t + 2);
;       WAIT_L(8); BAR; WAIT_L(0); MMA(0, 0, At, B0); BAR; SCHED;
;       LDB(B1, 1, 1); STAGE(SB(1, 0), Bt, ldb, bcol, t + 3);
;       BAR; WAIT_L(0); MMA(0, 1, At, B1); BAR;
	v_add_u32_e32 v165, s76, v154
	v_lshl_add_u64 v[166:167], v[240:241], 0, s[40:41]
	v_readfirstlane_b32 s63, v165
	s_mov_b32 m0, s63
	v_lshl_add_u64 v[172:173], v[242:243], 0, s[40:41]
	global_load_lds_dwordx4 v[166:167], off
	v_add_u32_e32 v166, 0x2000, v165
	s_nop 0
	v_readfirstlane_b32 s63, v166
	s_mov_b32 m0, s63
	s_nop 0
	global_load_lds_dwordx4 v[172:173], off
	s_waitcnt vmcnt(6)
	s_barrier
	s_setprio 0
	v_mfma_f32_16x16x32_bf16 v[28:31], v[188:191], v[216:219], v[28:31]
	v_mfma_f32_16x16x32_bf16 v[24:27], v[188:191], v[224:227], v[24:27]
	v_mfma_f32_16x16x32_bf16 v[20:23], v[196:199], v[216:219], v[20:23]
	v_mfma_f32_16x16x32_bf16 v[16:19], v[196:199], v[224:227], v[16:19]
	v_mfma_f32_16x16x32_bf16 v[12:15], v[204:207], v[216:219], v[12:15]
	v_mfma_f32_16x16x32_bf16 v[8:11], v[204:207], v[224:227], v[8:11]
	v_mfma_f32_16x16x32_bf16 v[4:7], v[212:215], v[216:219], v[4:7]
	v_mfma_f32_16x16x32_bf16 v[0:3], v[212:215], v[224:227], v[0:3]
	v_mfma_f32_16x16x32_bf16 v[28:31], v[192:195], v[220:223], v[28:31]
	v_mfma_f32_16x16x32_bf16 v[24:27], v[192:195], v[228:231], v[24:27]
	v_mfma_f32_16x16x32_bf16 v[20:23], v[200:203], v[220:223], v[20:23]
	v_mfma_f32_16x16x32_bf16 v[16:19], v[200:203], v[228:231], v[16:19]
	v_mfma_f32_16x16x32_bf16 v[12:15], v[208:211], v[220:223], v[12:15]
	v_mfma_f32_16x16x32_bf16 v[8:11], v[208:211], v[228:231], v[8:11]
	v_mfma_f32_16x16x32_bf16 v[4:7], v[232:235], v[220:223], v[4:7]
	v_mfma_f32_16x16x32_bf16 v[0:3], v[232:235], v[228:231], v[0:3]
	s_setprio 1
	s_barrier
	ds_read_b128 v[172:175], v155
	ds_read_b128 v[176:179], v155 offset:1024
	ds_read_b128 v[180:183], v155 offset:2048
	ds_read_b128 v[184:187], v155 offset:3072
	v_add_u32_e32 v167, 0x4000, v148
	v_add_u32_e32 v168, 0x6000, v148
	v_readfirstlane_b32 s63, v167
	v_lshl_add_u64 v[220:221], v[236:237], 0, s[42:43]
	s_mov_b32 m0, s63
	v_readfirstlane_b32 s63, v168
	ds_read_b128 v[188:191], v152 offset:32768
	ds_read_b128 v[192:195], v152 offset:33792
	ds_read_b128 v[196:199], v151 offset:32768
	ds_read_b128 v[200:203], v151 offset:33792
	ds_read_b128 v[204:207], v150 offset:32768
	ds_read_b128 v[208:211], v150 offset:33792
	ds_read_b128 v[212:215], v149 offset:32768
	ds_read_b128 v[216:219], v149 offset:33792
	global_load_lds_dwordx4 v[220:221], off
	v_lshl_add_u64 v[220:221], v[238:239], 0, s[42:43]
	s_mov_b32 m0, s63
	s_nop 0
	global_load_lds_dwordx4 v[220:221], off
	s_waitcnt lgkmcnt(8)
	s_barrier
	s_waitcnt lgkmcnt(0)
	s_setprio 0
	s_waitcnt lgkmcnt(0)
	v_mfma_f32_16x16x32_bf16 v[124:127], v[188:191], v[172:175], v[124:127]
	v_mfma_f32_16x16x32_bf16 v[120:123], v[188:191], v[180:183], v[120:123]
	v_mfma_f32_16x16x32_bf16 v[116:119], v[196:199], v[172:175], v[116:119]
	v_mfma_f32_16x16x32_bf16 v[112:115], v[196:199], v[180:183], v[112:115]
	v_mfma_f32_16x16x32_bf16 v[108:111], v[204:207], v[172:175], v[108:111]
	v_mfma_f32_16x16x32_bf16 v[104:107], v[204:207], v[180:183], v[104:107]
	v_mfma_f32_16x16x32_bf16 v[100:103], v[212:215], v[172:175], v[100:103]
	v_mfma_f32_16x16x32_bf16 v[96:99], v[212:215], v[180:183], v[96:99]
	v_mfma_f32_16x16x32_bf16 v[124:127], v[192:195], v[176:179], v[124:127]
	v_mfma_f32_16x16x32_bf16 v[120:123], v[192:195], v[184:187], v[120:123]
	v_mfma_f32_16x16x32_bf16 v[116:119], v[200:203], v[176:179], v[116:119]
	v_mfma_f32_16x16x32_bf16 v[112:115], v[200:203], v[184:187], v[112:115]
	v_mfma_f32_16x16x32_bf16 v[108:111], v[208:211], v[176:179], v[108:111]
	v_mfma_f32_16x16x32_bf16 v[104:107], v[208:211], v[184:187], v[104:107]
	v_mfma_f32_16x16x32_bf16 v[100:103], v[216:219], v[176:179], v[100:103]
	v_mfma_f32_16x16x32_bf16 v[96:99], v[216:219], v[184:187], v[96:99]
	s_setprio 1
	s_barrier
	v_readfirstlane_b32 s63, v156
	v_add_u32_e32 v171, 0x2000, v156
	v_lshl_add_u64 v[244:245], v[240:241], 0, s[44:45]
	s_mov_b32 m0, s63
	v_readfirstlane_b32 s63, v171
	ds_read_b128 v[220:223], v153
	ds_read_b128 v[224:227], v153 offset:1024
	ds_read_b128 v[228:231], v153 offset:2048
	ds_read_b128 v[232:235], v153 offset:3072
	global_load_lds_dwordx4 v[244:245], off
	v_lshl_add_u64 v[244:245], v[242:243], 0, s[44:45]
	s_mov_b32 m0, s63
	s_nop 0
	global_load_lds_dwordx4 v[244:245], off
	s_barrier
	s_waitcnt lgkmcnt(0)
	s_setprio 0
	s_waitcnt lgkmcnt(0)
	v_mfma_f32_16x16x32_bf16 v[92:95], v[188:191], v[220:223], v[92:95]
	v_mfma_f32_16x16x32_bf16 v[88:91], v[188:191], v[228:231], v[88:91]
	v_mfma_f32_16x16x32_bf16 v[84:87], v[196:199], v[220:223], v[84:87]
	v_mfma_f32_16x16x32_bf16 v[80:83], v[196:199], v[228:231], v[80:83]
	v_mfma_f32_16x16x32_bf16 v[76:79], v[204:207], v[220:223], v[76:79]
	v_mfma_f32_16x16x32_bf16 v[72:75], v[204:207], v[228:231], v[72:75]
	v_mfma_f32_16x16x32_bf16 v[68:71], v[212:215], v[220:223], v[68:71]
	v_mfma_f32_16x16x32_bf16 v[64:67], v[212:215], v[228:231], v[64:67]
	v_mfma_f32_16x16x32_bf16 v[92:95], v[192:195], v[224:227], v[92:95]
	v_mfma_f32_16x16x32_bf16 v[88:91], v[192:195], v[232:235], v[88:91]
	v_mfma_f32_16x16x32_bf16 v[84:87], v[200:203], v[224:227], v[84:87]
	v_mfma_f32_16x16x32_bf16 v[80:83], v[200:203], v[232:235], v[80:83]
	v_mfma_f32_16x16x32_bf16 v[76:79], v[208:211], v[224:227], v[76:79]
	v_mfma_f32_16x16x32_bf16 v[72:75], v[208:211], v[232:235], v[72:75]
	v_mfma_f32_16x16x32_bf16 v[68:71], v[216:219], v[224:227], v[68:71]
	v_mfma_f32_16x16x32_bf16 v[64:67], v[216:219], v[232:235], v[64:67]
	s_setprio 1
	v_readfirstlane_b32 s63, v157
	v_lshl_add_u64 v[236:237], v[236:237], 0, s[46:47]
	s_mov_b32 m0, s63
	v_readfirstlane_b32 s63, v158
	s_barrier
; #define STAGE(P, BASE, LD, br, kt) do { const char* _g = (const char*)((BASE) + (size_t)(br) * (LD) + (size_t)(kt) * 64); \
;     for (int _i = 0; _i < 2; ++_i) { int _b = tidx * 16 + _i * 8192; int _r, _c; stage_rc(_b, _r, _c); \
;       __builtin_amdgcn_global_load_lds((const unsigned*)(_g + (unsigned)((_r * (LD) + _c) * 2)), (unsigned*)((char*)(P) + _b), 16, 0, 0); } } while (0)
; #define LDA(dst, b, h) for (int m = 0; m < 4; ++m) for (int k = 0; k < 2; ++k) \
;     dst[m][k] = *reinterpret_cast<const bf16x8*>((char*)SA(b, h) + lds_byte(wr * 64 + m * 16 + fr, k * 32 + fq * 8))
; #define LDB(dst, b, h) for (int n = 0; n < 2; ++n) for (int k = 0; k < 2; ++k) \
;     dst[n][k] = *reinterpret_cast<const bf16x8*>((char*)SB(b, h) + lds_byte(wc * 32 + n * 16 + fr, k * 32 + fq * 8))
; #define MMA(ai, bj, At_, Bt_) do { __builtin_amdgcn_s_setprio(1); \
;     for (int k = 0; k < 2; ++k) for (int m = 0; m < 4; ++m) for (int n = 0; n < 2; ++n) \
;       acc[ai][bj][m][n] = __builtin_amdgcn_mfma_f32_16x16x32_bf16(At_[m][k], Bt_[n][k], acc[ai][bj][m][n], 0, 0, 0); \
;     __builtin_amdgcn_s_setprio(0); } while (0)
; #define WAIT_V(n) asm volatile("s_waitcnt vmcnt(" #n ")" ::: "memory")
; #define WAIT_L(n) asm volatile("s_waitcnt lgkmcnt(" #n ")" ::: "memory")
; #define BAR __builtin_amdgcn_s_barrier()
; #define SCHED __builtin_amdgcn_sched_barrier(0)
; template <int EPI, int lda, int ldb, int N, int K>
; __device__ __forceinline__ void gemm_phase(const u16* __restrict__ A, const u16* __restrict__ Bt, const GemmEpi ep, int wv) {
;     ...
;       LDA(At, 1, 1); STAGE(SA(1, 0), Ab, lda, brow, t + 3);
;       BAR; WAIT_L(0); MMA(1, 0, At, B0); BAR; SCHED;
;       STAGE(SB(1, 1), Bt, ldb, bcol + HALF, t + 3);
;       WAIT_V(6); BAR; MMA(1, 1, At, B1); BAR;
;     }
;     { LDB(B0, 0, 0); LDA(At, 0, 0); STAGE(SA(1, 1), Ab, lda, brow + HALF, nt - 1);
;       BAR; WAIT_L(0); MMA(0, 0, At, B0); BAR;
	ds_read_b128 v[188:191], v152 offset:49152
	ds_read_b128 v[192:195], v152 offset:50176
	ds_read_b128 v[196:199], v151 offset:49152
	ds_read_b128 v[200:203], v151 offset:50176
	ds_read_b128 v[204:207], v150 offset:49152
	ds_read_b128 v[208:211], v150 offset:50176
	ds_read_b128 v[212:215], v149 offset:49152
	ds_read_b128 v[216:219], v149 offset:50176
	global_load_lds_dwordx4 v[236:237], off
	v_lshl_add_u64 v[236:237], v[238:239], 0, s[46:47]
	s_mov_b32 m0, s63
	s_nop 0
	global_load_lds_dwordx4 v[236:237], off
	s_barrier
	s_waitcnt lgkmcnt(0)
	s_setprio 0
	s_waitcnt lgkmcnt(0)
	v_mfma_f32_16x16x32_bf16 v[60:63], v[188:191], v[172:175], v[60:63]
	v_mfma_f32_16x16x32_bf16 v[56:59], v[188:191], v[180:183], v[56:59]
	v_mfma_f32_16x16x32_bf16 v[52:55], v[196:199], v[172:175], v[52:55]
	v_mfma_f32_16x16x32_bf16 v[48:51], v[196:199], v[180:183], v[48:51]
	v_mfma_f32_16x16x32_bf16 v[44:47], v[204:207], v[172:175], v[44:47]
	v_mfma_f32_16x16x32_bf16 v[40:43], v[204:207], v[180:183], v[40:43]
	v_mfma_f32_16x16x32_bf16 v[36:39], v[212:215], v[172:175], v[36:39]
	v_mfma_f32_16x16x32_bf16 v[32:35], v[212:215], v[180:183], v[32:35]
	v_mfma_f32_16x16x32_bf16 v[60:63], v[192:195], v[176:179], v[60:63]
	v_mfma_f32_16x16x32_bf16 v[56:59], v[192:195], v[184:187], v[56:59]
	v_mfma_f32_16x16x32_bf16 v[52:55], v[200:203], v[176:179], v[52:55]
	v_mfma_f32_16x16x32_bf16 v[48:51], v[200:203], v[184:187], v[48:51]
	v_mfma_f32_16x16x32_bf16 v[44:47], v[208:211], v[176:179], v[44:47]
	v_mfma_f32_16x16x32_bf16 v[40:43], v[208:211], v[184:187], v[40:43]
	v_mfma_f32_16x16x32_bf16 v[36:39], v[216:219], v[176:179], v[36:39]
	v_mfma_f32_16x16x32_bf16 v[32:35], v[216:219], v[184:187], v[32:35]
	s_setprio 1
	s_barrier
	v_readfirstlane_b32 s63, v159
	v_add_u32_e32 v171, 0x2000, v159
	v_lshl_add_u64 v[172:173], v[240:241], 0, s[48:49]
	s_mov_b32 m0, s63
	v_readfirstlane_b32 s63, v171
	global_load_lds_dwordx4 v[172:173], off
	v_lshl_add_u64 v[172:173], v[242:243], 0, s[48:49]
	s_mov_b32 m0, s63
	s_nop 0
	global_load_lds_dwordx4 v[172:173], off
	s_waitcnt vmcnt(6)
	s_barrier
	s_setprio 0
	v_mfma_f32_16x16x32_bf16 v[28:31], v[188:191], v[220:223], v[28:31]
	v_mfma_f32_16x16x32_bf16 v[24:27], v[188:191], v[228:231], v[24:27]
	v_mfma_f32_16x16x32_bf16 v[20:23], v[196:199], v[220:223], v[20:23]
	v_mfma_f32_16x16x32_bf16 v[16:19], v[196:199], v[228:231], v[16:19]
	v_mfma_f32_16x16x32_bf16 v[12:15], v[204:207], v[220:223], v[12:15]
	v_mfma_f32_16x16x32_bf16 v[8:11], v[204:207], v[228:231], v[8:11]
	v_mfma_f32_16x16x32_bf16 v[4:7], v[212:215], v[220:223], v[4:7]
	v_mfma_f32_16x16x32_bf16 v[0:3], v[212:215], v[228:231], v[0:3]
	v_mfma_f32_16x16x32_bf16 v[28:31], v[192:195], v[224:227], v[28:31]
	v_mfma_f32_16x16x32_bf16 v[24:27], v[192:195], v[232:235], v[24:27]
	v_mfma_f32_16x16x32_bf16 v[20:23], v[200:203], v[224:227], v[20:23]
	v_mfma_f32_16x16x32_bf16 v[16:19], v[200:203], v[232:235], v[16:19]
	v_mfma_f32_16x16x32_bf16 v[12:15], v[208:211], v[224:227], v[12:15]
	v_mfma_f32_16x16x32_bf16 v[8:11], v[208:211], v[232:235], v[8:11]
	v_mfma_f32_16x16x32_bf16 v[4:7], v[216:219], v[224:227], v[4:7]
	v_mfma_f32_16x16x32_bf16 v[0:3], v[216:219], v[232:235], v[0:3]
	s_setprio 1
	s_add_i32 s62, s62, 2
	s_add_u32 s60, s60, 0x100
	s_addc_u32 s61, s61, 0
	s_cmp_gt_u32 s62, 27
	s_barrier
	s_cbranch_scc0 .LBB0_1147
	s_add_i32 s60, s58, 0x80
	s_mul_hi_i32 s61, s60, 0x1080
	s_mulk_i32 s60, 0x1080
	s_add_u32 s60, s69, s60
	s_addc_u32 s61, s70, s61
	v_lshl_add_u64 v[208:209], s[60:61], 0, v[128:129]
	v_readfirstlane_b32 s62, v169
	v_lshl_add_u64 v[208:209], v[208:209], 0, s[50:51]
	s_mov_b32 m0, s62
	ds_read_b128 v[134:137], v161
	ds_read_b128 v[138:141], v161 offset:1024
	ds_read_b128 v[156:159], v161 offset:2048
	ds_read_b128 v[172:175], v161 offset:3072
	ds_read_b128 v[176:179], v152
	ds_read_b128 v[180:183], v152 offset:1024
	ds_read_b128 v[184:187], v151
	ds_read_b128 v[188:191], v151 offset:1024
	ds_read_b128 v[192:195], v150
	ds_read_b128 v[196:199], v150 offset:1024
	ds_read_b128 v[200:203], v149
	ds_read_b128 v[204:207], v149 offset:1024
	global_load_lds_dwordx4 v[208:209], off
	v_lshl_add_u64 v[208:209], s[60:61], 0, v[132:133]
	v_readfirstlane_b32 s60, v170
	v_lshl_add_u64 v[208:209], v[208:209], 0, s[50:51]
	s_mov_b32 m0, s60
	s_nop 0
	global_load_lds_dwordx4 v[208:209], off
	s_barrier
	s_waitcnt lgkmcnt(0)
	s_setprio 0
	s_waitcnt lgkmcnt(0)
	v_mfma_f32_16x16x32_bf16 v[124:127], v[176:179], v[134:137], v[124:127]
	v_mfma_f32_16x16x32_bf16 v[120:123], v[176:179], v[156:159], v[120:123]
	v_mfma_f32_16x16x32_bf16 v[116:119], v[184:187], v[134:137], v[116:119]
	v_mfma_f32_16x16x32_bf16 v[112:115], v[184:187], v[156:159], v[112:115]
	v_mfma_f32_16x16x32_bf16 v[108:111], v[192:195], v[134:137], v[108:111]
	v_mfma_f32_16x16x32_bf16 v[104:107], v[192:195], v[156:159], v[104:107]
	v_mfma_f32_16x16x32_bf16 v[100:103], v[200:203], v[134:137], v[100:103]
	v_mfma_f32_16x16x32_bf16 v[96:99], v[200:203], v[156:159], v[96:99]
	v_mfma_f32_16x16x32_bf16 v[124:127], v[180:183], v[138:141], v[124:127]
	v_mfma_f32_16x16x32_bf16 v[120:123], v[180:183], v[172:175], v[120:123]
	v_mfma_f32_16x16x32_bf16 v[116:119], v[188:191], v[138:141], v[116:119]
	v_mfma_f32_16x16x32_bf16 v[112:115], v[188:191], v[172:175], v[112:115]
	v_mfma_f32_16x16x32_bf16 v[108:111], v[196:199], v[138:141], v[108:111]
	v_mfma_f32_16x16x32_bf16 v[104:107], v[196:199], v[172:175], v[104:107]
	v_mfma_f32_16x16x32_bf16 v[100:103], v[204:207], v[138:141], v[100:103]
	v_mfma_f32_16x16x32_bf16 v[96:99], v[204:207], v[172:175], v[96:99]
	s_setprio 1
	s_barrier
	ds_read_b128 v[208:211], v160
	ds_read_b128 v[212:215], v160 offset:1024
	ds_read_b128 v[216:219], v160 offset:2048
	ds_read_b128 v[220:223], v160 offset:3072
	s_barrier
; #define LDA(dst, b, h) for (int m = 0; m < 4; ++m) for (int k = 0; k < 2; ++k) \
;     dst[m][k] = *reinterpret_cast<const bf16x8*>((char*)SA(b, h) + lds_byte(wr * 64 + m * 16 + fr, k * 32 + fq * 8))
; #define LDB(dst, b, h) for (int n = 0; n < 2; ++n) for (int k = 0; k < 2; ++k) \
;     dst[n][k] = *reinterpret_cast<const bf16x8*>((char*)SB(b, h) + lds_byte(wc * 32 + n * 16 + fr, k * 32 + fq * 8))
; #define MMA(ai, bj, At_, Bt_) do { __builtin_amdgcn_s_setprio(1); \
;     for (int k = 0; k < 2; ++k) for (int m = 0; m < 4; ++m) for (int n = 0; n < 2; ++n) \
;       acc[ai][bj][m][n] = __builtin_amdgcn_mfma_f32_16x16x32_bf16(At_[m][k], Bt_[n][k], acc[ai][bj][m][n], 0, 0, 0); \
;     __builtin_amdgcn_s_setprio(0); } while (0)
; #define WAIT_V(n) asm volatile("s_waitcnt vmcnt(" #n ")" ::: "memory")
; #define WAIT_L(n) asm volatile("s_waitcnt lgkmcnt(" #n ")" ::: "memory")
; #define BAR __builtin_amdgcn_s_barrier()
; template <int EPI, int lda, int ldb, int N, int K>
; __device__ __forceinline__ void gemm_phase(const u16* __restrict__ A, const u16* __restrict__ Bt, const GemmEpi ep, int wv) {
;     ...
;       LDB(B1, 0, 1); BAR; WAIT_L(0); MMA(0, 1, At, B1); BAR;
;       LDA(At, 0, 1); WAIT_V(4); BAR; WAIT_L(0); MMA(1, 0, At, B0); MMA(1, 1, At, B1); BAR; }
;     { LDB(B0, 1, 0); LDA(At, 1, 0); WAIT_V(2); BAR; WAIT_L(0); MMA(0, 0, At, B0); BAR;
	s_waitcnt lgkmcnt(0)
	s_setprio 0
	s_waitcnt lgkmcnt(0)
	v_mfma_f32_16x16x32_bf16 v[92:95], v[176:179], v[208:211], v[92:95]
	v_mfma_f32_16x16x32_bf16 v[88:91], v[176:179], v[216:219], v[88:91]
	v_mfma_f32_16x16x32_bf16 v[76:79], v[192:195], v[208:211], v[76:79]
	v_mfma_f32_16x16x32_bf16 v[72:75], v[192:195], v[216:219], v[72:75]
	v_mfma_f32_16x16x32_bf16 v[84:87], v[184:187], v[208:211], v[84:87]
	v_mfma_f32_16x16x32_bf16 v[80:83], v[184:187], v[216:219], v[80:83]
	v_mfma_f32_16x16x32_bf16 v[68:71], v[200:203], v[208:211], v[68:71]
	v_mfma_f32_16x16x32_bf16 v[64:67], v[200:203], v[216:219], v[64:67]
	v_mfma_f32_16x16x32_bf16 v[92:95], v[180:183], v[212:215], v[92:95]
	v_mfma_f32_16x16x32_bf16 v[88:91], v[180:183], v[220:223], v[88:91]
	v_mfma_f32_16x16x32_bf16 v[76:79], v[196:199], v[212:215], v[76:79]
	v_mfma_f32_16x16x32_bf16 v[72:75], v[196:199], v[220:223], v[72:75]
	v_mfma_f32_16x16x32_bf16 v[176:179], v[188:191], v[212:215], v[84:87]
	v_mfma_f32_16x16x32_bf16 v[180:183], v[188:191], v[220:223], v[80:83]
	v_mfma_f32_16x16x32_bf16 v[184:187], v[204:207], v[212:215], v[68:71]
	v_mfma_f32_16x16x32_bf16 v[188:191], v[204:207], v[220:223], v[64:67]
	s_setprio 1
	s_barrier
	s_nop 0
	ds_read_b128 v[64:67], v152 offset:16384
	ds_read_b128 v[68:71], v152 offset:17408
	ds_read_b128 v[80:83], v151 offset:16384
	ds_read_b128 v[84:87], v151 offset:17408
	ds_read_b128 v[192:195], v150 offset:16384
	ds_read_b128 v[196:199], v150 offset:17408
	ds_read_b128 v[200:203], v149 offset:16384
	ds_read_b128 v[204:207], v149 offset:17408
	s_waitcnt vmcnt(4)
	s_barrier
	s_waitcnt lgkmcnt(0)
	s_setprio 0
	s_waitcnt lgkmcnt(0)
	v_mfma_f32_16x16x32_bf16 v[60:63], v[64:67], v[134:137], v[60:63]
	v_mfma_f32_16x16x32_bf16 v[56:59], v[64:67], v[156:159], v[56:59]
	v_mfma_f32_16x16x32_bf16 v[52:55], v[80:83], v[134:137], v[52:55]
	v_mfma_f32_16x16x32_bf16 v[48:51], v[80:83], v[156:159], v[48:51]
	v_mfma_f32_16x16x32_bf16 v[44:47], v[192:195], v[134:137], v[44:47]
	v_mfma_f32_16x16x32_bf16 v[40:43], v[192:195], v[156:159], v[40:43]
	v_mfma_f32_16x16x32_bf16 v[36:39], v[200:203], v[134:137], v[36:39]
	v_mfma_f32_16x16x32_bf16 v[32:35], v[200:203], v[156:159], v[32:35]
	v_mfma_f32_16x16x32_bf16 v[60:63], v[68:71], v[138:141], v[60:63]
	v_mfma_f32_16x16x32_bf16 v[56:59], v[68:71], v[172:175], v[56:59]
	v_mfma_f32_16x16x32_bf16 v[52:55], v[84:87], v[138:141], v[52:55]
	v_mfma_f32_16x16x32_bf16 v[48:51], v[84:87], v[172:175], v[48:51]
	v_mfma_f32_16x16x32_bf16 v[44:47], v[196:199], v[138:141], v[44:47]
	v_mfma_f32_16x16x32_bf16 v[40:43], v[196:199], v[172:175], v[40:43]
	v_mfma_f32_16x16x32_bf16 v[36:39], v[204:207], v[138:141], v[36:39]
	v_mfma_f32_16x16x32_bf16 v[32:35], v[204:207], v[172:175], v[32:35]
	s_setprio 1
	s_setprio 0
	v_mfma_f32_16x16x32_bf16 v[28:31], v[64:67], v[208:211], v[28:31]
	v_mfma_f32_16x16x32_bf16 v[24:27], v[64:67], v[216:219], v[24:27]
	v_mfma_f32_16x16x32_bf16 v[12:15], v[192:195], v[208:211], v[12:15]
	v_mfma_f32_16x16x32_bf16 v[8:11], v[192:195], v[216:219], v[8:11]
	v_mfma_f32_16x16x32_bf16 v[20:23], v[80:83], v[208:211], v[20:23]
	v_mfma_f32_16x16x32_bf16 v[16:19], v[80:83], v[216:219], v[16:19]
	v_mfma_f32_16x16x32_bf16 v[4:7], v[200:203], v[208:211], v[4:7]
	v_mfma_f32_16x16x32_bf16 v[0:3], v[200:203], v[216:219], v[0:3]
	v_mfma_f32_16x16x32_bf16 v[28:31], v[68:71], v[212:215], v[28:31]
	v_mfma_f32_16x16x32_bf16 v[24:27], v[68:71], v[220:223], v[24:27]
	v_mfma_f32_16x16x32_bf16 v[12:15], v[196:199], v[212:215], v[12:15]
	v_mfma_f32_16x16x32_bf16 v[8:11], v[196:199], v[220:223], v[8:11]
	v_mfma_f32_16x16x32_bf16 v[134:137], v[84:87], v[212:215], v[20:23]
	v_mfma_f32_16x16x32_bf16 v[138:141], v[84:87], v[220:223], v[16:19]
	v_mfma_f32_16x16x32_bf16 v[156:159], v[204:207], v[212:215], v[4:7]
	v_mfma_f32_16x16x32_bf16 v[170:173], v[204:207], v[220:223], v[0:3]
	s_setprio 1
	s_barrier
	s_nop 0
	ds_read_b128 v[0:3], v155
	ds_read_b128 v[4:7], v155 offset:1024
	ds_read_b128 v[16:19], v155 offset:2048
	ds_read_b128 v[192:195], v155 offset:3072
	ds_read_b128 v[20:23], v152 offset:32768
	ds_read_b128 v[196:199], v152 offset:33792
	ds_read_b128 v[200:203], v151 offset:32768
	ds_read_b128 v[204:207], v151 offset:33792
	ds_read_b128 v[208:211], v150 offset:32768
	ds_read_b128 v[212:215], v150 offset:33792
	ds_read_b128 v[216:219], v149 offset:32768
	ds_read_b128 v[220:223], v149 offset:33792
	s_waitcnt vmcnt(2)
	s_barrier
; #define LDA(dst, b, h) for (int m = 0; m < 4; ++m) for (int k = 0; k < 2; ++k) \
;     dst[m][k] = *reinterpret_cast<const bf16x8*>((char*)SA(b, h) + lds_byte(wr * 64 + m * 16 + fr, k * 32 + fq * 8))
; #define LDB(dst, b, h) for (int n = 0; n < 2; ++n) for (int k = 0; k < 2; ++k) \
;     dst[n][k] = *reinterpret_cast<const bf16x8*>((char*)SB(b, h) + lds_byte(wc * 32 + n * 16 + fr, k * 32 + fq * 8))
; #define MMA(ai, bj, At_, Bt_) do { __builtin_amdgcn_s_setprio(1); \
;     for (int k = 0; k < 2; ++k) for (int m = 0; m < 4; ++m) for (int n = 0; n < 2; ++n) \
;       acc[ai][bj][m][n] = __builtin_amdgcn_mfma_f32_16x16x32_bf16(At_[m][k], Bt_[n][k], acc[ai][bj][m][n], 0, 0, 0); \
;     __builtin_amdgcn_s_setprio(0); } while (0)
; #define WAIT_V(n) asm volatile("s_waitcnt vmcnt(" #n ")" ::: "memory")
; #define WAIT_L(n) asm volatile("s_waitcnt lgkmcnt(" #n ")" ::: "memory")
; #define BAR __builtin_amdgcn_s_barrier()
; template <int EPI, int lda, int ldb, int N, int K>
; __device__ __forceinline__ void gemm_phase(const u16* __restrict__ A, const u16* __restrict__ Bt, const GemmEpi ep, int wv) {
;     ...
;     { LDB(B0, 1, 0); LDA(At, 1, 0); WAIT_V(2); BAR; WAIT_L(0); MMA(0, 0, At, B0); BAR;
;       LDB(B1, 1, 1); WAIT_V(0); BAR; WAIT_L(0); MMA(0, 1, At, B1); BAR;
;       LDA(At, 1, 1); BAR; WAIT_L(0); MMA(1, 0, At, B0); MMA(1, 1, At, B1); BAR; }
;     if (wr == 0) BAR;
	s_waitcnt lgkmcnt(0)
	s_setprio 0
	s_waitcnt lgkmcnt(0)
	v_mfma_f32_16x16x32_bf16 v[64:67], v[20:23], v[0:3], v[124:127]
	v_mfma_f32_16x16x32_bf16 v[68:71], v[20:23], v[16:19], v[120:123]
	v_mfma_f32_16x16x32_bf16 v[80:83], v[200:203], v[0:3], v[116:119]
	v_mfma_f32_16x16x32_bf16 v[84:87], v[200:203], v[16:19], v[112:115]
	v_mfma_f32_16x16x32_bf16 v[108:111], v[208:211], v[0:3], v[108:111]
	v_mfma_f32_16x16x32_bf16 v[104:107], v[208:211], v[16:19], v[104:107]
	v_mfma_f32_16x16x32_bf16 v[120:123], v[216:219], v[0:3], v[100:103]
	v_mfma_f32_16x16x32_bf16 v[124:127], v[216:219], v[16:19], v[96:99]
	v_mfma_f32_16x16x32_bf16 v[116:119], v[196:199], v[4:7], v[64:67]
	v_mfma_f32_16x16x32_bf16 v[112:115], v[196:199], v[192:195], v[68:71]
	v_mfma_f32_16x16x32_bf16 v[100:103], v[204:207], v[4:7], v[80:83]
	v_mfma_f32_16x16x32_bf16 v[96:99], v[204:207], v[192:195], v[84:87]
	v_mfma_f32_16x16x32_bf16 v[84:87], v[212:215], v[4:7], v[108:111]
	v_mfma_f32_16x16x32_bf16 v[80:83], v[212:215], v[192:195], v[104:107]
	v_mfma_f32_16x16x32_bf16 v[68:71], v[220:223], v[4:7], v[120:123]
	v_mfma_f32_16x16x32_bf16 v[64:67], v[220:223], v[192:195], v[124:127]
	s_setprio 1
	s_barrier
	ds_read_b128 v[224:227], v153
	ds_read_b128 v[228:231], v153 offset:1024
	ds_read_b128 v[232:235], v153 offset:2048
	ds_read_b128 v[236:239], v153 offset:3072
	s_waitcnt vmcnt(0)
	s_barrier
	s_waitcnt lgkmcnt(0)
	s_setprio 0
	s_waitcnt lgkmcnt(0)
	v_mfma_f32_16x16x32_bf16 v[92:95], v[20:23], v[224:227], v[92:95]
	v_mfma_f32_16x16x32_bf16 v[20:23], v[20:23], v[232:235], v[88:91]
	v_mfma_f32_16x16x32_bf16 v[88:91], v[200:203], v[224:227], v[176:179]
	v_mfma_f32_16x16x32_bf16 v[104:107], v[200:203], v[232:235], v[180:183]
	v_mfma_f32_16x16x32_bf16 v[76:79], v[208:211], v[224:227], v[76:79]
	v_mfma_f32_16x16x32_bf16 v[72:75], v[208:211], v[232:235], v[72:75]
	v_mfma_f32_16x16x32_bf16 v[174:177], v[216:219], v[224:227], v[184:187]
	v_mfma_f32_16x16x32_bf16 v[178:181], v[216:219], v[232:235], v[188:191]
	v_mfma_f32_16x16x32_bf16 v[124:127], v[196:199], v[228:231], v[92:95]
	v_mfma_f32_16x16x32_bf16 v[120:123], v[196:199], v[236:239], v[20:23]
	v_mfma_f32_16x16x32_bf16 v[108:111], v[204:207], v[228:231], v[88:91]
	v_mfma_f32_16x16x32_bf16 v[104:107], v[204:207], v[236:239], v[104:107]
	v_mfma_f32_16x16x32_bf16 v[92:95], v[212:215], v[228:231], v[76:79]
	v_mfma_f32_16x16x32_bf16 v[88:91], v[212:215], v[236:239], v[72:75]
	v_mfma_f32_16x16x32_bf16 v[76:79], v[220:223], v[228:231], v[174:177]
	v_mfma_f32_16x16x32_bf16 v[72:75], v[220:223], v[236:239], v[178:181]
	s_setprio 1
	s_barrier
	ds_read_b128 v[174:177], v152 offset:49152
	ds_read_b128 v[152:155], v152 offset:50176
	ds_read_b128 v[178:181], v151 offset:49152
	ds_read_b128 v[182:185], v151 offset:50176
	ds_read_b128 v[186:189], v150 offset:49152
	ds_read_b128 v[196:199], v150 offset:50176
	ds_read_b128 v[200:203], v149 offset:49152
	ds_read_b128 v[204:207], v149 offset:50176
	s_barrier
	s_waitcnt lgkmcnt(0)
	s_setprio 0
	s_waitcnt lgkmcnt(0)
	v_mfma_f32_16x16x32_bf16 v[20:23], v[174:177], v[0:3], v[60:63]
	v_mfma_f32_16x16x32_bf16 v[56:59], v[174:177], v[16:19], v[56:59]
	v_mfma_f32_16x16x32_bf16 v[60:63], v[178:181], v[0:3], v[52:55]
	v_mfma_f32_16x16x32_bf16 v[208:211], v[178:181], v[16:19], v[48:51]
	v_mfma_f32_16x16x32_bf16 v[44:47], v[186:189], v[0:3], v[44:47]
	v_mfma_f32_16x16x32_bf16 v[40:43], v[186:189], v[16:19], v[40:43]
	v_mfma_f32_16x16x32_bf16 v[0:3], v[200:203], v[0:3], v[36:39]
	v_mfma_f32_16x16x32_bf16 v[212:215], v[200:203], v[16:19], v[32:35]
	v_mfma_f32_16x16x32_bf16 v[52:55], v[152:155], v[4:7], v[20:23]
	v_mfma_f32_16x16x32_bf16 v[48:51], v[152:155], v[192:195], v[56:59]
	v_mfma_f32_16x16x32_bf16 v[36:39], v[182:185], v[4:7], v[60:63]
	v_mfma_f32_16x16x32_bf16 v[32:35], v[182:185], v[192:195], v[208:211]
	v_mfma_f32_16x16x32_bf16 v[20:23], v[196:199], v[4:7], v[44:47]
	v_mfma_f32_16x16x32_bf16 v[16:19], v[196:199], v[192:195], v[40:43]
	v_mfma_f32_16x16x32_bf16 v[4:7], v[204:207], v[4:7], v[0:3]
	v_mfma_f32_16x16x32_bf16 v[0:3], v[204:207], v[192:195], v[212:215]
	s_setprio 1
	s_setprio 0
	v_mfma_f32_16x16x32_bf16 v[28:31], v[174:177], v[224:227], v[28:31]
	v_mfma_f32_16x16x32_bf16 v[24:27], v[174:177], v[232:235], v[24:27]
	v_mfma_f32_16x16x32_bf16 v[40:43], v[178:181], v[224:227], v[134:137]
	v_mfma_f32_16x16x32_bf16 v[134:137], v[178:181], v[232:235], v[138:141]
	v_mfma_f32_16x16x32_bf16 v[12:15], v[186:189], v[224:227], v[12:15]
	v_mfma_f32_16x16x32_bf16 v[8:11], v[186:189], v[232:235], v[8:11]
	v_mfma_f32_16x16x32_bf16 v[138:141], v[200:203], v[224:227], v[156:159]
	v_mfma_f32_16x16x32_bf16 v[156:159], v[200:203], v[232:235], v[170:173]
	v_mfma_f32_16x16x32_bf16 v[60:63], v[152:155], v[228:231], v[28:31]
	v_mfma_f32_16x16x32_bf16 v[56:59], v[152:155], v[236:239], v[24:27]
	v_mfma_f32_16x16x32_bf16 v[44:47], v[182:185], v[228:231], v[40:43]
	v_mfma_f32_16x16x32_bf16 v[40:43], v[182:185], v[236:239], v[134:137]
	v_mfma_f32_16x16x32_bf16 v[28:31], v[196:199], v[228:231], v[12:15]
	v_mfma_f32_16x16x32_bf16 v[24:27], v[196:199], v[236:239], v[8:11]
	v_mfma_f32_16x16x32_bf16 v[12:15], v[204:207], v[228:231], v[138:141]
	v_mfma_f32_16x16x32_bf16 v[8:11], v[204:207], v[236:239], v[156:159]
	s_setprio 1
	v_cmp_gt_u32_e32 vcc, s80, v130
	s_barrier
	s_and_saveexec_b64 s[60:61], vcc
	s_cbranch_execz .LBB0_1150
	s_barrier

; #define STAGE(P, BASE, LD, br, kt) do { const char* _g = (const char*)((BASE) + (size_t)(br) * (LD) + (size_t)(kt) * 64); \
;     for (int _i = 0; _i < 2; ++_i) { int _b = tidx * 16 + _i * 8192; int _r, _c; stage_rc(_b, _r, _c); \
;       __builtin_amdgcn_global_load_lds((const unsigned*)(_g + (unsigned)((_r * (LD) + _c) * 2)), (unsigned*)((char*)(P) + _b), 16, 0, 0); } } while (0)
; #define LDA(dst, b, h) for (int m = 0; m < 4; ++m) for (int k = 0; k < 2; ++k) \
;     dst[m][k] = *reinterpret_cast<const bf16x8*>((char*)SA(b, h) + lds_byte(wr * 64 + m * 16 + fr, k * 32 + fq * 8))
; #define LDB(dst, b, h) for (int n = 0; n < 2; ++n) for (int k = 0; k < 2; ++k) \
;     dst[n][k] = *reinterpret_cast<const bf16x8*>((char*)SB(b, h) + lds_byte(wc * 32 + n * 16 + fr, k * 32 + fq * 8))
; #define MMA(ai, bj, At_, Bt_) do { __builtin_amdgcn_s_setprio(1); \
;     for (int k = 0; k < 2; ++k) for (int m = 0; m < 4; ++m) for (int n = 0; n < 2; ++n) \
;       acc[ai][bj][m][n] = __builtin_amdgcn_mfma_f32_16x16x32_bf16(At_[m][k], Bt_[n][k], acc[ai][bj][m][n], 0, 0, 0); \
;     __builtin_amdgcn_s_setprio(0); } while (0)
; #define WAIT_V(n) asm volatile("s_waitcnt vmcnt(" #n ")" ::: "memory")
; #define WAIT_L(n) asm volatile("s_waitcnt lgkmcnt(" #n ")" ::: "memory")
; #define BAR __builtin_amdgcn_s_barrier()
; template <int EPI, int lda, int ldb, int N, int K>
; __device__ __forceinline__ void gemm_phase(const u16* __restrict__ A, const u16* __restrict__ Bt, const GemmEpi ep, int wv) {
;     ...
;     if constexpr (!PF) { TILE_COORDS(tile, brow, bcol, pn); STAGE4(brow, bcol, pn); }
;     const int wid = tidx >> 6, lane = tidx & 63, wr = wid >> 2, wc = wid & 3, fr = lane & 15, fq = lane >> 4;
;     const u16* Ab = A + (EPI == EPI_RG ? (pn >> 1) * 256 : 0);
;     f32x4 acc[2][2][4][2] = {};
;     bf16x8 At[4][2], B0[2][2], B1[2][2];
;     constexpr int nt = K / 64;
;     if (wr == 1) BAR;
;     WAIT_V(4); BAR;
;     STAGE(SB(1, 0), Bt, ldb, bcol, 1); STAGE(SA(1, 0), Ab, lda, brow, 1); STAGE(SB(1, 1), Bt, ldb, bcol + HALF, 1);
;     WAIT_V(6); BAR;
;     for (int t = 0; t < nt - 2; t += 2) {
;       LDB(B0, 0, 0); SCHED; LDA(At, 0, 0); STAGE(SA(1, 1), Ab, lda, brow + HALF, t + 1);
;       WAIT_L(8); BAR; WAIT_L(0); MMA(0, 0, At, B0); BAR; SCHED;
;       LDB(B1, 0, 1); STAGE(SB(0, 0), Bt, ldb, bcol, t + 2);
;       BAR; WAIT_L(0); MMA(0, 1, At, B1); BAR;
.LBB0_1248:
	s_or_b64 exec, exec, s[54:55]
	v_mov_b32_e32 v1, v129
	v_add_u32_e32 v7, s60, v6
	v_lshl_add_u64 v[12:13], s[46:47], 0, v[128:129]
	v_lshl_add_u64 v[14:15], s[46:47], 0, v[0:1]
	v_lshl_add_u64 v[2:3], s[52:53], 0, v[128:129]
	v_lshl_add_u64 v[0:1], s[52:53], 0, v[0:1]
	v_readfirstlane_b32 s53, v7
	v_add_u32_e32 v7, 0x2000, v7
	v_mov_b32_e32 v5, v129
	v_mov_b32_e32 v17, v129
	v_lshl_add_u64 v[26:27], v[12:13], 0, s[40:41]
	s_mov_b32 m0, s53
	v_readfirstlane_b32 s52, v7
	v_add_u32_e32 v7, 0x8000, v23
	v_lshl_add_u64 v[8:9], s[50:51], 0, v[4:5]
	v_lshl_add_u64 v[10:11], s[50:51], 0, v[16:17]
	s_waitcnt vmcnt(4)
	s_barrier
	global_load_lds_dwordx4 v[26:27], off
	v_lshl_add_u64 v[26:27], v[14:15], 0, s[40:41]
	s_mov_b32 m0, s52
	v_readfirstlane_b32 s51, v7
	v_add_u32_e32 v7, 0xa000, v23
	global_load_lds_dwordx4 v[26:27], off
	v_lshl_add_u64 v[26:27], v[8:9], 0, s[40:41]
	s_mov_b32 m0, s51
	v_readfirstlane_b32 s50, v7
	v_add_u32_e32 v25, s61, v6
	global_load_lds_dwordx4 v[26:27], off
	v_lshl_add_u64 v[26:27], v[10:11], 0, s[40:41]
	s_mov_b32 m0, s50
	v_readfirstlane_b32 s13, v25
	v_add_u32_e32 v25, 0x2000, v25
	global_load_lds_dwordx4 v[26:27], off
	v_lshl_add_u64 v[26:27], v[2:3], 0, s[40:41]
	s_mov_b32 m0, s13
	v_readfirstlane_b32 s11, v25
	global_load_lds_dwordx4 v[26:27], off
	v_lshl_add_u64 v[6:7], v[0:1], 0, s[40:41]
	s_mov_b32 m0, s11
	v_and_b32_e32 v132, 15, v20
	global_load_lds_dwordx4 v[6:7], off
	v_bfe_u32 v128, v20, 4, 2
	v_lshlrev_b32_e32 v7, 2, v20
	v_bfe_u32 v131, v130, 6, 2
	v_lshlrev_b32_e32 v25, 4, v128
	v_lshlrev_b32_e32 v6, 6, v132
	v_and_b32_e32 v50, 32, v7
	v_lshlrev_b32_e32 v126, 12, v131
	v_bitop3_b32 v127, v25, v50, v6 bitop3:0x36
	v_add3_u32 v133, s58, v127, v126
	s_waitcnt vmcnt(6)
	s_barrier
	ds_read_b128 v[26:29], v133
	ds_read_b128 v[30:33], v133 offset:1024
	ds_read_b128 v[34:37], v133 offset:2048
	ds_read_b128 v[38:41], v133 offset:3072
	v_lshl_add_u64 v[6:7], s[48:49], 0, v[4:5]
	v_lshl_add_u64 v[4:5], s[48:49], 0, v[16:17]
	v_lshlrev_b32_e32 v17, 6, v20
	v_and_b32_e32 v17, 0x3c0, v17
	v_add_u32_e32 v20, 0xc000, v23
	v_lshlrev_b32_e32 v16, 13, v143
	v_bitop3_b32 v17, v17, v50, v25 bitop3:0x36
	v_readfirstlane_b32 s47, v20
	v_add_u32_e32 v20, 0xe000, v23
	v_add3_u32 v228, 0, v127, v16
	v_add3_u32 v229, 0, v17, v16
	v_lshl_add_u64 v[16:17], v[6:7], 0, s[40:41]
	s_mov_b32 m0, s47
	v_readfirstlane_b32 s46, v20
	ds_read_b128 v[42:45], v228
	ds_read_b128 v[46:49], v228 offset:1024
	ds_read_b128 v[50:53], v229 offset:2048
	ds_read_b128 v[54:57], v229 offset:3072
	ds_read_b128 v[58:61], v229 offset:4096
	ds_read_b128 v[62:65], v229 offset:5120
	ds_read_b128 v[66:69], v229 offset:6144
	ds_read_b128 v[70:73], v229 offset:7168
	global_load_lds_dwordx4 v[16:17], off
	v_lshl_add_u64 v[16:17], v[4:5], 0, s[40:41]
	s_mov_b32 m0, s46
	s_nop 0
	global_load_lds_dwordx4 v[16:17], off
	s_waitcnt lgkmcnt(8)
	s_barrier
	s_waitcnt lgkmcnt(0)
	s_setprio 0
	s_waitcnt lgkmcnt(0)
	v_mfma_f32_16x16x32_bf16 v[74:77], v[42:45], v[26:29], 0
	v_mfma_f32_16x16x32_bf16 v[78:81], v[42:45], v[34:37], 0
	v_mfma_f32_16x16x32_bf16 v[82:85], v[50:53], v[26:29], 0
	v_mfma_f32_16x16x32_bf16 v[86:89], v[50:53], v[34:37], 0
	v_mfma_f32_16x16x32_bf16 v[90:93], v[58:61], v[26:29], 0
	v_mfma_f32_16x16x32_bf16 v[94:97], v[58:61], v[34:37], 0
	v_mfma_f32_16x16x32_bf16 v[98:101], v[66:69], v[26:29], 0
	v_mfma_f32_16x16x32_bf16 v[102:105], v[66:69], v[34:37], 0
	v_mfma_f32_16x16x32_bf16 v[74:77], v[46:49], v[30:33], v[74:77]
	v_mfma_f32_16x16x32_bf16 v[78:81], v[46:49], v[38:41], v[78:81]
	v_mfma_f32_16x16x32_bf16 v[82:85], v[54:57], v[30:33], v[82:85]
	v_mfma_f32_16x16x32_bf16 v[86:89], v[54:57], v[38:41], v[86:89]
	v_mfma_f32_16x16x32_bf16 v[90:93], v[62:65], v[30:33], v[90:93]
	v_mfma_f32_16x16x32_bf16 v[94:97], v[62:65], v[38:41], v[94:97]
	v_mfma_f32_16x16x32_bf16 v[98:101], v[70:73], v[30:33], v[98:101]
	v_mfma_f32_16x16x32_bf16 v[102:105], v[70:73], v[38:41], v[102:105]
	s_setprio 1
	s_barrier
	v_readfirstlane_b32 s48, v21
	v_add_u32_e32 v20, 0x2000, v21
	v_add3_u32 v224, s59, v127, v126
	v_lshl_add_u64 v[16:17], v[12:13], 0, s[42:43]
	s_mov_b32 m0, s48
	v_readfirstlane_b32 s48, v20
	ds_read_b128 v[106:109], v224
	ds_read_b128 v[110:113], v224 offset:1024
	ds_read_b128 v[114:117], v224 offset:2048
	ds_read_b128 v[118:121], v224 offset:3072
	global_load_lds_dwordx4 v[16:17], off
	v_lshl_add_u64 v[16:17], v[14:15], 0, s[42:43]
	s_mov_b32 m0, s48
	s_nop 0
	global_load_lds_dwordx4 v[16:17], off
	s_barrier
	s_waitcnt lgkmcnt(0)
	s_setprio 0
	s_waitcnt lgkmcnt(0)
	v_mfma_f32_16x16x32_bf16 v[122:125], v[42:45], v[106:109], 0
	v_mfma_f32_16x16x32_bf16 v[42:45], v[42:45], v[114:117], 0
	v_mfma_f32_16x16x32_bf16 v[134:137], v[50:53], v[106:109], 0
	v_mfma_f32_16x16x32_bf16 v[50:53], v[50:53], v[114:117], 0
	v_mfma_f32_16x16x32_bf16 v[144:147], v[58:61], v[106:109], 0
	v_mfma_f32_16x16x32_bf16 v[58:61], v[58:61], v[114:117], 0
	v_mfma_f32_16x16x32_bf16 v[148:151], v[66:69], v[106:109], 0
	v_mfma_f32_16x16x32_bf16 v[66:69], v[66:69], v[114:117], 0
	v_mfma_f32_16x16x32_bf16 v[122:125], v[46:49], v[110:113], v[122:125]
	v_mfma_f32_16x16x32_bf16 v[42:45], v[46:49], v[118:121], v[42:45]
	v_mfma_f32_16x16x32_bf16 v[46:49], v[54:57], v[110:113], v[134:137]
	v_mfma_f32_16x16x32_bf16 v[50:53], v[54:57], v[118:121], v[50:53]
	v_mfma_f32_16x16x32_bf16 v[54:57], v[62:65], v[110:113], v[144:147]
	v_mfma_f32_16x16x32_bf16 v[58:61], v[62:65], v[118:121], v[58:61]
	v_mfma_f32_16x16x32_bf16 v[62:65], v[70:73], v[110:113], v[148:151]
	v_mfma_f32_16x16x32_bf16 v[66:69], v[70:73], v[118:121], v[66:69]
	s_setprio 1
	v_readfirstlane_b32 s48, v23
	v_lshl_add_u64 v[16:17], v[8:9], 0, s[42:43]
	s_mov_b32 m0, s48
	v_readfirstlane_b32 s48, v24
	s_barrier
; #define STAGE(P, BASE, LD, br, kt) do { const char* _g = (const char*)((BASE) + (size_t)(br) * (LD) + (size_t)(kt) * 64); \
;     for (int _i = 0; _i < 2; ++_i) { int _b = tidx * 16 + _i * 8192; int _r, _c; stage_rc(_b, _r, _c); \
;       __builtin_amdgcn_global_load_lds((const unsigned*)(_g + (unsigned)((_r * (LD) + _c) * 2)), (unsigned*)((char*)(P) + _b), 16, 0, 0); } } while (0)
; #define LDA(dst, b, h) for (int m = 0; m < 4; ++m) for (int k = 0; k < 2; ++k) \
;     dst[m][k] = *reinterpret_cast<const bf16x8*>((char*)SA(b, h) + lds_byte(wr * 64 + m * 16 + fr, k * 32 + fq * 8))
; #define LDB(dst, b, h) for (int n = 0; n < 2; ++n) for (int k = 0; k < 2; ++k) \
;     dst[n][k] = *reinterpret_cast<const bf16x8*>((char*)SB(b, h) + lds_byte(wc * 32 + n * 16 + fr, k * 32 + fq * 8))
; #define MMA(ai, bj, At_, Bt_) do { __builtin_amdgcn_s_setprio(1); \
;     for (int k = 0; k < 2; ++k) for (int m = 0; m < 4; ++m) for (int n = 0; n < 2; ++n) \
;       acc[ai][bj][m][n] = __builtin_amdgcn_mfma_f32_16x16x32_bf16(At_[m][k], Bt_[n][k], acc[ai][bj][m][n], 0, 0, 0); \
;     __builtin_amdgcn_s_setprio(0); } while (0)
; #define WAIT_V(n) asm volatile("s_waitcnt vmcnt(" #n ")" ::: "memory")
; #define WAIT_L(n) asm volatile("s_waitcnt lgkmcnt(" #n ")" ::: "memory")
; #define BAR __builtin_amdgcn_s_barrier()
; #define SCHED __builtin_amdgcn_sched_barrier(0)
; template <int EPI, int lda, int ldb, int N, int K>
; __device__ __forceinline__ void gemm_phase(const u16* __restrict__ A, const u16* __restrict__ Bt, const GemmEpi ep, int wv) {
;     ...
;       BAR; WAIT_L(0); MMA(0, 1, At, B1); BAR;
;       LDA(At, 0, 1); STAGE(SA(0, 0), Ab, lda, brow, t + 2);
;       BAR; WAIT_L(0); MMA(1, 0, At, B0); BAR; SCHED;
;       STAGE(SB(0, 1), Bt, ldb, bcol + HALF, t + 2);
;       WAIT_V(6); BAR; MMA(1, 1, At, B1); BAR;
;       LDB(B0, 1, 0); SCHED; LDA(At, 1, 0); STAGE(SA(0, 1), Ab, lda, brow + HALF, t + 2);
;       WAIT_L(8); BAR; WAIT_L(0); MMA(0, 0, At, B0); BAR; SCHED;
	ds_read_b128 v[70:73], v228 offset:16384
	ds_read_b128 v[134:137], v228 offset:17408
	ds_read_b128 v[144:147], v229 offset:18432
	ds_read_b128 v[148:151], v229 offset:19456
	ds_read_b128 v[152:155], v229 offset:20480
	ds_read_b128 v[156:159], v229 offset:21504
	ds_read_b128 v[160:163], v229 offset:22528
	ds_read_b128 v[164:167], v229 offset:23552
	global_load_lds_dwordx4 v[16:17], off
	v_lshl_add_u64 v[16:17], v[10:11], 0, s[42:43]
	s_mov_b32 m0, s48
	s_nop 0
	global_load_lds_dwordx4 v[16:17], off
	s_barrier
	s_waitcnt lgkmcnt(0)
	s_setprio 0
	s_waitcnt lgkmcnt(0)
	v_mfma_f32_16x16x32_bf16 v[168:171], v[70:73], v[26:29], 0
	v_mfma_f32_16x16x32_bf16 v[172:175], v[70:73], v[34:37], 0
	v_mfma_f32_16x16x32_bf16 v[176:179], v[144:147], v[26:29], 0
	v_mfma_f32_16x16x32_bf16 v[180:183], v[144:147], v[34:37], 0
	v_mfma_f32_16x16x32_bf16 v[184:187], v[152:155], v[26:29], 0
	v_mfma_f32_16x16x32_bf16 v[188:191], v[152:155], v[34:37], 0
	v_mfma_f32_16x16x32_bf16 v[24:27], v[160:163], v[26:29], 0
	v_mfma_f32_16x16x32_bf16 v[34:37], v[160:163], v[34:37], 0
	v_mfma_f32_16x16x32_bf16 v[168:171], v[134:137], v[30:33], v[168:171]
	v_mfma_f32_16x16x32_bf16 v[176:179], v[148:151], v[30:33], v[176:179]
	v_mfma_f32_16x16x32_bf16 v[184:187], v[156:159], v[30:33], v[184:187]
	v_mfma_f32_16x16x32_bf16 v[24:27], v[164:167], v[30:33], v[24:27]
	v_mfma_f32_16x16x32_bf16 v[28:31], v[164:167], v[38:41], v[34:37]
	v_mfma_f32_16x16x32_bf16 v[172:175], v[134:137], v[38:41], v[172:175]
	v_mfma_f32_16x16x32_bf16 v[180:183], v[148:151], v[38:41], v[180:183]
	v_mfma_f32_16x16x32_bf16 v[188:191], v[156:159], v[38:41], v[188:191]
	s_setprio 1
	s_barrier
	v_readfirstlane_b32 s48, v22
	v_add_u32_e32 v20, 0x2000, v22
	v_lshl_add_u64 v[16:17], v[2:3], 0, s[42:43]
	s_mov_b32 m0, s48
	v_readfirstlane_b32 s48, v20
	global_load_lds_dwordx4 v[16:17], off
	v_lshl_add_u64 v[16:17], v[0:1], 0, s[42:43]
	s_mov_b32 m0, s48
	s_nop 0
	global_load_lds_dwordx4 v[16:17], off
	s_waitcnt vmcnt(6)
	s_barrier
	s_setprio 0
	v_mfma_f32_16x16x32_bf16 v[20:23], v[70:73], v[106:109], 0
	v_mfma_f32_16x16x32_bf16 v[32:35], v[70:73], v[114:117], 0
	v_mfma_f32_16x16x32_bf16 v[36:39], v[144:147], v[106:109], 0
	v_mfma_f32_16x16x32_bf16 v[70:73], v[144:147], v[114:117], 0
	v_mfma_f32_16x16x32_bf16 v[144:147], v[152:155], v[106:109], 0
	v_mfma_f32_16x16x32_bf16 v[152:155], v[152:155], v[114:117], 0
	v_mfma_f32_16x16x32_bf16 v[106:109], v[160:163], v[106:109], 0
	v_mfma_f32_16x16x32_bf16 v[114:117], v[160:163], v[114:117], 0
	v_mfma_f32_16x16x32_bf16 v[20:23], v[134:137], v[110:113], v[20:23]
	v_mfma_f32_16x16x32_bf16 v[32:35], v[134:137], v[118:121], v[32:35]
	v_mfma_f32_16x16x32_bf16 v[36:39], v[148:151], v[110:113], v[36:39]
	v_mfma_f32_16x16x32_bf16 v[70:73], v[148:151], v[118:121], v[70:73]
	v_mfma_f32_16x16x32_bf16 v[134:137], v[156:159], v[110:113], v[144:147]
	v_mfma_f32_16x16x32_bf16 v[106:109], v[164:167], v[110:113], v[106:109]
	v_mfma_f32_16x16x32_bf16 v[110:113], v[164:167], v[118:121], v[114:117]
	v_mfma_f32_16x16x32_bf16 v[144:147], v[156:159], v[118:121], v[152:155]
	s_setprio 1
	v_add3_u32 v225, s60, v127, v126
	s_barrier
	ds_read_b128 v[114:117], v225
	ds_read_b128 v[118:121], v225 offset:1024
	ds_read_b128 v[148:151], v225 offset:2048
	ds_read_b128 v[152:155], v225 offset:3072
	v_readfirstlane_b32 s48, v18
	v_lshl_add_u64 v[16:17], v[6:7], 0, s[42:43]
	s_mov_b32 m0, s48
	v_readfirstlane_b32 s48, v19
	ds_read_b128 v[156:159], v228 offset:32768
	ds_read_b128 v[160:163], v228 offset:33792
	ds_read_b128 v[164:167], v229 offset:34816
	ds_read_b128 v[192:195], v229 offset:35840
	ds_read_b128 v[196:199], v229 offset:36864
	ds_read_b128 v[200:203], v229 offset:37888
	ds_read_b128 v[204:207], v229 offset:38912
	ds_read_b128 v[208:211], v229 offset:39936
	global_load_lds_dwordx4 v[16:17], off
	v_lshl_add_u64 v[16:17], v[4:5], 0, s[42:43]
	s_mov_b32 m0, s48
	s_nop 0
	global_load_lds_dwordx4 v[16:17], off
	s_waitcnt lgkmcnt(8)
	s_barrier
	s_waitcnt lgkmcnt(0)
	s_setprio 0
	s_waitcnt lgkmcnt(0)
	v_mfma_f32_16x16x32_bf16 v[16:19], v[156:159], v[114:117], v[74:77]
	v_mfma_f32_16x16x32_bf16 v[74:77], v[156:159], v[148:151], v[78:81]
	v_mfma_f32_16x16x32_bf16 v[78:81], v[164:167], v[114:117], v[82:85]
	v_mfma_f32_16x16x32_bf16 v[82:85], v[164:167], v[148:151], v[86:89]
	v_mfma_f32_16x16x32_bf16 v[86:89], v[196:199], v[114:117], v[90:93]
	v_mfma_f32_16x16x32_bf16 v[90:93], v[196:199], v[148:151], v[94:97]
	v_mfma_f32_16x16x32_bf16 v[94:97], v[204:207], v[114:117], v[98:101]
	v_mfma_f32_16x16x32_bf16 v[98:101], v[204:207], v[148:151], v[102:105]
	v_mfma_f32_16x16x32_bf16 v[16:19], v[160:163], v[118:121], v[16:19]
	v_mfma_f32_16x16x32_bf16 v[74:77], v[160:163], v[152:155], v[74:77]
	v_mfma_f32_16x16x32_bf16 v[78:81], v[192:195], v[118:121], v[78:81]
	v_mfma_f32_16x16x32_bf16 v[82:85], v[192:195], v[152:155], v[82:85]
	v_mfma_f32_16x16x32_bf16 v[86:89], v[200:203], v[118:121], v[86:89]
	v_mfma_f32_16x16x32_bf16 v[90:93], v[200:203], v[152:155], v[90:93]
	v_mfma_f32_16x16x32_bf16 v[94:97], v[208:211], v[118:121], v[94:97]
	v_mfma_f32_16x16x32_bf16 v[98:101], v[208:211], v[152:155], v[98:101]
	s_setprio 1
	s_barrier
	s_mov_b32 m0, s53
	v_add3_u32 v226, s61, v127, v126
	v_lshl_add_u64 v[12:13], v[12:13], 0, s[44:45]
	ds_read_b128 v[102:105], v226
	ds_read_b128 v[212:215], v226 offset:1024
	ds_read_b128 v[216:219], v226 offset:2048
	ds_read_b128 v[220:223], v226 offset:3072
	global_load_lds_dwordx4 v[12:13], off
	v_lshl_add_u64 v[12:13], v[14:15], 0, s[44:45]
	s_mov_b32 m0, s52
	s_nop 0
	global_load_lds_dwordx4 v[12:13], off
	s_barrier
; #define STAGE(P, BASE, LD, br, kt) do { const char* _g = (const char*)((BASE) + (size_t)(br) * (LD) + (size_t)(kt) * 64); \
;     for (int _i = 0; _i < 2; ++_i) { int _b = tidx * 16 + _i * 8192; int _r, _c; stage_rc(_b, _r, _c); \
;       __builtin_amdgcn_global_load_lds((const unsigned*)(_g + (unsigned)((_r * (LD) + _c) * 2)), (unsigned*)((char*)(P) + _b), 16, 0, 0); } } while (0)
; #define LDA(dst, b, h) for (int m = 0; m < 4; ++m) for (int k = 0; k < 2; ++k) \
;     dst[m][k] = *reinterpret_cast<const bf16x8*>((char*)SA(b, h) + lds_byte(wr * 64 + m * 16 + fr, k * 32 + fq * 8))
; #define LDB(dst, b, h) for (int n = 0; n < 2; ++n) for (int k = 0; k < 2; ++k) \
;     dst[n][k] = *reinterpret_cast<const bf16x8*>((char*)SB(b, h) + lds_byte(wc * 32 + n * 16 + fr, k * 32 + fq * 8))
; #define MMA(ai, bj, At_, Bt_) do { __builtin_amdgcn_s_setprio(1); \
;     for (int k = 0; k < 2; ++k) for (int m = 0; m < 4; ++m) for (int n = 0; n < 2; ++n) \
;       acc[ai][bj][m][n] = __builtin_amdgcn_mfma_f32_16x16x32_bf16(At_[m][k], Bt_[n][k], acc[ai][bj][m][n], 0, 0, 0); \
;     __builtin_amdgcn_s_setprio(0); } while (0)
; #define WAIT_V(n) asm volatile("s_waitcnt vmcnt(" #n ")" ::: "memory")
; #define WAIT_L(n) asm volatile("s_waitcnt lgkmcnt(" #n ")" ::: "memory")
; #define BAR __builtin_amdgcn_s_barrier()
; #define SCHED __builtin_amdgcn_sched_barrier(0)
; template <int EPI, int lda, int ldb, int N, int K>
; __device__ __forceinline__ void gemm_phase(const u16* __restrict__ A, const u16* __restrict__ Bt, const GemmEpi ep, int wv) {
;     ...
;       LDB(B1, 1, 1); STAGE(SB(1, 0), Bt, ldb, bcol, t + 3);
;       BAR; WAIT_L(0); MMA(0, 1, At, B1); BAR;
;       LDA(At, 1, 1); STAGE(SA(1, 0), Ab, lda, brow, t + 3);
;       BAR; WAIT_L(0); MMA(1, 0, At, B0); BAR; SCHED;
;       STAGE(SB(1, 1), Bt, ldb, bcol + HALF, t + 3);
;       WAIT_V(6); BAR; MMA(1, 1, At, B1); BAR;
;     }
;     { LDB(B0, 0, 0); LDA(At, 0, 0); STAGE(SA(1, 1), Ab, lda, brow + HALF, nt - 1);
	s_waitcnt lgkmcnt(0)
	s_setprio 0
	s_waitcnt lgkmcnt(0)
	v_mfma_f32_16x16x32_bf16 v[12:15], v[156:159], v[102:105], v[122:125]
	v_mfma_f32_16x16x32_bf16 v[40:43], v[156:159], v[216:219], v[42:45]
	v_mfma_f32_16x16x32_bf16 v[44:47], v[164:167], v[102:105], v[46:49]
	v_mfma_f32_16x16x32_bf16 v[48:51], v[164:167], v[216:219], v[50:53]
	v_mfma_f32_16x16x32_bf16 v[52:55], v[196:199], v[102:105], v[54:57]
	v_mfma_f32_16x16x32_bf16 v[56:59], v[196:199], v[216:219], v[58:61]
	v_mfma_f32_16x16x32_bf16 v[60:63], v[204:207], v[102:105], v[62:65]
	v_mfma_f32_16x16x32_bf16 v[64:67], v[204:207], v[216:219], v[66:69]
	v_mfma_f32_16x16x32_bf16 v[12:15], v[160:163], v[212:215], v[12:15]
	v_mfma_f32_16x16x32_bf16 v[40:43], v[160:163], v[220:223], v[40:43]
	v_mfma_f32_16x16x32_bf16 v[44:47], v[192:195], v[212:215], v[44:47]
	v_mfma_f32_16x16x32_bf16 v[48:51], v[192:195], v[220:223], v[48:51]
	v_mfma_f32_16x16x32_bf16 v[52:55], v[200:203], v[212:215], v[52:55]
	v_mfma_f32_16x16x32_bf16 v[56:59], v[200:203], v[220:223], v[56:59]
	v_mfma_f32_16x16x32_bf16 v[60:63], v[208:211], v[212:215], v[60:63]
	v_mfma_f32_16x16x32_bf16 v[64:67], v[208:211], v[220:223], v[64:67]
	s_setprio 1
	s_mov_b32 m0, s51
	v_lshl_add_u64 v[8:9], v[8:9], 0, s[44:45]
	s_barrier
	ds_read_b128 v[122:125], v228 offset:49152
	ds_read_b128 v[156:159], v228 offset:50176
	ds_read_b128 v[160:163], v229 offset:51200
	ds_read_b128 v[164:167], v229 offset:52224
	ds_read_b128 v[192:195], v229 offset:53248
	ds_read_b128 v[196:199], v229 offset:54272
	ds_read_b128 v[200:203], v229 offset:55296
	ds_read_b128 v[204:207], v229 offset:56320
	global_load_lds_dwordx4 v[8:9], off
	v_lshl_add_u64 v[8:9], v[10:11], 0, s[44:45]
	s_mov_b32 m0, s50
	s_nop 0
	global_load_lds_dwordx4 v[8:9], off
	s_barrier
	s_waitcnt lgkmcnt(0)
	s_setprio 0
	s_waitcnt lgkmcnt(0)
	v_mfma_f32_16x16x32_bf16 v[8:11], v[122:125], v[114:117], v[168:171]
	v_mfma_f32_16x16x32_bf16 v[168:171], v[122:125], v[148:151], v[172:175]
	v_mfma_f32_16x16x32_bf16 v[24:27], v[200:203], v[114:117], v[24:27]
	v_mfma_f32_16x16x32_bf16 v[28:31], v[200:203], v[148:151], v[28:31]
	v_mfma_f32_16x16x32_bf16 v[172:175], v[160:163], v[114:117], v[176:179]
	v_mfma_f32_16x16x32_bf16 v[176:179], v[160:163], v[148:151], v[180:183]
	v_mfma_f32_16x16x32_bf16 v[180:183], v[192:195], v[114:117], v[184:187]
	v_mfma_f32_16x16x32_bf16 v[184:187], v[192:195], v[148:151], v[188:191]
	v_mfma_f32_16x16x32_bf16 v[8:11], v[156:159], v[118:121], v[8:11]
	v_mfma_f32_16x16x32_bf16 v[114:117], v[156:159], v[152:155], v[168:171]
	v_mfma_f32_16x16x32_bf16 v[24:27], v[204:207], v[118:121], v[24:27]
	v_mfma_f32_16x16x32_bf16 v[28:31], v[204:207], v[152:155], v[28:31]
	v_mfma_f32_16x16x32_bf16 v[148:151], v[164:167], v[118:121], v[172:175]
	v_mfma_f32_16x16x32_bf16 v[168:171], v[164:167], v[152:155], v[176:179]
	v_mfma_f32_16x16x32_bf16 v[172:175], v[196:199], v[118:121], v[180:183]
	v_mfma_f32_16x16x32_bf16 v[176:179], v[196:199], v[152:155], v[184:187]
	s_setprio 1
	s_barrier
	s_mov_b32 m0, s13
	v_lshl_add_u64 v[2:3], v[2:3], 0, s[44:45]
	global_load_lds_dwordx4 v[2:3], off
	v_lshl_add_u64 v[0:1], v[0:1], 0, s[44:45]
	s_mov_b32 m0, s11
	s_nop 0
	global_load_lds_dwordx4 v[0:1], off
	s_waitcnt vmcnt(6)
	s_barrier
	s_setprio 0
	v_mfma_f32_16x16x32_bf16 v[0:3], v[122:125], v[102:105], v[20:23]
	v_mfma_f32_16x16x32_bf16 v[20:23], v[122:125], v[216:219], v[32:35]
	v_mfma_f32_16x16x32_bf16 v[32:35], v[160:163], v[102:105], v[36:39]
	v_mfma_f32_16x16x32_bf16 v[36:39], v[160:163], v[216:219], v[70:73]
	v_mfma_f32_16x16x32_bf16 v[68:71], v[192:195], v[102:105], v[134:137]
	v_mfma_f32_16x16x32_bf16 v[118:121], v[192:195], v[216:219], v[144:147]
	v_mfma_f32_16x16x32_bf16 v[102:105], v[200:203], v[102:105], v[106:109]
	v_mfma_f32_16x16x32_bf16 v[106:109], v[200:203], v[216:219], v[110:113]
	v_mfma_f32_16x16x32_bf16 v[0:3], v[156:159], v[212:215], v[0:3]
	v_mfma_f32_16x16x32_bf16 v[20:23], v[156:159], v[220:223], v[20:23]
	v_mfma_f32_16x16x32_bf16 v[32:35], v[164:167], v[212:215], v[32:35]
	v_mfma_f32_16x16x32_bf16 v[36:39], v[164:167], v[220:223], v[36:39]
	v_mfma_f32_16x16x32_bf16 v[68:71], v[196:199], v[212:215], v[68:71]
	v_mfma_f32_16x16x32_bf16 v[110:113], v[196:199], v[220:223], v[118:121]
	v_mfma_f32_16x16x32_bf16 v[102:105], v[204:207], v[212:215], v[102:105]
	v_mfma_f32_16x16x32_bf16 v[106:109], v[204:207], v[220:223], v[106:109]
	s_setprio 1
	s_mov_b32 m0, s47
	v_lshl_add_u64 v[6:7], v[6:7], 0, s[44:45]
	s_barrier
	ds_read_b128 v[118:121], v133
	ds_read_b128 v[122:125], v133 offset:1024
	ds_read_b128 v[134:137], v133 offset:2048
	ds_read_b128 v[144:147], v133 offset:3072
	ds_read_b128 v[152:155], v228
	ds_read_b128 v[156:159], v228 offset:1024
	ds_read_b128 v[160:163], v229 offset:2048
	ds_read_b128 v[164:167], v229 offset:3072
	ds_read_b128 v[180:183], v229 offset:4096
	ds_read_b128 v[184:187], v229 offset:5120
	ds_read_b128 v[188:191], v229 offset:6144
	ds_read_b128 v[192:195], v229 offset:7168
	global_load_lds_dwordx4 v[6:7], off
	v_lshl_add_u64 v[4:5], v[4:5], 0, s[44:45]
	s_mov_b32 m0, s46
	s_nop 0
	global_load_lds_dwordx4 v[4:5], off
	s_barrier
; #define STAGE(P, BASE, LD, br, kt) do { const char* _g = (const char*)((BASE) + (size_t)(br) * (LD) + (size_t)(kt) * 64); \
;     for (int _i = 0; _i < 2; ++_i) { int _b = tidx * 16 + _i * 8192; int _r, _c; stage_rc(_b, _r, _c); \
;       __builtin_amdgcn_global_load_lds((const unsigned*)(_g + (unsigned)((_r * (LD) + _c) * 2)), (unsigned*)((char*)(P) + _b), 16, 0, 0); } } while (0)
; #define LDA(dst, b, h) for (int m = 0; m < 4; ++m) for (int k = 0; k < 2; ++k) \
;     dst[m][k] = *reinterpret_cast<const bf16x8*>((char*)SA(b, h) + lds_byte(wr * 64 + m * 16 + fr, k * 32 + fq * 8))
; #define LDB(dst, b, h) for (int n = 0; n < 2; ++n) for (int k = 0; k < 2; ++k) \
;     dst[n][k] = *reinterpret_cast<const bf16x8*>((char*)SB(b, h) + lds_byte(wc * 32 + n * 16 + fr, k * 32 + fq * 8))
; #define MMA(ai, bj, At_, Bt_) do { __builtin_amdgcn_s_setprio(1); \
;     for (int k = 0; k < 2; ++k) for (int m = 0; m < 4; ++m) for (int n = 0; n < 2; ++n) \
;       acc[ai][bj][m][n] = __builtin_amdgcn_mfma_f32_16x16x32_bf16(At_[m][k], Bt_[n][k], acc[ai][bj][m][n], 0, 0, 0); \
;     __builtin_amdgcn_s_setprio(0); } while (0)
; #define WAIT_V(n) asm volatile("s_waitcnt vmcnt(" #n ")" ::: "memory")
; #define WAIT_L(n) asm volatile("s_waitcnt lgkmcnt(" #n ")" ::: "memory")
; #define BAR __builtin_amdgcn_s_barrier()
; template <int EPI, int lda, int ldb, int N, int K>
; __device__ __forceinline__ void gemm_phase(const u16* __restrict__ A, const u16* __restrict__ Bt, const GemmEpi ep, int wv) {
;     ...
;     { LDB(B0, 0, 0); LDA(At, 0, 0); STAGE(SA(1, 1), Ab, lda, brow + HALF, nt - 1);
;       BAR; WAIT_L(0); MMA(0, 0, At, B0); BAR;
;       LDB(B1, 0, 1); BAR; WAIT_L(0); MMA(0, 1, At, B1); BAR;
;       LDA(At, 0, 1); WAIT_V(4); BAR; WAIT_L(0); MMA(1, 0, At, B0); MMA(1, 1, At, B1); BAR; }
	s_waitcnt lgkmcnt(0)
	s_setprio 0
	s_waitcnt lgkmcnt(0)
	v_mfma_f32_16x16x32_bf16 v[4:7], v[152:155], v[118:121], v[16:19]
	v_mfma_f32_16x16x32_bf16 v[16:19], v[152:155], v[134:137], v[74:77]
	v_mfma_f32_16x16x32_bf16 v[72:75], v[160:163], v[118:121], v[78:81]
	v_mfma_f32_16x16x32_bf16 v[76:79], v[160:163], v[134:137], v[82:85]
	v_mfma_f32_16x16x32_bf16 v[80:83], v[180:183], v[118:121], v[86:89]
	v_mfma_f32_16x16x32_bf16 v[84:87], v[180:183], v[134:137], v[90:93]
	v_mfma_f32_16x16x32_bf16 v[88:91], v[188:191], v[118:121], v[94:97]
	v_mfma_f32_16x16x32_bf16 v[92:95], v[188:191], v[134:137], v[98:101]
	v_mfma_f32_16x16x32_bf16 v[4:7], v[156:159], v[122:125], v[4:7]
	v_mfma_f32_16x16x32_bf16 v[16:19], v[156:159], v[144:147], v[16:19]
	v_mfma_f32_16x16x32_bf16 v[72:75], v[164:167], v[122:125], v[72:75]
	v_mfma_f32_16x16x32_bf16 v[76:79], v[164:167], v[144:147], v[76:79]
	v_mfma_f32_16x16x32_bf16 v[80:83], v[184:187], v[122:125], v[80:83]
	v_mfma_f32_16x16x32_bf16 v[84:87], v[184:187], v[144:147], v[84:87]
	v_mfma_f32_16x16x32_bf16 v[88:91], v[192:195], v[122:125], v[88:91]
	v_mfma_f32_16x16x32_bf16 v[92:95], v[192:195], v[144:147], v[92:95]
	s_setprio 1
	s_barrier
	ds_read_b128 v[96:99], v224
	ds_read_b128 v[196:199], v224 offset:1024
	ds_read_b128 v[200:203], v224 offset:2048
	ds_read_b128 v[204:207], v224 offset:3072
	s_barrier
	s_waitcnt lgkmcnt(0)
	s_setprio 0
	s_waitcnt lgkmcnt(0)
	v_mfma_f32_16x16x32_bf16 v[12:15], v[152:155], v[96:99], v[12:15]
	v_mfma_f32_16x16x32_bf16 v[40:43], v[152:155], v[200:203], v[40:43]
	v_mfma_f32_16x16x32_bf16 v[52:55], v[180:183], v[96:99], v[52:55]
	v_mfma_f32_16x16x32_bf16 v[56:59], v[180:183], v[200:203], v[56:59]
	v_mfma_f32_16x16x32_bf16 v[64:67], v[188:191], v[200:203], v[64:67]
	v_mfma_f32_16x16x32_bf16 v[44:47], v[160:163], v[96:99], v[44:47]
	v_mfma_f32_16x16x32_bf16 v[48:51], v[160:163], v[200:203], v[48:51]
	v_mfma_f32_16x16x32_bf16 v[60:63], v[188:191], v[96:99], v[60:63]
	v_mfma_f32_16x16x32_bf16 v[12:15], v[156:159], v[196:199], v[12:15]
	v_mfma_f32_16x16x32_bf16 v[40:43], v[156:159], v[204:207], v[40:43]
	v_mfma_f32_16x16x32_bf16 v[52:55], v[184:187], v[196:199], v[52:55]
	v_mfma_f32_16x16x32_bf16 v[56:59], v[184:187], v[204:207], v[56:59]
	v_mfma_f32_16x16x32_bf16 v[64:67], v[192:195], v[204:207], v[64:67]
	v_mfma_f32_16x16x32_bf16 v[152:155], v[164:167], v[196:199], v[44:47]
	v_mfma_f32_16x16x32_bf16 v[156:159], v[164:167], v[204:207], v[48:51]
	v_mfma_f32_16x16x32_bf16 v[160:163], v[192:195], v[196:199], v[60:63]
	s_setprio 1
	s_barrier
	ds_read_b128 v[44:47], v228 offset:16384
	ds_read_b128 v[48:51], v228 offset:17408
	ds_read_b128 v[60:63], v229 offset:18432
	ds_read_b128 v[164:167], v229 offset:19456
	ds_read_b128 v[180:183], v229 offset:20480
	ds_read_b128 v[184:187], v229 offset:21504
	ds_read_b128 v[188:191], v229 offset:22528
	ds_read_b128 v[192:195], v229 offset:23552
	s_waitcnt vmcnt(4)
	s_barrier
	s_waitcnt lgkmcnt(0)
	s_setprio 0
	s_waitcnt lgkmcnt(0)
	v_mfma_f32_16x16x32_bf16 v[8:11], v[44:47], v[118:121], v[8:11]
	v_mfma_f32_16x16x32_bf16 v[24:27], v[188:191], v[118:121], v[24:27]
	v_mfma_f32_16x16x32_bf16 v[28:31], v[188:191], v[134:137], v[28:31]
	v_mfma_f32_16x16x32_bf16 v[114:117], v[44:47], v[134:137], v[114:117]
	v_mfma_f32_16x16x32_bf16 v[148:151], v[60:63], v[118:121], v[148:151]
	v_mfma_f32_16x16x32_bf16 v[168:171], v[60:63], v[134:137], v[168:171]
	v_mfma_f32_16x16x32_bf16 v[172:175], v[180:183], v[118:121], v[172:175]
	v_mfma_f32_16x16x32_bf16 v[176:179], v[180:183], v[134:137], v[176:179]
	v_mfma_f32_16x16x32_bf16 v[8:11], v[48:51], v[122:125], v[8:11]
	v_mfma_f32_16x16x32_bf16 v[24:27], v[192:195], v[122:125], v[24:27]
	v_mfma_f32_16x16x32_bf16 v[28:31], v[192:195], v[144:147], v[28:31]
	v_mfma_f32_16x16x32_bf16 v[134:137], v[48:51], v[144:147], v[114:117]
	v_mfma_f32_16x16x32_bf16 v[148:151], v[164:167], v[122:125], v[148:151]
	v_mfma_f32_16x16x32_bf16 v[168:171], v[164:167], v[144:147], v[168:171]
	v_mfma_f32_16x16x32_bf16 v[172:175], v[184:187], v[122:125], v[172:175]
	v_mfma_f32_16x16x32_bf16 v[176:179], v[184:187], v[144:147], v[176:179]
	s_setprio 1
	s_setprio 0
	v_mfma_f32_16x16x32_bf16 v[0:3], v[44:47], v[96:99], v[0:3]
	v_mfma_f32_16x16x32_bf16 v[20:23], v[44:47], v[200:203], v[20:23]
	v_mfma_f32_16x16x32_bf16 v[44:47], v[180:183], v[96:99], v[68:71]
	v_mfma_f32_16x16x32_bf16 v[68:71], v[188:191], v[96:99], v[102:105]
	v_mfma_f32_16x16x32_bf16 v[32:35], v[60:63], v[96:99], v[32:35]
	v_mfma_f32_16x16x32_bf16 v[36:39], v[60:63], v[200:203], v[36:39]
	v_mfma_f32_16x16x32_bf16 v[60:63], v[180:183], v[200:203], v[110:113]
	v_mfma_f32_16x16x32_bf16 v[96:99], v[188:191], v[200:203], v[106:109]
	v_mfma_f32_16x16x32_bf16 v[20:23], v[48:51], v[204:207], v[20:23]
	v_mfma_f32_16x16x32_bf16 v[68:71], v[192:195], v[196:199], v[68:71]
	v_mfma_f32_16x16x32_bf16 v[144:147], v[48:51], v[196:199], v[0:3]
	v_mfma_f32_16x16x32_bf16 v[180:183], v[164:167], v[196:199], v[32:35]
	v_mfma_f32_16x16x32_bf16 v[164:167], v[164:167], v[204:207], v[36:39]
	v_mfma_f32_16x16x32_bf16 v[188:191], v[184:187], v[196:199], v[44:47]
	v_mfma_f32_16x16x32_bf16 v[184:187], v[184:187], v[204:207], v[60:63]
	v_mfma_f32_16x16x32_bf16 v[192:195], v[192:195], v[204:207], v[96:99]
	s_setprio 1
	s_barrier
	ds_read_b128 v[0:3], v225
	ds_read_b128 v[196:199], v225 offset:1024
	ds_read_b128 v[200:203], v225 offset:2048
	ds_read_b128 v[204:207], v225 offset:3072
	ds_read_b128 v[36:39], v228 offset:32768
	ds_read_b128 v[100:103], v228 offset:33792
	ds_read_b128 v[108:111], v229 offset:34816
	ds_read_b128 v[208:211], v229 offset:35840
	ds_read_b128 v[116:119], v229 offset:36864
	ds_read_b128 v[212:215], v229 offset:37888
	ds_read_b128 v[124:127], v229 offset:38912
	ds_read_b128 v[216:219], v229 offset:39936
	s_waitcnt vmcnt(2)
	s_barrier
; #define LDA(dst, b, h) for (int m = 0; m < 4; ++m) for (int k = 0; k < 2; ++k) \
;     dst[m][k] = *reinterpret_cast<const bf16x8*>((char*)SA(b, h) + lds_byte(wr * 64 + m * 16 + fr, k * 32 + fq * 8))
; #define LDB(dst, b, h) for (int n = 0; n < 2; ++n) for (int k = 0; k < 2; ++k) \
;     dst[n][k] = *reinterpret_cast<const bf16x8*>((char*)SB(b, h) + lds_byte(wc * 32 + n * 16 + fr, k * 32 + fq * 8))
; #define MMA(ai, bj, At_, Bt_) do { __builtin_amdgcn_s_setprio(1); \
;     for (int k = 0; k < 2; ++k) for (int m = 0; m < 4; ++m) for (int n = 0; n < 2; ++n) \
;       acc[ai][bj][m][n] = __builtin_amdgcn_mfma_f32_16x16x32_bf16(At_[m][k], Bt_[n][k], acc[ai][bj][m][n], 0, 0, 0); \
;     __builtin_amdgcn_s_setprio(0); } while (0)
; #define WAIT_V(n) asm volatile("s_waitcnt vmcnt(" #n ")" ::: "memory")
; #define WAIT_L(n) asm volatile("s_waitcnt lgkmcnt(" #n ")" ::: "memory")
; #define BAR __builtin_amdgcn_s_barrier()
; template <int EPI, int lda, int ldb, int N, int K>
; __device__ __forceinline__ void gemm_phase(const u16* __restrict__ A, const u16* __restrict__ Bt, const GemmEpi ep, int wv) {
;     ...
;     { LDB(B0, 1, 0); LDA(At, 1, 0); WAIT_V(2); BAR; WAIT_L(0); MMA(0, 0, At, B0); BAR;
;       LDB(B1, 1, 1); WAIT_V(0); BAR; WAIT_L(0); MMA(0, 1, At, B1); BAR;
;       LDA(At, 1, 1); BAR; WAIT_L(0); MMA(1, 0, At, B0); MMA(1, 1, At, B1); BAR; }
;     if (wr == 0) BAR;
	s_waitcnt lgkmcnt(0)
	s_setprio 0
	s_waitcnt lgkmcnt(0)
	v_mfma_f32_16x16x32_bf16 v[4:7], v[36:39], v[0:3], v[4:7]
	v_mfma_f32_16x16x32_bf16 v[16:19], v[36:39], v[200:203], v[16:19]
	v_mfma_f32_16x16x32_bf16 v[32:35], v[108:111], v[0:3], v[72:75]
	v_mfma_f32_16x16x32_bf16 v[44:47], v[108:111], v[200:203], v[76:79]
	v_mfma_f32_16x16x32_bf16 v[72:75], v[116:119], v[0:3], v[80:83]
	v_mfma_f32_16x16x32_bf16 v[76:79], v[116:119], v[200:203], v[84:87]
	v_mfma_f32_16x16x32_bf16 v[80:83], v[124:127], v[0:3], v[88:91]
	v_mfma_f32_16x16x32_bf16 v[84:87], v[124:127], v[200:203], v[92:95]
	v_mfma_f32_16x16x32_bf16 v[120:123], v[100:103], v[196:199], v[4:7]
	v_mfma_f32_16x16x32_bf16 v[60:63], v[100:103], v[204:207], v[16:19]
	v_mfma_f32_16x16x32_bf16 v[112:115], v[208:211], v[196:199], v[32:35]
	v_mfma_f32_16x16x32_bf16 v[48:51], v[208:211], v[204:207], v[44:47]
	v_mfma_f32_16x16x32_bf16 v[104:107], v[212:215], v[196:199], v[72:75]
	v_mfma_f32_16x16x32_bf16 v[44:47], v[212:215], v[204:207], v[76:79]
	v_mfma_f32_16x16x32_bf16 v[96:99], v[216:219], v[196:199], v[80:83]
	v_mfma_f32_16x16x32_bf16 v[32:35], v[216:219], v[204:207], v[84:87]
	s_setprio 1
	s_barrier
	ds_read_b128 v[4:7], v226
	ds_read_b128 v[220:223], v226 offset:1024
	ds_read_b128 v[76:79], v226 offset:2048
	ds_read_b128 v[224:227], v226 offset:3072
	s_waitcnt vmcnt(0)
	s_barrier
	s_waitcnt lgkmcnt(0)
	s_setprio 0
	s_waitcnt lgkmcnt(0)
	v_mfma_f32_16x16x32_bf16 v[12:15], v[36:39], v[4:7], v[12:15]
	v_mfma_f32_16x16x32_bf16 v[16:19], v[36:39], v[76:79], v[40:43]
	v_mfma_f32_16x16x32_bf16 v[36:39], v[108:111], v[4:7], v[152:155]
	v_mfma_f32_16x16x32_bf16 v[40:43], v[108:111], v[76:79], v[156:159]
	v_mfma_f32_16x16x32_bf16 v[72:75], v[116:119], v[4:7], v[52:55]
	v_mfma_f32_16x16x32_bf16 v[80:83], v[116:119], v[76:79], v[56:59]
	v_mfma_f32_16x16x32_bf16 v[84:87], v[124:127], v[4:7], v[160:163]
	v_mfma_f32_16x16x32_bf16 v[64:67], v[124:127], v[76:79], v[64:67]
	v_mfma_f32_16x16x32_bf16 v[124:127], v[100:103], v[220:223], v[12:15]
	v_mfma_f32_16x16x32_bf16 v[56:59], v[100:103], v[224:227], v[16:19]
	v_mfma_f32_16x16x32_bf16 v[116:119], v[208:211], v[220:223], v[36:39]
	v_mfma_f32_16x16x32_bf16 v[52:55], v[208:211], v[224:227], v[40:43]
	v_mfma_f32_16x16x32_bf16 v[108:111], v[212:215], v[220:223], v[72:75]
	v_mfma_f32_16x16x32_bf16 v[40:43], v[212:215], v[224:227], v[80:83]
	v_mfma_f32_16x16x32_bf16 v[100:103], v[216:219], v[220:223], v[84:87]
	v_mfma_f32_16x16x32_bf16 v[36:39], v[216:219], v[224:227], v[64:67]
	s_setprio 1
	s_barrier
	ds_read_b128 v[84:87], v228 offset:49152
	ds_read_b128 v[152:155], v228 offset:50176
	ds_read_b128 v[92:95], v229 offset:51200
	ds_read_b128 v[156:159], v229 offset:52224
	ds_read_b128 v[160:163], v229 offset:53248
	ds_read_b128 v[208:211], v229 offset:54272
	ds_read_b128 v[212:215], v229 offset:55296
	ds_read_b128 v[216:219], v229 offset:56320
	s_barrier
	s_waitcnt lgkmcnt(0)
	s_setprio 0
	s_waitcnt lgkmcnt(0)
	v_mfma_f32_16x16x32_bf16 v[8:11], v[84:87], v[0:3], v[8:11]
	v_mfma_f32_16x16x32_bf16 v[12:15], v[84:87], v[200:203], v[134:137]
	v_mfma_f32_16x16x32_bf16 v[16:19], v[92:95], v[0:3], v[148:151]
	v_mfma_f32_16x16x32_bf16 v[64:67], v[92:95], v[200:203], v[168:171]
	v_mfma_f32_16x16x32_bf16 v[72:75], v[160:163], v[0:3], v[172:175]
	v_mfma_f32_16x16x32_bf16 v[134:137], v[160:163], v[200:203], v[176:179]
	v_mfma_f32_16x16x32_bf16 v[0:3], v[212:215], v[0:3], v[24:27]
	v_mfma_f32_16x16x32_bf16 v[24:27], v[212:215], v[200:203], v[28:31]
	v_mfma_f32_16x16x32_bf16 v[88:91], v[152:155], v[196:199], v[8:11]
	v_mfma_f32_16x16x32_bf16 v[28:31], v[152:155], v[204:207], v[12:15]
	v_mfma_f32_16x16x32_bf16 v[80:83], v[156:159], v[196:199], v[16:19]
	v_mfma_f32_16x16x32_bf16 v[16:19], v[156:159], v[204:207], v[64:67]
	v_mfma_f32_16x16x32_bf16 v[72:75], v[208:211], v[196:199], v[72:75]
	v_mfma_f32_16x16x32_bf16 v[12:15], v[208:211], v[204:207], v[134:137]
	v_mfma_f32_16x16x32_bf16 v[64:67], v[216:219], v[196:199], v[0:3]
	v_mfma_f32_16x16x32_bf16 v[0:3], v[216:219], v[204:207], v[24:27]
	s_setprio 1
	s_setprio 0
	v_mfma_f32_16x16x32_bf16 v[8:11], v[84:87], v[4:7], v[144:147]
	v_mfma_f32_16x16x32_bf16 v[20:23], v[84:87], v[76:79], v[20:23]
	v_mfma_f32_16x16x32_bf16 v[84:87], v[92:95], v[4:7], v[180:183]
	v_mfma_f32_16x16x32_bf16 v[134:137], v[92:95], v[76:79], v[164:167]
	v_mfma_f32_16x16x32_bf16 v[144:147], v[160:163], v[4:7], v[188:191]
	v_mfma_f32_16x16x32_bf16 v[148:151], v[160:163], v[76:79], v[184:187]
	v_mfma_f32_16x16x32_bf16 v[4:7], v[212:215], v[4:7], v[68:71]
	v_mfma_f32_16x16x32_bf16 v[160:163], v[212:215], v[76:79], v[192:195]
	v_mfma_f32_16x16x32_bf16 v[92:95], v[152:155], v[220:223], v[8:11]
	v_mfma_f32_16x16x32_bf16 v[24:27], v[152:155], v[224:227], v[20:23]
	v_mfma_f32_16x16x32_bf16 v[84:87], v[156:159], v[220:223], v[84:87]
	v_mfma_f32_16x16x32_bf16 v[20:23], v[156:159], v[224:227], v[134:137]
	v_mfma_f32_16x16x32_bf16 v[76:79], v[208:211], v[220:223], v[144:147]
	v_mfma_f32_16x16x32_bf16 v[8:11], v[208:211], v[224:227], v[148:151]
	v_mfma_f32_16x16x32_bf16 v[68:71], v[216:219], v[220:223], v[4:7]
	v_mfma_f32_16x16x32_bf16 v[4:7], v[216:219], v[224:227], v[160:163]
	s_setprio 1
	v_cmp_gt_u32_e32 vcc, s62, v130
	s_barrier
	s_and_saveexec_b64 s[46:47], vcc
	s_cbranch_execz .LBB0_1245
	s_barrier
	s_branch .LBB0_1245

; #define STAGE(P, BASE, LD, br, kt) do { const char* _g = (const char*)((BASE) + (size_t)(br) * (LD) + (size_t)(kt) * 64); \
;     for (int _i = 0; _i < 2; ++_i) { int _b = tidx * 16 + _i * 8192; int _r, _c; stage_rc(_b, _r, _c); \
;       __builtin_amdgcn_global_load_lds((const unsigned*)(_g + (unsigned)((_r * (LD) + _c) * 2)), (unsigned*)((char*)(P) + _b), 16, 0, 0); } } while (0)
; #define LDA(dst, b, h) for (int m = 0; m < 4; ++m) for (int k = 0; k < 2; ++k) \
;     dst[m][k] = *reinterpret_cast<const bf16x8*>((char*)SA(b, h) + lds_byte(wr * 64 + m * 16 + fr, k * 32 + fq * 8))
; #define LDB(dst, b, h) for (int n = 0; n < 2; ++n) for (int k = 0; k < 2; ++k) \
;     dst[n][k] = *reinterpret_cast<const bf16x8*>((char*)SB(b, h) + lds_byte(wc * 32 + n * 16 + fr, k * 32 + fq * 8))
; #define MMA(ai, bj, At_, Bt_) do { __builtin_amdgcn_s_setprio(1); \
;     for (int k = 0; k < 2; ++k) for (int m = 0; m < 4; ++m) for (int n = 0; n < 2; ++n) \
;       acc[ai][bj][m][n] = __builtin_amdgcn_mfma_f32_16x16x32_bf16(At_[m][k], Bt_[n][k], acc[ai][bj][m][n], 0, 0, 0); \
;     __builtin_amdgcn_s_setprio(0); } while (0)
; #define WAIT_V(n) asm volatile("s_waitcnt vmcnt(" #n ")" ::: "memory")
; #define WAIT_L(n) asm volatile("s_waitcnt lgkmcnt(" #n ")" ::: "memory")
; #define BAR __builtin_amdgcn_s_barrier()
; template <int EPI, int lda, int ldb, int N, int K>
; __device__ __forceinline__ void gemm_phase(const u16* __restrict__ A, const u16* __restrict__ Bt, const GemmEpi ep, int wv) {
;     ...
;     if constexpr (!PF) { TILE_COORDS(tile, brow, bcol, pn); STAGE4(brow, bcol, pn); }
;     const int wid = tidx >> 6, lane = tidx & 63, wr = wid >> 2, wc = wid & 3, fr = lane & 15, fq = lane >> 4;
;     const u16* Ab = A + (EPI == EPI_RG ? (pn >> 1) * 256 : 0);
;     f32x4 acc[2][2][4][2] = {};
;     bf16x8 At[4][2], B0[2][2], B1[2][2];
;     constexpr int nt = K / 64;
;     if (wr == 1) BAR;
;     WAIT_V(4); BAR;
;     STAGE(SB(1, 0), Bt, ldb, bcol, 1); STAGE(SA(1, 0), Ab, lda, brow, 1); STAGE(SB(1, 1), Bt, ldb, bcol + HALF, 1);
;     WAIT_V(6); BAR;
;     for (int t = 0; t < nt - 2; t += 2) {
;       LDB(B0, 0, 0); SCHED; LDA(At, 0, 0); STAGE(SA(1, 1), Ab, lda, brow + HALF, t + 1);
;       WAIT_L(8); BAR; WAIT_L(0); MMA(0, 0, At, B0); BAR; SCHED;
;       LDB(B1, 0, 1); STAGE(SB(0, 0), Bt, ldb, bcol, t + 2);
;       BAR; WAIT_L(0); MMA(0, 1, At, B1); BAR;
.LBB0_1349:
	s_or_b64 exec, exec, s[54:55]
	v_mov_b32_e32 v1, v129
	v_add_u32_e32 v7, s58, v6
	v_lshl_add_u64 v[12:13], s[46:47], 0, v[128:129]
	v_lshl_add_u64 v[14:15], s[46:47], 0, v[0:1]
	v_lshl_add_u64 v[2:3], s[52:53], 0, v[128:129]
	v_lshl_add_u64 v[0:1], s[52:53], 0, v[0:1]
	v_readfirstlane_b32 s53, v7
	v_add_u32_e32 v7, 0x2000, v7
	v_mov_b32_e32 v5, v129
	v_mov_b32_e32 v17, v129
	v_lshl_add_u64 v[26:27], v[12:13], 0, s[36:37]
	s_mov_b32 m0, s53
	v_readfirstlane_b32 s52, v7
	v_add_u32_e32 v7, 0x8000, v23
	v_lshl_add_u64 v[8:9], s[50:51], 0, v[4:5]
	v_lshl_add_u64 v[10:11], s[50:51], 0, v[16:17]
	s_waitcnt vmcnt(4)
	s_barrier
	global_load_lds_dwordx4 v[26:27], off
	v_lshl_add_u64 v[26:27], v[14:15], 0, s[36:37]
	s_mov_b32 m0, s52
	v_readfirstlane_b32 s51, v7
	v_add_u32_e32 v7, 0xa000, v23
	global_load_lds_dwordx4 v[26:27], off
	v_lshl_add_u64 v[26:27], v[8:9], 0, s[36:37]
	s_mov_b32 m0, s51
	v_readfirstlane_b32 s50, v7
	v_add_u32_e32 v25, s59, v6
	global_load_lds_dwordx4 v[26:27], off
	v_lshl_add_u64 v[26:27], v[10:11], 0, s[36:37]
	s_mov_b32 m0, s50
	v_readfirstlane_b32 s11, v25
	v_add_u32_e32 v25, 0x2000, v25
	global_load_lds_dwordx4 v[26:27], off
	v_lshl_add_u64 v[26:27], v[2:3], 0, s[36:37]
	s_mov_b32 m0, s11
	v_readfirstlane_b32 s5, v25
	global_load_lds_dwordx4 v[26:27], off
	v_lshl_add_u64 v[6:7], v[0:1], 0, s[36:37]
	s_mov_b32 m0, s5
	v_and_b32_e32 v132, 15, v20
	global_load_lds_dwordx4 v[6:7], off
	v_bfe_u32 v128, v20, 4, 2
	v_lshlrev_b32_e32 v7, 2, v20
	v_bfe_u32 v131, v130, 6, 2
	v_lshlrev_b32_e32 v25, 4, v128
	v_lshlrev_b32_e32 v6, 6, v132
	v_and_b32_e32 v50, 32, v7
	v_lshlrev_b32_e32 v126, 12, v131
	v_bitop3_b32 v127, v25, v50, v6 bitop3:0x36
	v_add3_u32 v133, s56, v127, v126
	s_waitcnt vmcnt(6)
	s_barrier
	ds_read_b128 v[26:29], v133
	ds_read_b128 v[30:33], v133 offset:1024
	ds_read_b128 v[34:37], v133 offset:2048
	ds_read_b128 v[38:41], v133 offset:3072
	v_lshl_add_u64 v[6:7], s[48:49], 0, v[4:5]
	v_lshl_add_u64 v[4:5], s[48:49], 0, v[16:17]
	v_lshlrev_b32_e32 v17, 6, v20
	v_and_b32_e32 v17, 0x3c0, v17
	v_add_u32_e32 v20, 0xc000, v23
	v_lshlrev_b32_e32 v16, 13, v139
	v_bitop3_b32 v17, v17, v50, v25 bitop3:0x36
	v_readfirstlane_b32 s47, v20
	v_add_u32_e32 v20, 0xe000, v23
	v_add3_u32 v228, 0, v127, v16
	v_add3_u32 v229, 0, v17, v16
	v_lshl_add_u64 v[16:17], v[6:7], 0, s[36:37]
	s_mov_b32 m0, s47
	v_readfirstlane_b32 s46, v20
	ds_read_b128 v[42:45], v228
	ds_read_b128 v[46:49], v228 offset:1024
	ds_read_b128 v[50:53], v229 offset:2048
	ds_read_b128 v[54:57], v229 offset:3072
	ds_read_b128 v[58:61], v229 offset:4096
	ds_read_b128 v[62:65], v229 offset:5120
	ds_read_b128 v[66:69], v229 offset:6144
	ds_read_b128 v[70:73], v229 offset:7168
	global_load_lds_dwordx4 v[16:17], off
	v_lshl_add_u64 v[16:17], v[4:5], 0, s[36:37]
	s_mov_b32 m0, s46
	s_nop 0
	global_load_lds_dwordx4 v[16:17], off
	s_waitcnt lgkmcnt(8)
	s_barrier
	s_waitcnt lgkmcnt(0)
	s_setprio 0
	s_waitcnt lgkmcnt(0)
	v_mfma_f32_16x16x32_bf16 v[74:77], v[42:45], v[26:29], 0
	v_mfma_f32_16x16x32_bf16 v[78:81], v[42:45], v[34:37], 0
	v_mfma_f32_16x16x32_bf16 v[82:85], v[50:53], v[26:29], 0
	v_mfma_f32_16x16x32_bf16 v[86:89], v[50:53], v[34:37], 0
	v_mfma_f32_16x16x32_bf16 v[90:93], v[58:61], v[26:29], 0
	v_mfma_f32_16x16x32_bf16 v[94:97], v[58:61], v[34:37], 0
	v_mfma_f32_16x16x32_bf16 v[98:101], v[66:69], v[26:29], 0
	v_mfma_f32_16x16x32_bf16 v[102:105], v[66:69], v[34:37], 0
	v_mfma_f32_16x16x32_bf16 v[74:77], v[46:49], v[30:33], v[74:77]
	v_mfma_f32_16x16x32_bf16 v[78:81], v[46:49], v[38:41], v[78:81]
	v_mfma_f32_16x16x32_bf16 v[82:85], v[54:57], v[30:33], v[82:85]
	v_mfma_f32_16x16x32_bf16 v[86:89], v[54:57], v[38:41], v[86:89]
	v_mfma_f32_16x16x32_bf16 v[90:93], v[62:65], v[30:33], v[90:93]
	v_mfma_f32_16x16x32_bf16 v[94:97], v[62:65], v[38:41], v[94:97]
	v_mfma_f32_16x16x32_bf16 v[98:101], v[70:73], v[30:33], v[98:101]
	v_mfma_f32_16x16x32_bf16 v[102:105], v[70:73], v[38:41], v[102:105]
	s_setprio 1
	s_barrier
	v_readfirstlane_b32 s48, v21
	v_add_u32_e32 v20, 0x2000, v21
	v_add3_u32 v224, s57, v127, v126
	v_lshl_add_u64 v[16:17], v[12:13], 0, s[38:39]
	s_mov_b32 m0, s48
	v_readfirstlane_b32 s48, v20
	ds_read_b128 v[106:109], v224
	ds_read_b128 v[110:113], v224 offset:1024
	ds_read_b128 v[114:117], v224 offset:2048
	ds_read_b128 v[118:121], v224 offset:3072
	global_load_lds_dwordx4 v[16:17], off
	v_lshl_add_u64 v[16:17], v[14:15], 0, s[38:39]
	s_mov_b32 m0, s48
	s_nop 0
	global_load_lds_dwordx4 v[16:17], off
	s_barrier
	s_waitcnt lgkmcnt(0)
	s_setprio 0
	s_waitcnt lgkmcnt(0)
	v_mfma_f32_16x16x32_bf16 v[122:125], v[42:45], v[106:109], 0
	v_mfma_f32_16x16x32_bf16 v[42:45], v[42:45], v[114:117], 0
	v_mfma_f32_16x16x32_bf16 v[140:143], v[50:53], v[106:109], 0
	v_mfma_f32_16x16x32_bf16 v[50:53], v[50:53], v[114:117], 0
	v_mfma_f32_16x16x32_bf16 v[144:147], v[58:61], v[106:109], 0
	v_mfma_f32_16x16x32_bf16 v[58:61], v[58:61], v[114:117], 0
	v_mfma_f32_16x16x32_bf16 v[148:151], v[66:69], v[106:109], 0
	v_mfma_f32_16x16x32_bf16 v[66:69], v[66:69], v[114:117], 0
	v_mfma_f32_16x16x32_bf16 v[122:125], v[46:49], v[110:113], v[122:125]
	v_mfma_f32_16x16x32_bf16 v[42:45], v[46:49], v[118:121], v[42:45]
	v_mfma_f32_16x16x32_bf16 v[46:49], v[54:57], v[110:113], v[140:143]
	v_mfma_f32_16x16x32_bf16 v[50:53], v[54:57], v[118:121], v[50:53]
	v_mfma_f32_16x16x32_bf16 v[54:57], v[62:65], v[110:113], v[144:147]
	v_mfma_f32_16x16x32_bf16 v[58:61], v[62:65], v[118:121], v[58:61]
	v_mfma_f32_16x16x32_bf16 v[62:65], v[70:73], v[110:113], v[148:151]
	v_mfma_f32_16x16x32_bf16 v[66:69], v[70:73], v[118:121], v[66:69]
	s_setprio 1
	v_readfirstlane_b32 s48, v23
	v_lshl_add_u64 v[16:17], v[8:9], 0, s[38:39]
	s_mov_b32 m0, s48
	v_readfirstlane_b32 s48, v24
	s_barrier
; #define STAGE(P, BASE, LD, br, kt) do { const char* _g = (const char*)((BASE) + (size_t)(br) * (LD) + (size_t)(kt) * 64); \
;     for (int _i = 0; _i < 2; ++_i) { int _b = tidx * 16 + _i * 8192; int _r, _c; stage_rc(_b, _r, _c); \
;       __builtin_amdgcn_global_load_lds((const unsigned*)(_g + (unsigned)((_r * (LD) + _c) * 2)), (unsigned*)((char*)(P) + _b), 16, 0, 0); } } while (0)
; #define LDA(dst, b, h) for (int m = 0; m < 4; ++m) for (int k = 0; k < 2; ++k) \
;     dst[m][k] = *reinterpret_cast<const bf16x8*>((char*)SA(b, h) + lds_byte(wr * 64 + m * 16 + fr, k * 32 + fq * 8))
; #define LDB(dst, b, h) for (int n = 0; n < 2; ++n) for (int k = 0; k < 2; ++k) \
;     dst[n][k] = *reinterpret_cast<const bf16x8*>((char*)SB(b, h) + lds_byte(wc * 32 + n * 16 + fr, k * 32 + fq * 8))
; #define MMA(ai, bj, At_, Bt_) do { __builtin_amdgcn_s_setprio(1); \
;     for (int k = 0; k < 2; ++k) for (int m = 0; m < 4; ++m) for (int n = 0; n < 2; ++n) \
;       acc[ai][bj][m][n] = __builtin_amdgcn_mfma_f32_16x16x32_bf16(At_[m][k], Bt_[n][k], acc[ai][bj][m][n], 0, 0, 0); \
;     __builtin_amdgcn_s_setprio(0); } while (0)
; #define WAIT_V(n) asm volatile("s_waitcnt vmcnt(" #n ")" ::: "memory")
; #define WAIT_L(n) asm volatile("s_waitcnt lgkmcnt(" #n ")" ::: "memory")
; #define BAR __builtin_amdgcn_s_barrier()
; #define SCHED __builtin_amdgcn_sched_barrier(0)
; template <int EPI, int lda, int ldb, int N, int K>
; __device__ __forceinline__ void gemm_phase(const u16* __restrict__ A, const u16* __restrict__ Bt, const GemmEpi ep, int wv) {
;     ...
;       BAR; WAIT_L(0); MMA(0, 1, At, B1); BAR;
;       LDA(At, 0, 1); STAGE(SA(0, 0), Ab, lda, brow, t + 2);
;       BAR; WAIT_L(0); MMA(1, 0, At, B0); BAR; SCHED;
;       STAGE(SB(0, 1), Bt, ldb, bcol + HALF, t + 2);
;       WAIT_V(6); BAR; MMA(1, 1, At, B1); BAR;
;       LDB(B0, 1, 0); SCHED; LDA(At, 1, 0); STAGE(SA(0, 1), Ab, lda, brow + HALF, t + 2);
;       WAIT_L(8); BAR; WAIT_L(0); MMA(0, 0, At, B0); BAR; SCHED;
	ds_read_b128 v[70:73], v228 offset:16384
	ds_read_b128 v[140:143], v228 offset:17408
	ds_read_b128 v[144:147], v229 offset:18432
	ds_read_b128 v[148:151], v229 offset:19456
	ds_read_b128 v[152:155], v229 offset:20480
	ds_read_b128 v[156:159], v229 offset:21504
	ds_read_b128 v[160:163], v229 offset:22528
	ds_read_b128 v[164:167], v229 offset:23552
	global_load_lds_dwordx4 v[16:17], off
	v_lshl_add_u64 v[16:17], v[10:11], 0, s[38:39]
	s_mov_b32 m0, s48
	s_nop 0
	global_load_lds_dwordx4 v[16:17], off
	s_barrier
	s_waitcnt lgkmcnt(0)
	s_setprio 0
	s_waitcnt lgkmcnt(0)
	v_mfma_f32_16x16x32_bf16 v[168:171], v[70:73], v[26:29], 0
	v_mfma_f32_16x16x32_bf16 v[172:175], v[70:73], v[34:37], 0
	v_mfma_f32_16x16x32_bf16 v[176:179], v[144:147], v[26:29], 0
	v_mfma_f32_16x16x32_bf16 v[180:183], v[144:147], v[34:37], 0
	v_mfma_f32_16x16x32_bf16 v[184:187], v[152:155], v[26:29], 0
	v_mfma_f32_16x16x32_bf16 v[188:191], v[152:155], v[34:37], 0
	v_mfma_f32_16x16x32_bf16 v[24:27], v[160:163], v[26:29], 0
	v_mfma_f32_16x16x32_bf16 v[34:37], v[160:163], v[34:37], 0
	v_mfma_f32_16x16x32_bf16 v[168:171], v[140:143], v[30:33], v[168:171]
	v_mfma_f32_16x16x32_bf16 v[176:179], v[148:151], v[30:33], v[176:179]
	v_mfma_f32_16x16x32_bf16 v[184:187], v[156:159], v[30:33], v[184:187]
	v_mfma_f32_16x16x32_bf16 v[24:27], v[164:167], v[30:33], v[24:27]
	v_mfma_f32_16x16x32_bf16 v[28:31], v[164:167], v[38:41], v[34:37]
	v_mfma_f32_16x16x32_bf16 v[172:175], v[140:143], v[38:41], v[172:175]
	v_mfma_f32_16x16x32_bf16 v[180:183], v[148:151], v[38:41], v[180:183]
	v_mfma_f32_16x16x32_bf16 v[188:191], v[156:159], v[38:41], v[188:191]
	s_setprio 1
	s_barrier
	v_readfirstlane_b32 s48, v22
	v_add_u32_e32 v20, 0x2000, v22
	v_lshl_add_u64 v[16:17], v[2:3], 0, s[38:39]
	s_mov_b32 m0, s48
	v_readfirstlane_b32 s48, v20
	global_load_lds_dwordx4 v[16:17], off
	v_lshl_add_u64 v[16:17], v[0:1], 0, s[38:39]
	s_mov_b32 m0, s48
	s_nop 0
	global_load_lds_dwordx4 v[16:17], off
	s_waitcnt vmcnt(6)
	s_barrier
	s_setprio 0
	v_mfma_f32_16x16x32_bf16 v[20:23], v[70:73], v[106:109], 0
	v_mfma_f32_16x16x32_bf16 v[32:35], v[70:73], v[114:117], 0
	v_mfma_f32_16x16x32_bf16 v[36:39], v[144:147], v[106:109], 0
	v_mfma_f32_16x16x32_bf16 v[70:73], v[144:147], v[114:117], 0
	v_mfma_f32_16x16x32_bf16 v[144:147], v[152:155], v[106:109], 0
	v_mfma_f32_16x16x32_bf16 v[152:155], v[152:155], v[114:117], 0
	v_mfma_f32_16x16x32_bf16 v[106:109], v[160:163], v[106:109], 0
	v_mfma_f32_16x16x32_bf16 v[114:117], v[160:163], v[114:117], 0
	v_mfma_f32_16x16x32_bf16 v[20:23], v[140:143], v[110:113], v[20:23]
	v_mfma_f32_16x16x32_bf16 v[32:35], v[140:143], v[118:121], v[32:35]
	v_mfma_f32_16x16x32_bf16 v[36:39], v[148:151], v[110:113], v[36:39]
	v_mfma_f32_16x16x32_bf16 v[70:73], v[148:151], v[118:121], v[70:73]
	v_mfma_f32_16x16x32_bf16 v[140:143], v[156:159], v[110:113], v[144:147]
	v_mfma_f32_16x16x32_bf16 v[106:109], v[164:167], v[110:113], v[106:109]
	v_mfma_f32_16x16x32_bf16 v[110:113], v[164:167], v[118:121], v[114:117]
	v_mfma_f32_16x16x32_bf16 v[144:147], v[156:159], v[118:121], v[152:155]
	s_setprio 1
	v_add3_u32 v225, s58, v127, v126
	s_barrier
	ds_read_b128 v[114:117], v225
	ds_read_b128 v[118:121], v225 offset:1024
	ds_read_b128 v[148:151], v225 offset:2048
	ds_read_b128 v[152:155], v225 offset:3072
	v_readfirstlane_b32 s48, v18
	v_lshl_add_u64 v[16:17], v[6:7], 0, s[38:39]
	s_mov_b32 m0, s48
	v_readfirstlane_b32 s48, v19
	ds_read_b128 v[156:159], v228 offset:32768
	ds_read_b128 v[160:163], v228 offset:33792
	ds_read_b128 v[164:167], v229 offset:34816
	ds_read_b128 v[192:195], v229 offset:35840
	ds_read_b128 v[196:199], v229 offset:36864
	ds_read_b128 v[200:203], v229 offset:37888
	ds_read_b128 v[204:207], v229 offset:38912
	ds_read_b128 v[208:211], v229 offset:39936
	global_load_lds_dwordx4 v[16:17], off
	v_lshl_add_u64 v[16:17], v[4:5], 0, s[38:39]
	s_mov_b32 m0, s48
	s_nop 0
	global_load_lds_dwordx4 v[16:17], off
	s_waitcnt lgkmcnt(8)
	s_barrier
	s_waitcnt lgkmcnt(0)
	s_setprio 0
	s_waitcnt lgkmcnt(0)
	v_mfma_f32_16x16x32_bf16 v[16:19], v[156:159], v[114:117], v[74:77]
	v_mfma_f32_16x16x32_bf16 v[74:77], v[156:159], v[148:151], v[78:81]
	v_mfma_f32_16x16x32_bf16 v[78:81], v[164:167], v[114:117], v[82:85]
	v_mfma_f32_16x16x32_bf16 v[82:85], v[164:167], v[148:151], v[86:89]
	v_mfma_f32_16x16x32_bf16 v[86:89], v[196:199], v[114:117], v[90:93]
	v_mfma_f32_16x16x32_bf16 v[90:93], v[196:199], v[148:151], v[94:97]
	v_mfma_f32_16x16x32_bf16 v[94:97], v[204:207], v[114:117], v[98:101]
	v_mfma_f32_16x16x32_bf16 v[98:101], v[204:207], v[148:151], v[102:105]
	v_mfma_f32_16x16x32_bf16 v[16:19], v[160:163], v[118:121], v[16:19]
	v_mfma_f32_16x16x32_bf16 v[74:77], v[160:163], v[152:155], v[74:77]
	v_mfma_f32_16x16x32_bf16 v[78:81], v[192:195], v[118:121], v[78:81]
	v_mfma_f32_16x16x32_bf16 v[82:85], v[192:195], v[152:155], v[82:85]
	v_mfma_f32_16x16x32_bf16 v[86:89], v[200:203], v[118:121], v[86:89]
	v_mfma_f32_16x16x32_bf16 v[90:93], v[200:203], v[152:155], v[90:93]
	v_mfma_f32_16x16x32_bf16 v[94:97], v[208:211], v[118:121], v[94:97]
	v_mfma_f32_16x16x32_bf16 v[98:101], v[208:211], v[152:155], v[98:101]
	s_setprio 1
	s_barrier
	s_mov_b32 m0, s53
	v_add3_u32 v226, s59, v127, v126
	v_lshl_add_u64 v[12:13], v[12:13], 0, s[40:41]
	ds_read_b128 v[102:105], v226
	ds_read_b128 v[212:215], v226 offset:1024
	ds_read_b128 v[216:219], v226 offset:2048
	ds_read_b128 v[220:223], v226 offset:3072
	global_load_lds_dwordx4 v[12:13], off
	v_lshl_add_u64 v[12:13], v[14:15], 0, s[40:41]
	s_mov_b32 m0, s52
	s_nop 0
	global_load_lds_dwordx4 v[12:13], off
	s_barrier
; #define STAGE(P, BASE, LD, br, kt) do { const char* _g = (const char*)((BASE) + (size_t)(br) * (LD) + (size_t)(kt) * 64); \
;     for (int _i = 0; _i < 2; ++_i) { int _b = tidx * 16 + _i * 8192; int _r, _c; stage_rc(_b, _r, _c); \
;       __builtin_amdgcn_global_load_lds((const unsigned*)(_g + (unsigned)((_r * (LD) + _c) * 2)), (unsigned*)((char*)(P) + _b), 16, 0, 0); } } while (0)
; #define LDA(dst, b, h) for (int m = 0; m < 4; ++m) for (int k = 0; k < 2; ++k) \
;     dst[m][k] = *reinterpret_cast<const bf16x8*>((char*)SA(b, h) + lds_byte(wr * 64 + m * 16 + fr, k * 32 + fq * 8))
; #define LDB(dst, b, h) for (int n = 0; n < 2; ++n) for (int k = 0; k < 2; ++k) \
;     dst[n][k] = *reinterpret_cast<const bf16x8*>((char*)SB(b, h) + lds_byte(wc * 32 + n * 16 + fr, k * 32 + fq * 8))
; #define MMA(ai, bj, At_, Bt_) do { __builtin_amdgcn_s_setprio(1); \
;     for (int k = 0; k < 2; ++k) for (int m = 0; m < 4; ++m) for (int n = 0; n < 2; ++n) \
;       acc[ai][bj][m][n] = __builtin_amdgcn_mfma_f32_16x16x32_bf16(At_[m][k], Bt_[n][k], acc[ai][bj][m][n], 0, 0, 0); \
;     __builtin_amdgcn_s_setprio(0); } while (0)
; #define WAIT_V(n) asm volatile("s_waitcnt vmcnt(" #n ")" ::: "memory")
; #define WAIT_L(n) asm volatile("s_waitcnt lgkmcnt(" #n ")" ::: "memory")
; #define BAR __builtin_amdgcn_s_barrier()
; #define SCHED __builtin_amdgcn_sched_barrier(0)
; template <int EPI, int lda, int ldb, int N, int K>
; __device__ __forceinline__ void gemm_phase(const u16* __restrict__ A, const u16* __restrict__ Bt, const GemmEpi ep, int wv) {
;     ...
;       LDB(B1, 1, 1); STAGE(SB(1, 0), Bt, ldb, bcol, t + 3);
;       BAR; WAIT_L(0); MMA(0, 1, At, B1); BAR;
;       LDA(At, 1, 1); STAGE(SA(1, 0), Ab, lda, brow, t + 3);
;       BAR; WAIT_L(0); MMA(1, 0, At, B0); BAR; SCHED;
;       STAGE(SB(1, 1), Bt, ldb, bcol + HALF, t + 3);
;       WAIT_V(6); BAR; MMA(1, 1, At, B1); BAR;
;     }
;     { LDB(B0, 0, 0); LDA(At, 0, 0); STAGE(SA(1, 1), Ab, lda, brow + HALF, nt - 1);
	s_waitcnt lgkmcnt(0)
	s_setprio 0
	s_waitcnt lgkmcnt(0)
	v_mfma_f32_16x16x32_bf16 v[12:15], v[156:159], v[102:105], v[122:125]
	v_mfma_f32_16x16x32_bf16 v[40:43], v[156:159], v[216:219], v[42:45]
	v_mfma_f32_16x16x32_bf16 v[44:47], v[164:167], v[102:105], v[46:49]
	v_mfma_f32_16x16x32_bf16 v[48:51], v[164:167], v[216:219], v[50:53]
	v_mfma_f32_16x16x32_bf16 v[52:55], v[196:199], v[102:105], v[54:57]
	v_mfma_f32_16x16x32_bf16 v[56:59], v[196:199], v[216:219], v[58:61]
	v_mfma_f32_16x16x32_bf16 v[60:63], v[204:207], v[102:105], v[62:65]
	v_mfma_f32_16x16x32_bf16 v[64:67], v[204:207], v[216:219], v[66:69]
	v_mfma_f32_16x16x32_bf16 v[12:15], v[160:163], v[212:215], v[12:15]
	v_mfma_f32_16x16x32_bf16 v[40:43], v[160:163], v[220:223], v[40:43]
	v_mfma_f32_16x16x32_bf16 v[44:47], v[192:195], v[212:215], v[44:47]
	v_mfma_f32_16x16x32_bf16 v[48:51], v[192:195], v[220:223], v[48:51]
	v_mfma_f32_16x16x32_bf16 v[52:55], v[200:203], v[212:215], v[52:55]
	v_mfma_f32_16x16x32_bf16 v[56:59], v[200:203], v[220:223], v[56:59]
	v_mfma_f32_16x16x32_bf16 v[60:63], v[208:211], v[212:215], v[60:63]
	v_mfma_f32_16x16x32_bf16 v[64:67], v[208:211], v[220:223], v[64:67]
	s_setprio 1
	s_mov_b32 m0, s51
	v_lshl_add_u64 v[8:9], v[8:9], 0, s[40:41]
	s_barrier
	ds_read_b128 v[122:125], v228 offset:49152
	ds_read_b128 v[156:159], v228 offset:50176
	ds_read_b128 v[160:163], v229 offset:51200
	ds_read_b128 v[164:167], v229 offset:52224
	ds_read_b128 v[192:195], v229 offset:53248
	ds_read_b128 v[196:199], v229 offset:54272
	ds_read_b128 v[200:203], v229 offset:55296
	ds_read_b128 v[204:207], v229 offset:56320
	global_load_lds_dwordx4 v[8:9], off
	v_lshl_add_u64 v[8:9], v[10:11], 0, s[40:41]
	s_mov_b32 m0, s50
	s_nop 0
	global_load_lds_dwordx4 v[8:9], off
	s_barrier
	s_waitcnt lgkmcnt(0)
	s_setprio 0
	s_waitcnt lgkmcnt(0)
	v_mfma_f32_16x16x32_bf16 v[8:11], v[122:125], v[114:117], v[168:171]
	v_mfma_f32_16x16x32_bf16 v[168:171], v[122:125], v[148:151], v[172:175]
	v_mfma_f32_16x16x32_bf16 v[24:27], v[200:203], v[114:117], v[24:27]
	v_mfma_f32_16x16x32_bf16 v[28:31], v[200:203], v[148:151], v[28:31]
	v_mfma_f32_16x16x32_bf16 v[172:175], v[160:163], v[114:117], v[176:179]
	v_mfma_f32_16x16x32_bf16 v[176:179], v[160:163], v[148:151], v[180:183]
	v_mfma_f32_16x16x32_bf16 v[180:183], v[192:195], v[114:117], v[184:187]
	v_mfma_f32_16x16x32_bf16 v[184:187], v[192:195], v[148:151], v[188:191]
	v_mfma_f32_16x16x32_bf16 v[8:11], v[156:159], v[118:121], v[8:11]
	v_mfma_f32_16x16x32_bf16 v[114:117], v[156:159], v[152:155], v[168:171]
	v_mfma_f32_16x16x32_bf16 v[24:27], v[204:207], v[118:121], v[24:27]
	v_mfma_f32_16x16x32_bf16 v[28:31], v[204:207], v[152:155], v[28:31]
	v_mfma_f32_16x16x32_bf16 v[148:151], v[164:167], v[118:121], v[172:175]
	v_mfma_f32_16x16x32_bf16 v[168:171], v[164:167], v[152:155], v[176:179]
	v_mfma_f32_16x16x32_bf16 v[172:175], v[196:199], v[118:121], v[180:183]
	v_mfma_f32_16x16x32_bf16 v[176:179], v[196:199], v[152:155], v[184:187]
	s_setprio 1
	s_barrier
	s_mov_b32 m0, s11
	v_lshl_add_u64 v[2:3], v[2:3], 0, s[40:41]
	global_load_lds_dwordx4 v[2:3], off
	v_lshl_add_u64 v[0:1], v[0:1], 0, s[40:41]
	s_mov_b32 m0, s5
	s_nop 0
	global_load_lds_dwordx4 v[0:1], off
	s_waitcnt vmcnt(6)
	s_barrier
	s_setprio 0
	v_mfma_f32_16x16x32_bf16 v[0:3], v[122:125], v[102:105], v[20:23]
	v_mfma_f32_16x16x32_bf16 v[20:23], v[122:125], v[216:219], v[32:35]
	v_mfma_f32_16x16x32_bf16 v[32:35], v[160:163], v[102:105], v[36:39]
	v_mfma_f32_16x16x32_bf16 v[36:39], v[160:163], v[216:219], v[70:73]
	v_mfma_f32_16x16x32_bf16 v[68:71], v[192:195], v[102:105], v[140:143]
	v_mfma_f32_16x16x32_bf16 v[118:121], v[192:195], v[216:219], v[144:147]
	v_mfma_f32_16x16x32_bf16 v[102:105], v[200:203], v[102:105], v[106:109]
	v_mfma_f32_16x16x32_bf16 v[106:109], v[200:203], v[216:219], v[110:113]
	v_mfma_f32_16x16x32_bf16 v[0:3], v[156:159], v[212:215], v[0:3]
	v_mfma_f32_16x16x32_bf16 v[20:23], v[156:159], v[220:223], v[20:23]
	v_mfma_f32_16x16x32_bf16 v[32:35], v[164:167], v[212:215], v[32:35]
	v_mfma_f32_16x16x32_bf16 v[36:39], v[164:167], v[220:223], v[36:39]
	v_mfma_f32_16x16x32_bf16 v[68:71], v[196:199], v[212:215], v[68:71]
	v_mfma_f32_16x16x32_bf16 v[110:113], v[196:199], v[220:223], v[118:121]
	v_mfma_f32_16x16x32_bf16 v[102:105], v[204:207], v[212:215], v[102:105]
	v_mfma_f32_16x16x32_bf16 v[106:109], v[204:207], v[220:223], v[106:109]
	s_setprio 1
	s_mov_b32 m0, s47
	v_lshl_add_u64 v[6:7], v[6:7], 0, s[40:41]
	s_barrier
	ds_read_b128 v[118:121], v133
	ds_read_b128 v[122:125], v133 offset:1024
	ds_read_b128 v[140:143], v133 offset:2048
	ds_read_b128 v[144:147], v133 offset:3072
	ds_read_b128 v[152:155], v228
	ds_read_b128 v[156:159], v228 offset:1024
	ds_read_b128 v[160:163], v229 offset:2048
	ds_read_b128 v[164:167], v229 offset:3072
	ds_read_b128 v[180:183], v229 offset:4096
	ds_read_b128 v[184:187], v229 offset:5120
	ds_read_b128 v[188:191], v229 offset:6144
	ds_read_b128 v[192:195], v229 offset:7168
	global_load_lds_dwordx4 v[6:7], off
	v_lshl_add_u64 v[4:5], v[4:5], 0, s[40:41]
	s_mov_b32 m0, s46
	s_nop 0
	global_load_lds_dwordx4 v[4:5], off
	s_barrier
; #define STAGE(P, BASE, LD, br, kt) do { const char* _g = (const char*)((BASE) + (size_t)(br) * (LD) + (size_t)(kt) * 64); \
;     for (int _i = 0; _i < 2; ++_i) { int _b = tidx * 16 + _i * 8192; int _r, _c; stage_rc(_b, _r, _c); \
;       __builtin_amdgcn_global_load_lds((const unsigned*)(_g + (unsigned)((_r * (LD) + _c) * 2)), (unsigned*)((char*)(P) + _b), 16, 0, 0); } } while (0)
; #define LDA(dst, b, h) for (int m = 0; m < 4; ++m) for (int k = 0; k < 2; ++k) \
;     dst[m][k] = *reinterpret_cast<const bf16x8*>((char*)SA(b, h) + lds_byte(wr * 64 + m * 16 + fr, k * 32 + fq * 8))
; #define LDB(dst, b, h) for (int n = 0; n < 2; ++n) for (int k = 0; k < 2; ++k) \
;     dst[n][k] = *reinterpret_cast<const bf16x8*>((char*)SB(b, h) + lds_byte(wc * 32 + n * 16 + fr, k * 32 + fq * 8))
; #define MMA(ai, bj, At_, Bt_) do { __builtin_amdgcn_s_setprio(1); \
;     for (int k = 0; k < 2; ++k) for (int m = 0; m < 4; ++m) for (int n = 0; n < 2; ++n) \
;       acc[ai][bj][m][n] = __builtin_amdgcn_mfma_f32_16x16x32_bf16(At_[m][k], Bt_[n][k], acc[ai][bj][m][n], 0, 0, 0); \
;     __builtin_amdgcn_s_setprio(0); } while (0)
; #define WAIT_V(n) asm volatile("s_waitcnt vmcnt(" #n ")" ::: "memory")
; #define WAIT_L(n) asm volatile("s_waitcnt lgkmcnt(" #n ")" ::: "memory")
; #define BAR __builtin_amdgcn_s_barrier()
; template <int EPI, int lda, int ldb, int N, int K>
; __device__ __forceinline__ void gemm_phase(const u16* __restrict__ A, const u16* __restrict__ Bt, const GemmEpi ep, int wv) {
;     ...
;     { LDB(B0, 0, 0); LDA(At, 0, 0); STAGE(SA(1, 1), Ab, lda, brow + HALF, nt - 1);
;       BAR; WAIT_L(0); MMA(0, 0, At, B0); BAR;
;       LDB(B1, 0, 1); BAR; WAIT_L(0); MMA(0, 1, At, B1); BAR;
;       LDA(At, 0, 1); WAIT_V(4); BAR; WAIT_L(0); MMA(1, 0, At, B0); MMA(1, 1, At, B1); BAR; }
	s_waitcnt lgkmcnt(0)
	s_setprio 0
	s_waitcnt lgkmcnt(0)
	v_mfma_f32_16x16x32_bf16 v[4:7], v[152:155], v[118:121], v[16:19]
	v_mfma_f32_16x16x32_bf16 v[16:19], v[152:155], v[140:143], v[74:77]
	v_mfma_f32_16x16x32_bf16 v[72:75], v[160:163], v[118:121], v[78:81]
	v_mfma_f32_16x16x32_bf16 v[76:79], v[160:163], v[140:143], v[82:85]
	v_mfma_f32_16x16x32_bf16 v[80:83], v[180:183], v[118:121], v[86:89]
	v_mfma_f32_16x16x32_bf16 v[84:87], v[180:183], v[140:143], v[90:93]
	v_mfma_f32_16x16x32_bf16 v[88:91], v[188:191], v[118:121], v[94:97]
	v_mfma_f32_16x16x32_bf16 v[92:95], v[188:191], v[140:143], v[98:101]
	v_mfma_f32_16x16x32_bf16 v[4:7], v[156:159], v[122:125], v[4:7]
	v_mfma_f32_16x16x32_bf16 v[16:19], v[156:159], v[144:147], v[16:19]
	v_mfma_f32_16x16x32_bf16 v[72:75], v[164:167], v[122:125], v[72:75]
	v_mfma_f32_16x16x32_bf16 v[76:79], v[164:167], v[144:147], v[76:79]
	v_mfma_f32_16x16x32_bf16 v[80:83], v[184:187], v[122:125], v[80:83]
	v_mfma_f32_16x16x32_bf16 v[84:87], v[184:187], v[144:147], v[84:87]
	v_mfma_f32_16x16x32_bf16 v[88:91], v[192:195], v[122:125], v[88:91]
	v_mfma_f32_16x16x32_bf16 v[92:95], v[192:195], v[144:147], v[92:95]
	s_setprio 1
	s_barrier
	ds_read_b128 v[96:99], v224
	ds_read_b128 v[196:199], v224 offset:1024
	ds_read_b128 v[200:203], v224 offset:2048
	ds_read_b128 v[204:207], v224 offset:3072
	s_barrier
	s_waitcnt lgkmcnt(0)
	s_setprio 0
	s_waitcnt lgkmcnt(0)
	v_mfma_f32_16x16x32_bf16 v[12:15], v[152:155], v[96:99], v[12:15]
	v_mfma_f32_16x16x32_bf16 v[40:43], v[152:155], v[200:203], v[40:43]
	v_mfma_f32_16x16x32_bf16 v[52:55], v[180:183], v[96:99], v[52:55]
	v_mfma_f32_16x16x32_bf16 v[56:59], v[180:183], v[200:203], v[56:59]
	v_mfma_f32_16x16x32_bf16 v[64:67], v[188:191], v[200:203], v[64:67]
	v_mfma_f32_16x16x32_bf16 v[44:47], v[160:163], v[96:99], v[44:47]
	v_mfma_f32_16x16x32_bf16 v[48:51], v[160:163], v[200:203], v[48:51]
	v_mfma_f32_16x16x32_bf16 v[60:63], v[188:191], v[96:99], v[60:63]
	v_mfma_f32_16x16x32_bf16 v[12:15], v[156:159], v[196:199], v[12:15]
	v_mfma_f32_16x16x32_bf16 v[40:43], v[156:159], v[204:207], v[40:43]
	v_mfma_f32_16x16x32_bf16 v[52:55], v[184:187], v[196:199], v[52:55]
	v_mfma_f32_16x16x32_bf16 v[56:59], v[184:187], v[204:207], v[56:59]
	v_mfma_f32_16x16x32_bf16 v[64:67], v[192:195], v[204:207], v[64:67]
	v_mfma_f32_16x16x32_bf16 v[152:155], v[164:167], v[196:199], v[44:47]
	v_mfma_f32_16x16x32_bf16 v[156:159], v[164:167], v[204:207], v[48:51]
	v_mfma_f32_16x16x32_bf16 v[160:163], v[192:195], v[196:199], v[60:63]
	s_setprio 1
	s_barrier
	ds_read_b128 v[44:47], v228 offset:16384
	ds_read_b128 v[48:51], v228 offset:17408
	ds_read_b128 v[60:63], v229 offset:18432
	ds_read_b128 v[164:167], v229 offset:19456
	ds_read_b128 v[180:183], v229 offset:20480
	ds_read_b128 v[184:187], v229 offset:21504
	ds_read_b128 v[188:191], v229 offset:22528
	ds_read_b128 v[192:195], v229 offset:23552
	s_waitcnt vmcnt(4)
	s_barrier
	s_waitcnt lgkmcnt(0)
	s_setprio 0
	s_waitcnt lgkmcnt(0)
	v_mfma_f32_16x16x32_bf16 v[8:11], v[44:47], v[118:121], v[8:11]
	v_mfma_f32_16x16x32_bf16 v[24:27], v[188:191], v[118:121], v[24:27]
	v_mfma_f32_16x16x32_bf16 v[28:31], v[188:191], v[140:143], v[28:31]
	v_mfma_f32_16x16x32_bf16 v[114:117], v[44:47], v[140:143], v[114:117]
	v_mfma_f32_16x16x32_bf16 v[148:151], v[60:63], v[118:121], v[148:151]
	v_mfma_f32_16x16x32_bf16 v[168:171], v[60:63], v[140:143], v[168:171]
	v_mfma_f32_16x16x32_bf16 v[172:175], v[180:183], v[118:121], v[172:175]
	v_mfma_f32_16x16x32_bf16 v[176:179], v[180:183], v[140:143], v[176:179]
	v_mfma_f32_16x16x32_bf16 v[8:11], v[48:51], v[122:125], v[8:11]
	v_mfma_f32_16x16x32_bf16 v[24:27], v[192:195], v[122:125], v[24:27]
	v_mfma_f32_16x16x32_bf16 v[28:31], v[192:195], v[144:147], v[28:31]
	v_mfma_f32_16x16x32_bf16 v[140:143], v[48:51], v[144:147], v[114:117]
	v_mfma_f32_16x16x32_bf16 v[148:151], v[164:167], v[122:125], v[148:151]
	v_mfma_f32_16x16x32_bf16 v[168:171], v[164:167], v[144:147], v[168:171]
	v_mfma_f32_16x16x32_bf16 v[172:175], v[184:187], v[122:125], v[172:175]
	v_mfma_f32_16x16x32_bf16 v[176:179], v[184:187], v[144:147], v[176:179]
	s_setprio 1
	s_setprio 0
	v_mfma_f32_16x16x32_bf16 v[0:3], v[44:47], v[96:99], v[0:3]
	v_mfma_f32_16x16x32_bf16 v[20:23], v[44:47], v[200:203], v[20:23]
	v_mfma_f32_16x16x32_bf16 v[44:47], v[180:183], v[96:99], v[68:71]
	v_mfma_f32_16x16x32_bf16 v[68:71], v[188:191], v[96:99], v[102:105]
	v_mfma_f32_16x16x32_bf16 v[32:35], v[60:63], v[96:99], v[32:35]
	v_mfma_f32_16x16x32_bf16 v[36:39], v[60:63], v[200:203], v[36:39]
	v_mfma_f32_16x16x32_bf16 v[60:63], v[180:183], v[200:203], v[110:113]
	v_mfma_f32_16x16x32_bf16 v[96:99], v[188:191], v[200:203], v[106:109]
	v_mfma_f32_16x16x32_bf16 v[20:23], v[48:51], v[204:207], v[20:23]
	v_mfma_f32_16x16x32_bf16 v[68:71], v[192:195], v[196:199], v[68:71]
	v_mfma_f32_16x16x32_bf16 v[144:147], v[48:51], v[196:199], v[0:3]
	v_mfma_f32_16x16x32_bf16 v[180:183], v[164:167], v[196:199], v[32:35]
	v_mfma_f32_16x16x32_bf16 v[164:167], v[164:167], v[204:207], v[36:39]
	v_mfma_f32_16x16x32_bf16 v[188:191], v[184:187], v[196:199], v[44:47]
	v_mfma_f32_16x16x32_bf16 v[184:187], v[184:187], v[204:207], v[60:63]
	v_mfma_f32_16x16x32_bf16 v[192:195], v[192:195], v[204:207], v[96:99]
	s_setprio 1
	s_barrier
	ds_read_b128 v[0:3], v225
	ds_read_b128 v[196:199], v225 offset:1024
	ds_read_b128 v[200:203], v225 offset:2048
	ds_read_b128 v[204:207], v225 offset:3072
	ds_read_b128 v[36:39], v228 offset:32768
	ds_read_b128 v[100:103], v228 offset:33792
	ds_read_b128 v[108:111], v229 offset:34816
	ds_read_b128 v[208:211], v229 offset:35840
	ds_read_b128 v[116:119], v229 offset:36864
	ds_read_b128 v[212:215], v229 offset:37888
	ds_read_b128 v[124:127], v229 offset:38912
	ds_read_b128 v[216:219], v229 offset:39936
	s_waitcnt vmcnt(2)
	s_barrier
; #define LDA(dst, b, h) for (int m = 0; m < 4; ++m) for (int k = 0; k < 2; ++k) \
;     dst[m][k] = *reinterpret_cast<const bf16x8*>((char*)SA(b, h) + lds_byte(wr * 64 + m * 16 + fr, k * 32 + fq * 8))
; #define LDB(dst, b, h) for (int n = 0; n < 2; ++n) for (int k = 0; k < 2; ++k) \
;     dst[n][k] = *reinterpret_cast<const bf16x8*>((char*)SB(b, h) + lds_byte(wc * 32 + n * 16 + fr, k * 32 + fq * 8))
; #define MMA(ai, bj, At_, Bt_) do { __builtin_amdgcn_s_setprio(1); \
;     for (int k = 0; k < 2; ++k) for (int m = 0; m < 4; ++m) for (int n = 0; n < 2; ++n) \
;       acc[ai][bj][m][n] = __builtin_amdgcn_mfma_f32_16x16x32_bf16(At_[m][k], Bt_[n][k], acc[ai][bj][m][n], 0, 0, 0); \
;     __builtin_amdgcn_s_setprio(0); } while (0)
; #define WAIT_V(n) asm volatile("s_waitcnt vmcnt(" #n ")" ::: "memory")
; #define WAIT_L(n) asm volatile("s_waitcnt lgkmcnt(" #n ")" ::: "memory")
; #define BAR __builtin_amdgcn_s_barrier()
; template <int EPI, int lda, int ldb, int N, int K>
; __device__ __forceinline__ void gemm_phase(const u16* __restrict__ A, const u16* __restrict__ Bt, const GemmEpi ep, int wv) {
;     ...
;     { LDB(B0, 1, 0); LDA(At, 1, 0); WAIT_V(2); BAR; WAIT_L(0); MMA(0, 0, At, B0); BAR;
;       LDB(B1, 1, 1); WAIT_V(0); BAR; WAIT_L(0); MMA(0, 1, At, B1); BAR;
;       LDA(At, 1, 1); BAR; WAIT_L(0); MMA(1, 0, At, B0); MMA(1, 1, At, B1); BAR; }
;     if (wr == 0) BAR;
	s_waitcnt lgkmcnt(0)
	s_setprio 0
	s_waitcnt lgkmcnt(0)
	v_mfma_f32_16x16x32_bf16 v[4:7], v[36:39], v[0:3], v[4:7]
	v_mfma_f32_16x16x32_bf16 v[16:19], v[36:39], v[200:203], v[16:19]
	v_mfma_f32_16x16x32_bf16 v[32:35], v[108:111], v[0:3], v[72:75]
	v_mfma_f32_16x16x32_bf16 v[44:47], v[108:111], v[200:203], v[76:79]
	v_mfma_f32_16x16x32_bf16 v[72:75], v[116:119], v[0:3], v[80:83]
	v_mfma_f32_16x16x32_bf16 v[76:79], v[116:119], v[200:203], v[84:87]
	v_mfma_f32_16x16x32_bf16 v[80:83], v[124:127], v[0:3], v[88:91]
	v_mfma_f32_16x16x32_bf16 v[84:87], v[124:127], v[200:203], v[92:95]
	v_mfma_f32_16x16x32_bf16 v[120:123], v[100:103], v[196:199], v[4:7]
	v_mfma_f32_16x16x32_bf16 v[60:63], v[100:103], v[204:207], v[16:19]
	v_mfma_f32_16x16x32_bf16 v[112:115], v[208:211], v[196:199], v[32:35]
	v_mfma_f32_16x16x32_bf16 v[48:51], v[208:211], v[204:207], v[44:47]
	v_mfma_f32_16x16x32_bf16 v[104:107], v[212:215], v[196:199], v[72:75]
	v_mfma_f32_16x16x32_bf16 v[44:47], v[212:215], v[204:207], v[76:79]
	v_mfma_f32_16x16x32_bf16 v[96:99], v[216:219], v[196:199], v[80:83]
	v_mfma_f32_16x16x32_bf16 v[32:35], v[216:219], v[204:207], v[84:87]
	s_setprio 1
	s_barrier
	ds_read_b128 v[4:7], v226
	ds_read_b128 v[220:223], v226 offset:1024
	ds_read_b128 v[76:79], v226 offset:2048
	ds_read_b128 v[224:227], v226 offset:3072
	s_waitcnt vmcnt(0)
	s_barrier
	s_waitcnt lgkmcnt(0)
	s_setprio 0
	s_waitcnt lgkmcnt(0)
	v_mfma_f32_16x16x32_bf16 v[12:15], v[36:39], v[4:7], v[12:15]
	v_mfma_f32_16x16x32_bf16 v[16:19], v[36:39], v[76:79], v[40:43]
	v_mfma_f32_16x16x32_bf16 v[36:39], v[108:111], v[4:7], v[152:155]
	v_mfma_f32_16x16x32_bf16 v[40:43], v[108:111], v[76:79], v[156:159]
	v_mfma_f32_16x16x32_bf16 v[72:75], v[116:119], v[4:7], v[52:55]
	v_mfma_f32_16x16x32_bf16 v[80:83], v[116:119], v[76:79], v[56:59]
	v_mfma_f32_16x16x32_bf16 v[84:87], v[124:127], v[4:7], v[160:163]
	v_mfma_f32_16x16x32_bf16 v[64:67], v[124:127], v[76:79], v[64:67]
	v_mfma_f32_16x16x32_bf16 v[124:127], v[100:103], v[220:223], v[12:15]
	v_mfma_f32_16x16x32_bf16 v[56:59], v[100:103], v[224:227], v[16:19]
	v_mfma_f32_16x16x32_bf16 v[116:119], v[208:211], v[220:223], v[36:39]
	v_mfma_f32_16x16x32_bf16 v[52:55], v[208:211], v[224:227], v[40:43]
	v_mfma_f32_16x16x32_bf16 v[108:111], v[212:215], v[220:223], v[72:75]
	v_mfma_f32_16x16x32_bf16 v[40:43], v[212:215], v[224:227], v[80:83]
	v_mfma_f32_16x16x32_bf16 v[100:103], v[216:219], v[220:223], v[84:87]
	v_mfma_f32_16x16x32_bf16 v[36:39], v[216:219], v[224:227], v[64:67]
	s_setprio 1
	s_barrier
	ds_read_b128 v[84:87], v228 offset:49152
	ds_read_b128 v[152:155], v228 offset:50176
	ds_read_b128 v[92:95], v229 offset:51200
	ds_read_b128 v[156:159], v229 offset:52224
	ds_read_b128 v[160:163], v229 offset:53248
	ds_read_b128 v[208:211], v229 offset:54272
	ds_read_b128 v[212:215], v229 offset:55296
	ds_read_b128 v[216:219], v229 offset:56320
	s_barrier
	s_waitcnt lgkmcnt(0)
	s_setprio 0
	s_waitcnt lgkmcnt(0)
	v_mfma_f32_16x16x32_bf16 v[8:11], v[84:87], v[0:3], v[8:11]
	v_mfma_f32_16x16x32_bf16 v[12:15], v[84:87], v[200:203], v[140:143]
	v_mfma_f32_16x16x32_bf16 v[16:19], v[92:95], v[0:3], v[148:151]
	v_mfma_f32_16x16x32_bf16 v[64:67], v[92:95], v[200:203], v[168:171]
	v_mfma_f32_16x16x32_bf16 v[72:75], v[160:163], v[0:3], v[172:175]
	v_mfma_f32_16x16x32_bf16 v[140:143], v[160:163], v[200:203], v[176:179]
	v_mfma_f32_16x16x32_bf16 v[0:3], v[212:215], v[0:3], v[24:27]
	v_mfma_f32_16x16x32_bf16 v[24:27], v[212:215], v[200:203], v[28:31]
	v_mfma_f32_16x16x32_bf16 v[88:91], v[152:155], v[196:199], v[8:11]
	v_mfma_f32_16x16x32_bf16 v[28:31], v[152:155], v[204:207], v[12:15]
	v_mfma_f32_16x16x32_bf16 v[80:83], v[156:159], v[196:199], v[16:19]
	v_mfma_f32_16x16x32_bf16 v[16:19], v[156:159], v[204:207], v[64:67]
	v_mfma_f32_16x16x32_bf16 v[72:75], v[208:211], v[196:199], v[72:75]
	v_mfma_f32_16x16x32_bf16 v[12:15], v[208:211], v[204:207], v[140:143]
	v_mfma_f32_16x16x32_bf16 v[64:67], v[216:219], v[196:199], v[0:3]
	v_mfma_f32_16x16x32_bf16 v[0:3], v[216:219], v[204:207], v[24:27]
	s_setprio 1
	s_setprio 0
	v_mfma_f32_16x16x32_bf16 v[8:11], v[84:87], v[4:7], v[144:147]
	v_mfma_f32_16x16x32_bf16 v[20:23], v[84:87], v[76:79], v[20:23]
	v_mfma_f32_16x16x32_bf16 v[84:87], v[92:95], v[4:7], v[180:183]
	v_mfma_f32_16x16x32_bf16 v[140:143], v[92:95], v[76:79], v[164:167]
	v_mfma_f32_16x16x32_bf16 v[144:147], v[160:163], v[4:7], v[188:191]
	v_mfma_f32_16x16x32_bf16 v[148:151], v[160:163], v[76:79], v[184:187]
	v_mfma_f32_16x16x32_bf16 v[4:7], v[212:215], v[4:7], v[68:71]
	v_mfma_f32_16x16x32_bf16 v[160:163], v[212:215], v[76:79], v[192:195]
	v_mfma_f32_16x16x32_bf16 v[92:95], v[152:155], v[220:223], v[8:11]
	v_mfma_f32_16x16x32_bf16 v[24:27], v[152:155], v[224:227], v[20:23]
	v_mfma_f32_16x16x32_bf16 v[84:87], v[156:159], v[220:223], v[84:87]
	v_mfma_f32_16x16x32_bf16 v[20:23], v[156:159], v[224:227], v[140:143]
	v_mfma_f32_16x16x32_bf16 v[76:79], v[208:211], v[220:223], v[144:147]
	v_mfma_f32_16x16x32_bf16 v[8:11], v[208:211], v[224:227], v[148:151]
	v_mfma_f32_16x16x32_bf16 v[68:71], v[216:219], v[220:223], v[4:7]
	v_mfma_f32_16x16x32_bf16 v[4:7], v[216:219], v[224:227], v[160:163]
	s_setprio 1
	v_cmp_gt_u32_e32 vcc, s60, v130
	s_barrier
	s_and_saveexec_b64 s[46:47], vcc
	s_cbranch_execz .LBB0_1346
	s_barrier
	s_branch .LBB0_1346

; #define STAGE(P, BASE, LD, br, kt) do { const char* _g = (const char*)((BASE) + (size_t)(br) * (LD) + (size_t)(kt) * 64); \
;     for (int _i = 0; _i < 2; ++_i) { int _b = tidx * 16 + _i * 8192; int _r, _c; stage_rc(_b, _r, _c); \
;       __builtin_amdgcn_global_load_lds((const unsigned*)(_g + (unsigned)((_r * (LD) + _c) * 2)), (unsigned*)((char*)(P) + _b), 16, 0, 0); } } while (0)
; #define LDA(dst, b, h) for (int m = 0; m < 4; ++m) for (int k = 0; k < 2; ++k) \
;     dst[m][k] = *reinterpret_cast<const bf16x8*>((char*)SA(b, h) + lds_byte(wr * 64 + m * 16 + fr, k * 32 + fq * 8))
; #define LDB(dst, b, h) for (int n = 0; n < 2; ++n) for (int k = 0; k < 2; ++k) \
;     dst[n][k] = *reinterpret_cast<const bf16x8*>((char*)SB(b, h) + lds_byte(wc * 32 + n * 16 + fr, k * 32 + fq * 8))
; #define MMA(ai, bj, At_, Bt_) do { __builtin_amdgcn_s_setprio(1); \
;     for (int k = 0; k < 2; ++k) for (int m = 0; m < 4; ++m) for (int n = 0; n < 2; ++n) \
;       acc[ai][bj][m][n] = __builtin_amdgcn_mfma_f32_16x16x32_bf16(At_[m][k], Bt_[n][k], acc[ai][bj][m][n], 0, 0, 0); \
;     __builtin_amdgcn_s_setprio(0); } while (0)
; #define WAIT_L(n) asm volatile("s_waitcnt lgkmcnt(" #n ")" ::: "memory")
; #define BAR __builtin_amdgcn_s_barrier()
; #define SCHED __builtin_amdgcn_sched_barrier(0)
; template <int EPI, int lda, int ldb, int N, int K>
; __device__ __forceinline__ void gemm_phase(const u16* __restrict__ A, const u16* __restrict__ Bt, const GemmEpi ep, int wv) {
;     ...
;       LDB(B0, 0, 0); SCHED; LDA(At, 0, 0); STAGE(SA(1, 1), Ab, lda, brow + HALF, t + 1);
;       WAIT_L(8); BAR; WAIT_L(0); MMA(0, 0, At, B0); BAR; SCHED;
;       LDB(B1, 0, 1); STAGE(SB(0, 0), Bt, ldb, bcol, t + 2);
;       BAR; WAIT_L(0); MMA(0, 1, At, B1); BAR;
;       LDA(At, 0, 1); STAGE(SA(0, 0), Ab, lda, brow, t + 2);
;       BAR; WAIT_L(0); MMA(1, 0, At, B0); BAR; SCHED;
.LBB0_1448:
	ds_read_b128 v[164:167], v160
	ds_read_b128 v[170:173], v160 offset:1024
	ds_read_b128 v[174:177], v160 offset:2048
	ds_read_b128 v[178:181], v160 offset:3072
	v_add_u32_e32 v168, 0xc000, v143
	v_lshl_add_u64 v[234:235], v[138:139], 0, s[44:45]
	v_readfirstlane_b32 s47, v168
	v_add_u32_e32 v169, 0xe000, v143
	v_lshl_add_u64 v[162:163], v[234:235], 0, s[20:21]
	s_mov_b32 m0, s47
	v_lshl_add_u64 v[236:237], v[140:141], 0, s[44:45]
	v_readfirstlane_b32 s47, v169
	ds_read_b128 v[182:185], v151
	ds_read_b128 v[186:189], v151 offset:1024
	ds_read_b128 v[190:193], v150
	ds_read_b128 v[194:197], v150 offset:1024
	ds_read_b128 v[198:201], v149
	ds_read_b128 v[202:205], v149 offset:1024
	ds_read_b128 v[206:209], v148
	ds_read_b128 v[210:213], v148 offset:1024
	global_load_lds_dwordx4 v[162:163], off
	v_lshl_add_u64 v[162:163], v[236:237], 0, s[20:21]
	s_mov_b32 m0, s47
	s_nop 0
	global_load_lds_dwordx4 v[162:163], off
	s_waitcnt lgkmcnt(8)
	s_barrier
	s_waitcnt lgkmcnt(0)
	s_setprio 0
	s_waitcnt lgkmcnt(0)
	v_mfma_f32_16x16x32_bf16 v[124:127], v[164:167], v[182:185], v[124:127]
	v_mfma_f32_16x16x32_bf16 v[120:123], v[174:177], v[182:185], v[120:123]
	v_mfma_f32_16x16x32_bf16 v[116:119], v[164:167], v[190:193], v[116:119]
	v_mfma_f32_16x16x32_bf16 v[112:115], v[174:177], v[190:193], v[112:115]
	v_mfma_f32_16x16x32_bf16 v[108:111], v[164:167], v[198:201], v[108:111]
	v_mfma_f32_16x16x32_bf16 v[104:107], v[174:177], v[198:201], v[104:107]
	v_mfma_f32_16x16x32_bf16 v[100:103], v[164:167], v[206:209], v[100:103]
	v_mfma_f32_16x16x32_bf16 v[96:99], v[174:177], v[206:209], v[96:99]
	v_mfma_f32_16x16x32_bf16 v[124:127], v[170:173], v[186:189], v[124:127]
	v_mfma_f32_16x16x32_bf16 v[120:123], v[178:181], v[186:189], v[120:123]
	v_mfma_f32_16x16x32_bf16 v[116:119], v[170:173], v[194:197], v[116:119]
	v_mfma_f32_16x16x32_bf16 v[112:115], v[178:181], v[194:197], v[112:115]
	v_mfma_f32_16x16x32_bf16 v[108:111], v[170:173], v[202:205], v[108:111]
	v_mfma_f32_16x16x32_bf16 v[104:107], v[178:181], v[202:205], v[104:107]
	v_mfma_f32_16x16x32_bf16 v[100:103], v[170:173], v[210:213], v[100:103]
	v_mfma_f32_16x16x32_bf16 v[96:99], v[178:181], v[210:213], v[96:99]
	s_setprio 1
	s_barrier
	v_add_u32_e32 v161, s55, v153
	v_lshl_add_u64 v[238:239], v[134:135], 0, s[44:45]
	v_readfirstlane_b32 s47, v161
	v_lshl_add_u64 v[162:163], v[238:239], 0, s[22:23]
	s_mov_b32 m0, s47
	ds_read_b128 v[214:217], v159
	ds_read_b128 v[218:221], v159 offset:1024
	ds_read_b128 v[222:225], v159 offset:2048
	ds_read_b128 v[226:229], v159 offset:3072
	global_load_lds_dwordx4 v[162:163], off
	v_add_u32_e32 v162, 0x2000, v161
	v_lshl_add_u64 v[240:241], v[136:137], 0, s[44:45]
	v_readfirstlane_b32 s47, v162
	v_lshl_add_u64 v[230:231], v[240:241], 0, s[22:23]
	s_mov_b32 m0, s47
	s_nop 0
	global_load_lds_dwordx4 v[230:231], off
	s_barrier
	s_waitcnt lgkmcnt(0)
	s_setprio 0
	s_waitcnt lgkmcnt(0)
	v_mfma_f32_16x16x32_bf16 v[92:95], v[214:217], v[182:185], v[92:95]
	v_mfma_f32_16x16x32_bf16 v[88:91], v[222:225], v[182:185], v[88:91]
	v_mfma_f32_16x16x32_bf16 v[84:87], v[214:217], v[190:193], v[84:87]
	v_mfma_f32_16x16x32_bf16 v[80:83], v[222:225], v[190:193], v[80:83]
	v_mfma_f32_16x16x32_bf16 v[76:79], v[214:217], v[198:201], v[76:79]
	v_mfma_f32_16x16x32_bf16 v[72:75], v[222:225], v[198:201], v[72:75]
	v_mfma_f32_16x16x32_bf16 v[68:71], v[214:217], v[206:209], v[68:71]
	v_mfma_f32_16x16x32_bf16 v[64:67], v[222:225], v[206:209], v[64:67]
	v_mfma_f32_16x16x32_bf16 v[92:95], v[218:221], v[186:189], v[92:95]
	v_mfma_f32_16x16x32_bf16 v[88:91], v[226:229], v[186:189], v[88:91]
	v_mfma_f32_16x16x32_bf16 v[84:87], v[218:221], v[194:197], v[84:87]
	v_mfma_f32_16x16x32_bf16 v[80:83], v[226:229], v[194:197], v[80:83]
	v_mfma_f32_16x16x32_bf16 v[76:79], v[218:221], v[202:205], v[76:79]
	v_mfma_f32_16x16x32_bf16 v[72:75], v[226:229], v[202:205], v[72:75]
	v_mfma_f32_16x16x32_bf16 v[68:71], v[218:221], v[210:213], v[68:71]
	v_mfma_f32_16x16x32_bf16 v[64:67], v[226:229], v[210:213], v[64:67]
	s_setprio 1
	v_readfirstlane_b32 s47, v143
	v_add_u32_e32 v163, 0x2000, v143
	v_lshl_add_u64 v[230:231], v[234:235], 0, s[24:25]
	s_mov_b32 m0, s47
	v_readfirstlane_b32 s47, v163
	s_barrier
	ds_read_b128 v[182:185], v151 offset:16384
	ds_read_b128 v[186:189], v151 offset:17408
	ds_read_b128 v[190:193], v150 offset:16384
	ds_read_b128 v[194:197], v150 offset:17408
	ds_read_b128 v[198:201], v149 offset:16384
	ds_read_b128 v[202:205], v149 offset:17408
	ds_read_b128 v[206:209], v148 offset:16384
	ds_read_b128 v[210:213], v148 offset:17408
	global_load_lds_dwordx4 v[230:231], off
	v_lshl_add_u64 v[230:231], v[236:237], 0, s[24:25]
	s_mov_b32 m0, s47
	s_nop 0
	global_load_lds_dwordx4 v[230:231], off
	s_barrier
	s_waitcnt lgkmcnt(0)
	s_setprio 0
	s_waitcnt lgkmcnt(0)
	v_mfma_f32_16x16x32_bf16 v[60:63], v[164:167], v[182:185], v[60:63]
	v_mfma_f32_16x16x32_bf16 v[56:59], v[174:177], v[182:185], v[56:59]
	v_mfma_f32_16x16x32_bf16 v[52:55], v[164:167], v[190:193], v[52:55]
	v_mfma_f32_16x16x32_bf16 v[48:51], v[174:177], v[190:193], v[48:51]
	v_mfma_f32_16x16x32_bf16 v[44:47], v[164:167], v[198:201], v[44:47]
	v_mfma_f32_16x16x32_bf16 v[40:43], v[174:177], v[198:201], v[40:43]
	v_mfma_f32_16x16x32_bf16 v[36:39], v[164:167], v[206:209], v[36:39]
	v_mfma_f32_16x16x32_bf16 v[32:35], v[174:177], v[206:209], v[32:35]
	v_mfma_f32_16x16x32_bf16 v[60:63], v[170:173], v[186:189], v[60:63]
	v_mfma_f32_16x16x32_bf16 v[56:59], v[178:181], v[186:189], v[56:59]
	v_mfma_f32_16x16x32_bf16 v[52:55], v[170:173], v[194:197], v[52:55]
	v_mfma_f32_16x16x32_bf16 v[48:51], v[178:181], v[194:197], v[48:51]
	v_mfma_f32_16x16x32_bf16 v[44:47], v[170:173], v[202:205], v[44:47]
	v_mfma_f32_16x16x32_bf16 v[40:43], v[178:181], v[202:205], v[40:43]
	v_mfma_f32_16x16x32_bf16 v[36:39], v[170:173], v[210:213], v[36:39]
	v_mfma_f32_16x16x32_bf16 v[32:35], v[178:181], v[210:213], v[32:35]
	s_setprio 1
	s_barrier
; #define STAGE(P, BASE, LD, br, kt) do { const char* _g = (const char*)((BASE) + (size_t)(br) * (LD) + (size_t)(kt) * 64); \
;     for (int _i = 0; _i < 2; ++_i) { int _b = tidx * 16 + _i * 8192; int _r, _c; stage_rc(_b, _r, _c); \
;       __builtin_amdgcn_global_load_lds((const unsigned*)(_g + (unsigned)((_r * (LD) + _c) * 2)), (unsigned*)((char*)(P) + _b), 16, 0, 0); } } while (0)
; #define LDA(dst, b, h) for (int m = 0; m < 4; ++m) for (int k = 0; k < 2; ++k) \
;     dst[m][k] = *reinterpret_cast<const bf16x8*>((char*)SA(b, h) + lds_byte(wr * 64 + m * 16 + fr, k * 32 + fq * 8))
; #define LDB(dst, b, h) for (int n = 0; n < 2; ++n) for (int k = 0; k < 2; ++k) \
;     dst[n][k] = *reinterpret_cast<const bf16x8*>((char*)SB(b, h) + lds_byte(wc * 32 + n * 16 + fr, k * 32 + fq * 8))
; #define MMA(ai, bj, At_, Bt_) do { __builtin_amdgcn_s_setprio(1); \
;     for (int k = 0; k < 2; ++k) for (int m = 0; m < 4; ++m) for (int n = 0; n < 2; ++n) \
;       acc[ai][bj][m][n] = __builtin_amdgcn_mfma_f32_16x16x32_bf16(At_[m][k], Bt_[n][k], acc[ai][bj][m][n], 0, 0, 0); \
;     __builtin_amdgcn_s_setprio(0); } while (0)
; #define WAIT_V(n) asm volatile("s_waitcnt vmcnt(" #n ")" ::: "memory")
; #define WAIT_L(n) asm volatile("s_waitcnt lgkmcnt(" #n ")" ::: "memory")
; #define BAR __builtin_amdgcn_s_barrier()
; #define SCHED __builtin_amdgcn_sched_barrier(0)
; template <int EPI, int lda, int ldb, int N, int K>
; __device__ __forceinline__ void gemm_phase(const u16* __restrict__ A, const u16* __restrict__ Bt, const GemmEpi ep, int wv) {
;     ...
;       STAGE(SB(0, 1), Bt, ldb, bcol + HALF, t + 2);
;       WAIT_V(6); BAR; MMA(1, 1, At, B1); BAR;
;       LDB(B0, 1, 0); SCHED; LDA(At, 1, 0); STAGE(SA(0, 1), Ab, lda, brow + HALF, t + 2);
;       WAIT_L(8); BAR; WAIT_L(0); MMA(0, 0, At, B0); BAR; SCHED;
;       LDB(B1, 1, 1); STAGE(SB(1, 0), Bt, ldb, bcol, t + 3);
;       BAR; WAIT_L(0); MMA(0, 1, At, B1); BAR;
	v_add_u32_e32 v164, s56, v153
	v_add_u32_e32 v165, 0x2000, v164
	v_readfirstlane_b32 s47, v164
	v_lshl_add_u64 v[166:167], v[238:239], 0, s[26:27]
	s_mov_b32 m0, s47
	v_readfirstlane_b32 s47, v165
	global_load_lds_dwordx4 v[166:167], off
	v_lshl_add_u64 v[166:167], v[240:241], 0, s[26:27]
	s_mov_b32 m0, s47
	s_nop 0
	global_load_lds_dwordx4 v[166:167], off
	s_waitcnt vmcnt(6)
	s_barrier
	s_setprio 0
	v_mfma_f32_16x16x32_bf16 v[28:31], v[214:217], v[182:185], v[28:31]
	v_mfma_f32_16x16x32_bf16 v[24:27], v[222:225], v[182:185], v[24:27]
	v_mfma_f32_16x16x32_bf16 v[20:23], v[214:217], v[190:193], v[20:23]
	v_mfma_f32_16x16x32_bf16 v[16:19], v[222:225], v[190:193], v[16:19]
	v_mfma_f32_16x16x32_bf16 v[12:15], v[214:217], v[198:201], v[12:15]
	v_mfma_f32_16x16x32_bf16 v[8:11], v[222:225], v[198:201], v[8:11]
	v_mfma_f32_16x16x32_bf16 v[4:7], v[214:217], v[206:209], v[4:7]
	v_mfma_f32_16x16x32_bf16 v[0:3], v[222:225], v[206:209], v[0:3]
	v_mfma_f32_16x16x32_bf16 v[28:31], v[218:221], v[186:189], v[28:31]
	v_mfma_f32_16x16x32_bf16 v[24:27], v[226:229], v[186:189], v[24:27]
	v_mfma_f32_16x16x32_bf16 v[20:23], v[218:221], v[194:197], v[20:23]
	v_mfma_f32_16x16x32_bf16 v[16:19], v[226:229], v[194:197], v[16:19]
	v_mfma_f32_16x16x32_bf16 v[12:15], v[218:221], v[202:205], v[12:15]
	v_mfma_f32_16x16x32_bf16 v[8:11], v[226:229], v[202:205], v[8:11]
	v_mfma_f32_16x16x32_bf16 v[4:7], v[218:221], v[210:213], v[4:7]
	v_mfma_f32_16x16x32_bf16 v[0:3], v[226:229], v[210:213], v[0:3]
	s_setprio 1
	s_barrier
	ds_read_b128 v[170:173], v154
	ds_read_b128 v[174:177], v154 offset:1024
	ds_read_b128 v[178:181], v154 offset:2048
	ds_read_b128 v[182:185], v154 offset:3072
	v_add_u32_e32 v166, 0x4000, v143
	v_add_u32_e32 v167, 0x6000, v143
	v_readfirstlane_b32 s47, v166
	v_lshl_add_u64 v[218:219], v[234:235], 0, s[34:35]
	s_mov_b32 m0, s47
	v_readfirstlane_b32 s47, v167
	ds_read_b128 v[186:189], v151 offset:32768
	ds_read_b128 v[190:193], v151 offset:33792
	ds_read_b128 v[194:197], v150 offset:32768
	ds_read_b128 v[198:201], v150 offset:33792
	ds_read_b128 v[202:205], v149 offset:32768
	ds_read_b128 v[206:209], v149 offset:33792
	ds_read_b128 v[210:213], v148 offset:32768
	ds_read_b128 v[214:217], v148 offset:33792
	global_load_lds_dwordx4 v[218:219], off
	v_lshl_add_u64 v[218:219], v[236:237], 0, s[34:35]
	s_mov_b32 m0, s47
	s_nop 0
	global_load_lds_dwordx4 v[218:219], off
	s_waitcnt lgkmcnt(8)
	s_barrier
	s_waitcnt lgkmcnt(0)
	s_setprio 0
	s_waitcnt lgkmcnt(0)
	v_mfma_f32_16x16x32_bf16 v[124:127], v[170:173], v[186:189], v[124:127]
	v_mfma_f32_16x16x32_bf16 v[120:123], v[178:181], v[186:189], v[120:123]
	v_mfma_f32_16x16x32_bf16 v[116:119], v[170:173], v[194:197], v[116:119]
	v_mfma_f32_16x16x32_bf16 v[112:115], v[178:181], v[194:197], v[112:115]
	v_mfma_f32_16x16x32_bf16 v[108:111], v[170:173], v[202:205], v[108:111]
	v_mfma_f32_16x16x32_bf16 v[104:107], v[178:181], v[202:205], v[104:107]
	v_mfma_f32_16x16x32_bf16 v[100:103], v[170:173], v[210:213], v[100:103]
	v_mfma_f32_16x16x32_bf16 v[96:99], v[178:181], v[210:213], v[96:99]
	v_mfma_f32_16x16x32_bf16 v[124:127], v[174:177], v[190:193], v[124:127]
	v_mfma_f32_16x16x32_bf16 v[120:123], v[182:185], v[190:193], v[120:123]
	v_mfma_f32_16x16x32_bf16 v[116:119], v[174:177], v[198:201], v[116:119]
	v_mfma_f32_16x16x32_bf16 v[112:115], v[182:185], v[198:201], v[112:115]
	v_mfma_f32_16x16x32_bf16 v[108:111], v[174:177], v[206:209], v[108:111]
	v_mfma_f32_16x16x32_bf16 v[104:107], v[182:185], v[206:209], v[104:107]
	v_mfma_f32_16x16x32_bf16 v[100:103], v[174:177], v[214:217], v[100:103]
	v_mfma_f32_16x16x32_bf16 v[96:99], v[182:185], v[214:217], v[96:99]
	s_setprio 1
	s_barrier
	v_readfirstlane_b32 s47, v155
	v_add_u32_e32 v244, 0x2000, v155
	v_lshl_add_u64 v[242:243], v[238:239], 0, s[36:37]
	s_mov_b32 m0, s47
	v_readfirstlane_b32 s47, v244
	ds_read_b128 v[218:221], v152
	ds_read_b128 v[222:225], v152 offset:1024
	ds_read_b128 v[226:229], v152 offset:2048
	ds_read_b128 v[230:233], v152 offset:3072
	global_load_lds_dwordx4 v[242:243], off
	v_lshl_add_u64 v[242:243], v[240:241], 0, s[36:37]
	s_mov_b32 m0, s47
	s_nop 0
	global_load_lds_dwordx4 v[242:243], off
	s_barrier
	s_waitcnt lgkmcnt(0)
	s_setprio 0
	s_waitcnt lgkmcnt(0)
	v_mfma_f32_16x16x32_bf16 v[92:95], v[218:221], v[186:189], v[92:95]
	v_mfma_f32_16x16x32_bf16 v[88:91], v[226:229], v[186:189], v[88:91]
	v_mfma_f32_16x16x32_bf16 v[84:87], v[218:221], v[194:197], v[84:87]
	v_mfma_f32_16x16x32_bf16 v[80:83], v[226:229], v[194:197], v[80:83]
	v_mfma_f32_16x16x32_bf16 v[76:79], v[218:221], v[202:205], v[76:79]
	v_mfma_f32_16x16x32_bf16 v[72:75], v[226:229], v[202:205], v[72:75]
	v_mfma_f32_16x16x32_bf16 v[68:71], v[218:221], v[210:213], v[68:71]
	v_mfma_f32_16x16x32_bf16 v[64:67], v[226:229], v[210:213], v[64:67]
	v_mfma_f32_16x16x32_bf16 v[92:95], v[222:225], v[190:193], v[92:95]
	v_mfma_f32_16x16x32_bf16 v[88:91], v[230:233], v[190:193], v[88:91]
	v_mfma_f32_16x16x32_bf16 v[84:87], v[222:225], v[198:201], v[84:87]
	v_mfma_f32_16x16x32_bf16 v[80:83], v[230:233], v[198:201], v[80:83]
	v_mfma_f32_16x16x32_bf16 v[76:79], v[222:225], v[206:209], v[76:79]
	v_mfma_f32_16x16x32_bf16 v[72:75], v[230:233], v[206:209], v[72:75]
	v_mfma_f32_16x16x32_bf16 v[68:71], v[222:225], v[214:217], v[68:71]
	v_mfma_f32_16x16x32_bf16 v[64:67], v[230:233], v[214:217], v[64:67]
	s_setprio 1
	v_readfirstlane_b32 s47, v156
	v_lshl_add_u64 v[234:235], v[234:235], 0, s[38:39]
	s_mov_b32 m0, s47
	v_readfirstlane_b32 s47, v157
	s_barrier
; #define STAGE(P, BASE, LD, br, kt) do { const char* _g = (const char*)((BASE) + (size_t)(br) * (LD) + (size_t)(kt) * 64); \
;     for (int _i = 0; _i < 2; ++_i) { int _b = tidx * 16 + _i * 8192; int _r, _c; stage_rc(_b, _r, _c); \
;       __builtin_amdgcn_global_load_lds((const unsigned*)(_g + (unsigned)((_r * (LD) + _c) * 2)), (unsigned*)((char*)(P) + _b), 16, 0, 0); } } while (0)
; #define LDA(dst, b, h) for (int m = 0; m < 4; ++m) for (int k = 0; k < 2; ++k) \
;     dst[m][k] = *reinterpret_cast<const bf16x8*>((char*)SA(b, h) + lds_byte(wr * 64 + m * 16 + fr, k * 32 + fq * 8))
; #define LDB(dst, b, h) for (int n = 0; n < 2; ++n) for (int k = 0; k < 2; ++k) \
;     dst[n][k] = *reinterpret_cast<const bf16x8*>((char*)SB(b, h) + lds_byte(wc * 32 + n * 16 + fr, k * 32 + fq * 8))
; #define MMA(ai, bj, At_, Bt_) do { __builtin_amdgcn_s_setprio(1); \
;     for (int k = 0; k < 2; ++k) for (int m = 0; m < 4; ++m) for (int n = 0; n < 2; ++n) \
;       acc[ai][bj][m][n] = __builtin_amdgcn_mfma_f32_16x16x32_bf16(At_[m][k], Bt_[n][k], acc[ai][bj][m][n], 0, 0, 0); \
;     __builtin_amdgcn_s_setprio(0); } while (0)
; #define WAIT_V(n) asm volatile("s_waitcnt vmcnt(" #n ")" ::: "memory")
; #define WAIT_L(n) asm volatile("s_waitcnt lgkmcnt(" #n ")" ::: "memory")
; #define BAR __builtin_amdgcn_s_barrier()
; #define SCHED __builtin_amdgcn_sched_barrier(0)
; template <int EPI, int lda, int ldb, int N, int K>
; __device__ __forceinline__ void gemm_phase(const u16* __restrict__ A, const u16* __restrict__ Bt, const GemmEpi ep, int wv) {
;     ...
;       LDA(At, 1, 1); STAGE(SA(1, 0), Ab, lda, brow, t + 3);
;       BAR; WAIT_L(0); MMA(1, 0, At, B0); BAR; SCHED;
;       STAGE(SB(1, 1), Bt, ldb, bcol + HALF, t + 3);
;       WAIT_V(6); BAR; MMA(1, 1, At, B1); BAR;
;     }
;     { LDB(B0, 0, 0); LDA(At, 0, 0); STAGE(SA(1, 1), Ab, lda, brow + HALF, nt - 1);
;       BAR; WAIT_L(0); MMA(0, 0, At, B0); BAR;
	ds_read_b128 v[186:189], v151 offset:49152
	ds_read_b128 v[190:193], v151 offset:50176
	ds_read_b128 v[194:197], v150 offset:49152
	ds_read_b128 v[198:201], v150 offset:50176
	ds_read_b128 v[202:205], v149 offset:49152
	ds_read_b128 v[206:209], v149 offset:50176
	ds_read_b128 v[210:213], v148 offset:49152
	ds_read_b128 v[214:217], v148 offset:50176
	global_load_lds_dwordx4 v[234:235], off
	v_lshl_add_u64 v[234:235], v[236:237], 0, s[38:39]
	s_mov_b32 m0, s47
	s_nop 0
	global_load_lds_dwordx4 v[234:235], off
	s_barrier
	s_waitcnt lgkmcnt(0)
	s_setprio 0
	s_waitcnt lgkmcnt(0)
	v_mfma_f32_16x16x32_bf16 v[60:63], v[170:173], v[186:189], v[60:63]
	v_mfma_f32_16x16x32_bf16 v[56:59], v[178:181], v[186:189], v[56:59]
	v_mfma_f32_16x16x32_bf16 v[52:55], v[170:173], v[194:197], v[52:55]
	v_mfma_f32_16x16x32_bf16 v[48:51], v[178:181], v[194:197], v[48:51]
	v_mfma_f32_16x16x32_bf16 v[44:47], v[170:173], v[202:205], v[44:47]
	v_mfma_f32_16x16x32_bf16 v[40:43], v[178:181], v[202:205], v[40:43]
	v_mfma_f32_16x16x32_bf16 v[36:39], v[170:173], v[210:213], v[36:39]
	v_mfma_f32_16x16x32_bf16 v[32:35], v[178:181], v[210:213], v[32:35]
	v_mfma_f32_16x16x32_bf16 v[60:63], v[174:177], v[190:193], v[60:63]
	v_mfma_f32_16x16x32_bf16 v[56:59], v[182:185], v[190:193], v[56:59]
	v_mfma_f32_16x16x32_bf16 v[52:55], v[174:177], v[198:201], v[52:55]
	v_mfma_f32_16x16x32_bf16 v[48:51], v[182:185], v[198:201], v[48:51]
	v_mfma_f32_16x16x32_bf16 v[44:47], v[174:177], v[206:209], v[44:47]
	v_mfma_f32_16x16x32_bf16 v[40:43], v[182:185], v[206:209], v[40:43]
	v_mfma_f32_16x16x32_bf16 v[36:39], v[174:177], v[214:217], v[36:39]
	v_mfma_f32_16x16x32_bf16 v[32:35], v[182:185], v[214:217], v[32:35]
	s_setprio 1
	s_barrier
	v_readfirstlane_b32 s47, v158
	v_add_u32_e32 v172, 0x2000, v158
	v_lshl_add_u64 v[170:171], v[238:239], 0, s[40:41]
	s_mov_b32 m0, s47
	v_readfirstlane_b32 s47, v172
	global_load_lds_dwordx4 v[170:171], off
	v_lshl_add_u64 v[170:171], v[240:241], 0, s[40:41]
	s_mov_b32 m0, s47
	s_nop 0
	global_load_lds_dwordx4 v[170:171], off
	s_waitcnt vmcnt(6)
	s_barrier
	s_setprio 0
	v_mfma_f32_16x16x32_bf16 v[28:31], v[218:221], v[186:189], v[28:31]
	v_mfma_f32_16x16x32_bf16 v[24:27], v[226:229], v[186:189], v[24:27]
	v_mfma_f32_16x16x32_bf16 v[20:23], v[218:221], v[194:197], v[20:23]
	v_mfma_f32_16x16x32_bf16 v[16:19], v[226:229], v[194:197], v[16:19]
	v_mfma_f32_16x16x32_bf16 v[12:15], v[218:221], v[202:205], v[12:15]
	v_mfma_f32_16x16x32_bf16 v[8:11], v[226:229], v[202:205], v[8:11]
	v_mfma_f32_16x16x32_bf16 v[4:7], v[218:221], v[210:213], v[4:7]
	v_mfma_f32_16x16x32_bf16 v[0:3], v[226:229], v[210:213], v[0:3]
	v_mfma_f32_16x16x32_bf16 v[28:31], v[222:225], v[190:193], v[28:31]
	v_mfma_f32_16x16x32_bf16 v[24:27], v[230:233], v[190:193], v[24:27]
	v_mfma_f32_16x16x32_bf16 v[20:23], v[222:225], v[198:201], v[20:23]
	v_mfma_f32_16x16x32_bf16 v[16:19], v[230:233], v[198:201], v[16:19]
	v_mfma_f32_16x16x32_bf16 v[12:15], v[222:225], v[206:209], v[12:15]
	v_mfma_f32_16x16x32_bf16 v[8:11], v[230:233], v[206:209], v[8:11]
	v_mfma_f32_16x16x32_bf16 v[4:7], v[222:225], v[214:217], v[4:7]
	v_mfma_f32_16x16x32_bf16 v[0:3], v[230:233], v[214:217], v[0:3]
	s_setprio 1
	s_add_i32 s46, s46, 2
	s_add_u32 s44, s44, 0x100
	s_addc_u32 s45, s45, 0
	s_cmp_gt_u32 s46, 27
	s_barrier
	s_cbranch_scc0 .LBB0_1448
	s_lshl_b64 s[44:45], s[16:17], 12
	s_add_u32 s44, s14, s44
	s_addc_u32 s45, s15, s45
	s_add_u32 s44, s44, 0x80000
	s_addc_u32 s45, s45, 0
	v_lshl_add_u64 v[156:157], s[44:45], 0, v[128:129]
	v_readfirstlane_b32 s46, v168
	v_lshl_add_u64 v[156:157], v[156:157], 0, s[42:43]
	s_mov_b32 m0, s46
	ds_read_b128 v[134:137], v160
	ds_read_b128 v[138:141], v160 offset:1024
	ds_read_b128 v[170:173], v160 offset:2048
	ds_read_b128 v[174:177], v160 offset:3072
	ds_read_b128 v[178:181], v151
	ds_read_b128 v[182:185], v151 offset:1024
	ds_read_b128 v[186:189], v150
	ds_read_b128 v[190:193], v150 offset:1024
	ds_read_b128 v[194:197], v149
	ds_read_b128 v[198:201], v149 offset:1024
	ds_read_b128 v[202:205], v148
	ds_read_b128 v[206:209], v148 offset:1024
	global_load_lds_dwordx4 v[156:157], off
	v_lshl_add_u64 v[156:157], s[44:45], 0, v[132:133]
	v_readfirstlane_b32 s44, v169
	v_lshl_add_u64 v[156:157], v[156:157], 0, s[42:43]
	s_mov_b32 m0, s44
	s_nop 0
	global_load_lds_dwordx4 v[156:157], off
	s_barrier
	s_waitcnt lgkmcnt(0)
	s_setprio 0
	s_waitcnt lgkmcnt(0)
	v_mfma_f32_16x16x32_bf16 v[124:127], v[134:137], v[178:181], v[124:127]
	v_mfma_f32_16x16x32_bf16 v[120:123], v[170:173], v[178:181], v[120:123]
	v_mfma_f32_16x16x32_bf16 v[116:119], v[134:137], v[186:189], v[116:119]
	v_mfma_f32_16x16x32_bf16 v[112:115], v[170:173], v[186:189], v[112:115]
	v_mfma_f32_16x16x32_bf16 v[108:111], v[134:137], v[194:197], v[108:111]
	v_mfma_f32_16x16x32_bf16 v[104:107], v[170:173], v[194:197], v[104:107]
	v_mfma_f32_16x16x32_bf16 v[100:103], v[134:137], v[202:205], v[100:103]
	v_mfma_f32_16x16x32_bf16 v[96:99], v[170:173], v[202:205], v[96:99]
	v_mfma_f32_16x16x32_bf16 v[124:127], v[138:141], v[182:185], v[124:127]
	v_mfma_f32_16x16x32_bf16 v[120:123], v[174:177], v[182:185], v[120:123]
	v_mfma_f32_16x16x32_bf16 v[116:119], v[138:141], v[190:193], v[116:119]
	v_mfma_f32_16x16x32_bf16 v[112:115], v[174:177], v[190:193], v[112:115]
	v_mfma_f32_16x16x32_bf16 v[108:111], v[138:141], v[198:201], v[108:111]
	v_mfma_f32_16x16x32_bf16 v[104:107], v[174:177], v[198:201], v[104:107]
	v_mfma_f32_16x16x32_bf16 v[100:103], v[138:141], v[206:209], v[100:103]
	v_mfma_f32_16x16x32_bf16 v[96:99], v[174:177], v[206:209], v[96:99]
	s_setprio 1
	s_barrier
; #define LDA(dst, b, h) for (int m = 0; m < 4; ++m) for (int k = 0; k < 2; ++k) \
;     dst[m][k] = *reinterpret_cast<const bf16x8*>((char*)SA(b, h) + lds_byte(wr * 64 + m * 16 + fr, k * 32 + fq * 8))
; #define LDB(dst, b, h) for (int n = 0; n < 2; ++n) for (int k = 0; k < 2; ++k) \
;     dst[n][k] = *reinterpret_cast<const bf16x8*>((char*)SB(b, h) + lds_byte(wc * 32 + n * 16 + fr, k * 32 + fq * 8))
; #define MMA(ai, bj, At_, Bt_) do { __builtin_amdgcn_s_setprio(1); \
;     for (int k = 0; k < 2; ++k) for (int m = 0; m < 4; ++m) for (int n = 0; n < 2; ++n) \
;       acc[ai][bj][m][n] = __builtin_amdgcn_mfma_f32_16x16x32_bf16(At_[m][k], Bt_[n][k], acc[ai][bj][m][n], 0, 0, 0); \
;     __builtin_amdgcn_s_setprio(0); } while (0)
; #define WAIT_V(n) asm volatile("s_waitcnt vmcnt(" #n ")" ::: "memory")
; #define WAIT_L(n) asm volatile("s_waitcnt lgkmcnt(" #n ")" ::: "memory")
; #define BAR __builtin_amdgcn_s_barrier()
; template <int EPI, int lda, int ldb, int N, int K>
; __device__ __forceinline__ void gemm_phase(const u16* __restrict__ A, const u16* __restrict__ Bt, const GemmEpi ep, int wv) {
;     ...
;       LDB(B1, 0, 1); BAR; WAIT_L(0); MMA(0, 1, At, B1); BAR;
;       LDA(At, 0, 1); WAIT_V(4); BAR; WAIT_L(0); MMA(1, 0, At, B0); MMA(1, 1, At, B1); BAR; }
;     { LDB(B0, 1, 0); LDA(At, 1, 0); WAIT_V(2); BAR; WAIT_L(0); MMA(0, 0, At, B0); BAR;
	ds_read_b128 v[210:213], v159
	ds_read_b128 v[214:217], v159 offset:1024
	ds_read_b128 v[218:221], v159 offset:2048
	ds_read_b128 v[156:159], v159 offset:3072
	s_barrier
	s_waitcnt lgkmcnt(0)
	s_setprio 0
	s_waitcnt lgkmcnt(0)
	v_mfma_f32_16x16x32_bf16 v[92:95], v[210:213], v[178:181], v[92:95]
	v_mfma_f32_16x16x32_bf16 v[88:91], v[218:221], v[178:181], v[88:91]
	v_mfma_f32_16x16x32_bf16 v[76:79], v[210:213], v[194:197], v[76:79]
	v_mfma_f32_16x16x32_bf16 v[72:75], v[218:221], v[194:197], v[72:75]
	v_mfma_f32_16x16x32_bf16 v[84:87], v[210:213], v[186:189], v[84:87]
	v_mfma_f32_16x16x32_bf16 v[80:83], v[218:221], v[186:189], v[80:83]
	v_mfma_f32_16x16x32_bf16 v[68:71], v[210:213], v[202:205], v[68:71]
	v_mfma_f32_16x16x32_bf16 v[64:67], v[218:221], v[202:205], v[64:67]
	v_mfma_f32_16x16x32_bf16 v[92:95], v[214:217], v[182:185], v[92:95]
	v_mfma_f32_16x16x32_bf16 v[88:91], v[156:159], v[182:185], v[88:91]
	v_mfma_f32_16x16x32_bf16 v[76:79], v[214:217], v[198:201], v[76:79]
	v_mfma_f32_16x16x32_bf16 v[72:75], v[156:159], v[198:201], v[72:75]
	v_mfma_f32_16x16x32_bf16 v[178:181], v[214:217], v[190:193], v[84:87]
	v_mfma_f32_16x16x32_bf16 v[182:185], v[156:159], v[190:193], v[80:83]
	v_mfma_f32_16x16x32_bf16 v[186:189], v[214:217], v[206:209], v[68:71]
	v_mfma_f32_16x16x32_bf16 v[190:193], v[156:159], v[206:209], v[64:67]
	s_setprio 1
	s_barrier
	s_nop 0
	ds_read_b128 v[64:67], v151 offset:16384
	ds_read_b128 v[68:71], v151 offset:17408
	ds_read_b128 v[80:83], v150 offset:16384
	ds_read_b128 v[84:87], v150 offset:17408
	ds_read_b128 v[194:197], v149 offset:16384
	ds_read_b128 v[198:201], v149 offset:17408
	ds_read_b128 v[202:205], v148 offset:16384
	ds_read_b128 v[206:209], v148 offset:17408
	s_waitcnt vmcnt(4)
	s_barrier
	s_waitcnt lgkmcnt(0)
	s_setprio 0
	s_waitcnt lgkmcnt(0)
	v_mfma_f32_16x16x32_bf16 v[60:63], v[134:137], v[64:67], v[60:63]
	v_mfma_f32_16x16x32_bf16 v[56:59], v[170:173], v[64:67], v[56:59]
	v_mfma_f32_16x16x32_bf16 v[52:55], v[134:137], v[80:83], v[52:55]
	v_mfma_f32_16x16x32_bf16 v[48:51], v[170:173], v[80:83], v[48:51]
	v_mfma_f32_16x16x32_bf16 v[44:47], v[134:137], v[194:197], v[44:47]
	v_mfma_f32_16x16x32_bf16 v[40:43], v[170:173], v[194:197], v[40:43]
	v_mfma_f32_16x16x32_bf16 v[36:39], v[134:137], v[202:205], v[36:39]
	v_mfma_f32_16x16x32_bf16 v[32:35], v[170:173], v[202:205], v[32:35]
	v_mfma_f32_16x16x32_bf16 v[60:63], v[138:141], v[68:71], v[60:63]
	v_mfma_f32_16x16x32_bf16 v[56:59], v[174:177], v[68:71], v[56:59]
	v_mfma_f32_16x16x32_bf16 v[52:55], v[138:141], v[84:87], v[52:55]
	v_mfma_f32_16x16x32_bf16 v[48:51], v[174:177], v[84:87], v[48:51]
	v_mfma_f32_16x16x32_bf16 v[44:47], v[138:141], v[198:201], v[44:47]
	v_mfma_f32_16x16x32_bf16 v[40:43], v[174:177], v[198:201], v[40:43]
	v_mfma_f32_16x16x32_bf16 v[36:39], v[138:141], v[206:209], v[36:39]
	v_mfma_f32_16x16x32_bf16 v[32:35], v[174:177], v[206:209], v[32:35]
	s_setprio 1
	s_setprio 0
	v_mfma_f32_16x16x32_bf16 v[28:31], v[210:213], v[64:67], v[28:31]
	v_mfma_f32_16x16x32_bf16 v[20:23], v[210:213], v[80:83], v[20:23]
	v_mfma_f32_16x16x32_bf16 v[12:15], v[210:213], v[194:197], v[12:15]
	v_mfma_f32_16x16x32_bf16 v[4:7], v[210:213], v[202:205], v[4:7]
	v_mfma_f32_16x16x32_bf16 v[24:27], v[218:221], v[64:67], v[24:27]
	v_mfma_f32_16x16x32_bf16 v[16:19], v[218:221], v[80:83], v[16:19]
	v_mfma_f32_16x16x32_bf16 v[8:11], v[218:221], v[194:197], v[8:11]
	v_mfma_f32_16x16x32_bf16 v[0:3], v[218:221], v[202:205], v[0:3]
	v_mfma_f32_16x16x32_bf16 v[28:31], v[214:217], v[68:71], v[28:31]
	v_mfma_f32_16x16x32_bf16 v[20:23], v[214:217], v[84:87], v[20:23]
	v_mfma_f32_16x16x32_bf16 v[12:15], v[214:217], v[198:201], v[12:15]
	v_mfma_f32_16x16x32_bf16 v[4:7], v[214:217], v[206:209], v[4:7]
	v_mfma_f32_16x16x32_bf16 v[134:137], v[156:159], v[68:71], v[24:27]
	v_mfma_f32_16x16x32_bf16 v[138:141], v[156:159], v[84:87], v[16:19]
	v_mfma_f32_16x16x32_bf16 v[168:171], v[156:159], v[198:201], v[8:11]
	v_mfma_f32_16x16x32_bf16 v[156:159], v[156:159], v[206:209], v[0:3]
	s_setprio 1
	s_barrier
	s_nop 0
	ds_read_b128 v[0:3], v154
	ds_read_b128 v[8:11], v154 offset:1024
	ds_read_b128 v[16:19], v154 offset:2048
	ds_read_b128 v[172:175], v154 offset:3072
	ds_read_b128 v[24:27], v151 offset:32768
	ds_read_b128 v[194:197], v151 offset:33792
	ds_read_b128 v[198:201], v150 offset:32768
	ds_read_b128 v[202:205], v150 offset:33792
	ds_read_b128 v[206:209], v149 offset:32768
	ds_read_b128 v[210:213], v149 offset:33792
	ds_read_b128 v[214:217], v148 offset:32768
	ds_read_b128 v[218:221], v148 offset:33792
	s_waitcnt vmcnt(2)
	s_barrier
; #define LDA(dst, b, h) for (int m = 0; m < 4; ++m) for (int k = 0; k < 2; ++k) \
;     dst[m][k] = *reinterpret_cast<const bf16x8*>((char*)SA(b, h) + lds_byte(wr * 64 + m * 16 + fr, k * 32 + fq * 8))
; #define LDB(dst, b, h) for (int n = 0; n < 2; ++n) for (int k = 0; k < 2; ++k) \
;     dst[n][k] = *reinterpret_cast<const bf16x8*>((char*)SB(b, h) + lds_byte(wc * 32 + n * 16 + fr, k * 32 + fq * 8))
; #define MMA(ai, bj, At_, Bt_) do { __builtin_amdgcn_s_setprio(1); \
;     for (int k = 0; k < 2; ++k) for (int m = 0; m < 4; ++m) for (int n = 0; n < 2; ++n) \
;       acc[ai][bj][m][n] = __builtin_amdgcn_mfma_f32_16x16x32_bf16(At_[m][k], Bt_[n][k], acc[ai][bj][m][n], 0, 0, 0); \
;     __builtin_amdgcn_s_setprio(0); } while (0)
; #define WAIT_V(n) asm volatile("s_waitcnt vmcnt(" #n ")" ::: "memory")
; #define WAIT_L(n) asm volatile("s_waitcnt lgkmcnt(" #n ")" ::: "memory")
; #define BAR __builtin_amdgcn_s_barrier()
; template <int EPI, int lda, int ldb, int N, int K>
; __device__ __forceinline__ void gemm_phase(const u16* __restrict__ A, const u16* __restrict__ Bt, const GemmEpi ep, int wv) {
;     ...
;     { LDB(B0, 1, 0); LDA(At, 1, 0); WAIT_V(2); BAR; WAIT_L(0); MMA(0, 0, At, B0); BAR;
;       LDB(B1, 1, 1); WAIT_V(0); BAR; WAIT_L(0); MMA(0, 1, At, B1); BAR;
;       LDA(At, 1, 1); BAR; WAIT_L(0); MMA(1, 0, At, B0); MMA(1, 1, At, B1); BAR; }
;     if (wr == 0) BAR;
	s_waitcnt lgkmcnt(0)
	s_setprio 0
	s_waitcnt lgkmcnt(0)
	v_mfma_f32_16x16x32_bf16 v[64:67], v[0:3], v[24:27], v[124:127]
	v_mfma_f32_16x16x32_bf16 v[68:71], v[16:19], v[24:27], v[120:123]
	v_mfma_f32_16x16x32_bf16 v[80:83], v[0:3], v[198:201], v[116:119]
	v_mfma_f32_16x16x32_bf16 v[84:87], v[16:19], v[198:201], v[112:115]
	v_mfma_f32_16x16x32_bf16 v[108:111], v[0:3], v[206:209], v[108:111]
	v_mfma_f32_16x16x32_bf16 v[104:107], v[16:19], v[206:209], v[104:107]
	v_mfma_f32_16x16x32_bf16 v[120:123], v[0:3], v[214:217], v[100:103]
	v_mfma_f32_16x16x32_bf16 v[124:127], v[16:19], v[214:217], v[96:99]
	v_mfma_f32_16x16x32_bf16 v[116:119], v[8:11], v[194:197], v[64:67]
	v_mfma_f32_16x16x32_bf16 v[112:115], v[172:175], v[194:197], v[68:71]
	v_mfma_f32_16x16x32_bf16 v[100:103], v[8:11], v[202:205], v[80:83]
	v_mfma_f32_16x16x32_bf16 v[96:99], v[172:175], v[202:205], v[84:87]
	v_mfma_f32_16x16x32_bf16 v[84:87], v[8:11], v[210:213], v[108:111]
	v_mfma_f32_16x16x32_bf16 v[80:83], v[172:175], v[210:213], v[104:107]
	v_mfma_f32_16x16x32_bf16 v[68:71], v[8:11], v[218:221], v[120:123]
	v_mfma_f32_16x16x32_bf16 v[64:67], v[172:175], v[218:221], v[124:127]
	s_setprio 1
	s_barrier
	ds_read_b128 v[222:225], v152
	ds_read_b128 v[226:229], v152 offset:1024
	ds_read_b128 v[230:233], v152 offset:2048
	ds_read_b128 v[152:155], v152 offset:3072
	s_waitcnt vmcnt(0)
	s_barrier
	s_waitcnt lgkmcnt(0)
	s_setprio 0
	s_waitcnt lgkmcnt(0)
	v_mfma_f32_16x16x32_bf16 v[92:95], v[222:225], v[24:27], v[92:95]
	v_mfma_f32_16x16x32_bf16 v[24:27], v[230:233], v[24:27], v[88:91]
	v_mfma_f32_16x16x32_bf16 v[88:91], v[222:225], v[198:201], v[178:181]
	v_mfma_f32_16x16x32_bf16 v[104:107], v[230:233], v[198:201], v[182:185]
	v_mfma_f32_16x16x32_bf16 v[76:79], v[222:225], v[206:209], v[76:79]
	v_mfma_f32_16x16x32_bf16 v[72:75], v[230:233], v[206:209], v[72:75]
	v_mfma_f32_16x16x32_bf16 v[176:179], v[222:225], v[214:217], v[186:189]
	v_mfma_f32_16x16x32_bf16 v[180:183], v[230:233], v[214:217], v[190:193]
	v_mfma_f32_16x16x32_bf16 v[124:127], v[226:229], v[194:197], v[92:95]
	v_mfma_f32_16x16x32_bf16 v[120:123], v[152:155], v[194:197], v[24:27]
	v_mfma_f32_16x16x32_bf16 v[108:111], v[226:229], v[202:205], v[88:91]
	v_mfma_f32_16x16x32_bf16 v[104:107], v[152:155], v[202:205], v[104:107]
	v_mfma_f32_16x16x32_bf16 v[92:95], v[226:229], v[210:213], v[76:79]
	v_mfma_f32_16x16x32_bf16 v[88:91], v[152:155], v[210:213], v[72:75]
	v_mfma_f32_16x16x32_bf16 v[76:79], v[226:229], v[218:221], v[176:179]
	v_mfma_f32_16x16x32_bf16 v[72:75], v[152:155], v[218:221], v[180:183]
	s_setprio 1
	s_barrier
	ds_read_b128 v[176:179], v151 offset:49152
	ds_read_b128 v[180:183], v151 offset:50176
	ds_read_b128 v[184:187], v150 offset:49152
	ds_read_b128 v[188:191], v150 offset:50176
	ds_read_b128 v[192:195], v149 offset:49152
	ds_read_b128 v[196:199], v149 offset:50176
	ds_read_b128 v[200:203], v148 offset:49152
	ds_read_b128 v[148:151], v148 offset:50176
	s_barrier
	s_waitcnt lgkmcnt(0)
	s_setprio 0
	s_waitcnt lgkmcnt(0)
	v_mfma_f32_16x16x32_bf16 v[24:27], v[0:3], v[176:179], v[60:63]
	v_mfma_f32_16x16x32_bf16 v[60:63], v[16:19], v[176:179], v[56:59]
	v_mfma_f32_16x16x32_bf16 v[52:55], v[0:3], v[184:187], v[52:55]
	v_mfma_f32_16x16x32_bf16 v[204:207], v[16:19], v[184:187], v[48:51]
	v_mfma_f32_16x16x32_bf16 v[44:47], v[0:3], v[192:195], v[44:47]
	v_mfma_f32_16x16x32_bf16 v[208:211], v[16:19], v[192:195], v[40:43]
	v_mfma_f32_16x16x32_bf16 v[0:3], v[0:3], v[200:203], v[36:39]
	v_mfma_f32_16x16x32_bf16 v[36:39], v[16:19], v[200:203], v[32:35]
	v_mfma_f32_16x16x32_bf16 v[56:59], v[8:11], v[180:183], v[24:27]
	v_mfma_f32_16x16x32_bf16 v[48:51], v[172:175], v[180:183], v[60:63]
	v_mfma_f32_16x16x32_bf16 v[40:43], v[8:11], v[188:191], v[52:55]
	v_mfma_f32_16x16x32_bf16 v[32:35], v[172:175], v[188:191], v[204:207]
	v_mfma_f32_16x16x32_bf16 v[24:27], v[8:11], v[196:199], v[44:47]
	v_mfma_f32_16x16x32_bf16 v[16:19], v[172:175], v[196:199], v[208:211]
	v_mfma_f32_16x16x32_bf16 v[8:11], v[8:11], v[148:151], v[0:3]
	v_mfma_f32_16x16x32_bf16 v[0:3], v[172:175], v[148:151], v[36:39]
	s_setprio 1
	s_setprio 0
	v_mfma_f32_16x16x32_bf16 v[28:31], v[222:225], v[176:179], v[28:31]
	v_mfma_f32_16x16x32_bf16 v[36:39], v[230:233], v[176:179], v[134:137]
	v_mfma_f32_16x16x32_bf16 v[20:23], v[222:225], v[184:187], v[20:23]
	v_mfma_f32_16x16x32_bf16 v[134:137], v[230:233], v[184:187], v[138:141]
	v_mfma_f32_16x16x32_bf16 v[12:15], v[222:225], v[192:195], v[12:15]
	v_mfma_f32_16x16x32_bf16 v[138:141], v[230:233], v[192:195], v[168:171]
	v_mfma_f32_16x16x32_bf16 v[4:7], v[222:225], v[200:203], v[4:7]
	v_mfma_f32_16x16x32_bf16 v[156:159], v[230:233], v[200:203], v[156:159]
	v_mfma_f32_16x16x32_bf16 v[60:63], v[226:229], v[180:183], v[28:31]
	v_mfma_f32_16x16x32_bf16 v[52:55], v[152:155], v[180:183], v[36:39]
	v_mfma_f32_16x16x32_bf16 v[44:47], v[226:229], v[188:191], v[20:23]
	v_mfma_f32_16x16x32_bf16 v[36:39], v[152:155], v[188:191], v[134:137]
	v_mfma_f32_16x16x32_bf16 v[28:31], v[226:229], v[196:199], v[12:15]
	v_mfma_f32_16x16x32_bf16 v[20:23], v[152:155], v[196:199], v[138:141]
	v_mfma_f32_16x16x32_bf16 v[12:15], v[226:229], v[148:151], v[4:7]
	v_mfma_f32_16x16x32_bf16 v[4:7], v[152:155], v[148:151], v[156:159]
	s_setprio 1
	v_cmp_gt_u32_e32 vcc, s60, v130
	s_barrier
	s_and_saveexec_b64 s[44:45], vcc
	s_cbranch_execz .LBB0_1451
	s_barrier

; #define STAGE(P, BASE, LD, br, kt) do { const char* _g = (const char*)((BASE) + (size_t)(br) * (LD) + (size_t)(kt) * 64); \
;     for (int _i = 0; _i < 2; ++_i) { int _b = tidx * 16 + _i * 8192; int _r, _c; stage_rc(_b, _r, _c); \
;       __builtin_amdgcn_global_load_lds((const unsigned*)(_g + (unsigned)((_r * (LD) + _c) * 2)), (unsigned*)((char*)(P) + _b), 16, 0, 0); } } while (0)
; #define LDA(dst, b, h) for (int m = 0; m < 4; ++m) for (int k = 0; k < 2; ++k) \
;     dst[m][k] = *reinterpret_cast<const bf16x8*>((char*)SA(b, h) + lds_byte(wr * 64 + m * 16 + fr, k * 32 + fq * 8))
; #define LDB(dst, b, h) for (int n = 0; n < 2; ++n) for (int k = 0; k < 2; ++k) \
;     dst[n][k] = *reinterpret_cast<const bf16x8*>((char*)SB(b, h) + lds_byte(wc * 32 + n * 16 + fr, k * 32 + fq * 8))
; #define MMA(ai, bj, At_, Bt_) do { __builtin_amdgcn_s_setprio(1); \
;     for (int k = 0; k < 2; ++k) for (int m = 0; m < 4; ++m) for (int n = 0; n < 2; ++n) \
;       acc[ai][bj][m][n] = __builtin_amdgcn_mfma_f32_16x16x32_bf16(At_[m][k], Bt_[n][k], acc[ai][bj][m][n], 0, 0, 0); \
;     __builtin_amdgcn_s_setprio(0); } while (0)
; #define WAIT_L(n) asm volatile("s_waitcnt lgkmcnt(" #n ")" ::: "memory")
; #define BAR __builtin_amdgcn_s_barrier()
; #define SCHED __builtin_amdgcn_sched_barrier(0)
; template <int EPI, int lda, int ldb, int N, int K>
; __device__ __forceinline__ void gemm_phase(const u16* __restrict__ A, const u16* __restrict__ Bt, const GemmEpi ep, int wv) {
;     ...
;       LDB(B0, 0, 0); SCHED; LDA(At, 0, 0); STAGE(SA(1, 1), Ab, lda, brow + HALF, t + 1);
;       WAIT_L(8); BAR; WAIT_L(0); MMA(0, 0, At, B0); BAR; SCHED;
;       LDB(B1, 0, 1); STAGE(SB(0, 0), Bt, ldb, bcol, t + 2);
;       BAR; WAIT_L(0); MMA(0, 1, At, B1); BAR;
;       LDA(At, 0, 1); STAGE(SA(0, 0), Ab, lda, brow, t + 2);
;       BAR; WAIT_L(0); MMA(1, 0, At, B0); BAR; SCHED;
.LBB0_1564:
	ds_read_b128 v[172:175], v161
	ds_read_b128 v[176:179], v161 offset:1024
	ds_read_b128 v[180:183], v161 offset:2048
	ds_read_b128 v[184:187], v161 offset:3072
	v_add_u32_e32 v169, 0xc000, v148
	v_lshl_add_u64 v[236:237], v[136:137], 0, s[40:41]
	v_readfirstlane_b32 s43, v169
	v_add_u32_e32 v170, 0xe000, v148
	v_lshl_add_u64 v[162:163], v[236:237], 0, s[14:15]
	s_mov_b32 m0, s43
	v_lshl_add_u64 v[238:239], v[134:135], 0, s[40:41]
	v_readfirstlane_b32 s43, v170
	ds_read_b128 v[164:167], v152
	ds_read_b128 v[188:191], v152 offset:1024
	ds_read_b128 v[192:195], v151
	ds_read_b128 v[196:199], v151 offset:1024
	ds_read_b128 v[200:203], v150
	ds_read_b128 v[204:207], v150 offset:1024
	ds_read_b128 v[208:211], v149
	ds_read_b128 v[212:215], v149 offset:1024
	global_load_lds_dwordx4 v[162:163], off
	v_lshl_add_u64 v[162:163], v[238:239], 0, s[14:15]
	s_mov_b32 m0, s43
	s_nop 0
	global_load_lds_dwordx4 v[162:163], off
	s_waitcnt lgkmcnt(8)
	s_barrier
	s_waitcnt lgkmcnt(0)
	s_setprio 0
	s_waitcnt lgkmcnt(0)
	v_mfma_f32_16x16x32_bf16 v[124:127], v[172:175], v[164:167], v[124:127]
	v_mfma_f32_16x16x32_bf16 v[120:123], v[180:183], v[164:167], v[120:123]
	v_mfma_f32_16x16x32_bf16 v[116:119], v[172:175], v[192:195], v[116:119]
	v_mfma_f32_16x16x32_bf16 v[112:115], v[180:183], v[192:195], v[112:115]
	v_mfma_f32_16x16x32_bf16 v[108:111], v[172:175], v[200:203], v[108:111]
	v_mfma_f32_16x16x32_bf16 v[104:107], v[180:183], v[200:203], v[104:107]
	v_mfma_f32_16x16x32_bf16 v[100:103], v[172:175], v[208:211], v[100:103]
	v_mfma_f32_16x16x32_bf16 v[96:99], v[180:183], v[208:211], v[96:99]
	v_mfma_f32_16x16x32_bf16 v[124:127], v[176:179], v[188:191], v[124:127]
	v_mfma_f32_16x16x32_bf16 v[120:123], v[184:187], v[188:191], v[120:123]
	v_mfma_f32_16x16x32_bf16 v[116:119], v[176:179], v[196:199], v[116:119]
	v_mfma_f32_16x16x32_bf16 v[112:115], v[184:187], v[196:199], v[112:115]
	v_mfma_f32_16x16x32_bf16 v[108:111], v[176:179], v[204:207], v[108:111]
	v_mfma_f32_16x16x32_bf16 v[104:107], v[184:187], v[204:207], v[104:107]
	v_mfma_f32_16x16x32_bf16 v[100:103], v[176:179], v[212:215], v[100:103]
	v_mfma_f32_16x16x32_bf16 v[96:99], v[184:187], v[212:215], v[96:99]
	s_setprio 1
	s_barrier
	v_add_u32_e32 v162, s52, v153
	v_lshl_add_u64 v[240:241], v[140:141], 0, s[40:41]
	v_readfirstlane_b32 s43, v162
	v_add_u32_e32 v163, 0x2000, v162
	v_lshl_add_u64 v[232:233], v[240:241], 0, s[16:17]
	s_mov_b32 m0, s43
	v_lshl_add_u64 v[242:243], v[138:139], 0, s[40:41]
	v_readfirstlane_b32 s43, v163
	ds_read_b128 v[216:219], v160
	ds_read_b128 v[220:223], v160 offset:1024
	ds_read_b128 v[224:227], v160 offset:2048
	ds_read_b128 v[228:231], v160 offset:3072
	global_load_lds_dwordx4 v[232:233], off
	v_lshl_add_u64 v[232:233], v[242:243], 0, s[16:17]
	s_mov_b32 m0, s43
	s_nop 0
	global_load_lds_dwordx4 v[232:233], off
	s_barrier
	s_waitcnt lgkmcnt(0)
	s_setprio 0
	s_waitcnt lgkmcnt(0)
	v_mfma_f32_16x16x32_bf16 v[92:95], v[216:219], v[164:167], v[92:95]
	v_mfma_f32_16x16x32_bf16 v[88:91], v[224:227], v[164:167], v[88:91]
	v_mfma_f32_16x16x32_bf16 v[84:87], v[216:219], v[192:195], v[84:87]
	v_mfma_f32_16x16x32_bf16 v[80:83], v[224:227], v[192:195], v[80:83]
	v_mfma_f32_16x16x32_bf16 v[76:79], v[216:219], v[200:203], v[76:79]
	v_mfma_f32_16x16x32_bf16 v[72:75], v[224:227], v[200:203], v[72:75]
	v_mfma_f32_16x16x32_bf16 v[68:71], v[216:219], v[208:211], v[68:71]
	v_mfma_f32_16x16x32_bf16 v[64:67], v[224:227], v[208:211], v[64:67]
	v_mfma_f32_16x16x32_bf16 v[92:95], v[220:223], v[188:191], v[92:95]
	v_mfma_f32_16x16x32_bf16 v[88:91], v[228:231], v[188:191], v[88:91]
	v_mfma_f32_16x16x32_bf16 v[84:87], v[220:223], v[196:199], v[84:87]
	v_mfma_f32_16x16x32_bf16 v[80:83], v[228:231], v[196:199], v[80:83]
	v_mfma_f32_16x16x32_bf16 v[76:79], v[220:223], v[204:207], v[76:79]
	v_mfma_f32_16x16x32_bf16 v[72:75], v[228:231], v[204:207], v[72:75]
	v_mfma_f32_16x16x32_bf16 v[68:71], v[220:223], v[212:215], v[68:71]
	v_mfma_f32_16x16x32_bf16 v[64:67], v[228:231], v[212:215], v[64:67]
	s_setprio 1
	v_readfirstlane_b32 s43, v148
	v_lshl_add_u64 v[164:165], v[236:237], 0, s[18:19]
	s_mov_b32 m0, s43
	s_barrier
	ds_read_b128 v[188:191], v152 offset:16384
	ds_read_b128 v[192:195], v152 offset:17408
	ds_read_b128 v[196:199], v151 offset:16384
	ds_read_b128 v[200:203], v151 offset:17408
	ds_read_b128 v[204:207], v150 offset:16384
	ds_read_b128 v[208:211], v150 offset:17408
	ds_read_b128 v[212:215], v149 offset:16384
	ds_read_b128 v[232:235], v149 offset:17408
	global_load_lds_dwordx4 v[164:165], off
	v_add_u32_e32 v164, 0x2000, v148
	v_lshl_add_u64 v[166:167], v[238:239], 0, s[18:19]
	v_readfirstlane_b32 s43, v164
	s_mov_b32 m0, s43
	s_nop 0
	global_load_lds_dwordx4 v[166:167], off
	s_barrier
	s_waitcnt lgkmcnt(0)
	s_setprio 0
	s_waitcnt lgkmcnt(0)
	v_mfma_f32_16x16x32_bf16 v[60:63], v[172:175], v[188:191], v[60:63]
	v_mfma_f32_16x16x32_bf16 v[56:59], v[180:183], v[188:191], v[56:59]
	v_mfma_f32_16x16x32_bf16 v[52:55], v[172:175], v[196:199], v[52:55]
	v_mfma_f32_16x16x32_bf16 v[48:51], v[180:183], v[196:199], v[48:51]
	v_mfma_f32_16x16x32_bf16 v[44:47], v[172:175], v[204:207], v[44:47]
	v_mfma_f32_16x16x32_bf16 v[40:43], v[180:183], v[204:207], v[40:43]
	v_mfma_f32_16x16x32_bf16 v[36:39], v[172:175], v[212:215], v[36:39]
	v_mfma_f32_16x16x32_bf16 v[32:35], v[180:183], v[212:215], v[32:35]
	v_mfma_f32_16x16x32_bf16 v[60:63], v[176:179], v[192:195], v[60:63]
	v_mfma_f32_16x16x32_bf16 v[56:59], v[184:187], v[192:195], v[56:59]
	v_mfma_f32_16x16x32_bf16 v[52:55], v[176:179], v[200:203], v[52:55]
	v_mfma_f32_16x16x32_bf16 v[48:51], v[184:187], v[200:203], v[48:51]
	v_mfma_f32_16x16x32_bf16 v[44:47], v[176:179], v[208:211], v[44:47]
	v_mfma_f32_16x16x32_bf16 v[40:43], v[184:187], v[208:211], v[40:43]
	v_mfma_f32_16x16x32_bf16 v[36:39], v[176:179], v[232:235], v[36:39]
	v_mfma_f32_16x16x32_bf16 v[32:35], v[184:187], v[232:235], v[32:35]
	s_setprio 1
	s_barrier
; #define STAGE(P, BASE, LD, br, kt) do { const char* _g = (const char*)((BASE) + (size_t)(br) * (LD) + (size_t)(kt) * 64); \
;     for (int _i = 0; _i < 2; ++_i) { int _b = tidx * 16 + _i * 8192; int _r, _c; stage_rc(_b, _r, _c); \
;       __builtin_amdgcn_global_load_lds((const unsigned*)(_g + (unsigned)((_r * (LD) + _c) * 2)), (unsigned*)((char*)(P) + _b), 16, 0, 0); } } while (0)
; #define LDA(dst, b, h) for (int m = 0; m < 4; ++m) for (int k = 0; k < 2; ++k) \
;     dst[m][k] = *reinterpret_cast<const bf16x8*>((char*)SA(b, h) + lds_byte(wr * 64 + m * 16 + fr, k * 32 + fq * 8))
; #define LDB(dst, b, h) for (int n = 0; n < 2; ++n) for (int k = 0; k < 2; ++k) \
;     dst[n][k] = *reinterpret_cast<const bf16x8*>((char*)SB(b, h) + lds_byte(wc * 32 + n * 16 + fr, k * 32 + fq * 8))
; #define MMA(ai, bj, At_, Bt_) do { __builtin_amdgcn_s_setprio(1); \
;     for (int k = 0; k < 2; ++k) for (int m = 0; m < 4; ++m) for (int n = 0; n < 2; ++n) \
;       acc[ai][bj][m][n] = __builtin_amdgcn_mfma_f32_16x16x32_bf16(At_[m][k], Bt_[n][k], acc[ai][bj][m][n], 0, 0, 0); \
;     __builtin_amdgcn_s_setprio(0); } while (0)
; #define WAIT_V(n) asm volatile("s_waitcnt vmcnt(" #n ")" ::: "memory")
; #define WAIT_L(n) asm volatile("s_waitcnt lgkmcnt(" #n ")" ::: "memory")
; #define BAR __builtin_amdgcn_s_barrier()
; #define SCHED __builtin_amdgcn_sched_barrier(0)
; template <int EPI, int lda, int ldb, int N, int K>
; __device__ __forceinline__ void gemm_phase(const u16* __restrict__ A, const u16* __restrict__ Bt, const GemmEpi ep, int wv) {
;     ...
;       STAGE(SB(0, 1), Bt, ldb, bcol + HALF, t + 2);
;       WAIT_V(6); BAR; MMA(1, 1, At, B1); BAR;
;       LDB(B0, 1, 0); SCHED; LDA(At, 1, 0); STAGE(SA(0, 1), Ab, lda, brow + HALF, t + 2);
;       WAIT_L(8); BAR; WAIT_L(0); MMA(0, 0, At, B0); BAR; SCHED;
;       LDB(B1, 1, 1); STAGE(SB(1, 0), Bt, ldb, bcol, t + 3);
;       BAR; WAIT_L(0); MMA(0, 1, At, B1); BAR;
	v_add_u32_e32 v165, s53, v153
	v_lshl_add_u64 v[166:167], v[240:241], 0, s[20:21]
	v_readfirstlane_b32 s43, v165
	s_mov_b32 m0, s43
	v_lshl_add_u64 v[172:173], v[242:243], 0, s[20:21]
	global_load_lds_dwordx4 v[166:167], off
	v_add_u32_e32 v166, 0x2000, v165
	s_nop 0
	v_readfirstlane_b32 s43, v166
	s_mov_b32 m0, s43
	s_nop 0
	global_load_lds_dwordx4 v[172:173], off
	s_waitcnt vmcnt(6)
	s_barrier
	s_setprio 0
	v_mfma_f32_16x16x32_bf16 v[28:31], v[216:219], v[188:191], v[28:31]
	v_mfma_f32_16x16x32_bf16 v[24:27], v[224:227], v[188:191], v[24:27]
	v_mfma_f32_16x16x32_bf16 v[20:23], v[216:219], v[196:199], v[20:23]
	v_mfma_f32_16x16x32_bf16 v[16:19], v[224:227], v[196:199], v[16:19]
	v_mfma_f32_16x16x32_bf16 v[12:15], v[216:219], v[204:207], v[12:15]
	v_mfma_f32_16x16x32_bf16 v[8:11], v[224:227], v[204:207], v[8:11]
	v_mfma_f32_16x16x32_bf16 v[4:7], v[216:219], v[212:215], v[4:7]
	v_mfma_f32_16x16x32_bf16 v[0:3], v[224:227], v[212:215], v[0:3]
	v_mfma_f32_16x16x32_bf16 v[28:31], v[220:223], v[192:195], v[28:31]
	v_mfma_f32_16x16x32_bf16 v[24:27], v[228:231], v[192:195], v[24:27]
	v_mfma_f32_16x16x32_bf16 v[20:23], v[220:223], v[200:203], v[20:23]
	v_mfma_f32_16x16x32_bf16 v[16:19], v[228:231], v[200:203], v[16:19]
	v_mfma_f32_16x16x32_bf16 v[12:15], v[220:223], v[208:211], v[12:15]
	v_mfma_f32_16x16x32_bf16 v[8:11], v[228:231], v[208:211], v[8:11]
	v_mfma_f32_16x16x32_bf16 v[4:7], v[220:223], v[232:235], v[4:7]
	v_mfma_f32_16x16x32_bf16 v[0:3], v[228:231], v[232:235], v[0:3]
	s_setprio 1
	s_barrier
	ds_read_b128 v[172:175], v156
	ds_read_b128 v[176:179], v156 offset:1024
	ds_read_b128 v[180:183], v156 offset:2048
	ds_read_b128 v[184:187], v156 offset:3072
	v_add_u32_e32 v167, 0x4000, v148
	v_add_u32_e32 v168, 0x6000, v148
	v_readfirstlane_b32 s43, v167
	v_lshl_add_u64 v[220:221], v[236:237], 0, s[22:23]
	s_mov_b32 m0, s43
	v_readfirstlane_b32 s43, v168
	ds_read_b128 v[188:191], v152 offset:32768
	ds_read_b128 v[192:195], v152 offset:33792
	ds_read_b128 v[196:199], v151 offset:32768
	ds_read_b128 v[200:203], v151 offset:33792
	ds_read_b128 v[204:207], v150 offset:32768
	ds_read_b128 v[208:211], v150 offset:33792
	ds_read_b128 v[212:215], v149 offset:32768
	ds_read_b128 v[216:219], v149 offset:33792
	global_load_lds_dwordx4 v[220:221], off
	v_lshl_add_u64 v[220:221], v[238:239], 0, s[22:23]
	s_mov_b32 m0, s43
	s_nop 0
	global_load_lds_dwordx4 v[220:221], off
	s_waitcnt lgkmcnt(8)
	s_barrier
	s_waitcnt lgkmcnt(0)
	s_setprio 0
	s_waitcnt lgkmcnt(0)
	v_mfma_f32_16x16x32_bf16 v[124:127], v[172:175], v[188:191], v[124:127]
	v_mfma_f32_16x16x32_bf16 v[120:123], v[180:183], v[188:191], v[120:123]
	v_mfma_f32_16x16x32_bf16 v[116:119], v[172:175], v[196:199], v[116:119]
	v_mfma_f32_16x16x32_bf16 v[112:115], v[180:183], v[196:199], v[112:115]
	v_mfma_f32_16x16x32_bf16 v[108:111], v[172:175], v[204:207], v[108:111]
	v_mfma_f32_16x16x32_bf16 v[104:107], v[180:183], v[204:207], v[104:107]
	v_mfma_f32_16x16x32_bf16 v[100:103], v[172:175], v[212:215], v[100:103]
	v_mfma_f32_16x16x32_bf16 v[96:99], v[180:183], v[212:215], v[96:99]
	v_mfma_f32_16x16x32_bf16 v[124:127], v[176:179], v[192:195], v[124:127]
	v_mfma_f32_16x16x32_bf16 v[120:123], v[184:187], v[192:195], v[120:123]
	v_mfma_f32_16x16x32_bf16 v[116:119], v[176:179], v[200:203], v[116:119]
	v_mfma_f32_16x16x32_bf16 v[112:115], v[184:187], v[200:203], v[112:115]
	v_mfma_f32_16x16x32_bf16 v[108:111], v[176:179], v[208:211], v[108:111]
	v_mfma_f32_16x16x32_bf16 v[104:107], v[184:187], v[208:211], v[104:107]
	v_mfma_f32_16x16x32_bf16 v[100:103], v[176:179], v[216:219], v[100:103]
	v_mfma_f32_16x16x32_bf16 v[96:99], v[184:187], v[216:219], v[96:99]
	s_setprio 1
	s_barrier
	v_readfirstlane_b32 s43, v155
	v_add_u32_e32 v171, 0x2000, v155
	v_lshl_add_u64 v[244:245], v[240:241], 0, s[24:25]
	s_mov_b32 m0, s43
	v_readfirstlane_b32 s43, v171
	ds_read_b128 v[220:223], v154
	ds_read_b128 v[224:227], v154 offset:1024
	ds_read_b128 v[228:231], v154 offset:2048
	ds_read_b128 v[232:235], v154 offset:3072
	global_load_lds_dwordx4 v[244:245], off
	v_lshl_add_u64 v[244:245], v[242:243], 0, s[24:25]
	s_mov_b32 m0, s43
	s_nop 0
	global_load_lds_dwordx4 v[244:245], off
	s_barrier
	s_waitcnt lgkmcnt(0)
	s_setprio 0
	s_waitcnt lgkmcnt(0)
	v_mfma_f32_16x16x32_bf16 v[92:95], v[220:223], v[188:191], v[92:95]
	v_mfma_f32_16x16x32_bf16 v[88:91], v[228:231], v[188:191], v[88:91]
	v_mfma_f32_16x16x32_bf16 v[84:87], v[220:223], v[196:199], v[84:87]
	v_mfma_f32_16x16x32_bf16 v[80:83], v[228:231], v[196:199], v[80:83]
	v_mfma_f32_16x16x32_bf16 v[76:79], v[220:223], v[204:207], v[76:79]
	v_mfma_f32_16x16x32_bf16 v[72:75], v[228:231], v[204:207], v[72:75]
	v_mfma_f32_16x16x32_bf16 v[68:71], v[220:223], v[212:215], v[68:71]
	v_mfma_f32_16x16x32_bf16 v[64:67], v[228:231], v[212:215], v[64:67]
	v_mfma_f32_16x16x32_bf16 v[92:95], v[224:227], v[192:195], v[92:95]
	v_mfma_f32_16x16x32_bf16 v[88:91], v[232:235], v[192:195], v[88:91]
	v_mfma_f32_16x16x32_bf16 v[84:87], v[224:227], v[200:203], v[84:87]
	v_mfma_f32_16x16x32_bf16 v[80:83], v[232:235], v[200:203], v[80:83]
	v_mfma_f32_16x16x32_bf16 v[76:79], v[224:227], v[208:211], v[76:79]
	v_mfma_f32_16x16x32_bf16 v[72:75], v[232:235], v[208:211], v[72:75]
	v_mfma_f32_16x16x32_bf16 v[68:71], v[224:227], v[216:219], v[68:71]
	v_mfma_f32_16x16x32_bf16 v[64:67], v[232:235], v[216:219], v[64:67]
	s_setprio 1
	v_readfirstlane_b32 s43, v157
	v_lshl_add_u64 v[236:237], v[236:237], 0, s[26:27]
	s_mov_b32 m0, s43
	v_readfirstlane_b32 s43, v158
	s_barrier
; #define STAGE(P, BASE, LD, br, kt) do { const char* _g = (const char*)((BASE) + (size_t)(br) * (LD) + (size_t)(kt) * 64); \
;     for (int _i = 0; _i < 2; ++_i) { int _b = tidx * 16 + _i * 8192; int _r, _c; stage_rc(_b, _r, _c); \
;       __builtin_amdgcn_global_load_lds((const unsigned*)(_g + (unsigned)((_r * (LD) + _c) * 2)), (unsigned*)((char*)(P) + _b), 16, 0, 0); } } while (0)
; #define LDA(dst, b, h) for (int m = 0; m < 4; ++m) for (int k = 0; k < 2; ++k) \
;     dst[m][k] = *reinterpret_cast<const bf16x8*>((char*)SA(b, h) + lds_byte(wr * 64 + m * 16 + fr, k * 32 + fq * 8))
; #define LDB(dst, b, h) for (int n = 0; n < 2; ++n) for (int k = 0; k < 2; ++k) \
;     dst[n][k] = *reinterpret_cast<const bf16x8*>((char*)SB(b, h) + lds_byte(wc * 32 + n * 16 + fr, k * 32 + fq * 8))
; #define MMA(ai, bj, At_, Bt_) do { __builtin_amdgcn_s_setprio(1); \
;     for (int k = 0; k < 2; ++k) for (int m = 0; m < 4; ++m) for (int n = 0; n < 2; ++n) \
;       acc[ai][bj][m][n] = __builtin_amdgcn_mfma_f32_16x16x32_bf16(At_[m][k], Bt_[n][k], acc[ai][bj][m][n], 0, 0, 0); \
;     __builtin_amdgcn_s_setprio(0); } while (0)
; #define WAIT_V(n) asm volatile("s_waitcnt vmcnt(" #n ")" ::: "memory")
; #define WAIT_L(n) asm volatile("s_waitcnt lgkmcnt(" #n ")" ::: "memory")
; #define BAR __builtin_amdgcn_s_barrier()
; #define SCHED __builtin_amdgcn_sched_barrier(0)
; template <int EPI, int lda, int ldb, int N, int K>
; __device__ __forceinline__ void gemm_phase(const u16* __restrict__ A, const u16* __restrict__ Bt, const GemmEpi ep, int wv) {
;     ...
;       LDA(At, 1, 1); STAGE(SA(1, 0), Ab, lda, brow, t + 3);
;       BAR; WAIT_L(0); MMA(1, 0, At, B0); BAR; SCHED;
;       STAGE(SB(1, 1), Bt, ldb, bcol + HALF, t + 3);
;       WAIT_V(6); BAR; MMA(1, 1, At, B1); BAR;
;     }
;     { LDB(B0, 0, 0); LDA(At, 0, 0); STAGE(SA(1, 1), Ab, lda, brow + HALF, nt - 1);
;       BAR; WAIT_L(0); MMA(0, 0, At, B0); BAR;
;       LDB(B1, 0, 1); BAR; WAIT_L(0); MMA(0, 1, At, B1); BAR;
	ds_read_b128 v[188:191], v152 offset:49152
	ds_read_b128 v[192:195], v152 offset:50176
	ds_read_b128 v[196:199], v151 offset:49152
	ds_read_b128 v[200:203], v151 offset:50176
	ds_read_b128 v[204:207], v150 offset:49152
	ds_read_b128 v[208:211], v150 offset:50176
	ds_read_b128 v[212:215], v149 offset:49152
	ds_read_b128 v[216:219], v149 offset:50176
	global_load_lds_dwordx4 v[236:237], off
	v_lshl_add_u64 v[236:237], v[238:239], 0, s[26:27]
	s_mov_b32 m0, s43
	s_nop 0
	global_load_lds_dwordx4 v[236:237], off
	s_barrier
	s_waitcnt lgkmcnt(0)
	s_setprio 0
	s_waitcnt lgkmcnt(0)
	v_mfma_f32_16x16x32_bf16 v[60:63], v[172:175], v[188:191], v[60:63]
	v_mfma_f32_16x16x32_bf16 v[56:59], v[180:183], v[188:191], v[56:59]
	v_mfma_f32_16x16x32_bf16 v[52:55], v[172:175], v[196:199], v[52:55]
	v_mfma_f32_16x16x32_bf16 v[48:51], v[180:183], v[196:199], v[48:51]
	v_mfma_f32_16x16x32_bf16 v[44:47], v[172:175], v[204:207], v[44:47]
	v_mfma_f32_16x16x32_bf16 v[40:43], v[180:183], v[204:207], v[40:43]
	v_mfma_f32_16x16x32_bf16 v[36:39], v[172:175], v[212:215], v[36:39]
	v_mfma_f32_16x16x32_bf16 v[32:35], v[180:183], v[212:215], v[32:35]
	v_mfma_f32_16x16x32_bf16 v[60:63], v[176:179], v[192:195], v[60:63]
	v_mfma_f32_16x16x32_bf16 v[56:59], v[184:187], v[192:195], v[56:59]
	v_mfma_f32_16x16x32_bf16 v[52:55], v[176:179], v[200:203], v[52:55]
	v_mfma_f32_16x16x32_bf16 v[48:51], v[184:187], v[200:203], v[48:51]
	v_mfma_f32_16x16x32_bf16 v[44:47], v[176:179], v[208:211], v[44:47]
	v_mfma_f32_16x16x32_bf16 v[40:43], v[184:187], v[208:211], v[40:43]
	v_mfma_f32_16x16x32_bf16 v[36:39], v[176:179], v[216:219], v[36:39]
	v_mfma_f32_16x16x32_bf16 v[32:35], v[184:187], v[216:219], v[32:35]
	s_setprio 1
	s_barrier
	v_readfirstlane_b32 s43, v159
	v_add_u32_e32 v171, 0x2000, v159
	v_lshl_add_u64 v[172:173], v[240:241], 0, s[34:35]
	s_mov_b32 m0, s43
	v_readfirstlane_b32 s43, v171
	global_load_lds_dwordx4 v[172:173], off
	v_lshl_add_u64 v[172:173], v[242:243], 0, s[34:35]
	s_mov_b32 m0, s43
	s_nop 0
	global_load_lds_dwordx4 v[172:173], off
	s_waitcnt vmcnt(6)
	s_barrier
	s_setprio 0
	v_mfma_f32_16x16x32_bf16 v[28:31], v[220:223], v[188:191], v[28:31]
	v_mfma_f32_16x16x32_bf16 v[24:27], v[228:231], v[188:191], v[24:27]
	v_mfma_f32_16x16x32_bf16 v[20:23], v[220:223], v[196:199], v[20:23]
	v_mfma_f32_16x16x32_bf16 v[16:19], v[228:231], v[196:199], v[16:19]
	v_mfma_f32_16x16x32_bf16 v[12:15], v[220:223], v[204:207], v[12:15]
	v_mfma_f32_16x16x32_bf16 v[8:11], v[228:231], v[204:207], v[8:11]
	v_mfma_f32_16x16x32_bf16 v[4:7], v[220:223], v[212:215], v[4:7]
	v_mfma_f32_16x16x32_bf16 v[0:3], v[228:231], v[212:215], v[0:3]
	v_mfma_f32_16x16x32_bf16 v[28:31], v[224:227], v[192:195], v[28:31]
	v_mfma_f32_16x16x32_bf16 v[24:27], v[232:235], v[192:195], v[24:27]
	v_mfma_f32_16x16x32_bf16 v[20:23], v[224:227], v[200:203], v[20:23]
	v_mfma_f32_16x16x32_bf16 v[16:19], v[232:235], v[200:203], v[16:19]
	v_mfma_f32_16x16x32_bf16 v[12:15], v[224:227], v[208:211], v[12:15]
	v_mfma_f32_16x16x32_bf16 v[8:11], v[232:235], v[208:211], v[8:11]
	v_mfma_f32_16x16x32_bf16 v[4:7], v[224:227], v[216:219], v[4:7]
	v_mfma_f32_16x16x32_bf16 v[0:3], v[232:235], v[216:219], v[0:3]
	s_setprio 1
	s_add_i32 s42, s42, 2
	s_add_u32 s40, s40, 0x100
	s_addc_u32 s41, s41, 0
	s_cmp_gt_u32 s42, 27
	s_barrier
	s_cbranch_scc0 .LBB0_1564
	s_add_i32 s40, s38, 0x80
	s_mul_hi_i32 s41, s40, 0x1080
	s_mulk_i32 s40, 0x1080
	s_add_u32 s40, s49, s40
	s_addc_u32 s41, s50, s41
	v_lshl_add_u64 v[158:159], s[40:41], 0, v[128:129]
	v_readfirstlane_b32 s42, v169
	v_lshl_add_u64 v[158:159], v[158:159], 0, s[36:37]
	s_mov_b32 m0, s42
	ds_read_b128 v[134:137], v161
	ds_read_b128 v[138:141], v161 offset:1024
	ds_read_b128 v[172:175], v161 offset:2048
	ds_read_b128 v[176:179], v161 offset:3072
	ds_read_b128 v[180:183], v152
	ds_read_b128 v[184:187], v152 offset:1024
	ds_read_b128 v[188:191], v151
	ds_read_b128 v[192:195], v151 offset:1024
	ds_read_b128 v[196:199], v150
	ds_read_b128 v[200:203], v150 offset:1024
	ds_read_b128 v[204:207], v149
	ds_read_b128 v[208:211], v149 offset:1024
	global_load_lds_dwordx4 v[158:159], off
	v_lshl_add_u64 v[158:159], s[40:41], 0, v[132:133]
	v_readfirstlane_b32 s40, v170
	v_lshl_add_u64 v[158:159], v[158:159], 0, s[36:37]
	s_mov_b32 m0, s40
	s_nop 0
	global_load_lds_dwordx4 v[158:159], off
	s_barrier
	s_waitcnt lgkmcnt(0)
	s_setprio 0
	s_waitcnt lgkmcnt(0)
	v_mfma_f32_16x16x32_bf16 v[124:127], v[134:137], v[180:183], v[124:127]
	v_mfma_f32_16x16x32_bf16 v[120:123], v[172:175], v[180:183], v[120:123]
	v_mfma_f32_16x16x32_bf16 v[116:119], v[134:137], v[188:191], v[116:119]
	v_mfma_f32_16x16x32_bf16 v[112:115], v[172:175], v[188:191], v[112:115]
	v_mfma_f32_16x16x32_bf16 v[108:111], v[134:137], v[196:199], v[108:111]
	v_mfma_f32_16x16x32_bf16 v[104:107], v[172:175], v[196:199], v[104:107]
	v_mfma_f32_16x16x32_bf16 v[100:103], v[134:137], v[204:207], v[100:103]
	v_mfma_f32_16x16x32_bf16 v[96:99], v[172:175], v[204:207], v[96:99]
	v_mfma_f32_16x16x32_bf16 v[124:127], v[138:141], v[184:187], v[124:127]
	v_mfma_f32_16x16x32_bf16 v[120:123], v[176:179], v[184:187], v[120:123]
	v_mfma_f32_16x16x32_bf16 v[116:119], v[138:141], v[192:195], v[116:119]
	v_mfma_f32_16x16x32_bf16 v[112:115], v[176:179], v[192:195], v[112:115]
	v_mfma_f32_16x16x32_bf16 v[108:111], v[138:141], v[200:203], v[108:111]
	v_mfma_f32_16x16x32_bf16 v[104:107], v[176:179], v[200:203], v[104:107]
	v_mfma_f32_16x16x32_bf16 v[100:103], v[138:141], v[208:211], v[100:103]
	v_mfma_f32_16x16x32_bf16 v[96:99], v[176:179], v[208:211], v[96:99]
	s_setprio 1
	s_barrier
	ds_read_b128 v[212:215], v160
	ds_read_b128 v[216:219], v160 offset:1024
	ds_read_b128 v[220:223], v160 offset:2048
	ds_read_b128 v[158:161], v160 offset:3072
	s_barrier
; #define LDA(dst, b, h) for (int m = 0; m < 4; ++m) for (int k = 0; k < 2; ++k) \
;     dst[m][k] = *reinterpret_cast<const bf16x8*>((char*)SA(b, h) + lds_byte(wr * 64 + m * 16 + fr, k * 32 + fq * 8))
; #define LDB(dst, b, h) for (int n = 0; n < 2; ++n) for (int k = 0; k < 2; ++k) \
;     dst[n][k] = *reinterpret_cast<const bf16x8*>((char*)SB(b, h) + lds_byte(wc * 32 + n * 16 + fr, k * 32 + fq * 8))
; #define MMA(ai, bj, At_, Bt_) do { __builtin_amdgcn_s_setprio(1); \
;     for (int k = 0; k < 2; ++k) for (int m = 0; m < 4; ++m) for (int n = 0; n < 2; ++n) \
;       acc[ai][bj][m][n] = __builtin_amdgcn_mfma_f32_16x16x32_bf16(At_[m][k], Bt_[n][k], acc[ai][bj][m][n], 0, 0, 0); \
;     __builtin_amdgcn_s_setprio(0); } while (0)
; #define WAIT_V(n) asm volatile("s_waitcnt vmcnt(" #n ")" ::: "memory")
; #define WAIT_L(n) asm volatile("s_waitcnt lgkmcnt(" #n ")" ::: "memory")
; #define BAR __builtin_amdgcn_s_barrier()
; template <int EPI, int lda, int ldb, int N, int K>
; __device__ __forceinline__ void gemm_phase(const u16* __restrict__ A, const u16* __restrict__ Bt, const GemmEpi ep, int wv) {
;     ...
;       LDB(B1, 0, 1); BAR; WAIT_L(0); MMA(0, 1, At, B1); BAR;
;       LDA(At, 0, 1); WAIT_V(4); BAR; WAIT_L(0); MMA(1, 0, At, B0); MMA(1, 1, At, B1); BAR; }
;     { LDB(B0, 1, 0); LDA(At, 1, 0); WAIT_V(2); BAR; WAIT_L(0); MMA(0, 0, At, B0); BAR;
	s_waitcnt lgkmcnt(0)
	s_setprio 0
	s_waitcnt lgkmcnt(0)
	v_mfma_f32_16x16x32_bf16 v[92:95], v[212:215], v[180:183], v[92:95]
	v_mfma_f32_16x16x32_bf16 v[88:91], v[220:223], v[180:183], v[88:91]
	v_mfma_f32_16x16x32_bf16 v[76:79], v[212:215], v[196:199], v[76:79]
	v_mfma_f32_16x16x32_bf16 v[72:75], v[220:223], v[196:199], v[72:75]
	v_mfma_f32_16x16x32_bf16 v[84:87], v[212:215], v[188:191], v[84:87]
	v_mfma_f32_16x16x32_bf16 v[80:83], v[220:223], v[188:191], v[80:83]
	v_mfma_f32_16x16x32_bf16 v[68:71], v[212:215], v[204:207], v[68:71]
	v_mfma_f32_16x16x32_bf16 v[64:67], v[220:223], v[204:207], v[64:67]
	v_mfma_f32_16x16x32_bf16 v[92:95], v[216:219], v[184:187], v[92:95]
	v_mfma_f32_16x16x32_bf16 v[88:91], v[158:161], v[184:187], v[88:91]
	v_mfma_f32_16x16x32_bf16 v[76:79], v[216:219], v[200:203], v[76:79]
	v_mfma_f32_16x16x32_bf16 v[72:75], v[158:161], v[200:203], v[72:75]
	v_mfma_f32_16x16x32_bf16 v[180:183], v[216:219], v[192:195], v[84:87]
	v_mfma_f32_16x16x32_bf16 v[184:187], v[158:161], v[192:195], v[80:83]
	v_mfma_f32_16x16x32_bf16 v[188:191], v[216:219], v[208:211], v[68:71]
	v_mfma_f32_16x16x32_bf16 v[192:195], v[158:161], v[208:211], v[64:67]
	s_setprio 1
	s_barrier
	s_nop 0
	ds_read_b128 v[64:67], v152 offset:16384
	ds_read_b128 v[68:71], v152 offset:17408
	ds_read_b128 v[80:83], v151 offset:16384
	ds_read_b128 v[84:87], v151 offset:17408
	ds_read_b128 v[196:199], v150 offset:16384
	ds_read_b128 v[200:203], v150 offset:17408
	ds_read_b128 v[204:207], v149 offset:16384
	ds_read_b128 v[208:211], v149 offset:17408
	s_waitcnt vmcnt(4)
	s_barrier
	s_waitcnt lgkmcnt(0)
	s_setprio 0
	s_waitcnt lgkmcnt(0)
	v_mfma_f32_16x16x32_bf16 v[60:63], v[134:137], v[64:67], v[60:63]
	v_mfma_f32_16x16x32_bf16 v[56:59], v[172:175], v[64:67], v[56:59]
	v_mfma_f32_16x16x32_bf16 v[52:55], v[134:137], v[80:83], v[52:55]
	v_mfma_f32_16x16x32_bf16 v[48:51], v[172:175], v[80:83], v[48:51]
	v_mfma_f32_16x16x32_bf16 v[44:47], v[134:137], v[196:199], v[44:47]
	v_mfma_f32_16x16x32_bf16 v[40:43], v[172:175], v[196:199], v[40:43]
	v_mfma_f32_16x16x32_bf16 v[36:39], v[134:137], v[204:207], v[36:39]
	v_mfma_f32_16x16x32_bf16 v[32:35], v[172:175], v[204:207], v[32:35]
	v_mfma_f32_16x16x32_bf16 v[60:63], v[138:141], v[68:71], v[60:63]
	v_mfma_f32_16x16x32_bf16 v[56:59], v[176:179], v[68:71], v[56:59]
	v_mfma_f32_16x16x32_bf16 v[52:55], v[138:141], v[84:87], v[52:55]
	v_mfma_f32_16x16x32_bf16 v[48:51], v[176:179], v[84:87], v[48:51]
	v_mfma_f32_16x16x32_bf16 v[44:47], v[138:141], v[200:203], v[44:47]
	v_mfma_f32_16x16x32_bf16 v[40:43], v[176:179], v[200:203], v[40:43]
	v_mfma_f32_16x16x32_bf16 v[36:39], v[138:141], v[208:211], v[36:39]
	v_mfma_f32_16x16x32_bf16 v[32:35], v[176:179], v[208:211], v[32:35]
	s_setprio 1
	s_setprio 0
	v_mfma_f32_16x16x32_bf16 v[28:31], v[212:215], v[64:67], v[28:31]
	v_mfma_f32_16x16x32_bf16 v[24:27], v[220:223], v[64:67], v[24:27]
	v_mfma_f32_16x16x32_bf16 v[12:15], v[212:215], v[196:199], v[12:15]
	v_mfma_f32_16x16x32_bf16 v[8:11], v[220:223], v[196:199], v[8:11]
	v_mfma_f32_16x16x32_bf16 v[20:23], v[212:215], v[80:83], v[20:23]
	v_mfma_f32_16x16x32_bf16 v[16:19], v[220:223], v[80:83], v[16:19]
	v_mfma_f32_16x16x32_bf16 v[4:7], v[212:215], v[204:207], v[4:7]
	v_mfma_f32_16x16x32_bf16 v[0:3], v[220:223], v[204:207], v[0:3]
	v_mfma_f32_16x16x32_bf16 v[28:31], v[216:219], v[68:71], v[28:31]
	v_mfma_f32_16x16x32_bf16 v[24:27], v[158:161], v[68:71], v[24:27]
	v_mfma_f32_16x16x32_bf16 v[12:15], v[216:219], v[200:203], v[12:15]
	v_mfma_f32_16x16x32_bf16 v[8:11], v[158:161], v[200:203], v[8:11]
	v_mfma_f32_16x16x32_bf16 v[134:137], v[216:219], v[84:87], v[20:23]
	v_mfma_f32_16x16x32_bf16 v[138:141], v[158:161], v[84:87], v[16:19]
	v_mfma_f32_16x16x32_bf16 v[170:173], v[216:219], v[208:211], v[4:7]
	v_mfma_f32_16x16x32_bf16 v[158:161], v[158:161], v[208:211], v[0:3]
	s_setprio 1
	s_barrier
	s_nop 0
	ds_read_b128 v[0:3], v156
	ds_read_b128 v[4:7], v156 offset:1024
	ds_read_b128 v[16:19], v156 offset:2048
	ds_read_b128 v[174:177], v156 offset:3072
	ds_read_b128 v[20:23], v152 offset:32768
	ds_read_b128 v[196:199], v152 offset:33792
	ds_read_b128 v[200:203], v151 offset:32768
	ds_read_b128 v[204:207], v151 offset:33792
	ds_read_b128 v[208:211], v150 offset:32768
	ds_read_b128 v[212:215], v150 offset:33792
	ds_read_b128 v[216:219], v149 offset:32768
	ds_read_b128 v[220:223], v149 offset:33792
	s_waitcnt vmcnt(2)
	s_barrier
; #define UNR _Pragma("unroll")
; #define LDA(dst, b, h) for (int m = 0; m < 4; ++m) for (int k = 0; k < 2; ++k) \
;     dst[m][k] = *reinterpret_cast<const bf16x8*>((char*)SA(b, h) + lds_byte(wr * 64 + m * 16 + fr, k * 32 + fq * 8))
; #define LDB(dst, b, h) for (int n = 0; n < 2; ++n) for (int k = 0; k < 2; ++k) \
;     dst[n][k] = *reinterpret_cast<const bf16x8*>((char*)SB(b, h) + lds_byte(wc * 32 + n * 16 + fr, k * 32 + fq * 8))
; #define MMA(ai, bj, At_, Bt_) do { __builtin_amdgcn_s_setprio(1); \
;     for (int k = 0; k < 2; ++k) for (int m = 0; m < 4; ++m) for (int n = 0; n < 2; ++n) \
;       acc[ai][bj][m][n] = __builtin_amdgcn_mfma_f32_16x16x32_bf16(At_[m][k], Bt_[n][k], acc[ai][bj][m][n], 0, 0, 0); \
;     __builtin_amdgcn_s_setprio(0); } while (0)
; #define WAIT_V(n) asm volatile("s_waitcnt vmcnt(" #n ")" ::: "memory")
; #define WAIT_L(n) asm volatile("s_waitcnt lgkmcnt(" #n ")" ::: "memory")
; #define BAR __builtin_amdgcn_s_barrier()
; #define STAGE4(BROW, BCOL, PN) do { const u16* Ab_ = A + (EPI == EPI_RG ? ((PN) >> 1) * 256 : 0); \
;     STAGE(SB(0, 0), Bt, ldb, (BCOL), 0); STAGE(SA(0, 0), Ab_, lda, (BROW), 0); \
;     STAGE(SB(0, 1), Bt, ldb, (BCOL) + HALF, 0); STAGE(SA(0, 1), Ab_, lda, (BROW) + HALF, 0); } while (0)
; template <int EPI, int lda, int ldb, int N, int K>
; __device__ __forceinline__ void gemm_phase(const u16* __restrict__ A, const u16* __restrict__ Bt, const GemmEpi ep, int wv) {
;     ...
;     { LDB(B0, 1, 0); LDA(At, 1, 0); WAIT_V(2); BAR; WAIT_L(0); MMA(0, 0, At, B0); BAR;
;       LDB(B1, 1, 1); WAIT_V(0); BAR; WAIT_L(0); MMA(0, 1, At, B1); BAR;
;       LDA(At, 1, 1); BAR; WAIT_L(0); MMA(1, 0, At, B0); MMA(1, 1, At, B1); BAR; }
;     if (wr == 0) BAR;
;     int ntile = 0, nbrow = 0, nbcol = 0, npn = 0; bool more = false;
;     if constexpr (PF) { ntile = tile + gridDim.x; more = ntile < nwg; if (more) { TILE_COORDS(ntile, nbrow, nbcol, npn); STAGE4(nbrow, nbcol, npn); } }
;     float nss[8];
;     if constexpr (CONS) { UNR for (int pp = 0; pp < 8; ++pp) nss[pp] = 0.f;
;       if (more && tidx < 256) { UNR for (int pp = 0; pp < 8; ++pp) nss[pp] = ep.ss_in[(size_t)pp * T + nbrow + tidx]; } }
	s_waitcnt lgkmcnt(0)
	s_setprio 0
	s_waitcnt lgkmcnt(0)
	v_mfma_f32_16x16x32_bf16 v[64:67], v[0:3], v[20:23], v[124:127]
	v_mfma_f32_16x16x32_bf16 v[68:71], v[16:19], v[20:23], v[120:123]
	v_mfma_f32_16x16x32_bf16 v[80:83], v[0:3], v[200:203], v[116:119]
	v_mfma_f32_16x16x32_bf16 v[84:87], v[16:19], v[200:203], v[112:115]
	v_mfma_f32_16x16x32_bf16 v[108:111], v[0:3], v[208:211], v[108:111]
	v_mfma_f32_16x16x32_bf16 v[104:107], v[16:19], v[208:211], v[104:107]
	v_mfma_f32_16x16x32_bf16 v[120:123], v[0:3], v[216:219], v[100:103]
	v_mfma_f32_16x16x32_bf16 v[124:127], v[16:19], v[216:219], v[96:99]
	v_mfma_f32_16x16x32_bf16 v[116:119], v[4:7], v[196:199], v[64:67]
	v_mfma_f32_16x16x32_bf16 v[112:115], v[174:177], v[196:199], v[68:71]
	v_mfma_f32_16x16x32_bf16 v[100:103], v[4:7], v[204:207], v[80:83]
	v_mfma_f32_16x16x32_bf16 v[96:99], v[174:177], v[204:207], v[84:87]
	v_mfma_f32_16x16x32_bf16 v[84:87], v[4:7], v[212:215], v[108:111]
	v_mfma_f32_16x16x32_bf16 v[80:83], v[174:177], v[212:215], v[104:107]
	v_mfma_f32_16x16x32_bf16 v[68:71], v[4:7], v[220:223], v[120:123]
	v_mfma_f32_16x16x32_bf16 v[64:67], v[174:177], v[220:223], v[124:127]
	s_setprio 1
	s_barrier
	ds_read_b128 v[224:227], v154
	ds_read_b128 v[228:231], v154 offset:1024
	ds_read_b128 v[232:235], v154 offset:2048
	ds_read_b128 v[154:157], v154 offset:3072
	s_waitcnt vmcnt(0)
	s_barrier
	s_waitcnt lgkmcnt(0)
	s_setprio 0
	s_waitcnt lgkmcnt(0)
	v_mfma_f32_16x16x32_bf16 v[92:95], v[224:227], v[20:23], v[92:95]
	v_mfma_f32_16x16x32_bf16 v[20:23], v[232:235], v[20:23], v[88:91]
	v_mfma_f32_16x16x32_bf16 v[88:91], v[224:227], v[200:203], v[180:183]
	v_mfma_f32_16x16x32_bf16 v[104:107], v[232:235], v[200:203], v[184:187]
	v_mfma_f32_16x16x32_bf16 v[76:79], v[224:227], v[208:211], v[76:79]
	v_mfma_f32_16x16x32_bf16 v[72:75], v[232:235], v[208:211], v[72:75]
	v_mfma_f32_16x16x32_bf16 v[178:181], v[224:227], v[216:219], v[188:191]
	v_mfma_f32_16x16x32_bf16 v[182:185], v[232:235], v[216:219], v[192:195]
	v_mfma_f32_16x16x32_bf16 v[124:127], v[228:231], v[196:199], v[92:95]
	v_mfma_f32_16x16x32_bf16 v[120:123], v[154:157], v[196:199], v[20:23]
	v_mfma_f32_16x16x32_bf16 v[108:111], v[228:231], v[204:207], v[88:91]
	v_mfma_f32_16x16x32_bf16 v[104:107], v[154:157], v[204:207], v[104:107]
	v_mfma_f32_16x16x32_bf16 v[92:95], v[228:231], v[212:215], v[76:79]
	v_mfma_f32_16x16x32_bf16 v[88:91], v[154:157], v[212:215], v[72:75]
	v_mfma_f32_16x16x32_bf16 v[76:79], v[228:231], v[220:223], v[178:181]
	v_mfma_f32_16x16x32_bf16 v[72:75], v[154:157], v[220:223], v[182:185]
	s_setprio 1
	s_barrier
	ds_read_b128 v[178:181], v152 offset:49152
	ds_read_b128 v[182:185], v152 offset:50176
	ds_read_b128 v[186:189], v151 offset:49152
	ds_read_b128 v[190:193], v151 offset:50176
	ds_read_b128 v[194:197], v150 offset:49152
	ds_read_b128 v[150:153], v150 offset:50176
	ds_read_b128 v[198:201], v149 offset:49152
	ds_read_b128 v[202:205], v149 offset:50176
	s_barrier
	s_waitcnt lgkmcnt(0)
	s_setprio 0
	s_waitcnt lgkmcnt(0)
	v_mfma_f32_16x16x32_bf16 v[20:23], v[0:3], v[178:181], v[60:63]
	v_mfma_f32_16x16x32_bf16 v[56:59], v[16:19], v[178:181], v[56:59]
	v_mfma_f32_16x16x32_bf16 v[60:63], v[0:3], v[186:189], v[52:55]
	v_mfma_f32_16x16x32_bf16 v[206:209], v[16:19], v[186:189], v[48:51]
	v_mfma_f32_16x16x32_bf16 v[44:47], v[0:3], v[194:197], v[44:47]
	v_mfma_f32_16x16x32_bf16 v[40:43], v[16:19], v[194:197], v[40:43]
	v_mfma_f32_16x16x32_bf16 v[0:3], v[0:3], v[198:201], v[36:39]
	v_mfma_f32_16x16x32_bf16 v[210:213], v[16:19], v[198:201], v[32:35]
	v_mfma_f32_16x16x32_bf16 v[52:55], v[4:7], v[182:185], v[20:23]
	v_mfma_f32_16x16x32_bf16 v[48:51], v[174:177], v[182:185], v[56:59]
	v_mfma_f32_16x16x32_bf16 v[36:39], v[4:7], v[190:193], v[60:63]
	v_mfma_f32_16x16x32_bf16 v[32:35], v[174:177], v[190:193], v[206:209]
	v_mfma_f32_16x16x32_bf16 v[20:23], v[4:7], v[150:153], v[44:47]
	v_mfma_f32_16x16x32_bf16 v[16:19], v[174:177], v[150:153], v[40:43]
	v_mfma_f32_16x16x32_bf16 v[4:7], v[4:7], v[202:205], v[0:3]
	v_mfma_f32_16x16x32_bf16 v[0:3], v[174:177], v[202:205], v[210:213]
	s_setprio 1
	s_setprio 0
	v_mfma_f32_16x16x32_bf16 v[28:31], v[224:227], v[178:181], v[28:31]
	v_mfma_f32_16x16x32_bf16 v[24:27], v[232:235], v[178:181], v[24:27]
	v_mfma_f32_16x16x32_bf16 v[40:43], v[224:227], v[186:189], v[134:137]
	v_mfma_f32_16x16x32_bf16 v[134:137], v[232:235], v[186:189], v[138:141]
	v_mfma_f32_16x16x32_bf16 v[12:15], v[224:227], v[194:197], v[12:15]
	v_mfma_f32_16x16x32_bf16 v[8:11], v[232:235], v[194:197], v[8:11]
	v_mfma_f32_16x16x32_bf16 v[138:141], v[224:227], v[198:201], v[170:173]
	v_mfma_f32_16x16x32_bf16 v[158:161], v[232:235], v[198:201], v[158:161]
	v_mfma_f32_16x16x32_bf16 v[60:63], v[228:231], v[182:185], v[28:31]
	v_mfma_f32_16x16x32_bf16 v[56:59], v[154:157], v[182:185], v[24:27]
	v_mfma_f32_16x16x32_bf16 v[44:47], v[228:231], v[190:193], v[40:43]
	v_mfma_f32_16x16x32_bf16 v[40:43], v[154:157], v[190:193], v[134:137]
	v_mfma_f32_16x16x32_bf16 v[28:31], v[228:231], v[150:153], v[12:15]
	v_mfma_f32_16x16x32_bf16 v[24:27], v[154:157], v[150:153], v[8:11]
	v_mfma_f32_16x16x32_bf16 v[12:15], v[228:231], v[202:205], v[138:141]
	v_mfma_f32_16x16x32_bf16 v[8:11], v[154:157], v[202:205], v[158:161]
	s_setprio 1
	v_cmp_gt_u32_e32 vcc, s54, v130
	s_barrier
	s_and_saveexec_b64 s[40:41], vcc
	s_cbranch_execz .LBB0_1567
	s_barrier

; #define STAGE(P, BASE, LD, br, kt) do { const char* _g = (const char*)((BASE) + (size_t)(br) * (LD) + (size_t)(kt) * 64); \
;     for (int _i = 0; _i < 2; ++_i) { int _b = tidx * 16 + _i * 8192; int _r, _c; stage_rc(_b, _r, _c); \
;       __builtin_amdgcn_global_load_lds((const unsigned*)(_g + (unsigned)((_r * (LD) + _c) * 2)), (unsigned*)((char*)(P) + _b), 16, 0, 0); } } while (0)
; #define LDA(dst, b, h) for (int m = 0; m < 4; ++m) for (int k = 0; k < 2; ++k) \
;     dst[m][k] = *reinterpret_cast<const bf16x8*>((char*)SA(b, h) + lds_byte(wr * 64 + m * 16 + fr, k * 32 + fq * 8))
; #define LDB(dst, b, h) for (int n = 0; n < 2; ++n) for (int k = 0; k < 2; ++k) \
;     dst[n][k] = *reinterpret_cast<const bf16x8*>((char*)SB(b, h) + lds_byte(wc * 32 + n * 16 + fr, k * 32 + fq * 8))
; #define MMA(ai, bj, At_, Bt_) do { __builtin_amdgcn_s_setprio(1); \
;     for (int k = 0; k < 2; ++k) for (int m = 0; m < 4; ++m) for (int n = 0; n < 2; ++n) \
;       acc[ai][bj][m][n] = __builtin_amdgcn_mfma_f32_16x16x32_bf16(At_[m][k], Bt_[n][k], acc[ai][bj][m][n], 0, 0, 0); \
;     __builtin_amdgcn_s_setprio(0); } while (0)
; #define WAIT_L(n) asm volatile("s_waitcnt lgkmcnt(" #n ")" ::: "memory")
; #define BAR __builtin_amdgcn_s_barrier()
; #define SCHED __builtin_amdgcn_sched_barrier(0)
; template <int EPI, int lda, int ldb, int N, int K>
; __device__ __forceinline__ void gemm_phase(const u16* __restrict__ A, const u16* __restrict__ Bt, const GemmEpi ep, int wv) {
;     ...
;       LDB(B0, 0, 0); SCHED; LDA(At, 0, 0); STAGE(SA(1, 1), Ab, lda, brow + HALF, t + 1);
;       WAIT_L(8); BAR; WAIT_L(0); MMA(0, 0, At, B0); BAR; SCHED;
;       LDB(B1, 0, 1); STAGE(SB(0, 0), Bt, ldb, bcol, t + 2);
;       BAR; WAIT_L(0); MMA(0, 1, At, B1); BAR;
;       LDA(At, 0, 1); STAGE(SA(0, 0), Ab, lda, brow, t + 2);
;       BAR; WAIT_L(0); MMA(1, 0, At, B0); BAR; SCHED;
.LBB0_1624:
	ds_read_b128 v[174:177], v163
	ds_read_b128 v[178:181], v163 offset:1024
	ds_read_b128 v[182:185], v163 offset:2048
	ds_read_b128 v[186:189], v163 offset:3072
	v_add_u32_e32 v171, 0xc000, v149
	v_lshl_add_u64 v[238:239], v[134:135], 0, s[28:29]
	v_readfirstlane_b32 s50, v171
	v_add_u32_e32 v172, 0xe000, v149
	v_lshl_add_u64 v[164:165], v[238:239], 0, s[10:11]
	s_mov_b32 m0, s50
	v_lshl_add_u64 v[240:241], v[132:133], 0, s[28:29]
	v_readfirstlane_b32 s50, v172
	ds_read_b128 v[166:169], v154
	ds_read_b128 v[190:193], v154 offset:1024
	ds_read_b128 v[194:197], v153
	ds_read_b128 v[198:201], v153 offset:1024
	ds_read_b128 v[202:205], v151
	ds_read_b128 v[206:209], v151 offset:1024
	ds_read_b128 v[210:213], v150
	ds_read_b128 v[214:217], v150 offset:1024
	global_load_lds_dwordx4 v[164:165], off
	v_lshl_add_u64 v[164:165], v[240:241], 0, s[10:11]
	s_mov_b32 m0, s50
	s_nop 0
	global_load_lds_dwordx4 v[164:165], off
	s_waitcnt lgkmcnt(8)
	s_barrier
	s_waitcnt lgkmcnt(0)
	s_setprio 0
	s_waitcnt lgkmcnt(0)
	v_mfma_f32_16x16x32_bf16 v[124:127], v[166:169], v[174:177], v[124:127]
	v_mfma_f32_16x16x32_bf16 v[120:123], v[166:169], v[182:185], v[120:123]
	v_mfma_f32_16x16x32_bf16 v[116:119], v[194:197], v[174:177], v[116:119]
	v_mfma_f32_16x16x32_bf16 v[112:115], v[194:197], v[182:185], v[112:115]
	v_mfma_f32_16x16x32_bf16 v[108:111], v[202:205], v[174:177], v[108:111]
	v_mfma_f32_16x16x32_bf16 v[104:107], v[202:205], v[182:185], v[104:107]
	v_mfma_f32_16x16x32_bf16 v[100:103], v[210:213], v[174:177], v[100:103]
	v_mfma_f32_16x16x32_bf16 v[96:99], v[210:213], v[182:185], v[96:99]
	v_mfma_f32_16x16x32_bf16 v[124:127], v[190:193], v[178:181], v[124:127]
	v_mfma_f32_16x16x32_bf16 v[120:123], v[190:193], v[186:189], v[120:123]
	v_mfma_f32_16x16x32_bf16 v[116:119], v[198:201], v[178:181], v[116:119]
	v_mfma_f32_16x16x32_bf16 v[112:115], v[198:201], v[186:189], v[112:115]
	v_mfma_f32_16x16x32_bf16 v[108:111], v[206:209], v[178:181], v[108:111]
	v_mfma_f32_16x16x32_bf16 v[104:107], v[206:209], v[186:189], v[104:107]
	v_mfma_f32_16x16x32_bf16 v[100:103], v[214:217], v[178:181], v[100:103]
	v_mfma_f32_16x16x32_bf16 v[96:99], v[214:217], v[186:189], v[96:99]
	s_setprio 1
	s_barrier
	v_add_u32_e32 v164, s40, v155
	v_lshl_add_u64 v[242:243], v[142:143], 0, s[28:29]
	v_readfirstlane_b32 s50, v164
	v_add_u32_e32 v165, 0x2000, v164
	v_lshl_add_u64 v[234:235], v[242:243], 0, s[12:13]
	s_mov_b32 m0, s50
	v_lshl_add_u64 v[244:245], v[140:141], 0, s[28:29]
	v_readfirstlane_b32 s50, v165
	ds_read_b128 v[218:221], v162
	ds_read_b128 v[222:225], v162 offset:1024
	ds_read_b128 v[226:229], v162 offset:2048
	ds_read_b128 v[230:233], v162 offset:3072
	global_load_lds_dwordx4 v[234:235], off
	v_lshl_add_u64 v[234:235], v[244:245], 0, s[12:13]
	s_mov_b32 m0, s50
	s_nop 0
	global_load_lds_dwordx4 v[234:235], off
	s_barrier
	s_waitcnt lgkmcnt(0)
	s_setprio 0
	s_waitcnt lgkmcnt(0)
	v_mfma_f32_16x16x32_bf16 v[92:95], v[166:169], v[218:221], v[92:95]
	v_mfma_f32_16x16x32_bf16 v[88:91], v[166:169], v[226:229], v[88:91]
	v_mfma_f32_16x16x32_bf16 v[84:87], v[194:197], v[218:221], v[84:87]
	v_mfma_f32_16x16x32_bf16 v[80:83], v[194:197], v[226:229], v[80:83]
	v_mfma_f32_16x16x32_bf16 v[76:79], v[202:205], v[218:221], v[76:79]
	v_mfma_f32_16x16x32_bf16 v[72:75], v[202:205], v[226:229], v[72:75]
	v_mfma_f32_16x16x32_bf16 v[68:71], v[210:213], v[218:221], v[68:71]
	v_mfma_f32_16x16x32_bf16 v[64:67], v[210:213], v[226:229], v[64:67]
	v_mfma_f32_16x16x32_bf16 v[92:95], v[190:193], v[222:225], v[92:95]
	v_mfma_f32_16x16x32_bf16 v[88:91], v[190:193], v[230:233], v[88:91]
	v_mfma_f32_16x16x32_bf16 v[84:87], v[198:201], v[222:225], v[84:87]
	v_mfma_f32_16x16x32_bf16 v[80:83], v[198:201], v[230:233], v[80:83]
	v_mfma_f32_16x16x32_bf16 v[76:79], v[206:209], v[222:225], v[76:79]
	v_mfma_f32_16x16x32_bf16 v[72:75], v[206:209], v[230:233], v[72:75]
	v_mfma_f32_16x16x32_bf16 v[68:71], v[214:217], v[222:225], v[68:71]
	v_mfma_f32_16x16x32_bf16 v[64:67], v[214:217], v[230:233], v[64:67]
	s_setprio 1
	v_readfirstlane_b32 s50, v149
	v_lshl_add_u64 v[166:167], v[238:239], 0, s[14:15]
	s_mov_b32 m0, s50
	s_barrier
	ds_read_b128 v[190:193], v154 offset:16384
	ds_read_b128 v[194:197], v154 offset:17408
	ds_read_b128 v[198:201], v153 offset:16384
	ds_read_b128 v[202:205], v153 offset:17408
	ds_read_b128 v[206:209], v151 offset:16384
	ds_read_b128 v[210:213], v151 offset:17408
	ds_read_b128 v[214:217], v150 offset:16384
	ds_read_b128 v[234:237], v150 offset:17408
	global_load_lds_dwordx4 v[166:167], off
	v_add_u32_e32 v166, 0x2000, v149
	v_lshl_add_u64 v[168:169], v[240:241], 0, s[14:15]
	v_readfirstlane_b32 s50, v166
	s_mov_b32 m0, s50
	s_nop 0
	global_load_lds_dwordx4 v[168:169], off
	s_barrier
	s_waitcnt lgkmcnt(0)
	s_setprio 0
	s_waitcnt lgkmcnt(0)
	v_mfma_f32_16x16x32_bf16 v[60:63], v[190:193], v[174:177], v[60:63]
	v_mfma_f32_16x16x32_bf16 v[56:59], v[190:193], v[182:185], v[56:59]
	v_mfma_f32_16x16x32_bf16 v[52:55], v[198:201], v[174:177], v[52:55]
	v_mfma_f32_16x16x32_bf16 v[48:51], v[198:201], v[182:185], v[48:51]
	v_mfma_f32_16x16x32_bf16 v[44:47], v[206:209], v[174:177], v[44:47]
	v_mfma_f32_16x16x32_bf16 v[40:43], v[206:209], v[182:185], v[40:43]
	v_mfma_f32_16x16x32_bf16 v[36:39], v[214:217], v[174:177], v[36:39]
	v_mfma_f32_16x16x32_bf16 v[32:35], v[214:217], v[182:185], v[32:35]
	v_mfma_f32_16x16x32_bf16 v[60:63], v[194:197], v[178:181], v[60:63]
	v_mfma_f32_16x16x32_bf16 v[56:59], v[194:197], v[186:189], v[56:59]
	v_mfma_f32_16x16x32_bf16 v[52:55], v[202:205], v[178:181], v[52:55]
	v_mfma_f32_16x16x32_bf16 v[48:51], v[202:205], v[186:189], v[48:51]
	v_mfma_f32_16x16x32_bf16 v[44:47], v[210:213], v[178:181], v[44:47]
	v_mfma_f32_16x16x32_bf16 v[40:43], v[210:213], v[186:189], v[40:43]
	v_mfma_f32_16x16x32_bf16 v[36:39], v[234:237], v[178:181], v[36:39]
	v_mfma_f32_16x16x32_bf16 v[32:35], v[234:237], v[186:189], v[32:35]
	s_setprio 1
	s_barrier
; #define STAGE(P, BASE, LD, br, kt) do { const char* _g = (const char*)((BASE) + (size_t)(br) * (LD) + (size_t)(kt) * 64); \
;     for (int _i = 0; _i < 2; ++_i) { int _b = tidx * 16 + _i * 8192; int _r, _c; stage_rc(_b, _r, _c); \
;       __builtin_amdgcn_global_load_lds((const unsigned*)(_g + (unsigned)((_r * (LD) + _c) * 2)), (unsigned*)((char*)(P) + _b), 16, 0, 0); } } while (0)
; #define LDA(dst, b, h) for (int m = 0; m < 4; ++m) for (int k = 0; k < 2; ++k) \
;     dst[m][k] = *reinterpret_cast<const bf16x8*>((char*)SA(b, h) + lds_byte(wr * 64 + m * 16 + fr, k * 32 + fq * 8))
; #define LDB(dst, b, h) for (int n = 0; n < 2; ++n) for (int k = 0; k < 2; ++k) \
;     dst[n][k] = *reinterpret_cast<const bf16x8*>((char*)SB(b, h) + lds_byte(wc * 32 + n * 16 + fr, k * 32 + fq * 8))
; #define MMA(ai, bj, At_, Bt_) do { __builtin_amdgcn_s_setprio(1); \
;     for (int k = 0; k < 2; ++k) for (int m = 0; m < 4; ++m) for (int n = 0; n < 2; ++n) \
;       acc[ai][bj][m][n] = __builtin_amdgcn_mfma_f32_16x16x32_bf16(At_[m][k], Bt_[n][k], acc[ai][bj][m][n], 0, 0, 0); \
;     __builtin_amdgcn_s_setprio(0); } while (0)
; #define WAIT_V(n) asm volatile("s_waitcnt vmcnt(" #n ")" ::: "memory")
; #define WAIT_L(n) asm volatile("s_waitcnt lgkmcnt(" #n ")" ::: "memory")
; #define BAR __builtin_amdgcn_s_barrier()
; #define SCHED __builtin_amdgcn_sched_barrier(0)
; template <int EPI, int lda, int ldb, int N, int K>
; __device__ __forceinline__ void gemm_phase(const u16* __restrict__ A, const u16* __restrict__ Bt, const GemmEpi ep, int wv) {
;     ...
;       STAGE(SB(0, 1), Bt, ldb, bcol + HALF, t + 2);
;       WAIT_V(6); BAR; MMA(1, 1, At, B1); BAR;
;       LDB(B0, 1, 0); SCHED; LDA(At, 1, 0); STAGE(SA(0, 1), Ab, lda, brow + HALF, t + 2);
;       WAIT_L(8); BAR; WAIT_L(0); MMA(0, 0, At, B0); BAR; SCHED;
;       LDB(B1, 1, 1); STAGE(SB(1, 0), Bt, ldb, bcol, t + 3);
;       BAR; WAIT_L(0); MMA(0, 1, At, B1); BAR;
	v_add_u32_e32 v167, s41, v155
	v_lshl_add_u64 v[246:247], v[138:139], 0, s[28:29]
	v_readfirstlane_b32 s50, v167
	v_lshl_add_u64 v[168:169], v[246:247], 0, s[16:17]
	s_mov_b32 m0, s50
	v_lshl_add_u64 v[248:249], v[136:137], 0, s[28:29]
	global_load_lds_dwordx4 v[168:169], off
	v_add_u32_e32 v168, 0x2000, v167
	v_lshl_add_u64 v[174:175], v[248:249], 0, s[16:17]
	v_readfirstlane_b32 s50, v168
	s_mov_b32 m0, s50
	s_nop 0
	global_load_lds_dwordx4 v[174:175], off
	s_waitcnt vmcnt(6)
	s_barrier
	s_setprio 0
	v_mfma_f32_16x16x32_bf16 v[28:31], v[190:193], v[218:221], v[28:31]
	v_mfma_f32_16x16x32_bf16 v[24:27], v[190:193], v[226:229], v[24:27]
	v_mfma_f32_16x16x32_bf16 v[20:23], v[198:201], v[218:221], v[20:23]
	v_mfma_f32_16x16x32_bf16 v[16:19], v[198:201], v[226:229], v[16:19]
	v_mfma_f32_16x16x32_bf16 v[12:15], v[206:209], v[218:221], v[12:15]
	v_mfma_f32_16x16x32_bf16 v[8:11], v[206:209], v[226:229], v[8:11]
	v_mfma_f32_16x16x32_bf16 v[4:7], v[214:217], v[218:221], v[4:7]
	v_mfma_f32_16x16x32_bf16 v[0:3], v[214:217], v[226:229], v[0:3]
	v_mfma_f32_16x16x32_bf16 v[28:31], v[194:197], v[222:225], v[28:31]
	v_mfma_f32_16x16x32_bf16 v[24:27], v[194:197], v[230:233], v[24:27]
	v_mfma_f32_16x16x32_bf16 v[20:23], v[202:205], v[222:225], v[20:23]
	v_mfma_f32_16x16x32_bf16 v[16:19], v[202:205], v[230:233], v[16:19]
	v_mfma_f32_16x16x32_bf16 v[12:15], v[210:213], v[222:225], v[12:15]
	v_mfma_f32_16x16x32_bf16 v[8:11], v[210:213], v[230:233], v[8:11]
	v_mfma_f32_16x16x32_bf16 v[4:7], v[234:237], v[222:225], v[4:7]
	v_mfma_f32_16x16x32_bf16 v[0:3], v[234:237], v[230:233], v[0:3]
	s_setprio 1
	s_barrier
	ds_read_b128 v[174:177], v158
	ds_read_b128 v[178:181], v158 offset:1024
	ds_read_b128 v[182:185], v158 offset:2048
	ds_read_b128 v[186:189], v158 offset:3072
	v_add_u32_e32 v169, 0x4000, v149
	v_add_u32_e32 v170, 0x6000, v149
	v_readfirstlane_b32 s50, v169
	v_lshl_add_u64 v[222:223], v[238:239], 0, s[18:19]
	s_mov_b32 m0, s50
	v_readfirstlane_b32 s50, v170
	ds_read_b128 v[190:193], v154 offset:32768
	ds_read_b128 v[194:197], v154 offset:33792
	ds_read_b128 v[198:201], v153 offset:32768
	ds_read_b128 v[202:205], v153 offset:33792
	ds_read_b128 v[206:209], v151 offset:32768
	ds_read_b128 v[210:213], v151 offset:33792
	ds_read_b128 v[214:217], v150 offset:32768
	ds_read_b128 v[218:221], v150 offset:33792
	global_load_lds_dwordx4 v[222:223], off
	v_lshl_add_u64 v[222:223], v[240:241], 0, s[18:19]
	s_mov_b32 m0, s50
	s_nop 0
	global_load_lds_dwordx4 v[222:223], off
	s_waitcnt lgkmcnt(8)
	s_barrier
	s_waitcnt lgkmcnt(0)
	s_setprio 0
	s_waitcnt lgkmcnt(0)
	v_mfma_f32_16x16x32_bf16 v[124:127], v[190:193], v[174:177], v[124:127]
	v_mfma_f32_16x16x32_bf16 v[120:123], v[190:193], v[182:185], v[120:123]
	v_mfma_f32_16x16x32_bf16 v[116:119], v[198:201], v[174:177], v[116:119]
	v_mfma_f32_16x16x32_bf16 v[112:115], v[198:201], v[182:185], v[112:115]
	v_mfma_f32_16x16x32_bf16 v[108:111], v[206:209], v[174:177], v[108:111]
	v_mfma_f32_16x16x32_bf16 v[104:107], v[206:209], v[182:185], v[104:107]
	v_mfma_f32_16x16x32_bf16 v[100:103], v[214:217], v[174:177], v[100:103]
	v_mfma_f32_16x16x32_bf16 v[96:99], v[214:217], v[182:185], v[96:99]
	v_mfma_f32_16x16x32_bf16 v[124:127], v[194:197], v[178:181], v[124:127]
	v_mfma_f32_16x16x32_bf16 v[120:123], v[194:197], v[186:189], v[120:123]
	v_mfma_f32_16x16x32_bf16 v[116:119], v[202:205], v[178:181], v[116:119]
	v_mfma_f32_16x16x32_bf16 v[112:115], v[202:205], v[186:189], v[112:115]
	v_mfma_f32_16x16x32_bf16 v[108:111], v[210:213], v[178:181], v[108:111]
	v_mfma_f32_16x16x32_bf16 v[104:107], v[210:213], v[186:189], v[104:107]
	v_mfma_f32_16x16x32_bf16 v[100:103], v[218:221], v[178:181], v[100:103]
	v_mfma_f32_16x16x32_bf16 v[96:99], v[218:221], v[186:189], v[96:99]
	s_setprio 1
	s_barrier
	v_readfirstlane_b32 s50, v157
	v_add_u32_e32 v173, 0x2000, v157
	v_lshl_add_u64 v[242:243], v[242:243], 0, s[20:21]
	s_mov_b32 m0, s50
	v_readfirstlane_b32 s50, v173
	ds_read_b128 v[222:225], v156
	ds_read_b128 v[226:229], v156 offset:1024
	ds_read_b128 v[230:233], v156 offset:2048
	ds_read_b128 v[234:237], v156 offset:3072
	global_load_lds_dwordx4 v[242:243], off
	v_lshl_add_u64 v[242:243], v[244:245], 0, s[20:21]
	s_mov_b32 m0, s50
	s_nop 0
	global_load_lds_dwordx4 v[242:243], off
	s_barrier
	s_waitcnt lgkmcnt(0)
	s_setprio 0
	s_waitcnt lgkmcnt(0)
	v_mfma_f32_16x16x32_bf16 v[92:95], v[190:193], v[222:225], v[92:95]
	v_mfma_f32_16x16x32_bf16 v[88:91], v[190:193], v[230:233], v[88:91]
	v_mfma_f32_16x16x32_bf16 v[84:87], v[198:201], v[222:225], v[84:87]
	v_mfma_f32_16x16x32_bf16 v[80:83], v[198:201], v[230:233], v[80:83]
	v_mfma_f32_16x16x32_bf16 v[76:79], v[206:209], v[222:225], v[76:79]
	v_mfma_f32_16x16x32_bf16 v[72:75], v[206:209], v[230:233], v[72:75]
	v_mfma_f32_16x16x32_bf16 v[68:71], v[214:217], v[222:225], v[68:71]
	v_mfma_f32_16x16x32_bf16 v[64:67], v[214:217], v[230:233], v[64:67]
	v_mfma_f32_16x16x32_bf16 v[92:95], v[194:197], v[226:229], v[92:95]
	v_mfma_f32_16x16x32_bf16 v[88:91], v[194:197], v[234:237], v[88:91]
	v_mfma_f32_16x16x32_bf16 v[84:87], v[202:205], v[226:229], v[84:87]
	v_mfma_f32_16x16x32_bf16 v[80:83], v[202:205], v[234:237], v[80:83]
	v_mfma_f32_16x16x32_bf16 v[76:79], v[210:213], v[226:229], v[76:79]
	v_mfma_f32_16x16x32_bf16 v[72:75], v[210:213], v[234:237], v[72:75]
	v_mfma_f32_16x16x32_bf16 v[68:71], v[218:221], v[226:229], v[68:71]
	v_mfma_f32_16x16x32_bf16 v[64:67], v[218:221], v[234:237], v[64:67]
	s_setprio 1
	v_readfirstlane_b32 s50, v159
	v_lshl_add_u64 v[238:239], v[238:239], 0, s[22:23]
	s_mov_b32 m0, s50
	v_readfirstlane_b32 s50, v160
	s_barrier
; #define STAGE(P, BASE, LD, br, kt) do { const char* _g = (const char*)((BASE) + (size_t)(br) * (LD) + (size_t)(kt) * 64); \
;     for (int _i = 0; _i < 2; ++_i) { int _b = tidx * 16 + _i * 8192; int _r, _c; stage_rc(_b, _r, _c); \
;       __builtin_amdgcn_global_load_lds((const unsigned*)(_g + (unsigned)((_r * (LD) + _c) * 2)), (unsigned*)((char*)(P) + _b), 16, 0, 0); } } while (0)
; #define LDA(dst, b, h) for (int m = 0; m < 4; ++m) for (int k = 0; k < 2; ++k) \
;     dst[m][k] = *reinterpret_cast<const bf16x8*>((char*)SA(b, h) + lds_byte(wr * 64 + m * 16 + fr, k * 32 + fq * 8))
; #define LDB(dst, b, h) for (int n = 0; n < 2; ++n) for (int k = 0; k < 2; ++k) \
;     dst[n][k] = *reinterpret_cast<const bf16x8*>((char*)SB(b, h) + lds_byte(wc * 32 + n * 16 + fr, k * 32 + fq * 8))
; #define MMA(ai, bj, At_, Bt_) do { __builtin_amdgcn_s_setprio(1); \
;     for (int k = 0; k < 2; ++k) for (int m = 0; m < 4; ++m) for (int n = 0; n < 2; ++n) \
;       acc[ai][bj][m][n] = __builtin_amdgcn_mfma_f32_16x16x32_bf16(At_[m][k], Bt_[n][k], acc[ai][bj][m][n], 0, 0, 0); \
;     __builtin_amdgcn_s_setprio(0); } while (0)
; #define WAIT_V(n) asm volatile("s_waitcnt vmcnt(" #n ")" ::: "memory")
; #define WAIT_L(n) asm volatile("s_waitcnt lgkmcnt(" #n ")" ::: "memory")
; #define BAR __builtin_amdgcn_s_barrier()
; #define SCHED __builtin_amdgcn_sched_barrier(0)
; template <int EPI, int lda, int ldb, int N, int K>
; __device__ __forceinline__ void gemm_phase(const u16* __restrict__ A, const u16* __restrict__ Bt, const GemmEpi ep, int wv) {
;     ...
;       LDA(At, 1, 1); STAGE(SA(1, 0), Ab, lda, brow, t + 3);
;       BAR; WAIT_L(0); MMA(1, 0, At, B0); BAR; SCHED;
;       STAGE(SB(1, 1), Bt, ldb, bcol + HALF, t + 3);
;       WAIT_V(6); BAR; MMA(1, 1, At, B1); BAR;
;     }
;     { LDB(B0, 0, 0); LDA(At, 0, 0); STAGE(SA(1, 1), Ab, lda, brow + HALF, nt - 1);
;       BAR; WAIT_L(0); MMA(0, 0, At, B0); BAR;
;       LDB(B1, 0, 1); BAR; WAIT_L(0); MMA(0, 1, At, B1); BAR;
	ds_read_b128 v[190:193], v154 offset:49152
	ds_read_b128 v[194:197], v154 offset:50176
	ds_read_b128 v[198:201], v153 offset:49152
	ds_read_b128 v[202:205], v153 offset:50176
	ds_read_b128 v[206:209], v151 offset:49152
	ds_read_b128 v[210:213], v151 offset:50176
	ds_read_b128 v[214:217], v150 offset:49152
	ds_read_b128 v[218:221], v150 offset:50176
	global_load_lds_dwordx4 v[238:239], off
	v_lshl_add_u64 v[238:239], v[240:241], 0, s[22:23]
	s_mov_b32 m0, s50
	s_nop 0
	global_load_lds_dwordx4 v[238:239], off
	s_barrier
	s_waitcnt lgkmcnt(0)
	s_setprio 0
	s_waitcnt lgkmcnt(0)
	v_mfma_f32_16x16x32_bf16 v[60:63], v[190:193], v[174:177], v[60:63]
	v_mfma_f32_16x16x32_bf16 v[56:59], v[190:193], v[182:185], v[56:59]
	v_mfma_f32_16x16x32_bf16 v[52:55], v[198:201], v[174:177], v[52:55]
	v_mfma_f32_16x16x32_bf16 v[48:51], v[198:201], v[182:185], v[48:51]
	v_mfma_f32_16x16x32_bf16 v[44:47], v[206:209], v[174:177], v[44:47]
	v_mfma_f32_16x16x32_bf16 v[40:43], v[206:209], v[182:185], v[40:43]
	v_mfma_f32_16x16x32_bf16 v[36:39], v[214:217], v[174:177], v[36:39]
	v_mfma_f32_16x16x32_bf16 v[32:35], v[214:217], v[182:185], v[32:35]
	v_mfma_f32_16x16x32_bf16 v[60:63], v[194:197], v[178:181], v[60:63]
	v_mfma_f32_16x16x32_bf16 v[56:59], v[194:197], v[186:189], v[56:59]
	v_mfma_f32_16x16x32_bf16 v[52:55], v[202:205], v[178:181], v[52:55]
	v_mfma_f32_16x16x32_bf16 v[48:51], v[202:205], v[186:189], v[48:51]
	v_mfma_f32_16x16x32_bf16 v[44:47], v[210:213], v[178:181], v[44:47]
	v_mfma_f32_16x16x32_bf16 v[40:43], v[210:213], v[186:189], v[40:43]
	v_mfma_f32_16x16x32_bf16 v[36:39], v[218:221], v[178:181], v[36:39]
	v_mfma_f32_16x16x32_bf16 v[32:35], v[218:221], v[186:189], v[32:35]
	s_setprio 1
	s_barrier
	v_readfirstlane_b32 s50, v161
	v_add_u32_e32 v173, 0x2000, v161
	v_lshl_add_u64 v[174:175], v[246:247], 0, s[24:25]
	s_mov_b32 m0, s50
	v_readfirstlane_b32 s50, v173
	global_load_lds_dwordx4 v[174:175], off
	v_lshl_add_u64 v[174:175], v[248:249], 0, s[24:25]
	s_mov_b32 m0, s50
	s_nop 0
	global_load_lds_dwordx4 v[174:175], off
	s_waitcnt vmcnt(6)
	s_barrier
	s_setprio 0
	v_mfma_f32_16x16x32_bf16 v[28:31], v[190:193], v[222:225], v[28:31]
	v_mfma_f32_16x16x32_bf16 v[24:27], v[190:193], v[230:233], v[24:27]
	v_mfma_f32_16x16x32_bf16 v[20:23], v[198:201], v[222:225], v[20:23]
	v_mfma_f32_16x16x32_bf16 v[16:19], v[198:201], v[230:233], v[16:19]
	v_mfma_f32_16x16x32_bf16 v[12:15], v[206:209], v[222:225], v[12:15]
	v_mfma_f32_16x16x32_bf16 v[8:11], v[206:209], v[230:233], v[8:11]
	v_mfma_f32_16x16x32_bf16 v[4:7], v[214:217], v[222:225], v[4:7]
	v_mfma_f32_16x16x32_bf16 v[0:3], v[214:217], v[230:233], v[0:3]
	v_mfma_f32_16x16x32_bf16 v[28:31], v[194:197], v[226:229], v[28:31]
	v_mfma_f32_16x16x32_bf16 v[24:27], v[194:197], v[234:237], v[24:27]
	v_mfma_f32_16x16x32_bf16 v[20:23], v[202:205], v[226:229], v[20:23]
	v_mfma_f32_16x16x32_bf16 v[16:19], v[202:205], v[234:237], v[16:19]
	v_mfma_f32_16x16x32_bf16 v[12:15], v[210:213], v[226:229], v[12:15]
	v_mfma_f32_16x16x32_bf16 v[8:11], v[210:213], v[234:237], v[8:11]
	v_mfma_f32_16x16x32_bf16 v[4:7], v[218:221], v[226:229], v[4:7]
	v_mfma_f32_16x16x32_bf16 v[0:3], v[218:221], v[234:237], v[0:3]
	s_setprio 1
	s_add_i32 s49, s49, 2
	s_add_u32 s28, s28, 0x100
	s_addc_u32 s29, s29, 0
	s_cmpk_gt_u32 s49, 0x51
	s_barrier
	s_cbranch_scc0 .LBB0_1624
	s_add_i32 s28, s48, 0x80
	s_mul_hi_i32 s29, s28, 0x2b00
	s_mulk_i32 s28, 0x2b00
	s_add_u32 s28, s34, s28
	s_addc_u32 s29, s35, s29
	s_add_u32 s28, s28, 0x2a80
	s_addc_u32 s29, s29, 0
	v_readfirstlane_b32 s49, v171
	v_lshl_add_u64 v[160:161], s[28:29], 0, v[128:129]
	s_mov_b32 m0, s49
	ds_read_b128 v[132:135], v163
	ds_read_b128 v[136:139], v163 offset:1024
	ds_read_b128 v[140:143], v163 offset:2048
	ds_read_b128 v[174:177], v163 offset:3072
	ds_read_b128 v[178:181], v154
	ds_read_b128 v[182:185], v154 offset:1024
	ds_read_b128 v[186:189], v153
	ds_read_b128 v[190:193], v153 offset:1024
	ds_read_b128 v[194:197], v151
	ds_read_b128 v[198:201], v151 offset:1024
	ds_read_b128 v[202:205], v150
	ds_read_b128 v[206:209], v150 offset:1024
	global_load_lds_dwordx4 v[160:161], off
	v_lshl_add_u64 v[160:161], s[28:29], 0, v[130:131]
	v_readfirstlane_b32 s28, v172
	s_mov_b32 m0, s28
	s_nop 0
	global_load_lds_dwordx4 v[160:161], off
	s_barrier
	s_waitcnt lgkmcnt(0)
	s_setprio 0
	s_waitcnt lgkmcnt(0)
	v_mfma_f32_16x16x32_bf16 v[124:127], v[178:181], v[132:135], v[124:127]
	v_mfma_f32_16x16x32_bf16 v[120:123], v[178:181], v[140:143], v[120:123]
	v_mfma_f32_16x16x32_bf16 v[116:119], v[186:189], v[132:135], v[116:119]
	v_mfma_f32_16x16x32_bf16 v[112:115], v[186:189], v[140:143], v[112:115]
	v_mfma_f32_16x16x32_bf16 v[108:111], v[194:197], v[132:135], v[108:111]
	v_mfma_f32_16x16x32_bf16 v[104:107], v[194:197], v[140:143], v[104:107]
	v_mfma_f32_16x16x32_bf16 v[100:103], v[202:205], v[132:135], v[100:103]
	v_mfma_f32_16x16x32_bf16 v[96:99], v[202:205], v[140:143], v[96:99]
	v_mfma_f32_16x16x32_bf16 v[124:127], v[182:185], v[136:139], v[124:127]
	v_mfma_f32_16x16x32_bf16 v[120:123], v[182:185], v[174:177], v[120:123]
	v_mfma_f32_16x16x32_bf16 v[116:119], v[190:193], v[136:139], v[116:119]
	v_mfma_f32_16x16x32_bf16 v[112:115], v[190:193], v[174:177], v[112:115]
	v_mfma_f32_16x16x32_bf16 v[108:111], v[198:201], v[136:139], v[108:111]
	v_mfma_f32_16x16x32_bf16 v[104:107], v[198:201], v[174:177], v[104:107]
	v_mfma_f32_16x16x32_bf16 v[100:103], v[206:209], v[136:139], v[100:103]
	v_mfma_f32_16x16x32_bf16 v[96:99], v[206:209], v[174:177], v[96:99]
	s_setprio 1
	s_barrier
	ds_read_b128 v[210:213], v162
	ds_read_b128 v[214:217], v162 offset:1024
	ds_read_b128 v[218:221], v162 offset:2048
	ds_read_b128 v[160:163], v162 offset:3072
	s_barrier
; #define LDA(dst, b, h) for (int m = 0; m < 4; ++m) for (int k = 0; k < 2; ++k) \
;     dst[m][k] = *reinterpret_cast<const bf16x8*>((char*)SA(b, h) + lds_byte(wr * 64 + m * 16 + fr, k * 32 + fq * 8))
; #define LDB(dst, b, h) for (int n = 0; n < 2; ++n) for (int k = 0; k < 2; ++k) \
;     dst[n][k] = *reinterpret_cast<const bf16x8*>((char*)SB(b, h) + lds_byte(wc * 32 + n * 16 + fr, k * 32 + fq * 8))
; #define MMA(ai, bj, At_, Bt_) do { __builtin_amdgcn_s_setprio(1); \
;     for (int k = 0; k < 2; ++k) for (int m = 0; m < 4; ++m) for (int n = 0; n < 2; ++n) \
;       acc[ai][bj][m][n] = __builtin_amdgcn_mfma_f32_16x16x32_bf16(At_[m][k], Bt_[n][k], acc[ai][bj][m][n], 0, 0, 0); \
;     __builtin_amdgcn_s_setprio(0); } while (0)
; #define WAIT_V(n) asm volatile("s_waitcnt vmcnt(" #n ")" ::: "memory")
; #define WAIT_L(n) asm volatile("s_waitcnt lgkmcnt(" #n ")" ::: "memory")
; #define BAR __builtin_amdgcn_s_barrier()
; template <int EPI, int lda, int ldb, int N, int K>
; __device__ __forceinline__ void gemm_phase(const u16* __restrict__ A, const u16* __restrict__ Bt, const GemmEpi ep, int wv) {
;     ...
;       LDB(B1, 0, 1); BAR; WAIT_L(0); MMA(0, 1, At, B1); BAR;
;       LDA(At, 0, 1); WAIT_V(4); BAR; WAIT_L(0); MMA(1, 0, At, B0); MMA(1, 1, At, B1); BAR; }
;     { LDB(B0, 1, 0); LDA(At, 1, 0); WAIT_V(2); BAR; WAIT_L(0); MMA(0, 0, At, B0); BAR;
	s_waitcnt lgkmcnt(0)
	s_setprio 0
	s_waitcnt lgkmcnt(0)
	v_mfma_f32_16x16x32_bf16 v[92:95], v[178:181], v[210:213], v[92:95]
	v_mfma_f32_16x16x32_bf16 v[88:91], v[178:181], v[218:221], v[88:91]
	v_mfma_f32_16x16x32_bf16 v[72:75], v[194:197], v[218:221], v[72:75]
	v_mfma_f32_16x16x32_bf16 v[68:71], v[202:205], v[210:213], v[68:71]
	v_mfma_f32_16x16x32_bf16 v[84:87], v[186:189], v[210:213], v[84:87]
	v_mfma_f32_16x16x32_bf16 v[80:83], v[186:189], v[218:221], v[80:83]
	v_mfma_f32_16x16x32_bf16 v[76:79], v[194:197], v[210:213], v[76:79]
	v_mfma_f32_16x16x32_bf16 v[64:67], v[202:205], v[218:221], v[64:67]
	v_mfma_f32_16x16x32_bf16 v[92:95], v[182:185], v[214:217], v[92:95]
	v_mfma_f32_16x16x32_bf16 v[88:91], v[182:185], v[160:163], v[88:91]
	v_mfma_f32_16x16x32_bf16 v[72:75], v[198:201], v[160:163], v[72:75]
	v_mfma_f32_16x16x32_bf16 v[68:71], v[206:209], v[214:217], v[68:71]
	v_mfma_f32_16x16x32_bf16 v[178:181], v[190:193], v[214:217], v[84:87]
	v_mfma_f32_16x16x32_bf16 v[182:185], v[190:193], v[160:163], v[80:83]
	v_mfma_f32_16x16x32_bf16 v[186:189], v[198:201], v[214:217], v[76:79]
	v_mfma_f32_16x16x32_bf16 v[190:193], v[206:209], v[160:163], v[64:67]
	s_setprio 1
	s_barrier
	s_nop 0
	ds_read_b128 v[64:67], v154 offset:16384
	ds_read_b128 v[76:79], v154 offset:17408
	ds_read_b128 v[80:83], v153 offset:16384
	ds_read_b128 v[84:87], v153 offset:17408
	ds_read_b128 v[194:197], v151 offset:16384
	ds_read_b128 v[198:201], v151 offset:17408
	ds_read_b128 v[202:205], v150 offset:16384
	ds_read_b128 v[206:209], v150 offset:17408
	s_waitcnt vmcnt(4)
	s_barrier
	s_waitcnt lgkmcnt(0)
	s_setprio 0
	s_waitcnt lgkmcnt(0)
	v_mfma_f32_16x16x32_bf16 v[60:63], v[64:67], v[132:135], v[60:63]
	v_mfma_f32_16x16x32_bf16 v[56:59], v[64:67], v[140:143], v[56:59]
	v_mfma_f32_16x16x32_bf16 v[52:55], v[80:83], v[132:135], v[52:55]
	v_mfma_f32_16x16x32_bf16 v[48:51], v[80:83], v[140:143], v[48:51]
	v_mfma_f32_16x16x32_bf16 v[44:47], v[194:197], v[132:135], v[44:47]
	v_mfma_f32_16x16x32_bf16 v[40:43], v[194:197], v[140:143], v[40:43]
	v_mfma_f32_16x16x32_bf16 v[36:39], v[202:205], v[132:135], v[36:39]
	v_mfma_f32_16x16x32_bf16 v[32:35], v[202:205], v[140:143], v[32:35]
	v_mfma_f32_16x16x32_bf16 v[60:63], v[76:79], v[136:139], v[60:63]
	v_mfma_f32_16x16x32_bf16 v[56:59], v[76:79], v[174:177], v[56:59]
	v_mfma_f32_16x16x32_bf16 v[52:55], v[84:87], v[136:139], v[52:55]
	v_mfma_f32_16x16x32_bf16 v[48:51], v[84:87], v[174:177], v[48:51]
	v_mfma_f32_16x16x32_bf16 v[44:47], v[198:201], v[136:139], v[44:47]
	v_mfma_f32_16x16x32_bf16 v[40:43], v[198:201], v[174:177], v[40:43]
	v_mfma_f32_16x16x32_bf16 v[36:39], v[206:209], v[136:139], v[36:39]
	v_mfma_f32_16x16x32_bf16 v[32:35], v[206:209], v[174:177], v[32:35]
	s_setprio 1
	s_setprio 0
	v_mfma_f32_16x16x32_bf16 v[28:31], v[64:67], v[210:213], v[28:31]
	v_mfma_f32_16x16x32_bf16 v[24:27], v[64:67], v[218:221], v[24:27]
	v_mfma_f32_16x16x32_bf16 v[12:15], v[194:197], v[210:213], v[12:15]
	v_mfma_f32_16x16x32_bf16 v[8:11], v[194:197], v[218:221], v[8:11]
	v_mfma_f32_16x16x32_bf16 v[20:23], v[80:83], v[210:213], v[20:23]
	v_mfma_f32_16x16x32_bf16 v[16:19], v[80:83], v[218:221], v[16:19]
	v_mfma_f32_16x16x32_bf16 v[4:7], v[202:205], v[210:213], v[4:7]
	v_mfma_f32_16x16x32_bf16 v[0:3], v[202:205], v[218:221], v[0:3]
	v_mfma_f32_16x16x32_bf16 v[28:31], v[76:79], v[214:217], v[28:31]
	v_mfma_f32_16x16x32_bf16 v[24:27], v[76:79], v[160:163], v[24:27]
	v_mfma_f32_16x16x32_bf16 v[12:15], v[198:201], v[214:217], v[12:15]
	v_mfma_f32_16x16x32_bf16 v[8:11], v[198:201], v[160:163], v[8:11]
	v_mfma_f32_16x16x32_bf16 v[132:135], v[84:87], v[214:217], v[20:23]
	v_mfma_f32_16x16x32_bf16 v[136:139], v[84:87], v[160:163], v[16:19]
	v_mfma_f32_16x16x32_bf16 v[140:143], v[206:209], v[214:217], v[4:7]
	v_mfma_f32_16x16x32_bf16 v[160:163], v[206:209], v[160:163], v[0:3]
	s_setprio 1
	s_barrier
	s_nop 0
	ds_read_b128 v[0:3], v158
	ds_read_b128 v[4:7], v158 offset:1024
	ds_read_b128 v[16:19], v158 offset:2048
	ds_read_b128 v[172:175], v158 offset:3072
	ds_read_b128 v[20:23], v154 offset:32768
	ds_read_b128 v[194:197], v154 offset:33792
	ds_read_b128 v[198:201], v153 offset:32768
	ds_read_b128 v[202:205], v153 offset:33792
	ds_read_b128 v[206:209], v151 offset:32768
	ds_read_b128 v[210:213], v151 offset:33792
	ds_read_b128 v[214:217], v150 offset:32768
	ds_read_b128 v[218:221], v150 offset:33792
	s_waitcnt vmcnt(2)
	s_barrier
; #define UNR _Pragma("unroll")
; #define LDA(dst, b, h) for (int m = 0; m < 4; ++m) for (int k = 0; k < 2; ++k) \
;     dst[m][k] = *reinterpret_cast<const bf16x8*>((char*)SA(b, h) + lds_byte(wr * 64 + m * 16 + fr, k * 32 + fq * 8))
; #define LDB(dst, b, h) for (int n = 0; n < 2; ++n) for (int k = 0; k < 2; ++k) \
;     dst[n][k] = *reinterpret_cast<const bf16x8*>((char*)SB(b, h) + lds_byte(wc * 32 + n * 16 + fr, k * 32 + fq * 8))
; #define MMA(ai, bj, At_, Bt_) do { __builtin_amdgcn_s_setprio(1); \
;     for (int k = 0; k < 2; ++k) for (int m = 0; m < 4; ++m) for (int n = 0; n < 2; ++n) \
;       acc[ai][bj][m][n] = __builtin_amdgcn_mfma_f32_16x16x32_bf16(At_[m][k], Bt_[n][k], acc[ai][bj][m][n], 0, 0, 0); \
;     __builtin_amdgcn_s_setprio(0); } while (0)
; #define WAIT_V(n) asm volatile("s_waitcnt vmcnt(" #n ")" ::: "memory")
; #define WAIT_L(n) asm volatile("s_waitcnt lgkmcnt(" #n ")" ::: "memory")
; #define BAR __builtin_amdgcn_s_barrier()
; #define STAGE4(BROW, BCOL, PN) do { const u16* Ab_ = A + (EPI == EPI_RG ? ((PN) >> 1) * 256 : 0); \
;     STAGE(SB(0, 0), Bt, ldb, (BCOL), 0); STAGE(SA(0, 0), Ab_, lda, (BROW), 0); \
;     STAGE(SB(0, 1), Bt, ldb, (BCOL) + HALF, 0); STAGE(SA(0, 1), Ab_, lda, (BROW) + HALF, 0); } while (0)
; template <int EPI, int lda, int ldb, int N, int K>
; __device__ __forceinline__ void gemm_phase(const u16* __restrict__ A, const u16* __restrict__ Bt, const GemmEpi ep, int wv) {
;     ...
;     { LDB(B0, 1, 0); LDA(At, 1, 0); WAIT_V(2); BAR; WAIT_L(0); MMA(0, 0, At, B0); BAR;
;       LDB(B1, 1, 1); WAIT_V(0); BAR; WAIT_L(0); MMA(0, 1, At, B1); BAR;
;       LDA(At, 1, 1); BAR; WAIT_L(0); MMA(1, 0, At, B0); MMA(1, 1, At, B1); BAR; }
;     if (wr == 0) BAR;
;     int ntile = 0, nbrow = 0, nbcol = 0, npn = 0; bool more = false;
;     if constexpr (PF) { ntile = tile + gridDim.x; more = ntile < nwg; if (more) { TILE_COORDS(ntile, nbrow, nbcol, npn); STAGE4(nbrow, nbcol, npn); } }
;     float nss[8];
;     if constexpr (CONS) { UNR for (int pp = 0; pp < 8; ++pp) nss[pp] = 0.f;
;       if (more && tidx < 256) { UNR for (int pp = 0; pp < 8; ++pp) nss[pp] = ep.ss_in[(size_t)pp * T + nbrow + tidx]; } }
	s_waitcnt lgkmcnt(0)
	s_setprio 0
	s_waitcnt lgkmcnt(0)
	v_mfma_f32_16x16x32_bf16 v[64:67], v[20:23], v[0:3], v[124:127]
	v_mfma_f32_16x16x32_bf16 v[76:79], v[20:23], v[16:19], v[120:123]
	v_mfma_f32_16x16x32_bf16 v[80:83], v[198:201], v[0:3], v[116:119]
	v_mfma_f32_16x16x32_bf16 v[84:87], v[198:201], v[16:19], v[112:115]
	v_mfma_f32_16x16x32_bf16 v[108:111], v[206:209], v[0:3], v[108:111]
	v_mfma_f32_16x16x32_bf16 v[104:107], v[206:209], v[16:19], v[104:107]
	v_mfma_f32_16x16x32_bf16 v[120:123], v[214:217], v[0:3], v[100:103]
	v_mfma_f32_16x16x32_bf16 v[124:127], v[214:217], v[16:19], v[96:99]
	v_mfma_f32_16x16x32_bf16 v[116:119], v[194:197], v[4:7], v[64:67]
	v_mfma_f32_16x16x32_bf16 v[112:115], v[194:197], v[172:175], v[76:79]
	v_mfma_f32_16x16x32_bf16 v[100:103], v[202:205], v[4:7], v[80:83]
	v_mfma_f32_16x16x32_bf16 v[96:99], v[202:205], v[172:175], v[84:87]
	v_mfma_f32_16x16x32_bf16 v[84:87], v[210:213], v[4:7], v[108:111]
	v_mfma_f32_16x16x32_bf16 v[80:83], v[210:213], v[172:175], v[104:107]
	v_mfma_f32_16x16x32_bf16 v[76:79], v[218:221], v[4:7], v[120:123]
	v_mfma_f32_16x16x32_bf16 v[64:67], v[218:221], v[172:175], v[124:127]
	s_setprio 1
	s_barrier
	ds_read_b128 v[222:225], v156
	ds_read_b128 v[226:229], v156 offset:1024
	ds_read_b128 v[230:233], v156 offset:2048
	ds_read_b128 v[156:159], v156 offset:3072
	s_waitcnt vmcnt(0)
	s_barrier
	s_waitcnt lgkmcnt(0)
	s_setprio 0
	s_waitcnt lgkmcnt(0)
	v_mfma_f32_16x16x32_bf16 v[92:95], v[20:23], v[222:225], v[92:95]
	v_mfma_f32_16x16x32_bf16 v[20:23], v[20:23], v[230:233], v[88:91]
	v_mfma_f32_16x16x32_bf16 v[88:91], v[198:201], v[222:225], v[178:181]
	v_mfma_f32_16x16x32_bf16 v[104:107], v[198:201], v[230:233], v[182:185]
	v_mfma_f32_16x16x32_bf16 v[176:179], v[206:209], v[222:225], v[186:189]
	v_mfma_f32_16x16x32_bf16 v[72:75], v[206:209], v[230:233], v[72:75]
	v_mfma_f32_16x16x32_bf16 v[68:71], v[214:217], v[222:225], v[68:71]
	v_mfma_f32_16x16x32_bf16 v[180:183], v[214:217], v[230:233], v[190:193]
	v_mfma_f32_16x16x32_bf16 v[124:127], v[194:197], v[226:229], v[92:95]
	v_mfma_f32_16x16x32_bf16 v[120:123], v[194:197], v[156:159], v[20:23]
	v_mfma_f32_16x16x32_bf16 v[108:111], v[202:205], v[226:229], v[88:91]
	v_mfma_f32_16x16x32_bf16 v[104:107], v[202:205], v[156:159], v[104:107]
	v_mfma_f32_16x16x32_bf16 v[92:95], v[210:213], v[226:229], v[176:179]
	v_mfma_f32_16x16x32_bf16 v[88:91], v[210:213], v[156:159], v[72:75]
	v_mfma_f32_16x16x32_bf16 v[72:75], v[218:221], v[226:229], v[68:71]
	v_mfma_f32_16x16x32_bf16 v[68:71], v[218:221], v[156:159], v[180:183]
	s_setprio 1
	s_barrier
	ds_read_b128 v[176:179], v154 offset:49152
	ds_read_b128 v[180:183], v154 offset:50176
	ds_read_b128 v[184:187], v153 offset:49152
	ds_read_b128 v[188:191], v153 offset:50176
	ds_read_b128 v[192:195], v151 offset:49152
	ds_read_b128 v[196:199], v151 offset:50176
	ds_read_b128 v[200:203], v150 offset:49152
	ds_read_b128 v[204:207], v150 offset:50176
	s_barrier
	s_waitcnt lgkmcnt(0)
	s_setprio 0
	s_waitcnt lgkmcnt(0)
	v_mfma_f32_16x16x32_bf16 v[20:23], v[176:179], v[0:3], v[60:63]
	v_mfma_f32_16x16x32_bf16 v[56:59], v[176:179], v[16:19], v[56:59]
	v_mfma_f32_16x16x32_bf16 v[60:63], v[184:187], v[0:3], v[52:55]
	v_mfma_f32_16x16x32_bf16 v[208:211], v[184:187], v[16:19], v[48:51]
	v_mfma_f32_16x16x32_bf16 v[44:47], v[192:195], v[0:3], v[44:47]
	v_mfma_f32_16x16x32_bf16 v[40:43], v[192:195], v[16:19], v[40:43]
	v_mfma_f32_16x16x32_bf16 v[0:3], v[200:203], v[0:3], v[36:39]
	v_mfma_f32_16x16x32_bf16 v[212:215], v[200:203], v[16:19], v[32:35]
	v_mfma_f32_16x16x32_bf16 v[52:55], v[180:183], v[4:7], v[20:23]
	v_mfma_f32_16x16x32_bf16 v[48:51], v[180:183], v[172:175], v[56:59]
	v_mfma_f32_16x16x32_bf16 v[36:39], v[188:191], v[4:7], v[60:63]
	v_mfma_f32_16x16x32_bf16 v[32:35], v[188:191], v[172:175], v[208:211]
	v_mfma_f32_16x16x32_bf16 v[20:23], v[196:199], v[4:7], v[44:47]
	v_mfma_f32_16x16x32_bf16 v[16:19], v[196:199], v[172:175], v[40:43]
	v_mfma_f32_16x16x32_bf16 v[4:7], v[204:207], v[4:7], v[0:3]
	v_mfma_f32_16x16x32_bf16 v[0:3], v[204:207], v[172:175], v[212:215]
	s_setprio 1
	s_setprio 0
	v_mfma_f32_16x16x32_bf16 v[28:31], v[176:179], v[222:225], v[28:31]
	v_mfma_f32_16x16x32_bf16 v[24:27], v[176:179], v[230:233], v[24:27]
	v_mfma_f32_16x16x32_bf16 v[40:43], v[184:187], v[222:225], v[132:135]
	v_mfma_f32_16x16x32_bf16 v[132:135], v[184:187], v[230:233], v[136:139]
	v_mfma_f32_16x16x32_bf16 v[12:15], v[192:195], v[222:225], v[12:15]
	v_mfma_f32_16x16x32_bf16 v[8:11], v[192:195], v[230:233], v[8:11]
	v_mfma_f32_16x16x32_bf16 v[136:139], v[200:203], v[222:225], v[140:143]
	v_mfma_f32_16x16x32_bf16 v[140:143], v[200:203], v[230:233], v[160:163]
	v_mfma_f32_16x16x32_bf16 v[60:63], v[180:183], v[226:229], v[28:31]
	v_mfma_f32_16x16x32_bf16 v[56:59], v[180:183], v[156:159], v[24:27]
	v_mfma_f32_16x16x32_bf16 v[44:47], v[188:191], v[226:229], v[40:43]
	v_mfma_f32_16x16x32_bf16 v[40:43], v[188:191], v[156:159], v[132:135]
	v_mfma_f32_16x16x32_bf16 v[28:31], v[196:199], v[226:229], v[12:15]
	v_mfma_f32_16x16x32_bf16 v[24:27], v[196:199], v[156:159], v[8:11]
	v_mfma_f32_16x16x32_bf16 v[12:15], v[204:207], v[226:229], v[136:139]
	v_mfma_f32_16x16x32_bf16 v[8:11], v[204:207], v[156:159], v[140:143]
	s_setprio 1
	v_cmp_gt_u32_e32 vcc, s46, v147
	s_barrier
	s_and_saveexec_b64 s[28:29], vcc
	s_cbranch_execz .LBB0_1627
	s_barrier
